# 4-slot K/V rings (period-4 unroll), V staged one tile earlier, next tile's first operand fragments prefetched across the barrier, first 4 PV MFMAs above the max tree
# speedup vs baseline: 1.0151x; 1.0151x over previous
; __device__ __forceinline__ void attn_unit(LAS unsigned char* lds, const bf16_t* Z, bf16_t* A2, const float* tabg, int seq_base, int S, int h, int qb, float lam) {
;     const int tid = otid(), w = __builtin_amdgcn_readfirstlane(tid >> 6), lane = tid & 63, r32 = lane & 31, hi = lane >> 5, g4 = lane >> 4, i16 = lane & 15;
;     const int rg = w & 3, m = w >> 2;
;     LAS unsigned char* Kb = lds + OFF_K; LAS unsigned char* Vb = lds + OFF_V;
;     LAS float* scr = (LAS float*)(lds + OFF_SCR) + w * 64;
;     LAS float* tab = (LAS float*)(lds + OFF_TAB);
;     for (int i = tid; i < 449; i += 512) { int d = i - 224; d = d < -128 ? -128 : (d > 128 ? 128 : d); tab[i] = tabg[h * 257 + d + 128]; }
;     const int qlo = qb * 128 + rg * 32;
;     bf16x8 qf[4];
;     { const bf16_t* qrow = Z + (size_t)(seq_base + qlo + r32) * NZ + h * 128 + m * 64 + 8 * hi;
; #pragma unroll
;       for (int ds = 0; ds < 4; ++ds) qf[ds] = *(const bf16x8*)(qrow + 16 * ds); }
;     const char* kvbase = (const char*)(Z + (size_t)seq_base * NZ + h * 128);
;     unsigned koff[2], voff[2];
; #pragma unroll
;     for (int i = 0; i < 2; ++i) { const int row = (i * 8 + w) * 4 + (lane >> 4), cp = lane & 15;
;         koff[i] = (unsigned)(row * NZ + 512 + ((cp ^ (row & 15)) << 3)) * 2u; voff[i] = (unsigned)(row * NZ + 1024 + ((cp ^ (4 * (row & 3))) << 3)) * 2u; }
;     const unsigned kb_u = (unsigned)(size_t)Kb + (unsigned)w * 1024u, vb_u = (unsigned)(size_t)Vb + (unsigned)w * 1024u;
;     ...
;     ATT_STAGE(0, 0); ATT_STAGE(1, 1);
;     asm volatile("s_waitcnt vmcnt(4) lgkmcnt(0)" ::: "memory"); __builtin_amdgcn_s_barrier(); asm volatile("" ::: "memory");
; #pragma unroll
;     for (int ds = 0; ds < 4; ++ds) asm volatile("" : "+v"(qf[ds]));
;     const float tabL = tab[0], tabR = tab[448];
;     f32x16 O[4];
; #pragma unroll
;     for (int d = 0; d < 4; ++d)
; #pragma unroll
;         for (int r = 0; r < 16; ++r) O[d][r] = 0.f;
;     float mu = 0.f; f32x2 ls2 = {0.f, 0.f};
;     f32x16 cblk; float coff_cur = __builtin_nanf("");
; #pragma unroll
;     for (int r = 0; r < 16; ++r) cblk[r] = 0.f;
;     const int NT = S >> 6;
;     const unsigned kfo = r32 * 256 + ((unsigned)((m * 8 + hi) ^ (r32 & 15)) << 4);
;     const unsigned vj = (i16 >> 2) & 3;
;     const unsigned vfo = (4 * hi + (i16 >> 2)) * 256 + (vj << 6) + 32 * (g4 & 1) + 8 * (i16 & 3);
;     int bc = 0, bn = 2;
.LBB0_292:
	s_or_b64 exec, exec, s[8:9]
	s_waitcnt lgkmcnt(0)
	s_add_u32 s8, s4, 0x7800000
	s_addc_u32 s9, s5, 0
	s_lshl_b32 s10, s26, 11
	s_and_b32 s11, s10, 0x2000
	s_and_b32 s10, s25, 32
	s_ashr_i32 s15, s27, 6
	s_or_b32 s10, s10, s23
	s_and_b32 s17, s15, 3
	s_lshl_b32 s14, s10, 7
	s_lshl_b32 s10, s17, 5
	s_or_b32 s34, s10, s14
	v_and_b32_e32 v148, 31, v68
	s_or_b32 s14, s34, s11
	v_or_b32_e32 v2, s14, v148
	s_ashr_i32 s16, s27, 8
	v_lshlrev_b32_e32 v162, 12, v2
	v_lshl_add_u64 v[2:3], s[8:9], 0, v[162:163]
	s_lshl_b32 s48, s30, 8
	s_lshl_b32 s28, s16, 6
	v_bfe_u32 v159, v68, 5, 1
	v_lshl_add_u64 v[2:3], v[2:3], 0, s[48:49]
	s_ashr_i32 s29, s28, 31
	v_lshl_add_u64 v[2:3], s[28:29], 1, v[2:3]
	v_lshlrev_b32_e32 v162, 4, v159
	v_lshl_add_u64 v[2:3], v[2:3], 0, v[162:163]
	global_load_dwordx4 v[116:119], v[2:3], off
	global_load_dwordx4 v[120:123], v[2:3], off offset:32
	global_load_dwordx4 v[124:127], v[2:3], off offset:64
	global_load_dwordx4 v[128:131], v[2:3], off offset:96
	s_lshl_b32 s11, s11, 12
	s_add_u32 s8, s8, s11
	v_bfe_u32 v4, v68, 4, 2
	s_addc_u32 s9, s9, 0
	s_lshl_b32 s11, s15, 2
	v_or_b32_e32 v5, s11, v4
	v_lshlrev_b32_e32 v35, 5, v4
	v_bitop3_b32 v4, s11, v68, v4 bitop3:0x36
	v_lshlrev_b32_e32 v4, 3, v4
	v_and_b32_e32 v34, 15, v68
	v_lshlrev_b32_e32 v5, 11, v5
	v_and_b32_e32 v4, 0x78, v4
	v_lshlrev_b32_e32 v6, 3, v34
	v_or_b32_e32 v7, v4, v5
	v_lshl_or_b32 v149, v7, 1, v249
	v_bitop3_b32 v7, v5, v35, v6 bitop3:0xf6
	v_add_u32_e32 v5, 0x10000, v5
	v_or_b32_e32 v4, v4, v5
	s_add_u32 s8, s8, s48
	v_lshl_or_b32 v161, v4, 1, v249
	v_bitop3_b32 v4, v5, v35, v6 bitop3:0xf6
	s_addc_u32 s9, s9, 0
	s_lshl_b32 s29, s15, 10
	s_add_i32 s11, 0, 0xc000
	v_lshl_or_b32 v160, v7, 1, v250
	v_lshl_or_b32 v176, v4, 1, v250
	s_add_i32 s28, s29, 0
	s_add_i32 s29, s29, s11
	s_mov_b32 s15, m0
	s_mov_b32 m0, s28
	s_nop 0
	global_load_lds_dwordx4 v149, s[8:9]
	s_mov_b32 m0, s29
	s_nop 0
	global_load_lds_dwordx4 v160, s[8:9]
	s_add_u32 m0, s28, 0x2000
	s_nop 0
	global_load_lds_dwordx4 v161, s[8:9]
	s_add_u32 m0, s29, 0x2000
	s_nop 0
	global_load_lds_dwordx4 v176, s[8:9]
	s_mov_b32 m0, s15
	s_add_u32 s36, s8, 0x40000
	s_addc_u32 s37, s9, 0
	s_add_i32 s15, s28, 0x4000
	s_add_i32 s31, s29, 0x4000
	s_mov_b32 s33, m0
	s_mov_b32 m0, s15
	s_nop 0
	global_load_lds_dwordx4 v149, s[36:37]
	s_mov_b32 m0, s31
	s_nop 0
	global_load_lds_dwordx4 v160, s[36:37]
	s_add_u32 m0, s15, 0x2000
	s_nop 0
	global_load_lds_dwordx4 v161, s[36:37]
	s_add_u32 m0, s31, 0x2000
	s_nop 0
	global_load_lds_dwordx4 v176, s[36:37]
	s_mov_b32 m0, s33
	s_mov_b32 s32, m0
	s_mov_b32 s4, s8
	s_add_u32 s8, s8, 0x40000
	s_addc_u32 s9, s9, 0
	s_add_u32 s42, s8, 0x40000
	s_addc_u32 s43, s9, 0
	s_add_u32 m0, s28, 0x8000
	v_add_u32_e32 v172, 0x80000, v149
	global_load_lds_dwordx4 v149, s[42:43]
	s_add_u32 m0, s28, 0xa000
	v_add_u32_e32 v173, 0x80000, v161
	global_load_lds_dwordx4 v161, s[42:43]
	v_add_u32_e32 v174, 0x40000, v160
	v_add_u32_e32 v175, 0x40000, v176
	s_lshl_b32 s15, s30, 7
	s_and_b32 s37, s27, 0x3fffffc0
	s_lshl_b32 s37, s37, 2
	s_add_i32 s30, s37, 0x18000
	v_and_b32_e32 v183, 63, v68
	v_lshl_add_u32 v185, v159, 4, s30
	v_lshl_add_u32 v184, v148, 2, s30
	s_add_i32 s33, s34, 0x9f
	v_add_lshl_u32 v251, s34, v148, 2
	v_lshlrev_b32_e32 v252, 4, v159
	v_sub_u32_e32 v162, v252, v251
	s_add_i32 s34, s34, 0xffffff41
	s_ashr_i32 s11, s34, 6
	s_add_i32 s11, s11, 1
	s_lshl_b32 s11, s11, 6
	s_max_i32 s11, s11, 0
	s_add_i32 s31, s33, 63
	s_andn2_b32 s31, s31, 63
	s_sub_u32 s31, s31, 64
	s_lshr_b32 s10, s11, 6
	s_sub_i32 s10, s10, 2
	s_max_i32 s10, s10, 0
	s_lshl_b32 s37, s16, 3
	v_lshlrev_b32_e32 v19, 8, v148
	v_bitop3_b32 v251, s37, v34, v159 bitop3:0x36
	v_lshlrev_b32_e32 v252, 2, v159
	v_lshrrev_b32_e32 v253, 2, v34
	v_lshlrev_b32_e32 v254, 3, v68
	v_lshl_add_u32 v19, v251, 4, v19
	v_or_b32_e32 v252, v252, v253
	v_and_b32_e32 v254, 24, v254
	v_and_b32_e32 v251, 32, v35
	v_lshlrev_b32_e32 v252, 8, v252
	v_lshl_or_b32 v253, v253, 6, v254
	v_xor_b32_e32 v180, 32, v19
	v_or3_b32 v179, v252, v251, v253
	v_xor_b32_e32 v181, 64, v19
	v_xor_b32_e32 v182, 0x60, v19
	v_add_u32_e32 v228, 0xc000, v179
	v_xor_b32_e32 v229, 0x40, v179
	v_add_u32_e32 v229, 0xc000, v229
	v_xor_b32_e32 v230, 0x80, v179
	v_add_u32_e32 v230, 0xc000, v230
	v_xor_b32_e32 v231, 0xc0, v179
	v_add_u32_e32 v231, 0xc000, v231
	v_add_u32_e32 v164, 0x1d000, v19
	v_add_u32_e32 v168, 0xd000, v228
	v_add_u32_e32 v165, 0x1d000, v180
	v_add_u32_e32 v169, 0xd000, v229
	v_add_u32_e32 v166, 0x1d000, v181
	v_add_u32_e32 v170, 0xd000, v230
	v_add_u32_e32 v167, 0x1d000, v182
	v_add_u32_e32 v171, 0xd000, v231
	v_mov_b64_e32 v[20:21], 0
	v_mov_b64_e32 v[22:23], 0
	v_mov_b64_e32 v[24:25], 0
	v_mov_b64_e32 v[26:27], 0
	v_mov_b64_e32 v[28:29], 0
	v_mov_b64_e32 v[30:31], 0
	v_mov_b64_e32 v[32:33], 0
	v_mov_b64_e32 v[34:35], 0
	v_mov_b64_e32 v[36:37], 0
	v_mov_b64_e32 v[38:39], 0
	v_mov_b64_e32 v[40:41], 0
	v_mov_b64_e32 v[42:43], 0
	v_mov_b64_e32 v[44:45], 0
	v_mov_b64_e32 v[46:47], 0
	v_mov_b64_e32 v[48:49], 0
	v_mov_b64_e32 v[50:51], 0
	v_mov_b64_e32 v[52:53], 0
	v_mov_b64_e32 v[54:55], 0
	v_mov_b64_e32 v[56:57], 0
	v_mov_b64_e32 v[58:59], 0
	v_mov_b64_e32 v[60:61], 0
	v_mov_b64_e32 v[62:63], 0
	v_mov_b64_e32 v[64:65], 0
	v_mov_b64_e32 v[66:67], 0
	v_mov_b64_e32 v[68:69], 0
	v_mov_b64_e32 v[70:71], 0
	v_mov_b64_e32 v[72:73], 0
	v_mov_b64_e32 v[74:75], 0
	v_mov_b64_e32 v[76:77], 0
	v_mov_b64_e32 v[78:79], 0
	v_mov_b64_e32 v[80:81], 0
	v_mov_b64_e32 v[82:83], 0
	v_mov_b64_e32 v[150:151], 0
	v_mov_b32_e32 v186, 0
	s_waitcnt vmcnt(6) lgkmcnt(0)
	s_barrier
; __device__ __forceinline__ void attn_unit(LAS unsigned char* lds, const bf16_t* Z, bf16_t* A2, const float* tabg, int seq_base, int S, int h, int qb, float lam) {
;     ...
;     const float tabL = tab[0], tabR = tab[448];
;     f32x16 O[4];
; #pragma unroll
;     for (int d = 0; d < 4; ++d)
; #pragma unroll
;         for (int r = 0; r < 16; ++r) O[d][r] = 0.f;
;     float mu = 0.f; f32x2 ls2 = {0.f, 0.f};
;     f32x16 cblk; float coff_cur = __builtin_nanf("");
; #pragma unroll
;     for (int r = 0; r < 16; ++r) cblk[r] = 0.f;
;     const int NT = S >> 6;
;     const unsigned kfo = r32 * 256 + ((unsigned)((m * 8 + hi) ^ (r32 & 15)) << 4);
;     const unsigned vj = (i16 >> 2) & 3;
;     const unsigned vfo = (4 * hi + (i16 >> 2)) * 256 + (vj << 6) + 32 * (g4 & 1) + 8 * (i16 & 3);
;     int bc = 0, bn = 2;
;     for (int t = 0; t < NT; ++t) {
;         if (t + 2 < NT) ATT_STAGE(t + 2, bn);
;         const LAS unsigned char* Kt = Kb + bc * KT; const LAS unsigned char* Vt = Vb + bc * VT;
;         const int kv0 = t * 64;
;         bool near = true; float cc = 0.f;
;         if (kv0 - (qlo + 31) >= 128) { near = false; cc = tabR; } else if (qlo - (kv0 + 63) >= 128) { near = false; cc = tabL; }
;         { const float coff = cc - mu;
;           if (__any(!(coff == coff_cur))) { coff_cur = coff;
; #pragma unroll
;               for (int r = 0; r < 16; ++r) cblk[r] = coff;
;               asm volatile("" : "+v"(cblk)); } }
;         f32x16 p0, p1;
;         {
;             bf16x8 kf[8];
; #pragma unroll
;             for (int ds = 0; ds < 4; ++ds) { kf[2 * ds] = *(const LAS bf16x8*)(Kt + (kfo ^ (unsigned)(ds << 5))); kf[2 * ds + 1] = *(const LAS bf16x8*)(Kt + 32 * 256 + (kfo ^ (unsigned)(ds << 5))); }
;             __builtin_amdgcn_sched_barrier(0);
;             p0 = __builtin_amdgcn_mfma_f32_32x32x16_bf16(kf[0], qf[0], cblk, 0, 0, 0);
;             p1 = __builtin_amdgcn_mfma_f32_32x32x16_bf16(kf[1], qf[0], cblk, 0, 0, 0);
; #pragma unroll
;             for (int ds = 1; ds < 4; ++ds) {
;                 p0 = __builtin_amdgcn_mfma_f32_32x32x16_bf16(kf[2 * ds], qf[ds], p0, 0, 0, 0);
;                 p1 = __builtin_amdgcn_mfma_f32_32x32x16_bf16(kf[2 * ds + 1], qf[ds], p1, 0, 0, 0);
;             }
;         }
;     ...
;         const unsigned vbase = (unsigned)(size_t)Vt + vfo;
;         s16x4 va[8], vb[8];
;         VREADS1(va, 0);
;         if (near) {
	v_mov_b32_e32 v187, 0x18800
	ds_read_b32 v177, v187
	ds_read_b32 v178, v187 offset:1792
	ds_read_b128 v[132:135], v19
	ds_read_b128 v[136:139], v19 offset:8192
	ds_read_b128 v[140:143], v180
	ds_read_b128 v[144:147], v180 offset:8192
	ds_read_b128 v[220:223], v181
	ds_read_b128 v[224:227], v181 offset:8192
	ds_read_b128 v[232:235], v182
	ds_read_b128 v[236:239], v182 offset:8192
	s_waitcnt lgkmcnt(8)
	s_cmp_eq_u32 s11, 0
	s_cselect_b32 s37, 0, 1
	s_mov_b32 s35, s37
	v_mov_b32_e32 v251, 0
	s_cmp_eq_u32 s37, 1
	s_cselect_b64 vcc, -1, 0
	v_cndmask_b32_e32 v251, v251, v177, vcc
	s_cmp_eq_u32 s37, 2
	s_cselect_b64 vcc, -1, 0
	v_cndmask_b32_e32 v251, v251, v178, vcc
	v_sub_f32_e32 v2, v251, v186
	v_mov_b32_e32 v3, v2
	v_mov_b64_e32 v[4:5], v[2:3]
	v_mov_b64_e32 v[6:7], v[2:3]
	v_mov_b64_e32 v[8:9], v[2:3]
	v_mov_b64_e32 v[10:11], v[2:3]
	v_mov_b64_e32 v[12:13], v[2:3]
	v_mov_b64_e32 v[14:15], v[2:3]
	v_mov_b64_e32 v[16:17], v[2:3]
	s_waitcnt lgkmcnt(7)
	v_mfma_f32_32x32x16_bf16 v[84:99], v[132:135], v[116:119], v[2:17]
	s_waitcnt lgkmcnt(6)
	v_mfma_f32_32x32x16_bf16 v[100:115], v[136:139], v[116:119], v[2:17]
	s_waitcnt lgkmcnt(5)
	v_mfma_f32_32x32x16_bf16 v[84:99], v[140:143], v[120:123], v[84:99]
	s_waitcnt lgkmcnt(4)
	v_mfma_f32_32x32x16_bf16 v[100:115], v[144:147], v[120:123], v[100:115]
	s_waitcnt lgkmcnt(3)
	v_mfma_f32_32x32x16_bf16 v[84:99], v[220:223], v[124:127], v[84:99]
	s_waitcnt lgkmcnt(2)
	v_mfma_f32_32x32x16_bf16 v[100:115], v[224:227], v[124:127], v[100:115]
	s_waitcnt lgkmcnt(1)
	v_mfma_f32_32x32x16_bf16 v[84:99], v[232:235], v[128:131], v[84:99]
	s_waitcnt lgkmcnt(0)
	v_mfma_f32_32x32x16_bf16 v[100:115], v[236:239], v[128:131], v[100:115]
	s_nop 15
	s_nop 15
	s_mov_b32 s5, 0
	s_cmp_lg_u32 s11, 0
	s_cbranch_scc1 .LatA_p0_nonear
	s_lshl_b32 s38, s5, 2
	s_add_i32 s38, s38, 0x18b80
	v_add_u32_e32 v187, s38, v162
	ds_read2_b32 v[196:197], v187 offset0:0 offset1:1
	ds_read2_b32 v[198:199], v187 offset0:2 offset1:3
	ds_read2_b32 v[200:201], v187 offset0:8 offset1:9
	ds_read2_b32 v[202:203], v187 offset0:10 offset1:11
	ds_read2_b32 v[212:213], v187 offset0:16 offset1:17
	ds_read2_b32 v[214:215], v187 offset0:18 offset1:19
	ds_read2_b32 v[216:217], v187 offset0:24 offset1:25
	ds_read2_b32 v[218:219], v187 offset0:26 offset1:27
	s_waitcnt lgkmcnt(0)
	v_pk_add_f32 v[84:85], v[84:85], v[196:197]
	v_pk_add_f32 v[86:87], v[86:87], v[198:199]
	v_pk_add_f32 v[88:89], v[88:89], v[200:201]
	v_pk_add_f32 v[90:91], v[90:91], v[202:203]
	v_pk_add_f32 v[92:93], v[92:93], v[212:213]
	v_pk_add_f32 v[94:95], v[94:95], v[214:215]
	v_pk_add_f32 v[96:97], v[96:97], v[216:217]
	v_pk_add_f32 v[98:99], v[98:99], v[218:219]
	ds_read2_b32 v[196:197], v187 offset0:32 offset1:33
	ds_read2_b32 v[198:199], v187 offset0:34 offset1:35
	ds_read2_b32 v[200:201], v187 offset0:40 offset1:41
	ds_read2_b32 v[202:203], v187 offset0:42 offset1:43
	ds_read2_b32 v[212:213], v187 offset0:48 offset1:49
	ds_read2_b32 v[214:215], v187 offset0:50 offset1:51
	ds_read2_b32 v[216:217], v187 offset0:56 offset1:57
	ds_read2_b32 v[218:219], v187 offset0:58 offset1:59
	s_waitcnt lgkmcnt(0)
	v_pk_add_f32 v[100:101], v[100:101], v[196:197]
	v_pk_add_f32 v[102:103], v[102:103], v[198:199]
	v_pk_add_f32 v[104:105], v[104:105], v[200:201]
	v_pk_add_f32 v[106:107], v[106:107], v[202:203]
	v_pk_add_f32 v[108:109], v[108:109], v[212:213]
	v_pk_add_f32 v[110:111], v[110:111], v[214:215]
	v_pk_add_f32 v[112:113], v[112:113], v[216:217]
	v_pk_add_f32 v[114:115], v[114:115], v[218:219]

; #define LAS __attribute__((address_space(3)))
; __device__ __forceinline__ void attn_unit(LAS unsigned char* lds, const bf16_t* Z, bf16_t* A2, const float* tabg, int seq_base, int S, int h, int qb, float lam) {
;     ...
;         if (t + 2 < NT) ATT_STAGE(t + 2, bn);
;         const LAS unsigned char* Kt = Kb + bc * KT; const LAS unsigned char* Vt = Vb + bc * VT;
;         const int kv0 = t * 64;
;         bool near = true; float cc = 0.f;
;         if (kv0 - (qlo + 31) >= 128) { near = false; cc = tabR; } else if (qlo - (kv0 + 63) >= 128) { near = false; cc = tabL; }
;         { const float coff = cc - mu;
;           if (__any(!(coff == coff_cur))) { coff_cur = coff;
; #pragma unroll
;               for (int r = 0; r < 16; ++r) cblk[r] = coff;
;               asm volatile("" : "+v"(cblk)); } }
;         f32x16 p0, p1;
;         {
;             bf16x8 kf[8];
; #pragma unroll
;             for (int ds = 0; ds < 4; ++ds) { kf[2 * ds] = *(const LAS bf16x8*)(Kt + (kfo ^ (unsigned)(ds << 5))); kf[2 * ds + 1] = *(const LAS bf16x8*)(Kt + 32 * 256 + (kfo ^ (unsigned)(ds << 5))); }
;             __builtin_amdgcn_sched_barrier(0);
;             p0 = __builtin_amdgcn_mfma_f32_32x32x16_bf16(kf[0], qf[0], cblk, 0, 0, 0);
;             p1 = __builtin_amdgcn_mfma_f32_32x32x16_bf16(kf[1], qf[0], cblk, 0, 0, 0);
; #pragma unroll
;             for (int ds = 1; ds < 4; ++ds) {
;                 p0 = __builtin_amdgcn_mfma_f32_32x32x16_bf16(kf[2 * ds], qf[ds], p0, 0, 0, 0);
;                 p1 = __builtin_amdgcn_mfma_f32_32x32x16_bf16(kf[2 * ds + 1], qf[ds], p1, 0, 0, 0);
;             }
;         }
;     ...
;         const unsigned vbase = (unsigned)(size_t)Vt + vfo;
;         s16x4 va[8], vb[8];
;         VREADS1(va, 0);
;         if (near) {
;             const LAS float* tp = tab + (kv0 + 4 * hi - (qlo + r32) + 224);
; #pragma unroll
;             for (int r = 0; r < 16; ++r) { p0[r] += tp[(r & 3) + 8 * (r >> 2)]; p1[r] += tp[32 + (r & 3) + 8 * (r >> 2)]; }
;         }
;         float mx = max2f(max16f(p0), max16f(p1));
;         const bool first = (t == 0);
;         if (first || __any(mx > THR)) {
;     ...
;         for (int r = 0; r < 16; ++r) { p0[r] = __builtin_amdgcn_exp2f(p0[r]); p1[r] = __builtin_amdgcn_exp2f(p1[r]); }
; #pragma unroll
;         for (int r = 0; r < 16; r += 2) { ls2 += (f32x2){p0[r], p0[r + 1]}; ls2 += (f32x2){p1[r], p1[r + 1]}; }
.LatA_rareret_h0:
	s_waitcnt lgkmcnt(6)
	s_add_u32 m0, s28, 0x1d000
	v_mfma_f32_32x32x16_bf16 v[188:203], v[132:135], v[116:119], v[2:17]
	global_load_lds_dwordx4 v172, s[8:9]
	ds_read_b128 v[236:239], v182 offset:24576
	v_exp_f32_e32 v84, v84
	v_exp_f32_e32 v85, v85
	v_exp_f32_e32 v86, v86
	v_exp_f32_e32 v87, v87
	v_pk_add_f32 v[150:151], v[150:151], v[84:85]
	v_pk_add_f32 v[150:151], v[150:151], v[86:87]
	v_exp_f32_e32 v88, v88
	s_waitcnt lgkmcnt(6)
	s_add_u32 m0, s29, 0x8000
	v_mfma_f32_32x32x16_bf16 v[204:219], v[136:139], v[116:119], v[2:17]
	global_load_lds_dwordx4 v174, s[8:9]
	ds_read_b64_tr_b16 v[132:133], v228 offset:0
	ds_read_b64_tr_b16 v[134:135], v228 offset:2048
	v_exp_f32_e32 v89, v89
	v_cvt_pk_bf16_f32 v84, v84, v85
	v_cvt_pk_bf16_f32 v85, v86, v87
	v_exp_f32_e32 v90, v90
	v_exp_f32_e32 v91, v91
	v_pk_add_f32 v[150:151], v[150:151], v[88:89]
	v_pk_add_f32 v[150:151], v[150:151], v[90:91]
	v_cvt_pk_bf16_f32 v86, v88, v89
	v_cvt_pk_bf16_f32 v87, v90, v91
	s_waitcnt lgkmcnt(7)
	s_add_u32 m0, s28, 0x1f000
	v_mfma_f32_32x32x16_bf16 v[188:203], v[140:143], v[120:123], v[188:203]
	global_load_lds_dwordx4 v173, s[8:9]
	ds_read_b64_tr_b16 v[136:137], v229 offset:0
	ds_read_b64_tr_b16 v[138:139], v229 offset:2048
	v_exp_f32_e32 v92, v92
	v_exp_f32_e32 v93, v93
	v_exp_f32_e32 v94, v94
	v_exp_f32_e32 v95, v95
	v_pk_add_f32 v[150:151], v[150:151], v[92:93]
	v_pk_add_f32 v[150:151], v[150:151], v[94:95]
	v_exp_f32_e32 v96, v96
	s_waitcnt lgkmcnt(8)
	s_add_u32 m0, s29, 0xa000
	v_mfma_f32_32x32x16_bf16 v[204:219], v[144:147], v[120:123], v[204:219]
	global_load_lds_dwordx4 v175, s[8:9]
	ds_read_b64_tr_b16 v[140:141], v230 offset:0
	ds_read_b64_tr_b16 v[142:143], v230 offset:2048
	v_exp_f32_e32 v97, v97
	v_cvt_pk_bf16_f32 v88, v92, v93
	v_cvt_pk_bf16_f32 v89, v94, v95
	v_exp_f32_e32 v98, v98
	v_exp_f32_e32 v99, v99
	v_pk_add_f32 v[150:151], v[150:151], v[96:97]
	v_pk_add_f32 v[150:151], v[150:151], v[98:99]
	v_cvt_pk_bf16_f32 v90, v96, v97
	v_cvt_pk_bf16_f32 v91, v98, v99
	s_waitcnt lgkmcnt(9)
	v_mfma_f32_32x32x16_bf16 v[188:203], v[220:223], v[124:127], v[188:203]
	ds_read_b64_tr_b16 v[144:145], v231 offset:0
	ds_read_b64_tr_b16 v[146:147], v231 offset:2048
	v_exp_f32_e32 v100, v100
	v_exp_f32_e32 v101, v101
	v_exp_f32_e32 v102, v102
	v_exp_f32_e32 v103, v103
	v_pk_add_f32 v[150:151], v[150:151], v[100:101]
	v_pk_add_f32 v[150:151], v[150:151], v[102:103]
	v_exp_f32_e32 v104, v104
	s_waitcnt lgkmcnt(10)
	v_mfma_f32_32x32x16_bf16 v[204:219], v[224:227], v[124:127], v[204:219]
	ds_read_b64_tr_b16 v[220:221], v228 offset:4096
	ds_read_b64_tr_b16 v[222:223], v228 offset:6144
	v_exp_f32_e32 v105, v105
	v_cvt_pk_bf16_f32 v100, v100, v101
	v_cvt_pk_bf16_f32 v101, v102, v103
	v_exp_f32_e32 v106, v106
	v_exp_f32_e32 v107, v107
	v_pk_add_f32 v[150:151], v[150:151], v[104:105]
	v_pk_add_f32 v[150:151], v[150:151], v[106:107]
	v_cvt_pk_bf16_f32 v102, v104, v105
	v_cvt_pk_bf16_f32 v103, v106, v107
	s_waitcnt lgkmcnt(11)
	v_mfma_f32_32x32x16_bf16 v[188:203], v[232:235], v[128:131], v[188:203]
	ds_read_b64_tr_b16 v[224:225], v229 offset:4096
	ds_read_b64_tr_b16 v[226:227], v229 offset:6144
	v_exp_f32_e32 v108, v108
	v_exp_f32_e32 v109, v109
	v_exp_f32_e32 v110, v110
	v_exp_f32_e32 v111, v111
	v_pk_add_f32 v[150:151], v[150:151], v[108:109]
	v_pk_add_f32 v[150:151], v[150:151], v[110:111]
	v_exp_f32_e32 v112, v112
	s_waitcnt lgkmcnt(12)
	v_mfma_f32_32x32x16_bf16 v[204:219], v[236:239], v[128:131], v[204:219]
	ds_read_b64_tr_b16 v[232:233], v230 offset:4096
	ds_read_b64_tr_b16 v[234:235], v230 offset:6144
	v_exp_f32_e32 v113, v113
	v_cvt_pk_bf16_f32 v104, v108, v109
	v_cvt_pk_bf16_f32 v105, v110, v111
	v_exp_f32_e32 v114, v114
	v_exp_f32_e32 v115, v115
	v_pk_add_f32 v[150:151], v[150:151], v[112:113]
	v_pk_add_f32 v[150:151], v[150:151], v[114:115]
	v_cvt_pk_bf16_f32 v106, v112, v113
	v_cvt_pk_bf16_f32 v107, v114, v115
	s_add_u32 s8, s8, 0x40000
	s_addc_u32 s9, s9, 0
	s_waitcnt vmcnt(4)
	s_barrier
	s_sub_u32 s10, s10, 1
	s_cbranch_scc1 .LatA_evs_h1
.LatA_evret_h1:
	s_waitcnt lgkmcnt(12)
	v_mfma_f32_32x32x16_bf16 v[20:35], v[84:87], v[132:135], v[20:35]
	ds_read_b64_tr_b16 v[236:237], v231 offset:4096
	ds_read_b64_tr_b16 v[238:239], v231 offset:6144
	s_waitcnt lgkmcnt(12)
	v_mfma_f32_32x32x16_bf16 v[36:51], v[84:87], v[136:139], v[36:51]
	ds_read_b64_tr_b16 v[132:133], v228 offset:8192
	ds_read_b64_tr_b16 v[134:135], v228 offset:10240
	s_waitcnt lgkmcnt(12)
	v_mfma_f32_32x32x16_bf16 v[52:67], v[84:87], v[140:143], v[52:67]
	ds_read_b64_tr_b16 v[136:137], v229 offset:8192
	ds_read_b64_tr_b16 v[138:139], v229 offset:10240
	s_waitcnt lgkmcnt(12)
	s_mov_b32 m0, s28
	v_mfma_f32_32x32x16_bf16 v[68:83], v[84:87], v[144:147], v[68:83]
	global_load_lds_dwordx4 v172, s[8:9]
	ds_read_b64_tr_b16 v[140:141], v230 offset:8192
	ds_read_b64_tr_b16 v[142:143], v230 offset:10240
	v_max3_f32 v251, v188, v189, v190
	v_max3_f32 v252, v191, v192, v193
	v_max3_f32 v251, v251, v194, v195
	v_max3_f32 v252, v252, v196, v197
	v_max3_f32 v251, v251, v198, v199
	v_max3_f32 v252, v252, v200, v201
	v_max3_f32 v251, v251, v202, v203
	v_max3_f32 v252, v252, v204, v205
	v_max3_f32 v251, v251, v206, v207
	v_max3_f32 v252, v252, v208, v209
	v_max3_f32 v251, v251, v210, v211
	v_max3_f32 v252, v252, v212, v213
	v_max3_f32 v251, v251, v214, v215
	v_max3_f32 v252, v252, v216, v217
	v_max3_f32 v251, v251, v218, v219
	v_max_f32_e32 v251, v251, v252
	v_cmp_lt_f32_e32 vcc, 0x41000000, v251
	s_cbranch_vccnz .LatA_rs_h1
; #define LAS __attribute__((address_space(3)))
; #define VREADS1(arr, d_) do { const unsigned ad_ = vbase ^ (unsigned)((d_) << 6); __builtin_amdgcn_sched_barrier(0); \
;         _Pragma("unroll") for (int ks_ = 0; ks_ < 4; ++ks_) { VTR(arr[ks_ * 2], ad_, ks_ * 4096); VTR(arr[ks_ * 2 + 1], ad_, ks_ * 4096 + 2048); } __builtin_amdgcn_sched_barrier(0); } while (0)
; #define PV1(arr, d_) do { _Pragma("unroll") for (int ks_ = 0; ks_ < 4; ++ks_) { const s16x4 lo_ = arr[ks_ * 2], hh_ = arr[ks_ * 2 + 1]; \
;         const bf16x8 bv_ = (bf16x8){lo_[0], lo_[1], lo_[2], lo_[3], hh_[0], hh_[1], hh_[2], hh_[3]}; \
;         O[d_] = __builtin_amdgcn_mfma_f32_32x32x16_bf16(pa[ks_], bv_, O[d_], 0, 0, 0); } __builtin_amdgcn_sched_barrier(0); } while (0)
; __device__ __forceinline__ void attn_unit(LAS unsigned char* lds, const bf16_t* Z, bf16_t* A2, const float* tabg, int seq_base, int S, int h, int qb, float lam) {
;     ...
;             for (int ds = 0; ds < 4; ++ds) { kf[2 * ds] = *(const LAS bf16x8*)(Kt + (kfo ^ (unsigned)(ds << 5))); kf[2 * ds + 1] = *(const LAS bf16x8*)(Kt + 32 * 256 + (kfo ^ (unsigned)(ds << 5))); }
;             __builtin_amdgcn_sched_barrier(0);
;             p0 = __builtin_amdgcn_mfma_f32_32x32x16_bf16(kf[0], qf[0], cblk, 0, 0, 0);
;             p1 = __builtin_amdgcn_mfma_f32_32x32x16_bf16(kf[1], qf[0], cblk, 0, 0, 0);
; #pragma unroll
;             for (int ds = 1; ds < 4; ++ds) {
;                 p0 = __builtin_amdgcn_mfma_f32_32x32x16_bf16(kf[2 * ds], qf[ds], p0, 0, 0, 0);
;                 p1 = __builtin_amdgcn_mfma_f32_32x32x16_bf16(kf[2 * ds + 1], qf[ds], p1, 0, 0, 0);
;             }
;     ...
; #pragma unroll
;         for (int r = 0; r < 16; ++r) { p0[r] = __builtin_amdgcn_exp2f(p0[r]); p1[r] = __builtin_amdgcn_exp2f(p1[r]); }
; #pragma unroll
;         for (int r = 0; r < 16; r += 2) { ls2 += (f32x2){p0[r], p0[r + 1]}; ls2 += (f32x2){p1[r], p1[r + 1]}; }
;         bf16x8 pa[4]; pa[0] = pack8(p0, 0); pa[1] = pack8(p0, 8); pa[2] = pack8(p1, 0); pa[3] = pack8(p1, 8);
;         LGKM0(); VREADS1(vb, 1); PV1(va, 0); LGKM0(); VREADS1(va, 2); PV1(vb, 1); LGKM0(); VREADS1(vb, 3); PV1(va, 2); LGKM0(); PV1(vb, 3);
;     ...
;         if (t + 2 < NT) asm volatile("s_waitcnt vmcnt(4) lgkmcnt(0)" ::: "memory"); else asm volatile("s_waitcnt vmcnt(0) lgkmcnt(0)" ::: "memory");
;         __builtin_amdgcn_s_barrier(); asm volatile("" ::: "memory");
.LatA_rareret_h1:
	s_waitcnt lgkmcnt(12)
	v_mfma_f32_32x32x16_bf16 v[20:35], v[88:91], v[220:223], v[20:35]
	ds_read_b64_tr_b16 v[144:145], v231 offset:8192
	ds_read_b64_tr_b16 v[146:147], v231 offset:10240
	v_exp_f32_e32 v188, v188
	v_exp_f32_e32 v189, v189
	v_exp_f32_e32 v190, v190
	s_waitcnt lgkmcnt(12)
	v_mfma_f32_32x32x16_bf16 v[36:51], v[88:91], v[224:227], v[36:51]
	ds_read_b64_tr_b16 v[220:221], v228 offset:12288
	ds_read_b64_tr_b16 v[222:223], v228 offset:14336
	v_exp_f32_e32 v191, v191
	v_pk_add_f32 v[150:151], v[150:151], v[188:189]
	s_waitcnt lgkmcnt(12)
	v_mfma_f32_32x32x16_bf16 v[52:67], v[88:91], v[232:235], v[52:67]
	ds_read_b64_tr_b16 v[224:225], v229 offset:12288
	ds_read_b64_tr_b16 v[226:227], v229 offset:14336
	v_pk_add_f32 v[150:151], v[150:151], v[190:191]
	v_exp_f32_e32 v192, v192
	v_exp_f32_e32 v193, v193
	v_cvt_pk_bf16_f32 v188, v188, v189
	s_waitcnt lgkmcnt(12)
	s_add_u32 m0, s29, 0xd000
	v_mfma_f32_32x32x16_bf16 v[68:83], v[88:91], v[236:239], v[68:83]
	global_load_lds_dwordx4 v174, s[8:9]
	ds_read_b64_tr_b16 v[232:233], v230 offset:12288
	ds_read_b64_tr_b16 v[234:235], v230 offset:14336
	v_cvt_pk_bf16_f32 v189, v190, v191
	v_exp_f32_e32 v194, v194
	v_exp_f32_e32 v195, v195
	s_waitcnt lgkmcnt(12)
	v_mfma_f32_32x32x16_bf16 v[20:35], v[100:103], v[132:135], v[20:35]
	ds_read_b64_tr_b16 v[236:237], v231 offset:12288
	ds_read_b64_tr_b16 v[238:239], v231 offset:14336
	v_pk_add_f32 v[150:151], v[150:151], v[192:193]
	v_pk_add_f32 v[150:151], v[150:151], v[194:195]
	v_cvt_pk_bf16_f32 v190, v192, v193
	v_cvt_pk_bf16_f32 v191, v194, v195
	s_waitcnt lgkmcnt(12)
	v_mfma_f32_32x32x16_bf16 v[36:51], v[100:103], v[136:139], v[36:51]
	ds_read_b128 v[132:135], v19 offset:32768
	v_exp_f32_e32 v196, v196
	v_exp_f32_e32 v197, v197
	v_exp_f32_e32 v198, v198
	s_waitcnt lgkmcnt(11)
	v_mfma_f32_32x32x16_bf16 v[52:67], v[100:103], v[140:143], v[52:67]
	ds_read_b128 v[136:139], v19 offset:40960
	v_exp_f32_e32 v199, v199
	v_pk_add_f32 v[150:151], v[150:151], v[196:197]
	s_waitcnt lgkmcnt(10)
	s_add_u32 m0, s28, 0x2000
	v_mfma_f32_32x32x16_bf16 v[68:83], v[100:103], v[144:147], v[68:83]
	global_load_lds_dwordx4 v173, s[8:9]
	ds_read_b128 v[140:143], v180 offset:32768
	v_pk_add_f32 v[150:151], v[150:151], v[198:199]
	v_exp_f32_e32 v200, v200
	v_exp_f32_e32 v201, v201
	v_cvt_pk_bf16_f32 v192, v196, v197
	s_waitcnt lgkmcnt(9)
	v_mfma_f32_32x32x16_bf16 v[20:35], v[104:107], v[220:223], v[20:35]
	ds_read_b128 v[144:147], v180 offset:40960
	v_cvt_pk_bf16_f32 v193, v198, v199
	v_exp_f32_e32 v202, v202
	v_exp_f32_e32 v203, v203
	s_waitcnt lgkmcnt(8)
	v_mfma_f32_32x32x16_bf16 v[36:51], v[104:107], v[224:227], v[36:51]
	ds_read_b128 v[220:223], v181 offset:32768
	v_pk_add_f32 v[150:151], v[150:151], v[200:201]
	v_pk_add_f32 v[150:151], v[150:151], v[202:203]
	v_cvt_pk_bf16_f32 v194, v200, v201
	v_cvt_pk_bf16_f32 v195, v202, v203
	s_waitcnt lgkmcnt(7)
	v_mfma_f32_32x32x16_bf16 v[52:67], v[104:107], v[232:235], v[52:67]
	ds_read_b128 v[224:227], v181 offset:40960
	v_exp_f32_e32 v204, v204
	v_exp_f32_e32 v205, v205
	v_exp_f32_e32 v206, v206
	s_waitcnt lgkmcnt(6)
	s_add_u32 m0, s29, 0xf000
	v_mfma_f32_32x32x16_bf16 v[68:83], v[104:107], v[236:239], v[68:83]
	global_load_lds_dwordx4 v175, s[8:9]
	ds_read_b128 v[232:235], v182 offset:32768
	v_exp_f32_e32 v207, v207
	v_pk_add_f32 v[150:151], v[150:151], v[204:205]
	s_waitcnt lgkmcnt(6)
	v_mfma_f32_32x32x16_bf16 v[84:99], v[132:135], v[116:119], v[2:17]
	ds_read_b128 v[236:239], v182 offset:40960
	v_pk_add_f32 v[150:151], v[150:151], v[206:207]
	v_exp_f32_e32 v208, v208
	v_exp_f32_e32 v209, v209
	v_cvt_pk_bf16_f32 v204, v204, v205
	s_waitcnt lgkmcnt(6)
	v_mfma_f32_32x32x16_bf16 v[100:115], v[136:139], v[116:119], v[2:17]
	ds_read_b64_tr_b16 v[132:133], v228 offset:16384
	ds_read_b64_tr_b16 v[134:135], v228 offset:18432
	v_cvt_pk_bf16_f32 v205, v206, v207
	v_exp_f32_e32 v210, v210
	v_exp_f32_e32 v211, v211
	s_waitcnt lgkmcnt(7)
	v_mfma_f32_32x32x16_bf16 v[84:99], v[140:143], v[120:123], v[84:99]
	ds_read_b64_tr_b16 v[136:137], v229 offset:16384
	ds_read_b64_tr_b16 v[138:139], v229 offset:18432
	v_pk_add_f32 v[150:151], v[150:151], v[208:209]
	v_pk_add_f32 v[150:151], v[150:151], v[210:211]
	v_cvt_pk_bf16_f32 v206, v208, v209
	v_cvt_pk_bf16_f32 v207, v210, v211
	s_waitcnt lgkmcnt(8)
	v_mfma_f32_32x32x16_bf16 v[100:115], v[144:147], v[120:123], v[100:115]
	ds_read_b64_tr_b16 v[140:141], v230 offset:16384
	ds_read_b64_tr_b16 v[142:143], v230 offset:18432
	v_exp_f32_e32 v212, v212
	v_exp_f32_e32 v213, v213
	v_exp_f32_e32 v214, v214
	s_waitcnt lgkmcnt(9)
	v_mfma_f32_32x32x16_bf16 v[84:99], v[220:223], v[124:127], v[84:99]
	ds_read_b64_tr_b16 v[144:145], v231 offset:16384
	ds_read_b64_tr_b16 v[146:147], v231 offset:18432
	v_exp_f32_e32 v215, v215
	v_pk_add_f32 v[150:151], v[150:151], v[212:213]
	s_waitcnt lgkmcnt(10)
	v_mfma_f32_32x32x16_bf16 v[100:115], v[224:227], v[124:127], v[100:115]
	ds_read_b64_tr_b16 v[220:221], v228 offset:20480
	ds_read_b64_tr_b16 v[222:223], v228 offset:22528
	v_pk_add_f32 v[150:151], v[150:151], v[214:215]
	v_exp_f32_e32 v216, v216
	v_exp_f32_e32 v217, v217
	v_cvt_pk_bf16_f32 v208, v212, v213
	s_waitcnt lgkmcnt(11)
	v_mfma_f32_32x32x16_bf16 v[84:99], v[232:235], v[128:131], v[84:99]
	ds_read_b64_tr_b16 v[224:225], v229 offset:20480
	ds_read_b64_tr_b16 v[226:227], v229 offset:22528
	v_cvt_pk_bf16_f32 v209, v214, v215
	v_exp_f32_e32 v218, v218
	v_exp_f32_e32 v219, v219
	s_waitcnt lgkmcnt(12)
	v_mfma_f32_32x32x16_bf16 v[100:115], v[236:239], v[128:131], v[100:115]
	ds_read_b64_tr_b16 v[232:233], v230 offset:20480
	ds_read_b64_tr_b16 v[234:235], v230 offset:22528
	v_pk_add_f32 v[150:151], v[150:151], v[216:217]
	v_pk_add_f32 v[150:151], v[150:151], v[218:219]
	v_cvt_pk_bf16_f32 v210, v216, v217
	v_cvt_pk_bf16_f32 v211, v218, v219
	s_add_u32 s8, s8, 0x40000
	s_addc_u32 s9, s9, 0
	s_waitcnt vmcnt(4)
	s_barrier
	s_sub_u32 s10, s10, 1
	s_cbranch_scc1 .LatA_evs_h2
; #define LAS __attribute__((address_space(3)))
; __device__ __forceinline__ float max2f(float a, float b) { float r; asm("v_max_f32_e32 %0, %1, %2" : "=v"(r) : "v"(a), "v"(b)); return r; }
; __device__ __forceinline__ void attn_unit(LAS unsigned char* lds, const bf16_t* Z, bf16_t* A2, const float* tabg, int seq_base, int S, int h, int qb, float lam) {
;     ...
;             for (int ds = 0; ds < 4; ++ds) { kf[2 * ds] = *(const LAS bf16x8*)(Kt + (kfo ^ (unsigned)(ds << 5))); kf[2 * ds + 1] = *(const LAS bf16x8*)(Kt + 32 * 256 + (kfo ^ (unsigned)(ds << 5))); }
;             __builtin_amdgcn_sched_barrier(0);
;             p0 = __builtin_amdgcn_mfma_f32_32x32x16_bf16(kf[0], qf[0], cblk, 0, 0, 0);
;             p1 = __builtin_amdgcn_mfma_f32_32x32x16_bf16(kf[1], qf[0], cblk, 0, 0, 0);
; #pragma unroll
;             for (int ds = 1; ds < 4; ++ds) {
;                 p0 = __builtin_amdgcn_mfma_f32_32x32x16_bf16(kf[2 * ds], qf[ds], p0, 0, 0, 0);
;                 p1 = __builtin_amdgcn_mfma_f32_32x32x16_bf16(kf[2 * ds + 1], qf[ds], p1, 0, 0, 0);
;             }
;         }
;     ...
;         const unsigned vbase = (unsigned)(size_t)Vt + vfo;
;         s16x4 va[8], vb[8];
;         VREADS1(va, 0);
;         if (near) {
;             const LAS float* tp = tab + (kv0 + 4 * hi - (qlo + r32) + 224);
; #pragma unroll
;             for (int r = 0; r < 16; ++r) { p0[r] += tp[(r & 3) + 8 * (r >> 2)]; p1[r] += tp[32 + (r & 3) + 8 * (r >> 2)]; }
;         }
;         float mx = max2f(max16f(p0), max16f(p1));
;         const bool first = (t == 0);
;         if (first || __any(mx > THR)) {
;     ...
; #pragma unroll
;         for (int r = 0; r < 16; ++r) { p0[r] = __builtin_amdgcn_exp2f(p0[r]); p1[r] = __builtin_amdgcn_exp2f(p1[r]); }
; #pragma unroll
;         for (int r = 0; r < 16; r += 2) { ls2 += (f32x2){p0[r], p0[r + 1]}; ls2 += (f32x2){p1[r], p1[r + 1]}; }
;         bf16x8 pa[4]; pa[0] = pack8(p0, 0); pa[1] = pack8(p0, 8); pa[2] = pack8(p1, 0); pa[3] = pack8(p1, 8);
;         LGKM0(); VREADS1(vb, 1); PV1(va, 0); LGKM0(); VREADS1(va, 2); PV1(vb, 1); LGKM0(); VREADS1(vb, 3); PV1(va, 2); LGKM0(); PV1(vb, 3);
;     ...
;         if (t + 2 < NT) asm volatile("s_waitcnt vmcnt(4) lgkmcnt(0)" ::: "memory"); else asm volatile("s_waitcnt vmcnt(0) lgkmcnt(0)" ::: "memory");
;         __builtin_amdgcn_s_barrier(); asm volatile("" ::: "memory");
.LatA_evret_h2:
	s_waitcnt lgkmcnt(12)
	v_mfma_f32_32x32x16_bf16 v[20:35], v[188:191], v[132:135], v[20:35]
	ds_read_b64_tr_b16 v[236:237], v231 offset:20480
	ds_read_b64_tr_b16 v[238:239], v231 offset:22528
	s_waitcnt lgkmcnt(12)
	v_mfma_f32_32x32x16_bf16 v[36:51], v[188:191], v[136:139], v[36:51]
	ds_read_b64_tr_b16 v[132:133], v228 offset:24576
	ds_read_b64_tr_b16 v[134:135], v228 offset:26624
	s_waitcnt lgkmcnt(12)
	v_mfma_f32_32x32x16_bf16 v[52:67], v[188:191], v[140:143], v[52:67]
	ds_read_b64_tr_b16 v[136:137], v229 offset:24576
	ds_read_b64_tr_b16 v[138:139], v229 offset:26624
	s_waitcnt lgkmcnt(12)
	s_add_u32 m0, s28, 0x4000
	v_mfma_f32_32x32x16_bf16 v[68:83], v[188:191], v[144:147], v[68:83]
	global_load_lds_dwordx4 v172, s[8:9]
	ds_read_b64_tr_b16 v[140:141], v230 offset:24576
	ds_read_b64_tr_b16 v[142:143], v230 offset:26624
	v_max3_f32 v251, v84, v85, v86
	v_max3_f32 v252, v87, v88, v89
	v_max3_f32 v251, v251, v90, v91
	v_max3_f32 v252, v252, v92, v93
	v_max3_f32 v251, v251, v94, v95
	v_max3_f32 v252, v252, v96, v97
	v_max3_f32 v251, v251, v98, v99
	v_max3_f32 v252, v252, v100, v101
	v_max3_f32 v251, v251, v102, v103
	v_max3_f32 v252, v252, v104, v105
	v_max3_f32 v251, v251, v106, v107
	v_max3_f32 v252, v252, v108, v109
	v_max3_f32 v251, v251, v110, v111
	v_max3_f32 v252, v252, v112, v113
	v_max3_f32 v251, v251, v114, v115
	v_max_f32_e32 v251, v251, v252
	v_cmp_lt_f32_e32 vcc, 0x41000000, v251
	s_cbranch_vccnz .LatA_rs_h2
.LatA_rareret_h2:
	s_waitcnt lgkmcnt(12)
	v_mfma_f32_32x32x16_bf16 v[20:35], v[192:195], v[220:223], v[20:35]
	ds_read_b64_tr_b16 v[144:145], v231 offset:24576
	ds_read_b64_tr_b16 v[146:147], v231 offset:26624
	v_exp_f32_e32 v84, v84
	v_exp_f32_e32 v85, v85
	v_exp_f32_e32 v86, v86
	s_waitcnt lgkmcnt(12)
	v_mfma_f32_32x32x16_bf16 v[36:51], v[192:195], v[224:227], v[36:51]
	ds_read_b64_tr_b16 v[220:221], v228 offset:28672
	ds_read_b64_tr_b16 v[222:223], v228 offset:30720
	v_exp_f32_e32 v87, v87
	v_pk_add_f32 v[150:151], v[150:151], v[84:85]
	s_waitcnt lgkmcnt(12)
	v_mfma_f32_32x32x16_bf16 v[52:67], v[192:195], v[232:235], v[52:67]
	ds_read_b64_tr_b16 v[224:225], v229 offset:28672
	ds_read_b64_tr_b16 v[226:227], v229 offset:30720
	v_pk_add_f32 v[150:151], v[150:151], v[86:87]
	v_exp_f32_e32 v88, v88
	v_exp_f32_e32 v89, v89
	v_cvt_pk_bf16_f32 v84, v84, v85
	s_waitcnt lgkmcnt(12)
	s_mov_b32 m0, s29
	v_mfma_f32_32x32x16_bf16 v[68:83], v[192:195], v[236:239], v[68:83]
	global_load_lds_dwordx4 v174, s[8:9]
	ds_read_b64_tr_b16 v[232:233], v230 offset:28672
	ds_read_b64_tr_b16 v[234:235], v230 offset:30720
	v_cvt_pk_bf16_f32 v85, v86, v87
	v_exp_f32_e32 v90, v90
	v_exp_f32_e32 v91, v91
	s_waitcnt lgkmcnt(12)
	v_mfma_f32_32x32x16_bf16 v[20:35], v[204:207], v[132:135], v[20:35]
	ds_read_b64_tr_b16 v[236:237], v231 offset:28672
	ds_read_b64_tr_b16 v[238:239], v231 offset:30720
	v_pk_add_f32 v[150:151], v[150:151], v[88:89]
	v_pk_add_f32 v[150:151], v[150:151], v[90:91]
	v_cvt_pk_bf16_f32 v86, v88, v89
	v_cvt_pk_bf16_f32 v87, v90, v91
	s_waitcnt lgkmcnt(12)
	v_mfma_f32_32x32x16_bf16 v[36:51], v[204:207], v[136:139], v[36:51]
	ds_read_b128 v[132:135], v164
	v_exp_f32_e32 v92, v92
	v_exp_f32_e32 v93, v93
	v_exp_f32_e32 v94, v94
	s_waitcnt lgkmcnt(11)
	v_mfma_f32_32x32x16_bf16 v[52:67], v[204:207], v[140:143], v[52:67]
	ds_read_b128 v[136:139], v164 offset:8192
	v_exp_f32_e32 v95, v95
	v_pk_add_f32 v[150:151], v[150:151], v[92:93]
	s_waitcnt lgkmcnt(10)
	s_add_u32 m0, s28, 0x6000
	v_mfma_f32_32x32x16_bf16 v[68:83], v[204:207], v[144:147], v[68:83]
	global_load_lds_dwordx4 v173, s[8:9]
	ds_read_b128 v[140:143], v165
	v_pk_add_f32 v[150:151], v[150:151], v[94:95]
	v_exp_f32_e32 v96, v96
	v_exp_f32_e32 v97, v97
	v_cvt_pk_bf16_f32 v88, v92, v93
	s_waitcnt lgkmcnt(9)
	v_mfma_f32_32x32x16_bf16 v[20:35], v[208:211], v[220:223], v[20:35]
	ds_read_b128 v[144:147], v165 offset:8192
	v_cvt_pk_bf16_f32 v89, v94, v95
	v_exp_f32_e32 v98, v98
	v_exp_f32_e32 v99, v99
	s_waitcnt lgkmcnt(8)
	v_mfma_f32_32x32x16_bf16 v[36:51], v[208:211], v[224:227], v[36:51]
	ds_read_b128 v[220:223], v166
	v_pk_add_f32 v[150:151], v[150:151], v[96:97]
	v_pk_add_f32 v[150:151], v[150:151], v[98:99]
	v_cvt_pk_bf16_f32 v90, v96, v97
	v_cvt_pk_bf16_f32 v91, v98, v99
	s_waitcnt lgkmcnt(7)
	v_mfma_f32_32x32x16_bf16 v[52:67], v[208:211], v[232:235], v[52:67]
	ds_read_b128 v[224:227], v166 offset:8192
	v_exp_f32_e32 v100, v100
	v_exp_f32_e32 v101, v101
	v_exp_f32_e32 v102, v102
	s_waitcnt lgkmcnt(6)
	s_add_u32 m0, s29, 0x2000
	v_mfma_f32_32x32x16_bf16 v[68:83], v[208:211], v[236:239], v[68:83]
	global_load_lds_dwordx4 v175, s[8:9]
	ds_read_b128 v[232:235], v167
	v_exp_f32_e32 v103, v103
	v_pk_add_f32 v[150:151], v[150:151], v[100:101]
	s_waitcnt lgkmcnt(6)
	v_mfma_f32_32x32x16_bf16 v[188:203], v[132:135], v[116:119], v[2:17]
	ds_read_b128 v[236:239], v167 offset:8192
	v_pk_add_f32 v[150:151], v[150:151], v[102:103]
	v_exp_f32_e32 v104, v104
	v_exp_f32_e32 v105, v105
	v_cvt_pk_bf16_f32 v100, v100, v101
	s_waitcnt lgkmcnt(6)
	v_mfma_f32_32x32x16_bf16 v[204:219], v[136:139], v[116:119], v[2:17]
	ds_read_b64_tr_b16 v[132:133], v228 offset:32768
	ds_read_b64_tr_b16 v[134:135], v228 offset:34816
	v_cvt_pk_bf16_f32 v101, v102, v103
	v_exp_f32_e32 v106, v106
	v_exp_f32_e32 v107, v107
	s_waitcnt lgkmcnt(7)
	v_mfma_f32_32x32x16_bf16 v[188:203], v[140:143], v[120:123], v[188:203]
	ds_read_b64_tr_b16 v[136:137], v229 offset:32768
	ds_read_b64_tr_b16 v[138:139], v229 offset:34816
	v_pk_add_f32 v[150:151], v[150:151], v[104:105]
	v_pk_add_f32 v[150:151], v[150:151], v[106:107]
	v_cvt_pk_bf16_f32 v102, v104, v105
	v_cvt_pk_bf16_f32 v103, v106, v107
	s_waitcnt lgkmcnt(8)
; #define LAS __attribute__((address_space(3)))
; __device__ __forceinline__ float max2f(float a, float b) { float r; asm("v_max_f32_e32 %0, %1, %2" : "=v"(r) : "v"(a), "v"(b)); return r; }
; #define VREADS1(arr, d_) do { const unsigned ad_ = vbase ^ (unsigned)((d_) << 6); __builtin_amdgcn_sched_barrier(0); \
;         _Pragma("unroll") for (int ks_ = 0; ks_ < 4; ++ks_) { VTR(arr[ks_ * 2], ad_, ks_ * 4096); VTR(arr[ks_ * 2 + 1], ad_, ks_ * 4096 + 2048); } __builtin_amdgcn_sched_barrier(0); } while (0)
; #define PV1(arr, d_) do { _Pragma("unroll") for (int ks_ = 0; ks_ < 4; ++ks_) { const s16x4 lo_ = arr[ks_ * 2], hh_ = arr[ks_ * 2 + 1]; \
;         const bf16x8 bv_ = (bf16x8){lo_[0], lo_[1], lo_[2], lo_[3], hh_[0], hh_[1], hh_[2], hh_[3]}; \
;         O[d_] = __builtin_amdgcn_mfma_f32_32x32x16_bf16(pa[ks_], bv_, O[d_], 0, 0, 0); } __builtin_amdgcn_sched_barrier(0); } while (0)
; #define LGKM0() do { __builtin_amdgcn_sched_barrier(0); asm volatile("s_waitcnt lgkmcnt(0)" ::: "memory"); __builtin_amdgcn_sched_barrier(0); } while (0)
; __device__ __forceinline__ void attn_unit(LAS unsigned char* lds, const bf16_t* Z, bf16_t* A2, const float* tabg, int seq_base, int S, int h, int qb, float lam) {
;     ...
;                 p0 = __builtin_amdgcn_mfma_f32_32x32x16_bf16(kf[2 * ds], qf[ds], p0, 0, 0, 0);
;                 p1 = __builtin_amdgcn_mfma_f32_32x32x16_bf16(kf[2 * ds + 1], qf[ds], p1, 0, 0, 0);
;             }
;         }
;     ...
;         const unsigned vbase = (unsigned)(size_t)Vt + vfo;
;         s16x4 va[8], vb[8];
;         VREADS1(va, 0);
;         if (near) {
;             const LAS float* tp = tab + (kv0 + 4 * hi - (qlo + r32) + 224);
; #pragma unroll
;             for (int r = 0; r < 16; ++r) { p0[r] += tp[(r & 3) + 8 * (r >> 2)]; p1[r] += tp[32 + (r & 3) + 8 * (r >> 2)]; }
;         }
;         float mx = max2f(max16f(p0), max16f(p1));
;         const bool first = (t == 0);
;         if (first || __any(mx > THR)) {
;     ...
;         LGKM0(); VREADS1(vb, 1); PV1(va, 0); LGKM0(); VREADS1(va, 2); PV1(vb, 1); LGKM0(); VREADS1(vb, 3); PV1(va, 2); LGKM0(); PV1(vb, 3);
;     ...
;         if (t + 2 < NT) asm volatile("s_waitcnt vmcnt(4) lgkmcnt(0)" ::: "memory"); else asm volatile("s_waitcnt vmcnt(0) lgkmcnt(0)" ::: "memory");
;         __builtin_amdgcn_s_barrier(); asm volatile("" ::: "memory");
	v_mfma_f32_32x32x16_bf16 v[204:219], v[144:147], v[120:123], v[204:219]
	ds_read_b64_tr_b16 v[140:141], v230 offset:32768
	ds_read_b64_tr_b16 v[142:143], v230 offset:34816
	v_exp_f32_e32 v108, v108
	v_exp_f32_e32 v109, v109
	v_exp_f32_e32 v110, v110
	s_waitcnt lgkmcnt(9)
	v_mfma_f32_32x32x16_bf16 v[188:203], v[220:223], v[124:127], v[188:203]
	ds_read_b64_tr_b16 v[144:145], v231 offset:32768
	ds_read_b64_tr_b16 v[146:147], v231 offset:34816
	v_exp_f32_e32 v111, v111
	v_pk_add_f32 v[150:151], v[150:151], v[108:109]
	s_waitcnt lgkmcnt(10)
	v_mfma_f32_32x32x16_bf16 v[204:219], v[224:227], v[124:127], v[204:219]
	ds_read_b64_tr_b16 v[220:221], v228 offset:36864
	ds_read_b64_tr_b16 v[222:223], v228 offset:38912
	v_pk_add_f32 v[150:151], v[150:151], v[110:111]
	v_exp_f32_e32 v112, v112
	v_exp_f32_e32 v113, v113
	v_cvt_pk_bf16_f32 v104, v108, v109
	s_waitcnt lgkmcnt(11)
	v_mfma_f32_32x32x16_bf16 v[188:203], v[232:235], v[128:131], v[188:203]
	ds_read_b64_tr_b16 v[224:225], v229 offset:36864
	ds_read_b64_tr_b16 v[226:227], v229 offset:38912
	v_cvt_pk_bf16_f32 v105, v110, v111
	v_exp_f32_e32 v114, v114
	v_exp_f32_e32 v115, v115
	s_waitcnt lgkmcnt(12)
	v_mfma_f32_32x32x16_bf16 v[204:219], v[236:239], v[128:131], v[204:219]
	ds_read_b64_tr_b16 v[232:233], v230 offset:36864
	ds_read_b64_tr_b16 v[234:235], v230 offset:38912
	v_pk_add_f32 v[150:151], v[150:151], v[112:113]
	v_pk_add_f32 v[150:151], v[150:151], v[114:115]
	v_cvt_pk_bf16_f32 v106, v112, v113
	v_cvt_pk_bf16_f32 v107, v114, v115
	s_add_u32 s8, s8, 0x40000
	s_addc_u32 s9, s9, 0
	s_waitcnt vmcnt(4)
	s_barrier
	s_sub_u32 s10, s10, 1
	s_cbranch_scc1 .LatA_evs_h3
.LatA_evret_h3:
	s_waitcnt lgkmcnt(12)
	v_mfma_f32_32x32x16_bf16 v[20:35], v[84:87], v[132:135], v[20:35]
	ds_read_b64_tr_b16 v[236:237], v231 offset:36864
	ds_read_b64_tr_b16 v[238:239], v231 offset:38912
	s_waitcnt lgkmcnt(12)
	v_mfma_f32_32x32x16_bf16 v[36:51], v[84:87], v[136:139], v[36:51]
	ds_read_b64_tr_b16 v[132:133], v228 offset:40960
	ds_read_b64_tr_b16 v[134:135], v228 offset:43008
	s_waitcnt lgkmcnt(12)
	v_mfma_f32_32x32x16_bf16 v[52:67], v[84:87], v[140:143], v[52:67]
	ds_read_b64_tr_b16 v[136:137], v229 offset:40960
	ds_read_b64_tr_b16 v[138:139], v229 offset:43008
	s_waitcnt lgkmcnt(12)
	s_add_u32 m0, s28, 0x8000
	v_mfma_f32_32x32x16_bf16 v[68:83], v[84:87], v[144:147], v[68:83]
	global_load_lds_dwordx4 v172, s[8:9]
	ds_read_b64_tr_b16 v[140:141], v230 offset:40960
	ds_read_b64_tr_b16 v[142:143], v230 offset:43008
	v_max3_f32 v251, v188, v189, v190
	v_max3_f32 v252, v191, v192, v193
	v_max3_f32 v251, v251, v194, v195
	v_max3_f32 v252, v252, v196, v197
	v_max3_f32 v251, v251, v198, v199
	v_max3_f32 v252, v252, v200, v201
	v_max3_f32 v251, v251, v202, v203
	v_max3_f32 v252, v252, v204, v205
	v_max3_f32 v251, v251, v206, v207
	v_max3_f32 v252, v252, v208, v209
	v_max3_f32 v251, v251, v210, v211
	v_max3_f32 v252, v252, v212, v213
	v_max3_f32 v251, v251, v214, v215
	v_max3_f32 v252, v252, v216, v217
	v_max3_f32 v251, v251, v218, v219
	v_max_f32_e32 v251, v251, v252
	v_cmp_lt_f32_e32 vcc, 0x41000000, v251
	s_cbranch_vccnz .LatA_rs_h3
; #define LAS __attribute__((address_space(3)))
; #define VREADS1(arr, d_) do { const unsigned ad_ = vbase ^ (unsigned)((d_) << 6); __builtin_amdgcn_sched_barrier(0); \
;         _Pragma("unroll") for (int ks_ = 0; ks_ < 4; ++ks_) { VTR(arr[ks_ * 2], ad_, ks_ * 4096); VTR(arr[ks_ * 2 + 1], ad_, ks_ * 4096 + 2048); } __builtin_amdgcn_sched_barrier(0); } while (0)
; #define LGKM0() do { __builtin_amdgcn_sched_barrier(0); asm volatile("s_waitcnt lgkmcnt(0)" ::: "memory"); __builtin_amdgcn_sched_barrier(0); } while (0)
; __device__ __forceinline__ void attn_unit(LAS unsigned char* lds, const bf16_t* Z, bf16_t* A2, const float* tabg, int seq_base, int S, int h, int qb, float lam) {
;     ...
;             for (int ds = 0; ds < 4; ++ds) { kf[2 * ds] = *(const LAS bf16x8*)(Kt + (kfo ^ (unsigned)(ds << 5))); kf[2 * ds + 1] = *(const LAS bf16x8*)(Kt + 32 * 256 + (kfo ^ (unsigned)(ds << 5))); }
;             __builtin_amdgcn_sched_barrier(0);
;             p0 = __builtin_amdgcn_mfma_f32_32x32x16_bf16(kf[0], qf[0], cblk, 0, 0, 0);
;             p1 = __builtin_amdgcn_mfma_f32_32x32x16_bf16(kf[1], qf[0], cblk, 0, 0, 0);
; #pragma unroll
;             for (int ds = 1; ds < 4; ++ds) {
;                 p0 = __builtin_amdgcn_mfma_f32_32x32x16_bf16(kf[2 * ds], qf[ds], p0, 0, 0, 0);
;                 p1 = __builtin_amdgcn_mfma_f32_32x32x16_bf16(kf[2 * ds + 1], qf[ds], p1, 0, 0, 0);
;             }
;     ...
; #pragma unroll
;         for (int r = 0; r < 16; ++r) { p0[r] = __builtin_amdgcn_exp2f(p0[r]); p1[r] = __builtin_amdgcn_exp2f(p1[r]); }
; #pragma unroll
;         for (int r = 0; r < 16; r += 2) { ls2 += (f32x2){p0[r], p0[r + 1]}; ls2 += (f32x2){p1[r], p1[r + 1]}; }
;         bf16x8 pa[4]; pa[0] = pack8(p0, 0); pa[1] = pack8(p0, 8); pa[2] = pack8(p1, 0); pa[3] = pack8(p1, 8);
;         LGKM0(); VREADS1(vb, 1); PV1(va, 0); LGKM0(); VREADS1(va, 2); PV1(vb, 1); LGKM0(); VREADS1(vb, 3); PV1(va, 2); LGKM0(); PV1(vb, 3);
;     ...
;         if (t + 2 < NT) asm volatile("s_waitcnt vmcnt(4) lgkmcnt(0)" ::: "memory"); else asm volatile("s_waitcnt vmcnt(0) lgkmcnt(0)" ::: "memory");
;         __builtin_amdgcn_s_barrier(); asm volatile("" ::: "memory");
;         bc = (bc == NST - 1) ? 0 : bc + 1; bn = (bn == NST - 1) ? 0 : bn + 1;
.LatA_rareret_h3:
	s_waitcnt lgkmcnt(12)
	v_mfma_f32_32x32x16_bf16 v[20:35], v[88:91], v[220:223], v[20:35]
	ds_read_b64_tr_b16 v[144:145], v231 offset:40960
	ds_read_b64_tr_b16 v[146:147], v231 offset:43008
	v_exp_f32_e32 v188, v188
	v_exp_f32_e32 v189, v189
	v_exp_f32_e32 v190, v190
	s_waitcnt lgkmcnt(12)
	v_mfma_f32_32x32x16_bf16 v[36:51], v[88:91], v[224:227], v[36:51]
	ds_read_b64_tr_b16 v[220:221], v228 offset:45056
	ds_read_b64_tr_b16 v[222:223], v228 offset:47104
	v_exp_f32_e32 v191, v191
	v_pk_add_f32 v[150:151], v[150:151], v[188:189]
	s_waitcnt lgkmcnt(12)
	v_mfma_f32_32x32x16_bf16 v[52:67], v[88:91], v[232:235], v[52:67]
	ds_read_b64_tr_b16 v[224:225], v229 offset:45056
	ds_read_b64_tr_b16 v[226:227], v229 offset:47104
	v_pk_add_f32 v[150:151], v[150:151], v[190:191]
	v_exp_f32_e32 v192, v192
	v_exp_f32_e32 v193, v193
	v_cvt_pk_bf16_f32 v188, v188, v189
	s_waitcnt lgkmcnt(12)
	s_add_u32 m0, s29, 0x4000
	v_mfma_f32_32x32x16_bf16 v[68:83], v[88:91], v[236:239], v[68:83]
	global_load_lds_dwordx4 v174, s[8:9]
	ds_read_b64_tr_b16 v[232:233], v230 offset:45056
	ds_read_b64_tr_b16 v[234:235], v230 offset:47104
	v_cvt_pk_bf16_f32 v189, v190, v191
	v_exp_f32_e32 v194, v194
	v_exp_f32_e32 v195, v195
	s_waitcnt lgkmcnt(12)
	v_mfma_f32_32x32x16_bf16 v[20:35], v[100:103], v[132:135], v[20:35]
	ds_read_b64_tr_b16 v[236:237], v231 offset:45056
	ds_read_b64_tr_b16 v[238:239], v231 offset:47104
	v_pk_add_f32 v[150:151], v[150:151], v[192:193]
	v_pk_add_f32 v[150:151], v[150:151], v[194:195]
	v_cvt_pk_bf16_f32 v190, v192, v193
	v_cvt_pk_bf16_f32 v191, v194, v195
	s_waitcnt lgkmcnt(12)
	v_mfma_f32_32x32x16_bf16 v[36:51], v[100:103], v[136:139], v[36:51]
	ds_read_b128 v[132:135], v19
	v_exp_f32_e32 v196, v196
	v_exp_f32_e32 v197, v197
	v_exp_f32_e32 v198, v198
	s_waitcnt lgkmcnt(11)
	v_mfma_f32_32x32x16_bf16 v[52:67], v[100:103], v[140:143], v[52:67]
	ds_read_b128 v[136:139], v19 offset:8192
	v_exp_f32_e32 v199, v199
	v_pk_add_f32 v[150:151], v[150:151], v[196:197]
	s_waitcnt lgkmcnt(10)
	s_add_u32 m0, s28, 0xa000
	v_mfma_f32_32x32x16_bf16 v[68:83], v[100:103], v[144:147], v[68:83]
	global_load_lds_dwordx4 v173, s[8:9]
	ds_read_b128 v[140:143], v180
	v_pk_add_f32 v[150:151], v[150:151], v[198:199]
	v_exp_f32_e32 v200, v200
	v_exp_f32_e32 v201, v201
	v_cvt_pk_bf16_f32 v192, v196, v197
	s_waitcnt lgkmcnt(9)
	v_mfma_f32_32x32x16_bf16 v[20:35], v[104:107], v[220:223], v[20:35]
	ds_read_b128 v[144:147], v180 offset:8192
	v_cvt_pk_bf16_f32 v193, v198, v199
	v_exp_f32_e32 v202, v202
	v_exp_f32_e32 v203, v203
	s_waitcnt lgkmcnt(8)
	v_mfma_f32_32x32x16_bf16 v[36:51], v[104:107], v[224:227], v[36:51]
	ds_read_b128 v[220:223], v181
	v_pk_add_f32 v[150:151], v[150:151], v[200:201]
	v_pk_add_f32 v[150:151], v[150:151], v[202:203]
	v_cvt_pk_bf16_f32 v194, v200, v201
	v_cvt_pk_bf16_f32 v195, v202, v203
	s_waitcnt lgkmcnt(7)
	v_mfma_f32_32x32x16_bf16 v[52:67], v[104:107], v[232:235], v[52:67]
	ds_read_b128 v[224:227], v181 offset:8192
	v_exp_f32_e32 v204, v204
	v_exp_f32_e32 v205, v205
	v_exp_f32_e32 v206, v206
	s_waitcnt lgkmcnt(6)
	s_add_u32 m0, s29, 0x6000
	v_mfma_f32_32x32x16_bf16 v[68:83], v[104:107], v[236:239], v[68:83]
	global_load_lds_dwordx4 v175, s[8:9]
	ds_read_b128 v[232:235], v182
	v_exp_f32_e32 v207, v207
	v_pk_add_f32 v[150:151], v[150:151], v[204:205]
	s_waitcnt lgkmcnt(6)
	v_mfma_f32_32x32x16_bf16 v[84:99], v[132:135], v[116:119], v[2:17]
	ds_read_b128 v[236:239], v182 offset:8192
	v_pk_add_f32 v[150:151], v[150:151], v[206:207]
	v_exp_f32_e32 v208, v208
	v_exp_f32_e32 v209, v209
	v_cvt_pk_bf16_f32 v204, v204, v205
	s_waitcnt lgkmcnt(6)
	v_mfma_f32_32x32x16_bf16 v[100:115], v[136:139], v[116:119], v[2:17]
	ds_read_b64_tr_b16 v[132:133], v168 offset:0
	ds_read_b64_tr_b16 v[134:135], v168 offset:2048
	v_cvt_pk_bf16_f32 v205, v206, v207
	v_exp_f32_e32 v210, v210
	v_exp_f32_e32 v211, v211
	s_waitcnt lgkmcnt(7)
	v_mfma_f32_32x32x16_bf16 v[84:99], v[140:143], v[120:123], v[84:99]
	ds_read_b64_tr_b16 v[136:137], v169 offset:0
	ds_read_b64_tr_b16 v[138:139], v169 offset:2048
	v_pk_add_f32 v[150:151], v[150:151], v[208:209]
	v_pk_add_f32 v[150:151], v[150:151], v[210:211]
	v_cvt_pk_bf16_f32 v206, v208, v209
	v_cvt_pk_bf16_f32 v207, v210, v211
	s_waitcnt lgkmcnt(8)
	v_mfma_f32_32x32x16_bf16 v[100:115], v[144:147], v[120:123], v[100:115]
	ds_read_b64_tr_b16 v[140:141], v170 offset:0
	ds_read_b64_tr_b16 v[142:143], v170 offset:2048
	v_exp_f32_e32 v212, v212
	v_exp_f32_e32 v213, v213
	v_exp_f32_e32 v214, v214
	s_waitcnt lgkmcnt(9)
	v_mfma_f32_32x32x16_bf16 v[84:99], v[220:223], v[124:127], v[84:99]
	ds_read_b64_tr_b16 v[144:145], v171 offset:0
	ds_read_b64_tr_b16 v[146:147], v171 offset:2048
	v_exp_f32_e32 v215, v215
	v_pk_add_f32 v[150:151], v[150:151], v[212:213]
	s_waitcnt lgkmcnt(10)
	v_mfma_f32_32x32x16_bf16 v[100:115], v[224:227], v[124:127], v[100:115]
	ds_read_b64_tr_b16 v[220:221], v168 offset:4096
	ds_read_b64_tr_b16 v[222:223], v168 offset:6144
	v_pk_add_f32 v[150:151], v[150:151], v[214:215]
	v_exp_f32_e32 v216, v216
	v_exp_f32_e32 v217, v217
	v_cvt_pk_bf16_f32 v208, v212, v213
	s_waitcnt lgkmcnt(11)
	v_mfma_f32_32x32x16_bf16 v[84:99], v[232:235], v[128:131], v[84:99]
	ds_read_b64_tr_b16 v[224:225], v169 offset:4096
	ds_read_b64_tr_b16 v[226:227], v169 offset:6144
	v_cvt_pk_bf16_f32 v209, v214, v215
	v_exp_f32_e32 v218, v218
	v_exp_f32_e32 v219, v219
	s_waitcnt lgkmcnt(12)
	v_mfma_f32_32x32x16_bf16 v[100:115], v[236:239], v[128:131], v[100:115]
	ds_read_b64_tr_b16 v[232:233], v170 offset:4096
	ds_read_b64_tr_b16 v[234:235], v170 offset:6144
	v_pk_add_f32 v[150:151], v[150:151], v[216:217]
	v_pk_add_f32 v[150:151], v[150:151], v[218:219]
	v_cvt_pk_bf16_f32 v210, v216, v217
	v_cvt_pk_bf16_f32 v211, v218, v219
	s_add_u32 s8, s8, 0x40000
	s_addc_u32 s9, s9, 0
	s_waitcnt vmcnt(4)
	s_barrier
	s_movk_i32 s36, 30

; #define LAS __attribute__((address_space(3)))
; __device__ __forceinline__ float max2f(float a, float b) { float r; asm("v_max_f32_e32 %0, %1, %2" : "=v"(r) : "v"(a), "v"(b)); return r; }
; #define VREADS1(arr, d_) do { const unsigned ad_ = vbase ^ (unsigned)((d_) << 6); __builtin_amdgcn_sched_barrier(0); \
;         _Pragma("unroll") for (int ks_ = 0; ks_ < 4; ++ks_) { VTR(arr[ks_ * 2], ad_, ks_ * 4096); VTR(arr[ks_ * 2 + 1], ad_, ks_ * 4096 + 2048); } __builtin_amdgcn_sched_barrier(0); } while (0)
; __device__ __forceinline__ void attn_unit(LAS unsigned char* lds, const bf16_t* Z, bf16_t* A2, const float* tabg, int seq_base, int S, int h, int qb, float lam) {
;     ...
;         const unsigned vbase = (unsigned)(size_t)Vt + vfo;
;         s16x4 va[8], vb[8];
;         VREADS1(va, 0);
;         if (near) {
;             const LAS float* tp = tab + (kv0 + 4 * hi - (qlo + r32) + 224);
; #pragma unroll
;             for (int r = 0; r < 16; ++r) { p0[r] += tp[(r & 3) + 8 * (r >> 2)]; p1[r] += tp[32 + (r & 3) + 8 * (r >> 2)]; }
;         }
;         float mx = max2f(max16f(p0), max16f(p1));
;         const bool first = (t == 0);
;         if (first || __any(mx > THR)) {
.LatA_evret_m0:
	s_waitcnt lgkmcnt(12)
	v_mfma_f32_32x32x16_bf16 v[20:35], v[188:191], v[132:135], v[20:35]
	ds_read_b64_tr_b16 v[236:237], v171 offset:4096
	ds_read_b64_tr_b16 v[238:239], v171 offset:6144
	s_waitcnt lgkmcnt(12)
	v_mfma_f32_32x32x16_bf16 v[36:51], v[188:191], v[136:139], v[36:51]
	ds_read_b64_tr_b16 v[132:133], v168 offset:8192
	ds_read_b64_tr_b16 v[134:135], v168 offset:10240
	s_waitcnt lgkmcnt(12)
	v_mfma_f32_32x32x16_bf16 v[52:67], v[188:191], v[140:143], v[52:67]
	ds_read_b64_tr_b16 v[136:137], v169 offset:8192
	ds_read_b64_tr_b16 v[138:139], v169 offset:10240
	s_waitcnt lgkmcnt(12)
	s_add_u32 m0, s28, 0x1d000
	v_mfma_f32_32x32x16_bf16 v[68:83], v[188:191], v[144:147], v[68:83]
	global_load_lds_dwordx4 v172, s[8:9]
	ds_read_b64_tr_b16 v[140:141], v170 offset:8192
	ds_read_b64_tr_b16 v[142:143], v170 offset:10240
	v_max3_f32 v251, v84, v85, v86
	v_max3_f32 v252, v87, v88, v89
	v_max3_f32 v251, v251, v90, v91
	v_max3_f32 v252, v252, v92, v93
	v_max3_f32 v251, v251, v94, v95
	v_max3_f32 v252, v252, v96, v97
	v_max3_f32 v251, v251, v98, v99
	v_max3_f32 v252, v252, v100, v101
	v_max3_f32 v251, v251, v102, v103
	v_max3_f32 v252, v252, v104, v105
	v_max3_f32 v251, v251, v106, v107
	v_max3_f32 v252, v252, v108, v109
	v_max3_f32 v251, v251, v110, v111
	v_max3_f32 v252, v252, v112, v113
	v_max3_f32 v251, v251, v114, v115
	v_max_f32_e32 v251, v251, v252
	v_cmp_lt_f32_e32 vcc, 0x41000000, v251
	s_cbranch_vccnz .LatA_rs_m0
; __device__ __forceinline__ void attn_unit(LAS unsigned char* lds, const bf16_t* Z, bf16_t* A2, const float* tabg, int seq_base, int S, int h, int qb, float lam) {
;     ...
;             bf16x8 kf[8];
; #pragma unroll
;             for (int ds = 0; ds < 4; ++ds) { kf[2 * ds] = *(const LAS bf16x8*)(Kt + (kfo ^ (unsigned)(ds << 5))); kf[2 * ds + 1] = *(const LAS bf16x8*)(Kt + 32 * 256 + (kfo ^ (unsigned)(ds << 5))); }
;             __builtin_amdgcn_sched_barrier(0);
;             p0 = __builtin_amdgcn_mfma_f32_32x32x16_bf16(kf[0], qf[0], cblk, 0, 0, 0);
;             p1 = __builtin_amdgcn_mfma_f32_32x32x16_bf16(kf[1], qf[0], cblk, 0, 0, 0);
; #pragma unroll
;             for (int ds = 1; ds < 4; ++ds) {
;                 p0 = __builtin_amdgcn_mfma_f32_32x32x16_bf16(kf[2 * ds], qf[ds], p0, 0, 0, 0);
;                 p1 = __builtin_amdgcn_mfma_f32_32x32x16_bf16(kf[2 * ds + 1], qf[ds], p1, 0, 0, 0);
;             }
;         }
;     ...
;         const unsigned vbase = (unsigned)(size_t)Vt + vfo;
;         s16x4 va[8], vb[8];
;         VREADS1(va, 0);
;         if (near) {
;             const LAS float* tp = tab + (kv0 + 4 * hi - (qlo + r32) + 224);
; #pragma unroll
;             for (int r = 0; r < 16; ++r) { p0[r] += tp[(r & 3) + 8 * (r >> 2)]; p1[r] += tp[32 + (r & 3) + 8 * (r >> 2)]; }
;         }
;         float mx = max2f(max16f(p0), max16f(p1));
;         const bool first = (t == 0);
;         if (first || __any(mx > THR)) {
;             { auto rr = __builtin_amdgcn_permlane32_swap(__float_as_uint(mx), __float_as_uint(mx), false, false); mx = max2f(__uint_as_float(rr[0]), __uint_as_float(rr[1])); }
;             const float delta = first ? mx : fmaxf(mx, 0.f);
;             const float alpha = first ? 1.0f : __builtin_amdgcn_exp2f(-delta);
;             mu += delta; ls2 *= alpha;
;             if (!first) {
;                 asm volatile("" ::: "memory");
;                 scr[r32] = alpha;
;                 asm volatile("s_waitcnt lgkmcnt(0)" ::: "memory");
; #pragma unroll
;                 for (int g = 0; g < 4; ++g) { const f32x4 a4 = *(const LAS f32x4*)(scr + 8 * g + 4 * hi);
; #pragma unroll
;                     for (int d = 0; d < 4; ++d) { O[d][4 * g + 0] *= a4[0]; O[d][4 * g + 1] *= a4[1]; O[d][4 * g + 2] *= a4[2]; O[d][4 * g + 3] *= a4[3]; } }
;                 asm volatile("s_waitcnt lgkmcnt(0)" ::: "memory");
;             }
; #pragma unroll
.LatA_rareret_m0:
	s_waitcnt lgkmcnt(12)
	v_mfma_f32_32x32x16_bf16 v[20:35], v[192:195], v[220:223], v[20:35]
	ds_read_b64_tr_b16 v[144:145], v171 offset:8192
	ds_read_b64_tr_b16 v[146:147], v171 offset:10240
	v_exp_f32_e32 v84, v84
	v_exp_f32_e32 v85, v85
	v_exp_f32_e32 v86, v86
	s_waitcnt lgkmcnt(12)
	v_mfma_f32_32x32x16_bf16 v[36:51], v[192:195], v[224:227], v[36:51]
	ds_read_b64_tr_b16 v[220:221], v168 offset:12288
	ds_read_b64_tr_b16 v[222:223], v168 offset:14336
	v_exp_f32_e32 v87, v87
	v_pk_add_f32 v[150:151], v[150:151], v[84:85]
	s_waitcnt lgkmcnt(12)
	v_mfma_f32_32x32x16_bf16 v[52:67], v[192:195], v[232:235], v[52:67]
	ds_read_b64_tr_b16 v[224:225], v169 offset:12288
	ds_read_b64_tr_b16 v[226:227], v169 offset:14336
	v_pk_add_f32 v[150:151], v[150:151], v[86:87]
	v_exp_f32_e32 v88, v88
	v_exp_f32_e32 v89, v89
	v_cvt_pk_bf16_f32 v84, v84, v85
	s_waitcnt lgkmcnt(12)
	s_add_u32 m0, s29, 0x8000
	v_mfma_f32_32x32x16_bf16 v[68:83], v[192:195], v[236:239], v[68:83]
	global_load_lds_dwordx4 v174, s[8:9]
	ds_read_b64_tr_b16 v[232:233], v170 offset:12288
	ds_read_b64_tr_b16 v[234:235], v170 offset:14336
	v_cvt_pk_bf16_f32 v85, v86, v87
	v_exp_f32_e32 v90, v90
	v_exp_f32_e32 v91, v91
	s_waitcnt lgkmcnt(12)
	v_mfma_f32_32x32x16_bf16 v[20:35], v[204:207], v[132:135], v[20:35]
	ds_read_b64_tr_b16 v[236:237], v171 offset:12288
	ds_read_b64_tr_b16 v[238:239], v171 offset:14336
	v_pk_add_f32 v[150:151], v[150:151], v[88:89]
	v_pk_add_f32 v[150:151], v[150:151], v[90:91]
	v_cvt_pk_bf16_f32 v86, v88, v89
	v_cvt_pk_bf16_f32 v87, v90, v91
	s_waitcnt lgkmcnt(12)
	v_mfma_f32_32x32x16_bf16 v[36:51], v[204:207], v[136:139], v[36:51]
	ds_read_b128 v[132:135], v19 offset:16384
	v_exp_f32_e32 v92, v92
	v_exp_f32_e32 v93, v93
	v_exp_f32_e32 v94, v94
	s_waitcnt lgkmcnt(11)
	v_mfma_f32_32x32x16_bf16 v[52:67], v[204:207], v[140:143], v[52:67]
	ds_read_b128 v[136:139], v19 offset:24576
	v_exp_f32_e32 v95, v95
	v_pk_add_f32 v[150:151], v[150:151], v[92:93]
	s_waitcnt lgkmcnt(10)
	s_add_u32 m0, s28, 0x1f000
	v_mfma_f32_32x32x16_bf16 v[68:83], v[204:207], v[144:147], v[68:83]
	global_load_lds_dwordx4 v173, s[8:9]
	ds_read_b128 v[140:143], v180 offset:16384
	v_pk_add_f32 v[150:151], v[150:151], v[94:95]
	v_exp_f32_e32 v96, v96
	v_exp_f32_e32 v97, v97
	v_cvt_pk_bf16_f32 v88, v92, v93
	s_waitcnt lgkmcnt(9)
	v_mfma_f32_32x32x16_bf16 v[20:35], v[208:211], v[220:223], v[20:35]
	ds_read_b128 v[144:147], v180 offset:24576
	v_cvt_pk_bf16_f32 v89, v94, v95
	v_exp_f32_e32 v98, v98
	v_exp_f32_e32 v99, v99
	s_waitcnt lgkmcnt(8)
	v_mfma_f32_32x32x16_bf16 v[36:51], v[208:211], v[224:227], v[36:51]
	ds_read_b128 v[220:223], v181 offset:16384
	v_pk_add_f32 v[150:151], v[150:151], v[96:97]
	v_pk_add_f32 v[150:151], v[150:151], v[98:99]
	v_cvt_pk_bf16_f32 v90, v96, v97
	v_cvt_pk_bf16_f32 v91, v98, v99
	s_waitcnt lgkmcnt(7)
	v_mfma_f32_32x32x16_bf16 v[52:67], v[208:211], v[232:235], v[52:67]
	ds_read_b128 v[224:227], v181 offset:24576
	v_exp_f32_e32 v100, v100
	v_exp_f32_e32 v101, v101
	v_exp_f32_e32 v102, v102
	s_waitcnt lgkmcnt(6)
	s_add_u32 m0, s29, 0xa000
	v_mfma_f32_32x32x16_bf16 v[68:83], v[208:211], v[236:239], v[68:83]
	global_load_lds_dwordx4 v175, s[8:9]
	ds_read_b128 v[232:235], v182 offset:16384
	v_exp_f32_e32 v103, v103
	v_pk_add_f32 v[150:151], v[150:151], v[100:101]
	s_waitcnt lgkmcnt(6)
	v_mfma_f32_32x32x16_bf16 v[188:203], v[132:135], v[116:119], v[2:17]
	ds_read_b128 v[236:239], v182 offset:24576
	v_pk_add_f32 v[150:151], v[150:151], v[102:103]
	v_exp_f32_e32 v104, v104
	v_exp_f32_e32 v105, v105
	v_cvt_pk_bf16_f32 v100, v100, v101
	s_waitcnt lgkmcnt(6)
	v_mfma_f32_32x32x16_bf16 v[204:219], v[136:139], v[116:119], v[2:17]
	ds_read_b64_tr_b16 v[132:133], v228 offset:0
	ds_read_b64_tr_b16 v[134:135], v228 offset:2048
	v_cvt_pk_bf16_f32 v101, v102, v103
	v_exp_f32_e32 v106, v106
	v_exp_f32_e32 v107, v107
	s_waitcnt lgkmcnt(7)
	v_mfma_f32_32x32x16_bf16 v[188:203], v[140:143], v[120:123], v[188:203]
	ds_read_b64_tr_b16 v[136:137], v229 offset:0
	ds_read_b64_tr_b16 v[138:139], v229 offset:2048
	v_pk_add_f32 v[150:151], v[150:151], v[104:105]
	v_pk_add_f32 v[150:151], v[150:151], v[106:107]
	v_cvt_pk_bf16_f32 v102, v104, v105
	v_cvt_pk_bf16_f32 v103, v106, v107
	s_waitcnt lgkmcnt(8)
	v_mfma_f32_32x32x16_bf16 v[204:219], v[144:147], v[120:123], v[204:219]
	ds_read_b64_tr_b16 v[140:141], v230 offset:0
	ds_read_b64_tr_b16 v[142:143], v230 offset:2048
	v_exp_f32_e32 v108, v108
	v_exp_f32_e32 v109, v109
	v_exp_f32_e32 v110, v110
	s_waitcnt lgkmcnt(9)
	v_mfma_f32_32x32x16_bf16 v[188:203], v[220:223], v[124:127], v[188:203]
	ds_read_b64_tr_b16 v[144:145], v231 offset:0
	ds_read_b64_tr_b16 v[146:147], v231 offset:2048
	v_exp_f32_e32 v111, v111
	v_pk_add_f32 v[150:151], v[150:151], v[108:109]
	s_waitcnt lgkmcnt(10)
	v_mfma_f32_32x32x16_bf16 v[204:219], v[224:227], v[124:127], v[204:219]
	ds_read_b64_tr_b16 v[220:221], v228 offset:4096
	ds_read_b64_tr_b16 v[222:223], v228 offset:6144
	v_pk_add_f32 v[150:151], v[150:151], v[110:111]
	v_exp_f32_e32 v112, v112
	v_exp_f32_e32 v113, v113
	v_cvt_pk_bf16_f32 v104, v108, v109
	s_waitcnt lgkmcnt(11)
	v_mfma_f32_32x32x16_bf16 v[188:203], v[232:235], v[128:131], v[188:203]
	ds_read_b64_tr_b16 v[224:225], v229 offset:4096
	ds_read_b64_tr_b16 v[226:227], v229 offset:6144
	v_cvt_pk_bf16_f32 v105, v110, v111
	v_exp_f32_e32 v114, v114
	v_exp_f32_e32 v115, v115
	s_waitcnt lgkmcnt(12)
	v_mfma_f32_32x32x16_bf16 v[204:219], v[236:239], v[128:131], v[204:219]
	ds_read_b64_tr_b16 v[232:233], v230 offset:4096
	ds_read_b64_tr_b16 v[234:235], v230 offset:6144
	v_pk_add_f32 v[150:151], v[150:151], v[112:113]
	v_pk_add_f32 v[150:151], v[150:151], v[114:115]
	v_cvt_pk_bf16_f32 v106, v112, v113
	v_cvt_pk_bf16_f32 v107, v114, v115
	s_add_u32 s8, s8, 0x40000
	s_addc_u32 s9, s9, 0
	s_waitcnt vmcnt(4)
	s_barrier
	s_sub_u32 s10, s10, 1
	s_cbranch_scc1 .LatA_evs_m1

; __device__ __forceinline__ void attn_unit(LAS unsigned char* lds, const bf16_t* Z, bf16_t* A2, const float* tabg, int seq_base, int S, int h, int qb, float lam) {
;     ...
;             bf16x8 kf[8];
; #pragma unroll
;             for (int ds = 0; ds < 4; ++ds) { kf[2 * ds] = *(const LAS bf16x8*)(Kt + (kfo ^ (unsigned)(ds << 5))); kf[2 * ds + 1] = *(const LAS bf16x8*)(Kt + 32 * 256 + (kfo ^ (unsigned)(ds << 5))); }
;             __builtin_amdgcn_sched_barrier(0);
;             p0 = __builtin_amdgcn_mfma_f32_32x32x16_bf16(kf[0], qf[0], cblk, 0, 0, 0);
;             p1 = __builtin_amdgcn_mfma_f32_32x32x16_bf16(kf[1], qf[0], cblk, 0, 0, 0);
; #pragma unroll
;             for (int ds = 1; ds < 4; ++ds) {
;                 p0 = __builtin_amdgcn_mfma_f32_32x32x16_bf16(kf[2 * ds], qf[ds], p0, 0, 0, 0);
;                 p1 = __builtin_amdgcn_mfma_f32_32x32x16_bf16(kf[2 * ds + 1], qf[ds], p1, 0, 0, 0);
;             }
;         }
;     ...
;         const unsigned vbase = (unsigned)(size_t)Vt + vfo;
;         s16x4 va[8], vb[8];
;         VREADS1(va, 0);
;         if (near) {
;             const LAS float* tp = tab + (kv0 + 4 * hi - (qlo + r32) + 224);
; #pragma unroll
;             for (int r = 0; r < 16; ++r) { p0[r] += tp[(r & 3) + 8 * (r >> 2)]; p1[r] += tp[32 + (r & 3) + 8 * (r >> 2)]; }
;         }
;         float mx = max2f(max16f(p0), max16f(p1));
;         const bool first = (t == 0);
;         if (first || __any(mx > THR)) {
;             { auto rr = __builtin_amdgcn_permlane32_swap(__float_as_uint(mx), __float_as_uint(mx), false, false); mx = max2f(__uint_as_float(rr[0]), __uint_as_float(rr[1])); }
;             const float delta = first ? mx : fmaxf(mx, 0.f);
;             const float alpha = first ? 1.0f : __builtin_amdgcn_exp2f(-delta);
;             mu += delta; ls2 *= alpha;
;             if (!first) {
;                 asm volatile("" ::: "memory");
;                 scr[r32] = alpha;
;                 asm volatile("s_waitcnt lgkmcnt(0)" ::: "memory");
; #pragma unroll
;                 for (int g = 0; g < 4; ++g) { const f32x4 a4 = *(const LAS f32x4*)(scr + 8 * g + 4 * hi);
; #pragma unroll
;                     for (int d = 0; d < 4; ++d) { O[d][4 * g + 0] *= a4[0]; O[d][4 * g + 1] *= a4[1]; O[d][4 * g + 2] *= a4[2]; O[d][4 * g + 3] *= a4[3]; } }
;                 asm volatile("s_waitcnt lgkmcnt(0)" ::: "memory");
;             }
; #pragma unroll
.LatA_rareret_m3:
	s_waitcnt lgkmcnt(12)
	v_mfma_f32_32x32x16_bf16 v[20:35], v[88:91], v[220:223], v[20:35]
	ds_read_b64_tr_b16 v[144:145], v231 offset:40960
	ds_read_b64_tr_b16 v[146:147], v231 offset:43008
	v_exp_f32_e32 v188, v188
	v_exp_f32_e32 v189, v189
	v_exp_f32_e32 v190, v190
	s_waitcnt lgkmcnt(12)
	v_mfma_f32_32x32x16_bf16 v[36:51], v[88:91], v[224:227], v[36:51]
	ds_read_b64_tr_b16 v[220:221], v228 offset:45056
	ds_read_b64_tr_b16 v[222:223], v228 offset:47104
	v_exp_f32_e32 v191, v191
	v_pk_add_f32 v[150:151], v[150:151], v[188:189]
	s_waitcnt lgkmcnt(12)
	v_mfma_f32_32x32x16_bf16 v[52:67], v[88:91], v[232:235], v[52:67]
	ds_read_b64_tr_b16 v[224:225], v229 offset:45056
	ds_read_b64_tr_b16 v[226:227], v229 offset:47104
	v_pk_add_f32 v[150:151], v[150:151], v[190:191]
	v_exp_f32_e32 v192, v192
	v_exp_f32_e32 v193, v193
	v_cvt_pk_bf16_f32 v188, v188, v189
	s_waitcnt lgkmcnt(12)
	s_add_u32 m0, s29, 0x4000
	v_mfma_f32_32x32x16_bf16 v[68:83], v[88:91], v[236:239], v[68:83]
	global_load_lds_dwordx4 v174, s[8:9]
	ds_read_b64_tr_b16 v[232:233], v230 offset:45056
	ds_read_b64_tr_b16 v[234:235], v230 offset:47104
	v_cvt_pk_bf16_f32 v189, v190, v191
	v_exp_f32_e32 v194, v194
	v_exp_f32_e32 v195, v195
	s_waitcnt lgkmcnt(12)
	v_mfma_f32_32x32x16_bf16 v[20:35], v[100:103], v[132:135], v[20:35]
	ds_read_b64_tr_b16 v[236:237], v231 offset:45056
	ds_read_b64_tr_b16 v[238:239], v231 offset:47104
	v_pk_add_f32 v[150:151], v[150:151], v[192:193]
	v_pk_add_f32 v[150:151], v[150:151], v[194:195]
	v_cvt_pk_bf16_f32 v190, v192, v193
	v_cvt_pk_bf16_f32 v191, v194, v195
	s_waitcnt lgkmcnt(12)
	v_mfma_f32_32x32x16_bf16 v[36:51], v[100:103], v[136:139], v[36:51]
	ds_read_b128 v[132:135], v19
	v_exp_f32_e32 v196, v196
	v_exp_f32_e32 v197, v197
	v_exp_f32_e32 v198, v198
	s_waitcnt lgkmcnt(11)
	v_mfma_f32_32x32x16_bf16 v[52:67], v[100:103], v[140:143], v[52:67]
	ds_read_b128 v[136:139], v19 offset:8192
	v_exp_f32_e32 v199, v199
	v_pk_add_f32 v[150:151], v[150:151], v[196:197]
	s_waitcnt lgkmcnt(10)
	s_add_u32 m0, s28, 0xa000
	v_mfma_f32_32x32x16_bf16 v[68:83], v[100:103], v[144:147], v[68:83]
	global_load_lds_dwordx4 v173, s[8:9]
	ds_read_b128 v[140:143], v180
	v_pk_add_f32 v[150:151], v[150:151], v[198:199]
	v_exp_f32_e32 v200, v200
	v_exp_f32_e32 v201, v201
	v_cvt_pk_bf16_f32 v192, v196, v197
	s_waitcnt lgkmcnt(9)
	v_mfma_f32_32x32x16_bf16 v[20:35], v[104:107], v[220:223], v[20:35]
	ds_read_b128 v[144:147], v180 offset:8192
	v_cvt_pk_bf16_f32 v193, v198, v199
	v_exp_f32_e32 v202, v202
	v_exp_f32_e32 v203, v203
	s_waitcnt lgkmcnt(8)
	v_mfma_f32_32x32x16_bf16 v[36:51], v[104:107], v[224:227], v[36:51]
	ds_read_b128 v[220:223], v181
	v_pk_add_f32 v[150:151], v[150:151], v[200:201]
	v_pk_add_f32 v[150:151], v[150:151], v[202:203]
	v_cvt_pk_bf16_f32 v194, v200, v201
	v_cvt_pk_bf16_f32 v195, v202, v203
	s_waitcnt lgkmcnt(7)
	v_mfma_f32_32x32x16_bf16 v[52:67], v[104:107], v[232:235], v[52:67]
	ds_read_b128 v[224:227], v181 offset:8192
	v_exp_f32_e32 v204, v204
	v_exp_f32_e32 v205, v205
	v_exp_f32_e32 v206, v206
	s_waitcnt lgkmcnt(6)
	s_add_u32 m0, s29, 0x6000
	v_mfma_f32_32x32x16_bf16 v[68:83], v[104:107], v[236:239], v[68:83]
	global_load_lds_dwordx4 v175, s[8:9]
	ds_read_b128 v[232:235], v182
	v_exp_f32_e32 v207, v207
	v_pk_add_f32 v[150:151], v[150:151], v[204:205]
	s_waitcnt lgkmcnt(6)
	v_mfma_f32_32x32x16_bf16 v[84:99], v[132:135], v[116:119], v[2:17]
	ds_read_b128 v[236:239], v182 offset:8192
	v_pk_add_f32 v[150:151], v[150:151], v[206:207]
	v_exp_f32_e32 v208, v208
	v_exp_f32_e32 v209, v209
	v_cvt_pk_bf16_f32 v204, v204, v205
	s_waitcnt lgkmcnt(6)
	v_mfma_f32_32x32x16_bf16 v[100:115], v[136:139], v[116:119], v[2:17]
	ds_read_b64_tr_b16 v[132:133], v168 offset:0
	ds_read_b64_tr_b16 v[134:135], v168 offset:2048
	v_cvt_pk_bf16_f32 v205, v206, v207
	v_exp_f32_e32 v210, v210
	v_exp_f32_e32 v211, v211
	s_waitcnt lgkmcnt(7)
	v_mfma_f32_32x32x16_bf16 v[84:99], v[140:143], v[120:123], v[84:99]
	ds_read_b64_tr_b16 v[136:137], v169 offset:0
	ds_read_b64_tr_b16 v[138:139], v169 offset:2048
	v_pk_add_f32 v[150:151], v[150:151], v[208:209]
	v_pk_add_f32 v[150:151], v[150:151], v[210:211]
	v_cvt_pk_bf16_f32 v206, v208, v209
	v_cvt_pk_bf16_f32 v207, v210, v211
	s_waitcnt lgkmcnt(8)
	v_mfma_f32_32x32x16_bf16 v[100:115], v[144:147], v[120:123], v[100:115]
	ds_read_b64_tr_b16 v[140:141], v170 offset:0
	ds_read_b64_tr_b16 v[142:143], v170 offset:2048
	v_exp_f32_e32 v212, v212
	v_exp_f32_e32 v213, v213
	v_exp_f32_e32 v214, v214
	s_waitcnt lgkmcnt(9)
	v_mfma_f32_32x32x16_bf16 v[84:99], v[220:223], v[124:127], v[84:99]
	ds_read_b64_tr_b16 v[144:145], v171 offset:0
	ds_read_b64_tr_b16 v[146:147], v171 offset:2048
	v_exp_f32_e32 v215, v215
	v_pk_add_f32 v[150:151], v[150:151], v[212:213]
	s_waitcnt lgkmcnt(10)
	v_mfma_f32_32x32x16_bf16 v[100:115], v[224:227], v[124:127], v[100:115]
	ds_read_b64_tr_b16 v[220:221], v168 offset:4096
	ds_read_b64_tr_b16 v[222:223], v168 offset:6144
	v_pk_add_f32 v[150:151], v[150:151], v[214:215]
	v_exp_f32_e32 v216, v216
	v_exp_f32_e32 v217, v217
	v_cvt_pk_bf16_f32 v208, v212, v213
	s_waitcnt lgkmcnt(11)
	v_mfma_f32_32x32x16_bf16 v[84:99], v[232:235], v[128:131], v[84:99]
	ds_read_b64_tr_b16 v[224:225], v169 offset:4096
	ds_read_b64_tr_b16 v[226:227], v169 offset:6144
	v_cvt_pk_bf16_f32 v209, v214, v215
	v_exp_f32_e32 v218, v218
	v_exp_f32_e32 v219, v219
	s_waitcnt lgkmcnt(12)
	v_mfma_f32_32x32x16_bf16 v[100:115], v[236:239], v[128:131], v[100:115]
	ds_read_b64_tr_b16 v[232:233], v170 offset:4096
	ds_read_b64_tr_b16 v[234:235], v170 offset:6144
	v_pk_add_f32 v[150:151], v[150:151], v[216:217]
	v_pk_add_f32 v[150:151], v[150:151], v[218:219]
	v_cvt_pk_bf16_f32 v210, v216, v217
	v_cvt_pk_bf16_f32 v211, v218, v219
	s_add_u32 s8, s8, 0x40000
	s_addc_u32 s9, s9, 0
	s_waitcnt vmcnt(4)
	s_barrier
	s_sub_u32 s36, s36, 1
	s_cmp_lg_u32 s36, 0
	s_cbranch_scc1 .LatA_loop
	s_sub_u32 s10, s10, 1
	s_cbranch_scc1 .LatA_evs_x4

; #define LAS __attribute__((address_space(3)))
; __device__ __forceinline__ void attn_unit(LAS unsigned char* lds, const bf16_t* Z, bf16_t* A2, const float* tabg, int seq_base, int S, int h, int qb, float lam) {
;     ...
;             for (int ds = 0; ds < 4; ++ds) { kf[2 * ds] = *(const LAS bf16x8*)(Kt + (kfo ^ (unsigned)(ds << 5))); kf[2 * ds + 1] = *(const LAS bf16x8*)(Kt + 32 * 256 + (kfo ^ (unsigned)(ds << 5))); }
;             __builtin_amdgcn_sched_barrier(0);
;             p0 = __builtin_amdgcn_mfma_f32_32x32x16_bf16(kf[0], qf[0], cblk, 0, 0, 0);
;             p1 = __builtin_amdgcn_mfma_f32_32x32x16_bf16(kf[1], qf[0], cblk, 0, 0, 0);
; #pragma unroll
;             for (int ds = 1; ds < 4; ++ds) {
;                 p0 = __builtin_amdgcn_mfma_f32_32x32x16_bf16(kf[2 * ds], qf[ds], p0, 0, 0, 0);
;                 p1 = __builtin_amdgcn_mfma_f32_32x32x16_bf16(kf[2 * ds + 1], qf[ds], p1, 0, 0, 0);
;             }
;         }
;     ...
;         const unsigned vbase = (unsigned)(size_t)Vt + vfo;
;         s16x4 va[8], vb[8];
;         VREADS1(va, 0);
;         if (near) {
;             const LAS float* tp = tab + (kv0 + 4 * hi - (qlo + r32) + 224);
; #pragma unroll
;             for (int r = 0; r < 16; ++r) { p0[r] += tp[(r & 3) + 8 * (r >> 2)]; p1[r] += tp[32 + (r & 3) + 8 * (r >> 2)]; }
;         }
;         float mx = max2f(max16f(p0), max16f(p1));
;         const bool first = (t == 0);
;         if (first || __any(mx > THR)) {
;             { auto rr = __builtin_amdgcn_permlane32_swap(__float_as_uint(mx), __float_as_uint(mx), false, false); mx = max2f(__uint_as_float(rr[0]), __uint_as_float(rr[1])); }
;             const float delta = first ? mx : fmaxf(mx, 0.f);
;             const float alpha = first ? 1.0f : __builtin_amdgcn_exp2f(-delta);
;             mu += delta; ls2 *= alpha;
;             if (!first) {
;                 asm volatile("" ::: "memory");
;                 scr[r32] = alpha;
;                 asm volatile("s_waitcnt lgkmcnt(0)" ::: "memory");
; #pragma unroll
;                 for (int g = 0; g < 4; ++g) { const f32x4 a4 = *(const LAS f32x4*)(scr + 8 * g + 4 * hi);
; #pragma unroll
;                     for (int d = 0; d < 4; ++d) { O[d][4 * g + 0] *= a4[0]; O[d][4 * g + 1] *= a4[1]; O[d][4 * g + 2] *= a4[2]; O[d][4 * g + 3] *= a4[3]; } }
;                 asm volatile("s_waitcnt lgkmcnt(0)" ::: "memory");
;             }
; #pragma unroll
.LatA_evret_x3:
	s_waitcnt lgkmcnt(12)
	v_mfma_f32_32x32x16_bf16 v[20:35], v[84:87], v[132:135], v[20:35]
	ds_read_b64_tr_b16 v[236:237], v231 offset:4096
	ds_read_b64_tr_b16 v[238:239], v231 offset:6144
	s_waitcnt lgkmcnt(12)
	v_mfma_f32_32x32x16_bf16 v[36:51], v[84:87], v[136:139], v[36:51]
	ds_read_b64_tr_b16 v[132:133], v228 offset:8192
	ds_read_b64_tr_b16 v[134:135], v228 offset:10240
	s_waitcnt lgkmcnt(12)
	v_mfma_f32_32x32x16_bf16 v[52:67], v[84:87], v[140:143], v[52:67]
	ds_read_b64_tr_b16 v[136:137], v229 offset:8192
	ds_read_b64_tr_b16 v[138:139], v229 offset:10240
	s_waitcnt lgkmcnt(12)
	v_mfma_f32_32x32x16_bf16 v[68:83], v[84:87], v[144:147], v[68:83]
	ds_read_b64_tr_b16 v[140:141], v230 offset:8192
	ds_read_b64_tr_b16 v[142:143], v230 offset:10240
	v_max3_f32 v251, v188, v189, v190
	v_max3_f32 v252, v191, v192, v193
	v_max3_f32 v251, v251, v194, v195
	v_max3_f32 v252, v252, v196, v197
	v_max3_f32 v251, v251, v198, v199
	v_max3_f32 v252, v252, v200, v201
	v_max3_f32 v251, v251, v202, v203
	v_max3_f32 v252, v252, v204, v205
	v_max3_f32 v251, v251, v206, v207
	v_max3_f32 v252, v252, v208, v209
	v_max3_f32 v251, v251, v210, v211
	v_max3_f32 v252, v252, v212, v213
	v_max3_f32 v251, v251, v214, v215
	v_max3_f32 v252, v252, v216, v217
	v_max3_f32 v251, v251, v218, v219
	v_max_f32_e32 v251, v251, v252
	v_cmp_lt_f32_e32 vcc, 0x41000000, v251
	s_cbranch_vccnz .LatA_rs_x3
.LatA_rareret_x3:
	s_waitcnt lgkmcnt(12)
	v_mfma_f32_32x32x16_bf16 v[20:35], v[88:91], v[220:223], v[20:35]
	ds_read_b64_tr_b16 v[144:145], v231 offset:8192
	ds_read_b64_tr_b16 v[146:147], v231 offset:10240
	v_exp_f32_e32 v188, v188
	v_exp_f32_e32 v189, v189
	v_exp_f32_e32 v190, v190
	s_waitcnt lgkmcnt(12)
	v_mfma_f32_32x32x16_bf16 v[36:51], v[88:91], v[224:227], v[36:51]
	ds_read_b64_tr_b16 v[220:221], v228 offset:12288
	ds_read_b64_tr_b16 v[222:223], v228 offset:14336
	v_exp_f32_e32 v191, v191
	v_pk_add_f32 v[150:151], v[150:151], v[188:189]
	s_waitcnt lgkmcnt(12)
	v_mfma_f32_32x32x16_bf16 v[52:67], v[88:91], v[232:235], v[52:67]
	ds_read_b64_tr_b16 v[224:225], v229 offset:12288
	ds_read_b64_tr_b16 v[226:227], v229 offset:14336
	v_pk_add_f32 v[150:151], v[150:151], v[190:191]
	v_exp_f32_e32 v192, v192
	v_exp_f32_e32 v193, v193
	v_cvt_pk_bf16_f32 v188, v188, v189
	s_waitcnt lgkmcnt(12)
	s_add_u32 m0, s29, 0xd000
	v_mfma_f32_32x32x16_bf16 v[68:83], v[88:91], v[236:239], v[68:83]
	global_load_lds_dwordx4 v174, s[8:9]
	ds_read_b64_tr_b16 v[232:233], v230 offset:12288
	ds_read_b64_tr_b16 v[234:235], v230 offset:14336
	v_cvt_pk_bf16_f32 v189, v190, v191
	v_exp_f32_e32 v194, v194
	v_exp_f32_e32 v195, v195
	s_waitcnt lgkmcnt(12)
	v_mfma_f32_32x32x16_bf16 v[20:35], v[100:103], v[132:135], v[20:35]
	ds_read_b64_tr_b16 v[236:237], v231 offset:12288
	ds_read_b64_tr_b16 v[238:239], v231 offset:14336
	v_pk_add_f32 v[150:151], v[150:151], v[192:193]
	v_pk_add_f32 v[150:151], v[150:151], v[194:195]
	v_cvt_pk_bf16_f32 v190, v192, v193
	v_cvt_pk_bf16_f32 v191, v194, v195
	s_waitcnt lgkmcnt(12)
	v_mfma_f32_32x32x16_bf16 v[36:51], v[100:103], v[136:139], v[36:51]
	ds_read_b128 v[132:135], v19 offset:32768
	v_exp_f32_e32 v196, v196
	v_exp_f32_e32 v197, v197
	v_exp_f32_e32 v198, v198
	s_waitcnt lgkmcnt(11)
	v_mfma_f32_32x32x16_bf16 v[52:67], v[100:103], v[140:143], v[52:67]
	ds_read_b128 v[136:139], v19 offset:40960
	v_exp_f32_e32 v199, v199
	v_pk_add_f32 v[150:151], v[150:151], v[196:197]
	s_waitcnt lgkmcnt(10)
	v_mfma_f32_32x32x16_bf16 v[68:83], v[100:103], v[144:147], v[68:83]
	ds_read_b128 v[140:143], v180 offset:32768
	v_pk_add_f32 v[150:151], v[150:151], v[198:199]
	v_exp_f32_e32 v200, v200
	v_exp_f32_e32 v201, v201
	v_cvt_pk_bf16_f32 v192, v196, v197
	s_waitcnt lgkmcnt(9)
	v_mfma_f32_32x32x16_bf16 v[20:35], v[104:107], v[220:223], v[20:35]
	ds_read_b128 v[144:147], v180 offset:40960
	v_cvt_pk_bf16_f32 v193, v198, v199
	v_exp_f32_e32 v202, v202
	v_exp_f32_e32 v203, v203
	s_waitcnt lgkmcnt(8)
	v_mfma_f32_32x32x16_bf16 v[36:51], v[104:107], v[224:227], v[36:51]
	ds_read_b128 v[220:223], v181 offset:32768
	v_pk_add_f32 v[150:151], v[150:151], v[200:201]
	v_pk_add_f32 v[150:151], v[150:151], v[202:203]
	v_cvt_pk_bf16_f32 v194, v200, v201
	v_cvt_pk_bf16_f32 v195, v202, v203
	s_waitcnt lgkmcnt(7)
	v_mfma_f32_32x32x16_bf16 v[52:67], v[104:107], v[232:235], v[52:67]
	ds_read_b128 v[224:227], v181 offset:40960
	v_exp_f32_e32 v204, v204
	v_exp_f32_e32 v205, v205
	v_exp_f32_e32 v206, v206
	s_waitcnt lgkmcnt(6)
	s_add_u32 m0, s29, 0xf000
	v_mfma_f32_32x32x16_bf16 v[68:83], v[104:107], v[236:239], v[68:83]
	global_load_lds_dwordx4 v175, s[8:9]
	ds_read_b128 v[232:235], v182 offset:32768
	v_exp_f32_e32 v207, v207
	v_pk_add_f32 v[150:151], v[150:151], v[204:205]
	s_waitcnt lgkmcnt(6)
	v_mfma_f32_32x32x16_bf16 v[84:99], v[132:135], v[116:119], v[2:17]
	ds_read_b128 v[236:239], v182 offset:40960
	v_pk_add_f32 v[150:151], v[150:151], v[206:207]
	v_exp_f32_e32 v208, v208
	v_exp_f32_e32 v209, v209
	v_cvt_pk_bf16_f32 v204, v204, v205
	s_waitcnt lgkmcnt(6)
	v_mfma_f32_32x32x16_bf16 v[100:115], v[136:139], v[116:119], v[2:17]
	ds_read_b64_tr_b16 v[132:133], v228 offset:16384
	ds_read_b64_tr_b16 v[134:135], v228 offset:18432
	v_cvt_pk_bf16_f32 v205, v206, v207
	v_exp_f32_e32 v210, v210
	v_exp_f32_e32 v211, v211
	s_waitcnt lgkmcnt(7)
	v_mfma_f32_32x32x16_bf16 v[84:99], v[140:143], v[120:123], v[84:99]
	ds_read_b64_tr_b16 v[136:137], v229 offset:16384
	ds_read_b64_tr_b16 v[138:139], v229 offset:18432
	v_pk_add_f32 v[150:151], v[150:151], v[208:209]
	v_pk_add_f32 v[150:151], v[150:151], v[210:211]
	v_cvt_pk_bf16_f32 v206, v208, v209
	v_cvt_pk_bf16_f32 v207, v210, v211
	s_waitcnt lgkmcnt(8)
; #define LAS __attribute__((address_space(3)))
; __device__ __forceinline__ void attn_unit(LAS unsigned char* lds, const bf16_t* Z, bf16_t* A2, const float* tabg, int seq_base, int S, int h, int qb, float lam) {
;     ...
;             for (int ds = 0; ds < 4; ++ds) { kf[2 * ds] = *(const LAS bf16x8*)(Kt + (kfo ^ (unsigned)(ds << 5))); kf[2 * ds + 1] = *(const LAS bf16x8*)(Kt + 32 * 256 + (kfo ^ (unsigned)(ds << 5))); }
;             __builtin_amdgcn_sched_barrier(0);
;             p0 = __builtin_amdgcn_mfma_f32_32x32x16_bf16(kf[0], qf[0], cblk, 0, 0, 0);
;             p1 = __builtin_amdgcn_mfma_f32_32x32x16_bf16(kf[1], qf[0], cblk, 0, 0, 0);
; #pragma unroll
;             for (int ds = 1; ds < 4; ++ds) {
;                 p0 = __builtin_amdgcn_mfma_f32_32x32x16_bf16(kf[2 * ds], qf[ds], p0, 0, 0, 0);
;                 p1 = __builtin_amdgcn_mfma_f32_32x32x16_bf16(kf[2 * ds + 1], qf[ds], p1, 0, 0, 0);
;             }
;         }
;     ...
;         const unsigned vbase = (unsigned)(size_t)Vt + vfo;
;         s16x4 va[8], vb[8];
;         VREADS1(va, 0);
;         if (near) {
;             const LAS float* tp = tab + (kv0 + 4 * hi - (qlo + r32) + 224);
; #pragma unroll
;             for (int r = 0; r < 16; ++r) { p0[r] += tp[(r & 3) + 8 * (r >> 2)]; p1[r] += tp[32 + (r & 3) + 8 * (r >> 2)]; }
;         }
;         float mx = max2f(max16f(p0), max16f(p1));
;         const bool first = (t == 0);
;         if (first || __any(mx > THR)) {
;             { auto rr = __builtin_amdgcn_permlane32_swap(__float_as_uint(mx), __float_as_uint(mx), false, false); mx = max2f(__uint_as_float(rr[0]), __uint_as_float(rr[1])); }
;             const float delta = first ? mx : fmaxf(mx, 0.f);
;             const float alpha = first ? 1.0f : __builtin_amdgcn_exp2f(-delta);
;             mu += delta; ls2 *= alpha;
;             if (!first) {
;                 asm volatile("" ::: "memory");
;                 scr[r32] = alpha;
;                 asm volatile("s_waitcnt lgkmcnt(0)" ::: "memory");
; #pragma unroll
;                 for (int g = 0; g < 4; ++g) { const f32x4 a4 = *(const LAS f32x4*)(scr + 8 * g + 4 * hi);
; #pragma unroll
;                     for (int d = 0; d < 4; ++d) { O[d][4 * g + 0] *= a4[0]; O[d][4 * g + 1] *= a4[1]; O[d][4 * g + 2] *= a4[2]; O[d][4 * g + 3] *= a4[3]; } }
;                 asm volatile("s_waitcnt lgkmcnt(0)" ::: "memory");
;             }
; #pragma unroll
	v_mfma_f32_32x32x16_bf16 v[100:115], v[144:147], v[120:123], v[100:115]
	ds_read_b64_tr_b16 v[140:141], v230 offset:16384
	ds_read_b64_tr_b16 v[142:143], v230 offset:18432
	v_exp_f32_e32 v212, v212
	v_exp_f32_e32 v213, v213
	v_exp_f32_e32 v214, v214
	s_waitcnt lgkmcnt(9)
	v_mfma_f32_32x32x16_bf16 v[84:99], v[220:223], v[124:127], v[84:99]
	ds_read_b64_tr_b16 v[144:145], v231 offset:16384
	ds_read_b64_tr_b16 v[146:147], v231 offset:18432
	v_exp_f32_e32 v215, v215
	v_pk_add_f32 v[150:151], v[150:151], v[212:213]
	s_waitcnt lgkmcnt(10)
	v_mfma_f32_32x32x16_bf16 v[100:115], v[224:227], v[124:127], v[100:115]
	ds_read_b64_tr_b16 v[220:221], v228 offset:20480
	ds_read_b64_tr_b16 v[222:223], v228 offset:22528
	v_pk_add_f32 v[150:151], v[150:151], v[214:215]
	v_exp_f32_e32 v216, v216
	v_exp_f32_e32 v217, v217
	v_cvt_pk_bf16_f32 v208, v212, v213
	s_waitcnt lgkmcnt(11)
	v_mfma_f32_32x32x16_bf16 v[84:99], v[232:235], v[128:131], v[84:99]
	ds_read_b64_tr_b16 v[224:225], v229 offset:20480
	ds_read_b64_tr_b16 v[226:227], v229 offset:22528
	v_cvt_pk_bf16_f32 v209, v214, v215
	v_exp_f32_e32 v218, v218
	v_exp_f32_e32 v219, v219
	s_waitcnt lgkmcnt(12)
	v_mfma_f32_32x32x16_bf16 v[100:115], v[236:239], v[128:131], v[100:115]
	ds_read_b64_tr_b16 v[232:233], v230 offset:20480
	ds_read_b64_tr_b16 v[234:235], v230 offset:22528
	v_pk_add_f32 v[150:151], v[150:151], v[216:217]
	v_pk_add_f32 v[150:151], v[150:151], v[218:219]
	v_cvt_pk_bf16_f32 v210, v216, v217
	v_cvt_pk_bf16_f32 v211, v218, v219
	s_add_u32 s8, s8, 0x40000
	s_addc_u32 s9, s9, 0
	s_waitcnt vmcnt(2)
	s_barrier
	s_sub_u32 s10, s10, 1
	s_cbranch_scc1 .LatA_evs_x2
.LatA_evret_x2:
	s_waitcnt lgkmcnt(12)
	v_mfma_f32_32x32x16_bf16 v[20:35], v[188:191], v[132:135], v[20:35]
	ds_read_b64_tr_b16 v[236:237], v231 offset:20480
	ds_read_b64_tr_b16 v[238:239], v231 offset:22528
	s_waitcnt lgkmcnt(12)
	v_mfma_f32_32x32x16_bf16 v[36:51], v[188:191], v[136:139], v[36:51]
	ds_read_b64_tr_b16 v[132:133], v228 offset:24576
	ds_read_b64_tr_b16 v[134:135], v228 offset:26624
	s_waitcnt lgkmcnt(12)
	v_mfma_f32_32x32x16_bf16 v[52:67], v[188:191], v[140:143], v[52:67]
	ds_read_b64_tr_b16 v[136:137], v229 offset:24576
	ds_read_b64_tr_b16 v[138:139], v229 offset:26624
	s_waitcnt lgkmcnt(12)
	v_mfma_f32_32x32x16_bf16 v[68:83], v[188:191], v[144:147], v[68:83]
	ds_read_b64_tr_b16 v[140:141], v230 offset:24576
	ds_read_b64_tr_b16 v[142:143], v230 offset:26624
	v_max3_f32 v251, v84, v85, v86
	v_max3_f32 v252, v87, v88, v89
	v_max3_f32 v251, v251, v90, v91
	v_max3_f32 v252, v252, v92, v93
	v_max3_f32 v251, v251, v94, v95
	v_max3_f32 v252, v252, v96, v97
	v_max3_f32 v251, v251, v98, v99
	v_max3_f32 v252, v252, v100, v101
	v_max3_f32 v251, v251, v102, v103
	v_max3_f32 v252, v252, v104, v105
	v_max3_f32 v251, v251, v106, v107
	v_max3_f32 v252, v252, v108, v109
	v_max3_f32 v251, v251, v110, v111
	v_max3_f32 v252, v252, v112, v113
	v_max3_f32 v251, v251, v114, v115
	v_max_f32_e32 v251, v251, v252
	v_cmp_lt_f32_e32 vcc, 0x41000000, v251
	s_cbranch_vccnz .LatA_rs_x2
.LatA_rareret_x2:
	s_waitcnt lgkmcnt(12)
	v_mfma_f32_32x32x16_bf16 v[20:35], v[192:195], v[220:223], v[20:35]
	ds_read_b64_tr_b16 v[144:145], v231 offset:24576
	ds_read_b64_tr_b16 v[146:147], v231 offset:26624
	v_exp_f32_e32 v84, v84
	v_exp_f32_e32 v85, v85
	v_exp_f32_e32 v86, v86
	s_waitcnt lgkmcnt(12)
	v_mfma_f32_32x32x16_bf16 v[36:51], v[192:195], v[224:227], v[36:51]
	ds_read_b64_tr_b16 v[220:221], v228 offset:28672
	ds_read_b64_tr_b16 v[222:223], v228 offset:30720
	v_exp_f32_e32 v87, v87
	v_pk_add_f32 v[150:151], v[150:151], v[84:85]
	s_waitcnt lgkmcnt(12)
	v_mfma_f32_32x32x16_bf16 v[52:67], v[192:195], v[232:235], v[52:67]
	ds_read_b64_tr_b16 v[224:225], v229 offset:28672
	ds_read_b64_tr_b16 v[226:227], v229 offset:30720
	v_pk_add_f32 v[150:151], v[150:151], v[86:87]
	v_exp_f32_e32 v88, v88
	v_exp_f32_e32 v89, v89
	v_cvt_pk_bf16_f32 v84, v84, v85
	s_waitcnt lgkmcnt(12)
	v_mfma_f32_32x32x16_bf16 v[68:83], v[192:195], v[236:239], v[68:83]
	ds_read_b64_tr_b16 v[232:233], v230 offset:28672
	ds_read_b64_tr_b16 v[234:235], v230 offset:30720
	v_cvt_pk_bf16_f32 v85, v86, v87
	v_exp_f32_e32 v90, v90
	v_exp_f32_e32 v91, v91
	s_waitcnt lgkmcnt(12)
	v_mfma_f32_32x32x16_bf16 v[20:35], v[204:207], v[132:135], v[20:35]
	ds_read_b64_tr_b16 v[236:237], v231 offset:28672
	ds_read_b64_tr_b16 v[238:239], v231 offset:30720
	v_pk_add_f32 v[150:151], v[150:151], v[88:89]
	v_pk_add_f32 v[150:151], v[150:151], v[90:91]
	v_cvt_pk_bf16_f32 v86, v88, v89
	v_cvt_pk_bf16_f32 v87, v90, v91
	s_waitcnt lgkmcnt(12)
	v_mfma_f32_32x32x16_bf16 v[36:51], v[204:207], v[136:139], v[36:51]
	ds_read_b128 v[132:135], v164
	v_exp_f32_e32 v92, v92
	v_exp_f32_e32 v93, v93
	v_exp_f32_e32 v94, v94
	s_waitcnt lgkmcnt(11)
	v_mfma_f32_32x32x16_bf16 v[52:67], v[204:207], v[140:143], v[52:67]
	ds_read_b128 v[136:139], v164 offset:8192
	v_exp_f32_e32 v95, v95
	v_pk_add_f32 v[150:151], v[150:151], v[92:93]
	s_waitcnt lgkmcnt(10)
	v_mfma_f32_32x32x16_bf16 v[68:83], v[204:207], v[144:147], v[68:83]
	ds_read_b128 v[140:143], v165
	v_pk_add_f32 v[150:151], v[150:151], v[94:95]
	v_exp_f32_e32 v96, v96
	v_exp_f32_e32 v97, v97
	v_cvt_pk_bf16_f32 v88, v92, v93
	s_waitcnt lgkmcnt(9)
	v_mfma_f32_32x32x16_bf16 v[20:35], v[208:211], v[220:223], v[20:35]
	ds_read_b128 v[144:147], v165 offset:8192
	v_cvt_pk_bf16_f32 v89, v94, v95
	v_exp_f32_e32 v98, v98
	v_exp_f32_e32 v99, v99
	s_waitcnt lgkmcnt(8)
	v_mfma_f32_32x32x16_bf16 v[36:51], v[208:211], v[224:227], v[36:51]
	ds_read_b128 v[220:223], v166
	v_pk_add_f32 v[150:151], v[150:151], v[96:97]
	v_pk_add_f32 v[150:151], v[150:151], v[98:99]
	v_cvt_pk_bf16_f32 v90, v96, v97
	v_cvt_pk_bf16_f32 v91, v98, v99
	s_waitcnt lgkmcnt(7)
; #define LAS __attribute__((address_space(3)))
; __device__ __forceinline__ void attn_unit(LAS unsigned char* lds, const bf16_t* Z, bf16_t* A2, const float* tabg, int seq_base, int S, int h, int qb, float lam) {
;     ...
;             for (int ds = 0; ds < 4; ++ds) { kf[2 * ds] = *(const LAS bf16x8*)(Kt + (kfo ^ (unsigned)(ds << 5))); kf[2 * ds + 1] = *(const LAS bf16x8*)(Kt + 32 * 256 + (kfo ^ (unsigned)(ds << 5))); }
;             __builtin_amdgcn_sched_barrier(0);
;             p0 = __builtin_amdgcn_mfma_f32_32x32x16_bf16(kf[0], qf[0], cblk, 0, 0, 0);
;             p1 = __builtin_amdgcn_mfma_f32_32x32x16_bf16(kf[1], qf[0], cblk, 0, 0, 0);
; #pragma unroll
;             for (int ds = 1; ds < 4; ++ds) {
;                 p0 = __builtin_amdgcn_mfma_f32_32x32x16_bf16(kf[2 * ds], qf[ds], p0, 0, 0, 0);
;                 p1 = __builtin_amdgcn_mfma_f32_32x32x16_bf16(kf[2 * ds + 1], qf[ds], p1, 0, 0, 0);
;             }
;         }
;     ...
;         const unsigned vbase = (unsigned)(size_t)Vt + vfo;
;         s16x4 va[8], vb[8];
;         VREADS1(va, 0);
;         if (near) {
;             const LAS float* tp = tab + (kv0 + 4 * hi - (qlo + r32) + 224);
; #pragma unroll
;             for (int r = 0; r < 16; ++r) { p0[r] += tp[(r & 3) + 8 * (r >> 2)]; p1[r] += tp[32 + (r & 3) + 8 * (r >> 2)]; }
;         }
;         float mx = max2f(max16f(p0), max16f(p1));
;         const bool first = (t == 0);
;         if (first || __any(mx > THR)) {
;             { auto rr = __builtin_amdgcn_permlane32_swap(__float_as_uint(mx), __float_as_uint(mx), false, false); mx = max2f(__uint_as_float(rr[0]), __uint_as_float(rr[1])); }
;             const float delta = first ? mx : fmaxf(mx, 0.f);
;             const float alpha = first ? 1.0f : __builtin_amdgcn_exp2f(-delta);
;             mu += delta; ls2 *= alpha;
;             if (!first) {
;                 asm volatile("" ::: "memory");
;                 scr[r32] = alpha;
;                 asm volatile("s_waitcnt lgkmcnt(0)" ::: "memory");
; #pragma unroll
;                 for (int g = 0; g < 4; ++g) { const f32x4 a4 = *(const LAS f32x4*)(scr + 8 * g + 4 * hi);
; #pragma unroll
;                     for (int d = 0; d < 4; ++d) { O[d][4 * g + 0] *= a4[0]; O[d][4 * g + 1] *= a4[1]; O[d][4 * g + 2] *= a4[2]; O[d][4 * g + 3] *= a4[3]; } }
;                 asm volatile("s_waitcnt lgkmcnt(0)" ::: "memory");
;             }
; #pragma unroll
	v_mfma_f32_32x32x16_bf16 v[52:67], v[208:211], v[232:235], v[52:67]
	ds_read_b128 v[224:227], v166 offset:8192
	v_exp_f32_e32 v100, v100
	v_exp_f32_e32 v101, v101
	v_exp_f32_e32 v102, v102
	s_waitcnt lgkmcnt(6)
	v_mfma_f32_32x32x16_bf16 v[68:83], v[208:211], v[236:239], v[68:83]
	ds_read_b128 v[232:235], v167
	v_exp_f32_e32 v103, v103
	v_pk_add_f32 v[150:151], v[150:151], v[100:101]
	s_waitcnt lgkmcnt(6)
	v_mfma_f32_32x32x16_bf16 v[188:203], v[132:135], v[116:119], v[2:17]
	ds_read_b128 v[236:239], v167 offset:8192
	v_pk_add_f32 v[150:151], v[150:151], v[102:103]
	v_exp_f32_e32 v104, v104
	v_exp_f32_e32 v105, v105
	v_cvt_pk_bf16_f32 v100, v100, v101
	s_waitcnt lgkmcnt(6)
	v_mfma_f32_32x32x16_bf16 v[204:219], v[136:139], v[116:119], v[2:17]
	ds_read_b64_tr_b16 v[132:133], v228 offset:32768
	ds_read_b64_tr_b16 v[134:135], v228 offset:34816
	v_cvt_pk_bf16_f32 v101, v102, v103
	v_exp_f32_e32 v106, v106
	v_exp_f32_e32 v107, v107
	s_waitcnt lgkmcnt(7)
	v_mfma_f32_32x32x16_bf16 v[188:203], v[140:143], v[120:123], v[188:203]
	ds_read_b64_tr_b16 v[136:137], v229 offset:32768
	ds_read_b64_tr_b16 v[138:139], v229 offset:34816
	v_pk_add_f32 v[150:151], v[150:151], v[104:105]
	v_pk_add_f32 v[150:151], v[150:151], v[106:107]
	v_cvt_pk_bf16_f32 v102, v104, v105
	v_cvt_pk_bf16_f32 v103, v106, v107
	s_waitcnt lgkmcnt(8)
	v_mfma_f32_32x32x16_bf16 v[204:219], v[144:147], v[120:123], v[204:219]
	ds_read_b64_tr_b16 v[140:141], v230 offset:32768
	ds_read_b64_tr_b16 v[142:143], v230 offset:34816
	v_exp_f32_e32 v108, v108
	v_exp_f32_e32 v109, v109
	v_exp_f32_e32 v110, v110
	s_waitcnt lgkmcnt(9)
	v_mfma_f32_32x32x16_bf16 v[188:203], v[220:223], v[124:127], v[188:203]
	ds_read_b64_tr_b16 v[144:145], v231 offset:32768
	ds_read_b64_tr_b16 v[146:147], v231 offset:34816
	v_exp_f32_e32 v111, v111
	v_pk_add_f32 v[150:151], v[150:151], v[108:109]
	s_waitcnt lgkmcnt(10)
	v_mfma_f32_32x32x16_bf16 v[204:219], v[224:227], v[124:127], v[204:219]
	ds_read_b64_tr_b16 v[220:221], v228 offset:36864
	ds_read_b64_tr_b16 v[222:223], v228 offset:38912
	v_pk_add_f32 v[150:151], v[150:151], v[110:111]
	v_exp_f32_e32 v112, v112
	v_exp_f32_e32 v113, v113
	v_cvt_pk_bf16_f32 v104, v108, v109
	s_waitcnt lgkmcnt(11)
	v_mfma_f32_32x32x16_bf16 v[188:203], v[232:235], v[128:131], v[188:203]
	ds_read_b64_tr_b16 v[224:225], v229 offset:36864
	ds_read_b64_tr_b16 v[226:227], v229 offset:38912
	v_cvt_pk_bf16_f32 v105, v110, v111
	v_exp_f32_e32 v114, v114
	v_exp_f32_e32 v115, v115
	s_waitcnt lgkmcnt(12)
	v_mfma_f32_32x32x16_bf16 v[204:219], v[236:239], v[128:131], v[204:219]
	ds_read_b64_tr_b16 v[232:233], v230 offset:36864
	ds_read_b64_tr_b16 v[234:235], v230 offset:38912
	v_pk_add_f32 v[150:151], v[150:151], v[112:113]
	v_pk_add_f32 v[150:151], v[150:151], v[114:115]
	v_cvt_pk_bf16_f32 v106, v112, v113
	v_cvt_pk_bf16_f32 v107, v114, v115
	s_add_u32 s8, s8, 0x40000
	s_addc_u32 s9, s9, 0
	s_waitcnt vmcnt(0)
	s_barrier
	s_sub_u32 s10, s10, 1
	s_cbranch_scc1 .LatA_evs_x1
.LatA_evret_x1:
	s_waitcnt lgkmcnt(12)
	v_mfma_f32_32x32x16_bf16 v[20:35], v[84:87], v[132:135], v[20:35]
	ds_read_b64_tr_b16 v[236:237], v231 offset:36864
	ds_read_b64_tr_b16 v[238:239], v231 offset:38912
	s_waitcnt lgkmcnt(12)
	v_mfma_f32_32x32x16_bf16 v[36:51], v[84:87], v[136:139], v[36:51]
	ds_read_b64_tr_b16 v[132:133], v228 offset:40960
	ds_read_b64_tr_b16 v[134:135], v228 offset:43008
	s_waitcnt lgkmcnt(12)
	v_mfma_f32_32x32x16_bf16 v[52:67], v[84:87], v[140:143], v[52:67]
	ds_read_b64_tr_b16 v[136:137], v229 offset:40960
	ds_read_b64_tr_b16 v[138:139], v229 offset:43008
	s_waitcnt lgkmcnt(12)
	v_mfma_f32_32x32x16_bf16 v[68:83], v[84:87], v[144:147], v[68:83]
	ds_read_b64_tr_b16 v[140:141], v230 offset:40960
	ds_read_b64_tr_b16 v[142:143], v230 offset:43008
	v_max3_f32 v251, v188, v189, v190
	v_max3_f32 v252, v191, v192, v193
	v_max3_f32 v251, v251, v194, v195
	v_max3_f32 v252, v252, v196, v197
	v_max3_f32 v251, v251, v198, v199
	v_max3_f32 v252, v252, v200, v201
	v_max3_f32 v251, v251, v202, v203
	v_max3_f32 v252, v252, v204, v205
	v_max3_f32 v251, v251, v206, v207
	v_max3_f32 v252, v252, v208, v209
	v_max3_f32 v251, v251, v210, v211
	v_max3_f32 v252, v252, v212, v213
	v_max3_f32 v251, v251, v214, v215
	v_max3_f32 v252, v252, v216, v217
	v_max3_f32 v251, v251, v218, v219
	v_max_f32_e32 v251, v251, v252
	v_cmp_lt_f32_e32 vcc, 0x41000000, v251
	s_cbranch_vccnz .LatA_rs_x1
; #define LAS __attribute__((address_space(3)))
; __device__ __forceinline__ void attn_unit(LAS unsigned char* lds, const bf16_t* Z, bf16_t* A2, const float* tabg, int seq_base, int S, int h, int qb, float lam) {
;     ...
;         const unsigned vbase = (unsigned)(size_t)Vt + vfo;
;         s16x4 va[8], vb[8];
;         VREADS1(va, 0);
;         if (near) {
;             const LAS float* tp = tab + (kv0 + 4 * hi - (qlo + r32) + 224);
; #pragma unroll
;             for (int r = 0; r < 16; ++r) { p0[r] += tp[(r & 3) + 8 * (r >> 2)]; p1[r] += tp[32 + (r & 3) + 8 * (r >> 2)]; }
;         }
;         float mx = max2f(max16f(p0), max16f(p1));
;         const bool first = (t == 0);
;         if (first || __any(mx > THR)) {
;             { auto rr = __builtin_amdgcn_permlane32_swap(__float_as_uint(mx), __float_as_uint(mx), false, false); mx = max2f(__uint_as_float(rr[0]), __uint_as_float(rr[1])); }
;             const float delta = first ? mx : fmaxf(mx, 0.f);
;             const float alpha = first ? 1.0f : __builtin_amdgcn_exp2f(-delta);
;             mu += delta; ls2 *= alpha;
;             if (!first) {
;                 asm volatile("" ::: "memory");
;                 scr[r32] = alpha;
;                 asm volatile("s_waitcnt lgkmcnt(0)" ::: "memory");
; #pragma unroll
;                 for (int g = 0; g < 4; ++g) { const f32x4 a4 = *(const LAS f32x4*)(scr + 8 * g + 4 * hi);
; #pragma unroll
;                     for (int d = 0; d < 4; ++d) { O[d][4 * g + 0] *= a4[0]; O[d][4 * g + 1] *= a4[1]; O[d][4 * g + 2] *= a4[2]; O[d][4 * g + 3] *= a4[3]; } }
;                 asm volatile("s_waitcnt lgkmcnt(0)" ::: "memory");
;             }
; #pragma unroll
;             for (int r = 0; r < 16; ++r) { p0[r] -= delta; p1[r] -= delta; }
;             asm volatile("" : "+v"(p0), "+v"(p1));
;         }
; #pragma unroll
;         for (int r = 0; r < 16; ++r) { p0[r] = __builtin_amdgcn_exp2f(p0[r]); p1[r] = __builtin_amdgcn_exp2f(p1[r]); }
; #pragma unroll
;         for (int r = 0; r < 16; r += 2) { ls2 += (f32x2){p0[r], p0[r + 1]}; ls2 += (f32x2){p1[r], p1[r + 1]}; }
;         bf16x8 pa[4]; pa[0] = pack8(p0, 0); pa[1] = pack8(p0, 8); pa[2] = pack8(p1, 0); pa[3] = pack8(p1, 8);
;         LGKM0(); VREADS1(vb, 1); PV1(va, 0); LGKM0(); VREADS1(va, 2); PV1(vb, 1); LGKM0(); VREADS1(vb, 3); PV1(va, 2); LGKM0(); PV1(vb, 3);
.LatA_rareret_x1:
	s_waitcnt lgkmcnt(12)
	v_mfma_f32_32x32x16_bf16 v[20:35], v[88:91], v[220:223], v[20:35]
	ds_read_b64_tr_b16 v[144:145], v231 offset:40960
	ds_read_b64_tr_b16 v[146:147], v231 offset:43008
	v_exp_f32_e32 v188, v188
	v_exp_f32_e32 v189, v189
	v_exp_f32_e32 v190, v190
	v_exp_f32_e32 v191, v191
	s_waitcnt lgkmcnt(12)
	v_mfma_f32_32x32x16_bf16 v[36:51], v[88:91], v[224:227], v[36:51]
	ds_read_b64_tr_b16 v[220:221], v228 offset:45056
	ds_read_b64_tr_b16 v[222:223], v228 offset:47104
	v_pk_add_f32 v[150:151], v[150:151], v[188:189]
	v_pk_add_f32 v[150:151], v[150:151], v[190:191]
	v_exp_f32_e32 v192, v192
	v_exp_f32_e32 v193, v193
	v_cvt_pk_bf16_f32 v188, v188, v189
	v_cvt_pk_bf16_f32 v189, v190, v191
	s_waitcnt lgkmcnt(12)
	v_mfma_f32_32x32x16_bf16 v[52:67], v[88:91], v[232:235], v[52:67]
	ds_read_b64_tr_b16 v[224:225], v229 offset:45056
	ds_read_b64_tr_b16 v[226:227], v229 offset:47104
	v_exp_f32_e32 v194, v194
	v_exp_f32_e32 v195, v195
	v_pk_add_f32 v[150:151], v[150:151], v[192:193]
	v_pk_add_f32 v[150:151], v[150:151], v[194:195]
	v_cvt_pk_bf16_f32 v190, v192, v193
	v_cvt_pk_bf16_f32 v191, v194, v195
	s_waitcnt lgkmcnt(12)
	v_mfma_f32_32x32x16_bf16 v[68:83], v[88:91], v[236:239], v[68:83]
	ds_read_b64_tr_b16 v[232:233], v230 offset:45056
	ds_read_b64_tr_b16 v[234:235], v230 offset:47104
	v_exp_f32_e32 v196, v196
	v_exp_f32_e32 v197, v197
	v_exp_f32_e32 v198, v198
	v_exp_f32_e32 v199, v199
	s_waitcnt lgkmcnt(12)
	v_mfma_f32_32x32x16_bf16 v[20:35], v[100:103], v[132:135], v[20:35]
	ds_read_b64_tr_b16 v[236:237], v231 offset:45056
	ds_read_b64_tr_b16 v[238:239], v231 offset:47104
	v_pk_add_f32 v[150:151], v[150:151], v[196:197]
	v_pk_add_f32 v[150:151], v[150:151], v[198:199]
	v_exp_f32_e32 v200, v200
	v_exp_f32_e32 v201, v201
	v_cvt_pk_bf16_f32 v192, v196, v197
	v_cvt_pk_bf16_f32 v193, v198, v199
	s_waitcnt lgkmcnt(12)
	v_mfma_f32_32x32x16_bf16 v[36:51], v[100:103], v[136:139], v[36:51]
	ds_read_b64_tr_b16 v[132:133], v168 offset:0
	ds_read_b64_tr_b16 v[134:135], v168 offset:2048
	v_exp_f32_e32 v202, v202
	v_exp_f32_e32 v203, v203
	v_pk_add_f32 v[150:151], v[150:151], v[200:201]
	v_pk_add_f32 v[150:151], v[150:151], v[202:203]
	v_cvt_pk_bf16_f32 v194, v200, v201
	v_cvt_pk_bf16_f32 v195, v202, v203
	s_waitcnt lgkmcnt(12)
	v_mfma_f32_32x32x16_bf16 v[52:67], v[100:103], v[140:143], v[52:67]
	ds_read_b64_tr_b16 v[136:137], v169 offset:0
	ds_read_b64_tr_b16 v[138:139], v169 offset:2048
	v_exp_f32_e32 v204, v204
	v_exp_f32_e32 v205, v205
	v_exp_f32_e32 v206, v206
	v_exp_f32_e32 v207, v207
	s_waitcnt lgkmcnt(12)
	v_mfma_f32_32x32x16_bf16 v[68:83], v[100:103], v[144:147], v[68:83]
	ds_read_b64_tr_b16 v[140:141], v170 offset:0
	ds_read_b64_tr_b16 v[142:143], v170 offset:2048
	v_pk_add_f32 v[150:151], v[150:151], v[204:205]
	v_pk_add_f32 v[150:151], v[150:151], v[206:207]
	v_exp_f32_e32 v208, v208
	v_exp_f32_e32 v209, v209
	v_cvt_pk_bf16_f32 v204, v204, v205
	v_cvt_pk_bf16_f32 v205, v206, v207
	s_waitcnt lgkmcnt(12)
	v_mfma_f32_32x32x16_bf16 v[20:35], v[104:107], v[220:223], v[20:35]
	ds_read_b64_tr_b16 v[144:145], v171 offset:0
	ds_read_b64_tr_b16 v[146:147], v171 offset:2048
	v_exp_f32_e32 v210, v210
	v_exp_f32_e32 v211, v211
	v_pk_add_f32 v[150:151], v[150:151], v[208:209]
	v_pk_add_f32 v[150:151], v[150:151], v[210:211]
	v_cvt_pk_bf16_f32 v206, v208, v209
	v_cvt_pk_bf16_f32 v207, v210, v211
	s_waitcnt lgkmcnt(12)
	v_mfma_f32_32x32x16_bf16 v[36:51], v[104:107], v[224:227], v[36:51]
	ds_read_b64_tr_b16 v[220:221], v168 offset:4096
	ds_read_b64_tr_b16 v[222:223], v168 offset:6144
	v_exp_f32_e32 v212, v212
	v_exp_f32_e32 v213, v213
	v_exp_f32_e32 v214, v214
	v_exp_f32_e32 v215, v215
	s_waitcnt lgkmcnt(12)
	v_mfma_f32_32x32x16_bf16 v[52:67], v[104:107], v[232:235], v[52:67]
	ds_read_b64_tr_b16 v[224:225], v169 offset:4096
	ds_read_b64_tr_b16 v[226:227], v169 offset:6144
	v_pk_add_f32 v[150:151], v[150:151], v[212:213]
	v_pk_add_f32 v[150:151], v[150:151], v[214:215]
	v_exp_f32_e32 v216, v216
	v_exp_f32_e32 v217, v217
	v_cvt_pk_bf16_f32 v208, v212, v213
	v_cvt_pk_bf16_f32 v209, v214, v215
	s_waitcnt lgkmcnt(12)
	v_mfma_f32_32x32x16_bf16 v[68:83], v[104:107], v[236:239], v[68:83]
	ds_read_b64_tr_b16 v[232:233], v170 offset:4096
	ds_read_b64_tr_b16 v[234:235], v170 offset:6144
	v_exp_f32_e32 v218, v218
	v_exp_f32_e32 v219, v219
	v_pk_add_f32 v[150:151], v[150:151], v[216:217]
	v_pk_add_f32 v[150:151], v[150:151], v[218:219]
	v_cvt_pk_bf16_f32 v210, v216, v217
	v_cvt_pk_bf16_f32 v211, v218, v219
	s_add_u32 s8, s8, 0x40000
	s_addc_u32 s9, s9, 0
	s_waitcnt vmcnt(0)
	s_barrier
; #define LAS __attribute__((address_space(3)))
; __device__ __forceinline__ void attn_unit(LAS unsigned char* lds, const bf16_t* Z, bf16_t* A2, const float* tabg, int seq_base, int S, int h, int qb, float lam) {
;     ...
;         const unsigned vbase = (unsigned)(size_t)Vt + vfo;
;         s16x4 va[8], vb[8];
;         VREADS1(va, 0);
;         if (near) {
;             const LAS float* tp = tab + (kv0 + 4 * hi - (qlo + r32) + 224);
; #pragma unroll
;             for (int r = 0; r < 16; ++r) { p0[r] += tp[(r & 3) + 8 * (r >> 2)]; p1[r] += tp[32 + (r & 3) + 8 * (r >> 2)]; }
;         }
;         float mx = max2f(max16f(p0), max16f(p1));
;         const bool first = (t == 0);
;         if (first || __any(mx > THR)) {
;             { auto rr = __builtin_amdgcn_permlane32_swap(__float_as_uint(mx), __float_as_uint(mx), false, false); mx = max2f(__uint_as_float(rr[0]), __uint_as_float(rr[1])); }
;             const float delta = first ? mx : fmaxf(mx, 0.f);
;             const float alpha = first ? 1.0f : __builtin_amdgcn_exp2f(-delta);
;             mu += delta; ls2 *= alpha;
;             if (!first) {
;                 asm volatile("" ::: "memory");
;                 scr[r32] = alpha;
;                 asm volatile("s_waitcnt lgkmcnt(0)" ::: "memory");
; #pragma unroll
;                 for (int g = 0; g < 4; ++g) { const f32x4 a4 = *(const LAS f32x4*)(scr + 8 * g + 4 * hi);
; #pragma unroll
;                     for (int d = 0; d < 4; ++d) { O[d][4 * g + 0] *= a4[0]; O[d][4 * g + 1] *= a4[1]; O[d][4 * g + 2] *= a4[2]; O[d][4 * g + 3] *= a4[3]; } }
;                 asm volatile("s_waitcnt lgkmcnt(0)" ::: "memory");
;             }
; #pragma unroll
;             for (int r = 0; r < 16; ++r) { p0[r] -= delta; p1[r] -= delta; }
;             asm volatile("" : "+v"(p0), "+v"(p1));
;         }
; #pragma unroll
;         for (int r = 0; r < 16; ++r) { p0[r] = __builtin_amdgcn_exp2f(p0[r]); p1[r] = __builtin_amdgcn_exp2f(p1[r]); }
; #pragma unroll
;         for (int r = 0; r < 16; r += 2) { ls2 += (f32x2){p0[r], p0[r + 1]}; ls2 += (f32x2){p1[r], p1[r + 1]}; }
;         bf16x8 pa[4]; pa[0] = pack8(p0, 0); pa[1] = pack8(p0, 8); pa[2] = pack8(p1, 0); pa[3] = pack8(p1, 8);
;         LGKM0(); VREADS1(vb, 1); PV1(va, 0); LGKM0(); VREADS1(va, 2); PV1(vb, 1); LGKM0(); VREADS1(vb, 3); PV1(va, 2); LGKM0(); PV1(vb, 3);
	s_waitcnt lgkmcnt(12)
	v_mfma_f32_32x32x16_bf16 v[20:35], v[188:191], v[132:135], v[20:35]
	ds_read_b64_tr_b16 v[236:237], v171 offset:4096
	ds_read_b64_tr_b16 v[238:239], v171 offset:6144
	s_waitcnt lgkmcnt(12)
	v_mfma_f32_32x32x16_bf16 v[36:51], v[188:191], v[136:139], v[36:51]
	ds_read_b64_tr_b16 v[132:133], v168 offset:8192
	ds_read_b64_tr_b16 v[134:135], v168 offset:10240
	s_waitcnt lgkmcnt(12)
	v_mfma_f32_32x32x16_bf16 v[52:67], v[188:191], v[140:143], v[52:67]
	ds_read_b64_tr_b16 v[136:137], v169 offset:8192
	ds_read_b64_tr_b16 v[138:139], v169 offset:10240
	s_waitcnt lgkmcnt(12)
	v_mfma_f32_32x32x16_bf16 v[68:83], v[188:191], v[144:147], v[68:83]
	ds_read_b64_tr_b16 v[140:141], v170 offset:8192
	ds_read_b64_tr_b16 v[142:143], v170 offset:10240
	s_waitcnt lgkmcnt(12)
	v_mfma_f32_32x32x16_bf16 v[20:35], v[192:195], v[220:223], v[20:35]
	ds_read_b64_tr_b16 v[144:145], v171 offset:8192
	ds_read_b64_tr_b16 v[146:147], v171 offset:10240
	s_waitcnt lgkmcnt(12)
	v_mfma_f32_32x32x16_bf16 v[36:51], v[192:195], v[224:227], v[36:51]
	ds_read_b64_tr_b16 v[220:221], v168 offset:12288
	ds_read_b64_tr_b16 v[222:223], v168 offset:14336
	s_waitcnt lgkmcnt(12)
	v_mfma_f32_32x32x16_bf16 v[52:67], v[192:195], v[232:235], v[52:67]
	ds_read_b64_tr_b16 v[224:225], v169 offset:12288
	ds_read_b64_tr_b16 v[226:227], v169 offset:14336
	s_waitcnt lgkmcnt(12)
	v_mfma_f32_32x32x16_bf16 v[68:83], v[192:195], v[236:239], v[68:83]
	ds_read_b64_tr_b16 v[232:233], v170 offset:12288
	ds_read_b64_tr_b16 v[234:235], v170 offset:14336
	s_waitcnt lgkmcnt(12)
	v_mfma_f32_32x32x16_bf16 v[20:35], v[204:207], v[132:135], v[20:35]
	ds_read_b64_tr_b16 v[236:237], v171 offset:12288
	ds_read_b64_tr_b16 v[238:239], v171 offset:14336
	s_waitcnt lgkmcnt(12)
	v_mfma_f32_32x32x16_bf16 v[36:51], v[204:207], v[136:139], v[36:51]
	s_waitcnt lgkmcnt(10)
	v_mfma_f32_32x32x16_bf16 v[52:67], v[204:207], v[140:143], v[52:67]
	s_waitcnt lgkmcnt(8)
	v_mfma_f32_32x32x16_bf16 v[68:83], v[204:207], v[144:147], v[68:83]
	s_waitcnt lgkmcnt(6)
	v_mfma_f32_32x32x16_bf16 v[20:35], v[208:211], v[220:223], v[20:35]
	s_waitcnt lgkmcnt(4)
	v_mfma_f32_32x32x16_bf16 v[36:51], v[208:211], v[224:227], v[36:51]
	s_waitcnt lgkmcnt(2)
	v_mfma_f32_32x32x16_bf16 v[52:67], v[208:211], v[232:235], v[52:67]
	s_waitcnt lgkmcnt(0)
	v_mfma_f32_32x32x16_bf16 v[68:83], v[208:211], v[236:239], v[68:83]
	s_waitcnt lgkmcnt(0)
	s_barrier
	s_mov_b32 m0, s32
	v_mov_b64_e32 v[164:165], 0x200
	v_mov_b64_e32 v[166:167], 0x1ff
	v_mov_b64_e32 v[168:169], 0x5ac
	v_mov_b64_e32 v[170:171], 0x5ab
	v_mov_b64_e32 v[172:173], 0x100
	v_mov_b64_e32 v[174:175], 0xff
	s_nop 15
	s_branch .LatA_done

; #define LAS __attribute__((address_space(3)))
; __device__ __forceinline__ float max2f(float a, float b) { float r; asm("v_max_f32_e32 %0, %1, %2" : "=v"(r) : "v"(a), "v"(b)); return r; }
; __device__ __forceinline__ void attn_unit(LAS unsigned char* lds, const bf16_t* Z, bf16_t* A2, const float* tabg, int seq_base, int S, int h, int qb, float lam) {
;     ...
;         if (near) {
;             const LAS float* tp = tab + (kv0 + 4 * hi - (qlo + r32) + 224);
; #pragma unroll
;             for (int r = 0; r < 16; ++r) { p0[r] += tp[(r & 3) + 8 * (r >> 2)]; p1[r] += tp[32 + (r & 3) + 8 * (r >> 2)]; }
;         }
;         float mx = max2f(max16f(p0), max16f(p1));
;         const bool first = (t == 0);
;         if (first || __any(mx > THR)) {
.LatA_evs_m1:
	s_mov_b32 s42, 2
	s_branch .LatA_ev_11
.LatA_rs_m1:
	s_mov_b32 s42, 1
	s_branch .LatA_rare_1114
.LatA_evs_m2:
	s_mov_b32 s42, 2
	s_branch .LatA_ev_01
.LatA_rs_m2:
	s_mov_b32 s42, 1
	s_branch .LatA_rare_2114

; #define LAS __attribute__((address_space(3)))
; __device__ __forceinline__ float max2f(float a, float b) { float r; asm("v_max_f32_e32 %0, %1, %2" : "=v"(r) : "v"(a), "v"(b)); return r; }
; __device__ __forceinline__ void attn_unit(LAS unsigned char* lds, const bf16_t* Z, bf16_t* A2, const float* tabg, int seq_base, int S, int h, int qb, float lam) {
;     ...
;         if (near) {
;             const LAS float* tp = tab + (kv0 + 4 * hi - (qlo + r32) + 224);
; #pragma unroll
;             for (int r = 0; r < 16; ++r) { p0[r] += tp[(r & 3) + 8 * (r >> 2)]; p1[r] += tp[32 + (r & 3) + 8 * (r >> 2)]; }
;         }
;         float mx = max2f(max16f(p0), max16f(p1));
;         const bool first = (t == 0);
;         if (first || __any(mx > THR)) {
.LatA_evs_x3:
	s_mov_b32 s42, 4
	s_branch .LatA_ev_11
.LatA_rs_x3:
	s_mov_b32 s42, 2
	s_branch .LatA_rare_1114
.LatA_evs_x2:
	s_mov_b32 s42, 4
	s_branch .LatA_ev_01
.LatA_rs_x2:
	s_mov_b32 s42, 2
	s_branch .LatA_rare_2114

; #define LAS __attribute__((address_space(3)))
; #define VREADS1(arr, d_) do { const unsigned ad_ = vbase ^ (unsigned)((d_) << 6); __builtin_amdgcn_sched_barrier(0); \
;         _Pragma("unroll") for (int ks_ = 0; ks_ < 4; ++ks_) { VTR(arr[ks_ * 2], ad_, ks_ * 4096); VTR(arr[ks_ * 2 + 1], ad_, ks_ * 4096 + 2048); } __builtin_amdgcn_sched_barrier(0); } while (0)
; __device__ __forceinline__ void attn_unit(LAS unsigned char* lds, const bf16_t* Z, bf16_t* A2, const float* tabg, int seq_base, int S, int h, int qb, float lam) {
;     ...
;         bool near = true; float cc = 0.f;
;         if (kv0 - (qlo + 31) >= 128) { near = false; cc = tabR; } else if (qlo - (kv0 + 63) >= 128) { near = false; cc = tabL; }
;         { const float coff = cc - mu;
;           if (__any(!(coff == coff_cur))) { coff_cur = coff;
; #pragma unroll
;               for (int r = 0; r < 16; ++r) cblk[r] = coff;
;               asm volatile("" : "+v"(cblk)); } }
;         f32x16 p0, p1;
;         {
;             bf16x8 kf[8];
; #pragma unroll
;             for (int ds = 0; ds < 4; ++ds) { kf[2 * ds] = *(const LAS bf16x8*)(Kt + (kfo ^ (unsigned)(ds << 5))); kf[2 * ds + 1] = *(const LAS bf16x8*)(Kt + 32 * 256 + (kfo ^ (unsigned)(ds << 5))); }
;             __builtin_amdgcn_sched_barrier(0);
;             p0 = __builtin_amdgcn_mfma_f32_32x32x16_bf16(kf[0], qf[0], cblk, 0, 0, 0);
;             p1 = __builtin_amdgcn_mfma_f32_32x32x16_bf16(kf[1], qf[0], cblk, 0, 0, 0);
; #pragma unroll
;             for (int ds = 1; ds < 4; ++ds) {
;                 p0 = __builtin_amdgcn_mfma_f32_32x32x16_bf16(kf[2 * ds], qf[ds], p0, 0, 0, 0);
;                 p1 = __builtin_amdgcn_mfma_f32_32x32x16_bf16(kf[2 * ds + 1], qf[ds], p1, 0, 0, 0);
;             }
;         }
;     ...
;         const unsigned vbase = (unsigned)(size_t)Vt + vfo;
;         s16x4 va[8], vb[8];
;         VREADS1(va, 0);
;         if (near) {
;             const LAS float* tp = tab + (kv0 + 4 * hi - (qlo + r32) + 224);
; #pragma unroll
;             for (int r = 0; r < 16; ++r) { p0[r] += tp[(r & 3) + 8 * (r >> 2)]; p1[r] += tp[32 + (r & 3) + 8 * (r >> 2)]; }
.LatA_ev_11:
	s_sub_u32 s5, s8, s4
	s_lshr_b32 s5, s5, 12
	s_sub_u32 s5, s5, 64
	s_cmp_ge_u32 s5, s11
	s_cselect_b32 s37, 1, 0
	s_cmp_le_u32 s5, s31
	s_cselect_b32 s38, 1, 0
	s_and_b32 s37, s37, s38
	s_add_u32 s38, s5, 64
	s_cmp_le_u32 s38, s31
	s_cselect_b32 s10, 0, 0x7fffffff
	s_cmp_eq_u32 s37, 0
	s_cbranch_scc1 .LatA_evnn_11
	s_lshl_b32 s38, s5, 2
	s_add_i32 s38, s38, 0x18b80
	v_add_u32_e32 v187, s38, v162
	ds_read2_b32 v[92:93], v187 offset0:0 offset1:1
	ds_read2_b32 v[94:95], v187 offset0:2 offset1:3
	ds_read2_b32 v[96:97], v187 offset0:8 offset1:9
	ds_read2_b32 v[98:99], v187 offset0:10 offset1:11
	ds_read2_b32 v[108:109], v187 offset0:16 offset1:17
	ds_read2_b32 v[110:111], v187 offset0:18 offset1:19
	ds_read2_b32 v[112:113], v187 offset0:24 offset1:25
	ds_read2_b32 v[114:115], v187 offset0:26 offset1:27
	s_waitcnt lgkmcnt(0)
	v_pk_add_f32 v[188:189], v[188:189], v[92:93]
	v_pk_add_f32 v[190:191], v[190:191], v[94:95]
	v_pk_add_f32 v[192:193], v[192:193], v[96:97]
	v_pk_add_f32 v[194:195], v[194:195], v[98:99]
	v_pk_add_f32 v[196:197], v[196:197], v[108:109]
	v_pk_add_f32 v[198:199], v[198:199], v[110:111]
	v_pk_add_f32 v[200:201], v[200:201], v[112:113]
	v_pk_add_f32 v[202:203], v[202:203], v[114:115]
	ds_read2_b32 v[92:93], v187 offset0:32 offset1:33
	ds_read2_b32 v[94:95], v187 offset0:34 offset1:35
	ds_read2_b32 v[96:97], v187 offset0:40 offset1:41
	ds_read2_b32 v[98:99], v187 offset0:42 offset1:43
	ds_read2_b32 v[108:109], v187 offset0:48 offset1:49
	ds_read2_b32 v[110:111], v187 offset0:50 offset1:51
	ds_read2_b32 v[112:113], v187 offset0:56 offset1:57
	ds_read2_b32 v[114:115], v187 offset0:58 offset1:59
	s_waitcnt lgkmcnt(0)
	v_pk_add_f32 v[204:205], v[204:205], v[92:93]
	v_pk_add_f32 v[206:207], v[206:207], v[94:95]
	v_pk_add_f32 v[208:209], v[208:209], v[96:97]
	v_pk_add_f32 v[210:211], v[210:211], v[98:99]
	v_pk_add_f32 v[212:213], v[212:213], v[108:109]
	v_pk_add_f32 v[214:215], v[214:215], v[110:111]
	v_pk_add_f32 v[216:217], v[216:217], v[112:113]
	v_pk_add_f32 v[218:219], v[218:219], v[114:115]

; #define LAS __attribute__((address_space(3)))
; #define VREADS1(arr, d_) do { const unsigned ad_ = vbase ^ (unsigned)((d_) << 6); __builtin_amdgcn_sched_barrier(0); \
;         _Pragma("unroll") for (int ks_ = 0; ks_ < 4; ++ks_) { VTR(arr[ks_ * 2], ad_, ks_ * 4096); VTR(arr[ks_ * 2 + 1], ad_, ks_ * 4096 + 2048); } __builtin_amdgcn_sched_barrier(0); } while (0)
; __device__ __forceinline__ void attn_unit(LAS unsigned char* lds, const bf16_t* Z, bf16_t* A2, const float* tabg, int seq_base, int S, int h, int qb, float lam) {
;     ...
;         bool near = true; float cc = 0.f;
;         if (kv0 - (qlo + 31) >= 128) { near = false; cc = tabR; } else if (qlo - (kv0 + 63) >= 128) { near = false; cc = tabL; }
;         { const float coff = cc - mu;
;           if (__any(!(coff == coff_cur))) { coff_cur = coff;
; #pragma unroll
;               for (int r = 0; r < 16; ++r) cblk[r] = coff;
;               asm volatile("" : "+v"(cblk)); } }
;         f32x16 p0, p1;
;         {
;             bf16x8 kf[8];
; #pragma unroll
;             for (int ds = 0; ds < 4; ++ds) { kf[2 * ds] = *(const LAS bf16x8*)(Kt + (kfo ^ (unsigned)(ds << 5))); kf[2 * ds + 1] = *(const LAS bf16x8*)(Kt + 32 * 256 + (kfo ^ (unsigned)(ds << 5))); }
;             __builtin_amdgcn_sched_barrier(0);
;             p0 = __builtin_amdgcn_mfma_f32_32x32x16_bf16(kf[0], qf[0], cblk, 0, 0, 0);
;             p1 = __builtin_amdgcn_mfma_f32_32x32x16_bf16(kf[1], qf[0], cblk, 0, 0, 0);
; #pragma unroll
;             for (int ds = 1; ds < 4; ++ds) {
;                 p0 = __builtin_amdgcn_mfma_f32_32x32x16_bf16(kf[2 * ds], qf[ds], p0, 0, 0, 0);
;                 p1 = __builtin_amdgcn_mfma_f32_32x32x16_bf16(kf[2 * ds + 1], qf[ds], p1, 0, 0, 0);
;             }
;         }
;     ...
;         const unsigned vbase = (unsigned)(size_t)Vt + vfo;
;         s16x4 va[8], vb[8];
;         VREADS1(va, 0);
;         if (near) {
;             const LAS float* tp = tab + (kv0 + 4 * hi - (qlo + r32) + 224);
; #pragma unroll
;             for (int r = 0; r < 16; ++r) { p0[r] += tp[(r & 3) + 8 * (r >> 2)]; p1[r] += tp[32 + (r & 3) + 8 * (r >> 2)]; }
.LatA_evdisp_11:
	s_cmp_eq_u32 s42, 0
	s_cbranch_scc1 .LatA_evret_h1
	s_cmp_eq_u32 s42, 1
	s_cbranch_scc1 .LatA_evret_h3
	s_cmp_eq_u32 s42, 2
	s_cbranch_scc1 .LatA_evret_m1
	s_cmp_eq_u32 s42, 3
	s_cbranch_scc1 .LatA_evret_m3
	s_branch .LatA_evret_x3
.LatA_ev_01:
	s_sub_u32 s5, s8, s4
	s_lshr_b32 s5, s5, 12
	s_sub_u32 s5, s5, 64
	s_cmp_ge_u32 s5, s11
	s_cselect_b32 s37, 1, 0
	s_cmp_le_u32 s5, s31
	s_cselect_b32 s38, 1, 0
	s_and_b32 s37, s37, s38
	s_add_u32 s38, s5, 64
	s_cmp_le_u32 s38, s31
	s_cselect_b32 s10, 0, 0x7fffffff
	s_cmp_eq_u32 s37, 0
	s_cbranch_scc1 .LatA_evnn_01
	s_lshl_b32 s38, s5, 2
	s_add_i32 s38, s38, 0x18b80
	v_add_u32_e32 v187, s38, v162
	ds_read2_b32 v[196:197], v187 offset0:0 offset1:1
	ds_read2_b32 v[198:199], v187 offset0:2 offset1:3
	ds_read2_b32 v[200:201], v187 offset0:8 offset1:9
	ds_read2_b32 v[202:203], v187 offset0:10 offset1:11
	ds_read2_b32 v[212:213], v187 offset0:16 offset1:17
	ds_read2_b32 v[214:215], v187 offset0:18 offset1:19
	ds_read2_b32 v[216:217], v187 offset0:24 offset1:25
	ds_read2_b32 v[218:219], v187 offset0:26 offset1:27
	s_waitcnt lgkmcnt(0)
	v_pk_add_f32 v[84:85], v[84:85], v[196:197]
	v_pk_add_f32 v[86:87], v[86:87], v[198:199]
	v_pk_add_f32 v[88:89], v[88:89], v[200:201]
	v_pk_add_f32 v[90:91], v[90:91], v[202:203]
	v_pk_add_f32 v[92:93], v[92:93], v[212:213]
	v_pk_add_f32 v[94:95], v[94:95], v[214:215]
	v_pk_add_f32 v[96:97], v[96:97], v[216:217]
	v_pk_add_f32 v[98:99], v[98:99], v[218:219]
	ds_read2_b32 v[196:197], v187 offset0:32 offset1:33
	ds_read2_b32 v[198:199], v187 offset0:34 offset1:35
	ds_read2_b32 v[200:201], v187 offset0:40 offset1:41
	ds_read2_b32 v[202:203], v187 offset0:42 offset1:43
	ds_read2_b32 v[212:213], v187 offset0:48 offset1:49
	ds_read2_b32 v[214:215], v187 offset0:50 offset1:51
	ds_read2_b32 v[216:217], v187 offset0:56 offset1:57
	ds_read2_b32 v[218:219], v187 offset0:58 offset1:59
	s_waitcnt lgkmcnt(0)
	v_pk_add_f32 v[100:101], v[100:101], v[196:197]
	v_pk_add_f32 v[102:103], v[102:103], v[198:199]
	v_pk_add_f32 v[104:105], v[104:105], v[200:201]
	v_pk_add_f32 v[106:107], v[106:107], v[202:203]
	v_pk_add_f32 v[108:109], v[108:109], v[212:213]
	v_pk_add_f32 v[110:111], v[110:111], v[214:215]
	v_pk_add_f32 v[112:113], v[112:113], v[216:217]
	v_pk_add_f32 v[114:115], v[114:115], v[218:219]

; __device__ __forceinline__ void attn_unit(LAS unsigned char* lds, const bf16_t* Z, bf16_t* A2, const float* tabg, int seq_base, int S, int h, int qb, float lam) {
;     ...
;         bool near = true; float cc = 0.f;
;         if (kv0 - (qlo + 31) >= 128) { near = false; cc = tabR; } else if (qlo - (kv0 + 63) >= 128) { near = false; cc = tabL; }
;         { const float coff = cc - mu;
;           if (__any(!(coff == coff_cur))) { coff_cur = coff;
; #pragma unroll
;               for (int r = 0; r < 16; ++r) cblk[r] = coff;
;               asm volatile("" : "+v"(cblk)); } }
;         f32x16 p0, p1;
;         {
;             bf16x8 kf[8];
; #pragma unroll
;             for (int ds = 0; ds < 4; ++ds) { kf[2 * ds] = *(const LAS bf16x8*)(Kt + (kfo ^ (unsigned)(ds << 5))); kf[2 * ds + 1] = *(const LAS bf16x8*)(Kt + 32 * 256 + (kfo ^ (unsigned)(ds << 5))); }
;             __builtin_amdgcn_sched_barrier(0);
;             p0 = __builtin_amdgcn_mfma_f32_32x32x16_bf16(kf[0], qf[0], cblk, 0, 0, 0);
;             p1 = __builtin_amdgcn_mfma_f32_32x32x16_bf16(kf[1], qf[0], cblk, 0, 0, 0);
; #pragma unroll
;             for (int ds = 1; ds < 4; ++ds) {
;                 p0 = __builtin_amdgcn_mfma_f32_32x32x16_bf16(kf[2 * ds], qf[ds], p0, 0, 0, 0);
;                 p1 = __builtin_amdgcn_mfma_f32_32x32x16_bf16(kf[2 * ds + 1], qf[ds], p1, 0, 0, 0);
;             }
;         }
;     ...
;         const unsigned vbase = (unsigned)(size_t)Vt + vfo;
;         s16x4 va[8], vb[8];
;         VREADS1(va, 0);
;         if (near) {
;             const LAS float* tp = tab + (kv0 + 4 * hi - (qlo + r32) + 224);
; #pragma unroll
;             for (int r = 0; r < 16; ++r) { p0[r] += tp[(r & 3) + 8 * (r >> 2)]; p1[r] += tp[32 + (r & 3) + 8 * (r >> 2)]; }
;         }
;         float mx = max2f(max16f(p0), max16f(p1));
;         const bool first = (t == 0);
;         if (first || __any(mx > THR)) {
;             { auto rr = __builtin_amdgcn_permlane32_swap(__float_as_uint(mx), __float_as_uint(mx), false, false); mx = max2f(__uint_as_float(rr[0]), __uint_as_float(rr[1])); }
;             const float delta = first ? mx : fmaxf(mx, 0.f);
;             const float alpha = first ? 1.0f : __builtin_amdgcn_exp2f(-delta);
;             mu += delta; ls2 *= alpha;
;             if (!first) {
;                 asm volatile("" ::: "memory");
;                 scr[r32] = alpha;
.LatA_rare_1114:
	v_mov_b32_e32 v252, v251
	s_nop 1
	v_permlane32_swap_b32_e32 v251, v252
	v_max_f32_e32 v251, v251, v252
	v_max_f32_e32 v253, 0, v251
	v_exp_f32_e64 v254, -v253
	v_add_f32_e32 v186, v186, v253
	s_nop 0
	v_mul_f32_e32 v150, v150, v254
	v_mul_f32_e32 v151, v151, v254
	ds_write_b32 v184, v254
	s_waitcnt lgkmcnt(0)
	v_mfma_f32_32x32x16_bf16 v[20:35], v[88:91], v[220:223], v[20:35]
	v_mfma_f32_32x32x16_bf16 v[36:51], v[88:91], v[224:227], v[36:51]
	v_mfma_f32_32x32x16_bf16 v[52:67], v[88:91], v[232:235], v[52:67]
	v_mfma_f32_32x32x16_bf16 v[68:83], v[88:91], v[236:239], v[68:83]
	v_mfma_f32_32x32x16_bf16 v[20:35], v[100:103], v[132:135], v[20:35]
	v_mfma_f32_32x32x16_bf16 v[36:51], v[100:103], v[136:139], v[36:51]
	v_mfma_f32_32x32x16_bf16 v[52:67], v[100:103], v[140:143], v[52:67]
	ds_read_b64_tr_b16 v[144:145], v231 offset:8192
	ds_read_b64_tr_b16 v[146:147], v231 offset:10240
	ds_read_b64_tr_b16 v[220:221], v228 offset:12288
	ds_read_b64_tr_b16 v[222:223], v228 offset:14336
	ds_read_b64_tr_b16 v[224:225], v229 offset:12288
	ds_read_b64_tr_b16 v[226:227], v229 offset:14336
	ds_read_b64_tr_b16 v[232:233], v230 offset:12288
	ds_read_b64_tr_b16 v[234:235], v230 offset:14336
	ds_read_b64_tr_b16 v[236:237], v231 offset:12288
	ds_read_b64_tr_b16 v[238:239], v231 offset:14336
	s_waitcnt lgkmcnt(0)
	v_mfma_f32_32x32x16_bf16 v[68:83], v[100:103], v[144:147], v[68:83]
	v_mfma_f32_32x32x16_bf16 v[20:35], v[104:107], v[220:223], v[20:35]
	v_mfma_f32_32x32x16_bf16 v[36:51], v[104:107], v[224:227], v[36:51]
	v_mfma_f32_32x32x16_bf16 v[52:67], v[104:107], v[232:235], v[52:67]
	v_mfma_f32_32x32x16_bf16 v[68:83], v[104:107], v[236:239], v[68:83]
	ds_read_b128 v[92:95], v185
	ds_read_b128 v[96:99], v185 offset:32
	ds_read_b128 v[108:111], v185 offset:64
	ds_read_b128 v[112:115], v185 offset:96
	s_waitcnt lgkmcnt(0)
	s_nop 15
	s_nop 15
	v_pk_mul_f32 v[20:21], v[20:21], v[92:93]
	v_pk_mul_f32 v[22:23], v[22:23], v[94:95]
	v_pk_mul_f32 v[24:25], v[24:25], v[96:97]
	v_pk_mul_f32 v[26:27], v[26:27], v[98:99]
	v_pk_mul_f32 v[28:29], v[28:29], v[108:109]
	v_pk_mul_f32 v[30:31], v[30:31], v[110:111]
	v_pk_mul_f32 v[32:33], v[32:33], v[112:113]
	v_pk_mul_f32 v[34:35], v[34:35], v[114:115]
	v_pk_mul_f32 v[36:37], v[36:37], v[92:93]
	v_pk_mul_f32 v[38:39], v[38:39], v[94:95]
	v_pk_mul_f32 v[40:41], v[40:41], v[96:97]
	v_pk_mul_f32 v[42:43], v[42:43], v[98:99]
	v_pk_mul_f32 v[44:45], v[44:45], v[108:109]
	v_pk_mul_f32 v[46:47], v[46:47], v[110:111]
	v_pk_mul_f32 v[48:49], v[48:49], v[112:113]
	v_pk_mul_f32 v[50:51], v[50:51], v[114:115]
	v_pk_mul_f32 v[52:53], v[52:53], v[92:93]
	v_pk_mul_f32 v[54:55], v[54:55], v[94:95]
	v_pk_mul_f32 v[56:57], v[56:57], v[96:97]
	v_pk_mul_f32 v[58:59], v[58:59], v[98:99]
	v_pk_mul_f32 v[60:61], v[60:61], v[108:109]
	v_pk_mul_f32 v[62:63], v[62:63], v[110:111]
	v_pk_mul_f32 v[64:65], v[64:65], v[112:113]
	v_pk_mul_f32 v[66:67], v[66:67], v[114:115]
	v_pk_mul_f32 v[68:69], v[68:69], v[92:93]
	v_pk_mul_f32 v[70:71], v[70:71], v[94:95]
	v_pk_mul_f32 v[72:73], v[72:73], v[96:97]
	v_pk_mul_f32 v[74:75], v[74:75], v[98:99]
	v_pk_mul_f32 v[76:77], v[76:77], v[108:109]
	v_pk_mul_f32 v[78:79], v[78:79], v[110:111]
	v_pk_mul_f32 v[80:81], v[80:81], v[112:113]
	v_pk_mul_f32 v[82:83], v[82:83], v[114:115]
	v_mov_b32_e32 v252, v253
	v_pk_add_f32 v[188:189], v[188:189], v[252:253] neg_lo:[0,1] neg_hi:[0,1]
	v_pk_add_f32 v[190:191], v[190:191], v[252:253] neg_lo:[0,1] neg_hi:[0,1]
	v_pk_add_f32 v[192:193], v[192:193], v[252:253] neg_lo:[0,1] neg_hi:[0,1]
	v_pk_add_f32 v[194:195], v[194:195], v[252:253] neg_lo:[0,1] neg_hi:[0,1]
	v_pk_add_f32 v[196:197], v[196:197], v[252:253] neg_lo:[0,1] neg_hi:[0,1]
	v_pk_add_f32 v[198:199], v[198:199], v[252:253] neg_lo:[0,1] neg_hi:[0,1]
	v_pk_add_f32 v[200:201], v[200:201], v[252:253] neg_lo:[0,1] neg_hi:[0,1]
	v_pk_add_f32 v[202:203], v[202:203], v[252:253] neg_lo:[0,1] neg_hi:[0,1]
	v_pk_add_f32 v[204:205], v[204:205], v[252:253] neg_lo:[0,1] neg_hi:[0,1]
	v_pk_add_f32 v[206:207], v[206:207], v[252:253] neg_lo:[0,1] neg_hi:[0,1]
	v_pk_add_f32 v[208:209], v[208:209], v[252:253] neg_lo:[0,1] neg_hi:[0,1]
	v_pk_add_f32 v[210:211], v[210:211], v[252:253] neg_lo:[0,1] neg_hi:[0,1]
	v_pk_add_f32 v[212:213], v[212:213], v[252:253] neg_lo:[0,1] neg_hi:[0,1]
	v_pk_add_f32 v[214:215], v[214:215], v[252:253] neg_lo:[0,1] neg_hi:[0,1]
	v_pk_add_f32 v[216:217], v[216:217], v[252:253] neg_lo:[0,1] neg_hi:[0,1]
	v_pk_add_f32 v[218:219], v[218:219], v[252:253] neg_lo:[0,1] neg_hi:[0,1]
	v_mov_b64_e32 v[84:85], 0
	v_mov_b64_e32 v[86:87], 0
	v_mov_b64_e32 v[88:89], 0
	v_mov_b64_e32 v[90:91], 0
	v_mov_b64_e32 v[100:101], 0
	v_mov_b64_e32 v[102:103], 0
	v_mov_b64_e32 v[104:105], 0
	v_mov_b64_e32 v[106:107], 0
	s_sub_u32 s5, s8, s4
	s_lshr_b32 s5, s5, 12
	s_sub_u32 s5, s5, 64
	s_add_u32 s38, s5, 64
	s_cmp_lt_u32 s38, s11
	s_cselect_b32 s37, 1, 0
	s_cmp_gt_u32 s38, s31
	s_cselect_b32 s40, 2, 0
	s_or_b32 s37, s37, s40
	s_mov_b32 s35, s37
	v_mov_b32_e32 v251, 0
	s_cmp_eq_u32 s37, 1
	s_cselect_b64 vcc, -1, 0
	v_cndmask_b32_e32 v251, v251, v177, vcc
	s_cmp_eq_u32 s37, 2
	s_cselect_b64 vcc, -1, 0
	v_cndmask_b32_e32 v251, v251, v178, vcc
	v_sub_f32_e32 v2, v251, v186
	v_mov_b32_e32 v3, v2
	v_mov_b64_e32 v[4:5], v[2:3]
	v_mov_b64_e32 v[6:7], v[2:3]
	v_mov_b64_e32 v[8:9], v[2:3]
	v_mov_b64_e32 v[10:11], v[2:3]
	v_mov_b64_e32 v[12:13], v[2:3]
	v_mov_b64_e32 v[14:15], v[2:3]
	v_mov_b64_e32 v[16:17], v[2:3]
	s_nop 1
	s_cmp_eq_u32 s42, 0
	s_cbranch_scc1 .LatA_rareret_h1
	s_cmp_eq_u32 s42, 1
	s_cbranch_scc1 .LatA_rareret_m1
	s_branch .LatA_rareret_x3
; __device__ __forceinline__ void attn_unit(LAS unsigned char* lds, const bf16_t* Z, bf16_t* A2, const float* tabg, int seq_base, int S, int h, int qb, float lam) {
;     ...
;         bool near = true; float cc = 0.f;
;         if (kv0 - (qlo + 31) >= 128) { near = false; cc = tabR; } else if (qlo - (kv0 + 63) >= 128) { near = false; cc = tabL; }
;         { const float coff = cc - mu;
;           if (__any(!(coff == coff_cur))) { coff_cur = coff;
; #pragma unroll
;               for (int r = 0; r < 16; ++r) cblk[r] = coff;
;               asm volatile("" : "+v"(cblk)); } }
;         f32x16 p0, p1;
;         {
;             bf16x8 kf[8];
; #pragma unroll
;             for (int ds = 0; ds < 4; ++ds) { kf[2 * ds] = *(const LAS bf16x8*)(Kt + (kfo ^ (unsigned)(ds << 5))); kf[2 * ds + 1] = *(const LAS bf16x8*)(Kt + 32 * 256 + (kfo ^ (unsigned)(ds << 5))); }
;             __builtin_amdgcn_sched_barrier(0);
;             p0 = __builtin_amdgcn_mfma_f32_32x32x16_bf16(kf[0], qf[0], cblk, 0, 0, 0);
;             p1 = __builtin_amdgcn_mfma_f32_32x32x16_bf16(kf[1], qf[0], cblk, 0, 0, 0);
; #pragma unroll
;             for (int ds = 1; ds < 4; ++ds) {
;                 p0 = __builtin_amdgcn_mfma_f32_32x32x16_bf16(kf[2 * ds], qf[ds], p0, 0, 0, 0);
;                 p1 = __builtin_amdgcn_mfma_f32_32x32x16_bf16(kf[2 * ds + 1], qf[ds], p1, 0, 0, 0);
;             }
;         }
;     ...
;         const unsigned vbase = (unsigned)(size_t)Vt + vfo;
;         s16x4 va[8], vb[8];
;         VREADS1(va, 0);
;         if (near) {
;             const LAS float* tp = tab + (kv0 + 4 * hi - (qlo + r32) + 224);
; #pragma unroll
;             for (int r = 0; r < 16; ++r) { p0[r] += tp[(r & 3) + 8 * (r >> 2)]; p1[r] += tp[32 + (r & 3) + 8 * (r >> 2)]; }
;         }
;         float mx = max2f(max16f(p0), max16f(p1));
;         const bool first = (t == 0);
;         if (first || __any(mx > THR)) {
;             { auto rr = __builtin_amdgcn_permlane32_swap(__float_as_uint(mx), __float_as_uint(mx), false, false); mx = max2f(__uint_as_float(rr[0]), __uint_as_float(rr[1])); }
;             const float delta = first ? mx : fmaxf(mx, 0.f);
;             const float alpha = first ? 1.0f : __builtin_amdgcn_exp2f(-delta);
;             mu += delta; ls2 *= alpha;
;             if (!first) {
;                 asm volatile("" ::: "memory");
;                 scr[r32] = alpha;
.LatA_rare_2114:
	v_mov_b32_e32 v252, v251
	s_nop 1
	v_permlane32_swap_b32_e32 v251, v252
	v_max_f32_e32 v251, v251, v252
	v_max_f32_e32 v253, 0, v251
	v_exp_f32_e64 v254, -v253
	v_add_f32_e32 v186, v186, v253
	s_nop 0
	v_mul_f32_e32 v150, v150, v254
	v_mul_f32_e32 v151, v151, v254
	ds_write_b32 v184, v254
	s_waitcnt lgkmcnt(0)
	v_mfma_f32_32x32x16_bf16 v[20:35], v[192:195], v[220:223], v[20:35]
	v_mfma_f32_32x32x16_bf16 v[36:51], v[192:195], v[224:227], v[36:51]
	v_mfma_f32_32x32x16_bf16 v[52:67], v[192:195], v[232:235], v[52:67]
	v_mfma_f32_32x32x16_bf16 v[68:83], v[192:195], v[236:239], v[68:83]
	v_mfma_f32_32x32x16_bf16 v[20:35], v[204:207], v[132:135], v[20:35]
	v_mfma_f32_32x32x16_bf16 v[36:51], v[204:207], v[136:139], v[36:51]
	v_mfma_f32_32x32x16_bf16 v[52:67], v[204:207], v[140:143], v[52:67]
	ds_read_b64_tr_b16 v[144:145], v231 offset:24576
	ds_read_b64_tr_b16 v[146:147], v231 offset:26624
	ds_read_b64_tr_b16 v[220:221], v228 offset:28672
	ds_read_b64_tr_b16 v[222:223], v228 offset:30720
	ds_read_b64_tr_b16 v[224:225], v229 offset:28672
	ds_read_b64_tr_b16 v[226:227], v229 offset:30720
	ds_read_b64_tr_b16 v[232:233], v230 offset:28672
	ds_read_b64_tr_b16 v[234:235], v230 offset:30720
	ds_read_b64_tr_b16 v[236:237], v231 offset:28672
	ds_read_b64_tr_b16 v[238:239], v231 offset:30720
	s_waitcnt lgkmcnt(0)
	v_mfma_f32_32x32x16_bf16 v[68:83], v[204:207], v[144:147], v[68:83]
	v_mfma_f32_32x32x16_bf16 v[20:35], v[208:211], v[220:223], v[20:35]
	v_mfma_f32_32x32x16_bf16 v[36:51], v[208:211], v[224:227], v[36:51]
	v_mfma_f32_32x32x16_bf16 v[52:67], v[208:211], v[232:235], v[52:67]
	v_mfma_f32_32x32x16_bf16 v[68:83], v[208:211], v[236:239], v[68:83]
	ds_read_b128 v[196:199], v185
	ds_read_b128 v[200:203], v185 offset:32
	ds_read_b128 v[212:215], v185 offset:64
	ds_read_b128 v[216:219], v185 offset:96
	s_waitcnt lgkmcnt(0)
	s_nop 15
	s_nop 15
	v_pk_mul_f32 v[20:21], v[20:21], v[196:197]
	v_pk_mul_f32 v[22:23], v[22:23], v[198:199]
	v_pk_mul_f32 v[24:25], v[24:25], v[200:201]
	v_pk_mul_f32 v[26:27], v[26:27], v[202:203]
	v_pk_mul_f32 v[28:29], v[28:29], v[212:213]
	v_pk_mul_f32 v[30:31], v[30:31], v[214:215]
	v_pk_mul_f32 v[32:33], v[32:33], v[216:217]
	v_pk_mul_f32 v[34:35], v[34:35], v[218:219]
	v_pk_mul_f32 v[36:37], v[36:37], v[196:197]
	v_pk_mul_f32 v[38:39], v[38:39], v[198:199]
	v_pk_mul_f32 v[40:41], v[40:41], v[200:201]
	v_pk_mul_f32 v[42:43], v[42:43], v[202:203]
	v_pk_mul_f32 v[44:45], v[44:45], v[212:213]
	v_pk_mul_f32 v[46:47], v[46:47], v[214:215]
	v_pk_mul_f32 v[48:49], v[48:49], v[216:217]
	v_pk_mul_f32 v[50:51], v[50:51], v[218:219]
	v_pk_mul_f32 v[52:53], v[52:53], v[196:197]
	v_pk_mul_f32 v[54:55], v[54:55], v[198:199]
	v_pk_mul_f32 v[56:57], v[56:57], v[200:201]
	v_pk_mul_f32 v[58:59], v[58:59], v[202:203]
	v_pk_mul_f32 v[60:61], v[60:61], v[212:213]
	v_pk_mul_f32 v[62:63], v[62:63], v[214:215]
	v_pk_mul_f32 v[64:65], v[64:65], v[216:217]
	v_pk_mul_f32 v[66:67], v[66:67], v[218:219]
	v_pk_mul_f32 v[68:69], v[68:69], v[196:197]
	v_pk_mul_f32 v[70:71], v[70:71], v[198:199]
	v_pk_mul_f32 v[72:73], v[72:73], v[200:201]
	v_pk_mul_f32 v[74:75], v[74:75], v[202:203]
	v_pk_mul_f32 v[76:77], v[76:77], v[212:213]
	v_pk_mul_f32 v[78:79], v[78:79], v[214:215]
	v_pk_mul_f32 v[80:81], v[80:81], v[216:217]
	v_pk_mul_f32 v[82:83], v[82:83], v[218:219]
	v_mov_b32_e32 v252, v253
	v_pk_add_f32 v[84:85], v[84:85], v[252:253] neg_lo:[0,1] neg_hi:[0,1]
	v_pk_add_f32 v[86:87], v[86:87], v[252:253] neg_lo:[0,1] neg_hi:[0,1]
	v_pk_add_f32 v[88:89], v[88:89], v[252:253] neg_lo:[0,1] neg_hi:[0,1]
	v_pk_add_f32 v[90:91], v[90:91], v[252:253] neg_lo:[0,1] neg_hi:[0,1]
	v_pk_add_f32 v[92:93], v[92:93], v[252:253] neg_lo:[0,1] neg_hi:[0,1]
	v_pk_add_f32 v[94:95], v[94:95], v[252:253] neg_lo:[0,1] neg_hi:[0,1]
	v_pk_add_f32 v[96:97], v[96:97], v[252:253] neg_lo:[0,1] neg_hi:[0,1]
	v_pk_add_f32 v[98:99], v[98:99], v[252:253] neg_lo:[0,1] neg_hi:[0,1]
	v_pk_add_f32 v[100:101], v[100:101], v[252:253] neg_lo:[0,1] neg_hi:[0,1]
	v_pk_add_f32 v[102:103], v[102:103], v[252:253] neg_lo:[0,1] neg_hi:[0,1]
	v_pk_add_f32 v[104:105], v[104:105], v[252:253] neg_lo:[0,1] neg_hi:[0,1]
	v_pk_add_f32 v[106:107], v[106:107], v[252:253] neg_lo:[0,1] neg_hi:[0,1]
	v_pk_add_f32 v[108:109], v[108:109], v[252:253] neg_lo:[0,1] neg_hi:[0,1]
	v_pk_add_f32 v[110:111], v[110:111], v[252:253] neg_lo:[0,1] neg_hi:[0,1]
	v_pk_add_f32 v[112:113], v[112:113], v[252:253] neg_lo:[0,1] neg_hi:[0,1]
	v_pk_add_f32 v[114:115], v[114:115], v[252:253] neg_lo:[0,1] neg_hi:[0,1]
	v_mov_b64_e32 v[188:189], 0
	v_mov_b64_e32 v[190:191], 0
	v_mov_b64_e32 v[192:193], 0
	v_mov_b64_e32 v[194:195], 0
	v_mov_b64_e32 v[204:205], 0
	v_mov_b64_e32 v[206:207], 0
	v_mov_b64_e32 v[208:209], 0
	v_mov_b64_e32 v[210:211], 0
	s_sub_u32 s5, s8, s4
	s_lshr_b32 s5, s5, 12
	s_sub_u32 s5, s5, 64
	s_add_u32 s38, s5, 64
	s_cmp_lt_u32 s38, s11
	s_cselect_b32 s37, 1, 0
	s_cmp_gt_u32 s38, s31
	s_cselect_b32 s40, 2, 0
	s_or_b32 s37, s37, s40
	s_mov_b32 s35, s37
	v_mov_b32_e32 v251, 0
	s_cmp_eq_u32 s37, 1
	s_cselect_b64 vcc, -1, 0
	v_cndmask_b32_e32 v251, v251, v177, vcc
	s_cmp_eq_u32 s37, 2
	s_cselect_b64 vcc, -1, 0
	v_cndmask_b32_e32 v251, v251, v178, vcc
	v_sub_f32_e32 v2, v251, v186
	v_mov_b32_e32 v3, v2
	v_mov_b64_e32 v[4:5], v[2:3]
	v_mov_b64_e32 v[6:7], v[2:3]
	v_mov_b64_e32 v[8:9], v[2:3]
	v_mov_b64_e32 v[10:11], v[2:3]
	v_mov_b64_e32 v[12:13], v[2:3]
	v_mov_b64_e32 v[14:15], v[2:3]
	v_mov_b64_e32 v[16:17], v[2:3]
	s_nop 1
	s_cmp_eq_u32 s42, 0
	s_cbranch_scc1 .LatA_rareret_h2
	s_cmp_eq_u32 s42, 1
	s_cbranch_scc1 .LatA_rareret_m2
	s_branch .LatA_rareret_x2
; __device__ __forceinline__ void attn_unit(LAS unsigned char* lds, const bf16_t* Z, bf16_t* A2, const float* tabg, int seq_base, int S, int h, int qb, float lam) {
;     ...
;         bool near = true; float cc = 0.f;
;         if (kv0 - (qlo + 31) >= 128) { near = false; cc = tabR; } else if (qlo - (kv0 + 63) >= 128) { near = false; cc = tabL; }
;         { const float coff = cc - mu;
;           if (__any(!(coff == coff_cur))) { coff_cur = coff;
; #pragma unroll
;               for (int r = 0; r < 16; ++r) cblk[r] = coff;
;               asm volatile("" : "+v"(cblk)); } }
;         f32x16 p0, p1;
;         {
;             bf16x8 kf[8];
; #pragma unroll
;             for (int ds = 0; ds < 4; ++ds) { kf[2 * ds] = *(const LAS bf16x8*)(Kt + (kfo ^ (unsigned)(ds << 5))); kf[2 * ds + 1] = *(const LAS bf16x8*)(Kt + 32 * 256 + (kfo ^ (unsigned)(ds << 5))); }
;             __builtin_amdgcn_sched_barrier(0);
;             p0 = __builtin_amdgcn_mfma_f32_32x32x16_bf16(kf[0], qf[0], cblk, 0, 0, 0);
;             p1 = __builtin_amdgcn_mfma_f32_32x32x16_bf16(kf[1], qf[0], cblk, 0, 0, 0);
; #pragma unroll
;             for (int ds = 1; ds < 4; ++ds) {
;                 p0 = __builtin_amdgcn_mfma_f32_32x32x16_bf16(kf[2 * ds], qf[ds], p0, 0, 0, 0);
;                 p1 = __builtin_amdgcn_mfma_f32_32x32x16_bf16(kf[2 * ds + 1], qf[ds], p1, 0, 0, 0);
;             }
;         }
;     ...
;         const unsigned vbase = (unsigned)(size_t)Vt + vfo;
;         s16x4 va[8], vb[8];
;         VREADS1(va, 0);
;         if (near) {
;             const LAS float* tp = tab + (kv0 + 4 * hi - (qlo + r32) + 224);
; #pragma unroll
;             for (int r = 0; r < 16; ++r) { p0[r] += tp[(r & 3) + 8 * (r >> 2)]; p1[r] += tp[32 + (r & 3) + 8 * (r >> 2)]; }
;         }
;         float mx = max2f(max16f(p0), max16f(p1));
;         const bool first = (t == 0);
;         if (first || __any(mx > THR)) {
;             { auto rr = __builtin_amdgcn_permlane32_swap(__float_as_uint(mx), __float_as_uint(mx), false, false); mx = max2f(__uint_as_float(rr[0]), __uint_as_float(rr[1])); }
;             const float delta = first ? mx : fmaxf(mx, 0.f);
;             const float alpha = first ? 1.0f : __builtin_amdgcn_exp2f(-delta);
;             mu += delta; ls2 *= alpha;
;             if (!first) {
;                 asm volatile("" ::: "memory");
;                 scr[r32] = alpha;
.LatA_rare_3114:
	v_mov_b32_e32 v252, v251
	s_nop 1
	v_permlane32_swap_b32_e32 v251, v252
	v_max_f32_e32 v251, v251, v252
	v_max_f32_e32 v253, 0, v251
	v_exp_f32_e64 v254, -v253
	v_add_f32_e32 v186, v186, v253
	s_nop 0
	v_mul_f32_e32 v150, v150, v254
	v_mul_f32_e32 v151, v151, v254
	ds_write_b32 v184, v254
	s_waitcnt lgkmcnt(0)
	v_mfma_f32_32x32x16_bf16 v[20:35], v[88:91], v[220:223], v[20:35]
	v_mfma_f32_32x32x16_bf16 v[36:51], v[88:91], v[224:227], v[36:51]
	v_mfma_f32_32x32x16_bf16 v[52:67], v[88:91], v[232:235], v[52:67]
	v_mfma_f32_32x32x16_bf16 v[68:83], v[88:91], v[236:239], v[68:83]
	v_mfma_f32_32x32x16_bf16 v[20:35], v[100:103], v[132:135], v[20:35]
	v_mfma_f32_32x32x16_bf16 v[36:51], v[100:103], v[136:139], v[36:51]
	v_mfma_f32_32x32x16_bf16 v[52:67], v[100:103], v[140:143], v[52:67]
	ds_read_b64_tr_b16 v[144:145], v231 offset:40960
	ds_read_b64_tr_b16 v[146:147], v231 offset:43008
	ds_read_b64_tr_b16 v[220:221], v228 offset:45056
	ds_read_b64_tr_b16 v[222:223], v228 offset:47104
	ds_read_b64_tr_b16 v[224:225], v229 offset:45056
	ds_read_b64_tr_b16 v[226:227], v229 offset:47104
	ds_read_b64_tr_b16 v[232:233], v230 offset:45056
	ds_read_b64_tr_b16 v[234:235], v230 offset:47104
	ds_read_b64_tr_b16 v[236:237], v231 offset:45056
	ds_read_b64_tr_b16 v[238:239], v231 offset:47104
	s_waitcnt lgkmcnt(0)
	v_mfma_f32_32x32x16_bf16 v[68:83], v[100:103], v[144:147], v[68:83]
	v_mfma_f32_32x32x16_bf16 v[20:35], v[104:107], v[220:223], v[20:35]
	v_mfma_f32_32x32x16_bf16 v[36:51], v[104:107], v[224:227], v[36:51]
	v_mfma_f32_32x32x16_bf16 v[52:67], v[104:107], v[232:235], v[52:67]
	v_mfma_f32_32x32x16_bf16 v[68:83], v[104:107], v[236:239], v[68:83]
	ds_read_b128 v[92:95], v185
	ds_read_b128 v[96:99], v185 offset:32
	ds_read_b128 v[108:111], v185 offset:64
	ds_read_b128 v[112:115], v185 offset:96
	s_waitcnt lgkmcnt(0)
	s_nop 15
	s_nop 15
	v_pk_mul_f32 v[20:21], v[20:21], v[92:93]
	v_pk_mul_f32 v[22:23], v[22:23], v[94:95]
	v_pk_mul_f32 v[24:25], v[24:25], v[96:97]
	v_pk_mul_f32 v[26:27], v[26:27], v[98:99]
	v_pk_mul_f32 v[28:29], v[28:29], v[108:109]
	v_pk_mul_f32 v[30:31], v[30:31], v[110:111]
	v_pk_mul_f32 v[32:33], v[32:33], v[112:113]
	v_pk_mul_f32 v[34:35], v[34:35], v[114:115]
	v_pk_mul_f32 v[36:37], v[36:37], v[92:93]
	v_pk_mul_f32 v[38:39], v[38:39], v[94:95]
	v_pk_mul_f32 v[40:41], v[40:41], v[96:97]
	v_pk_mul_f32 v[42:43], v[42:43], v[98:99]
	v_pk_mul_f32 v[44:45], v[44:45], v[108:109]
	v_pk_mul_f32 v[46:47], v[46:47], v[110:111]
	v_pk_mul_f32 v[48:49], v[48:49], v[112:113]
	v_pk_mul_f32 v[50:51], v[50:51], v[114:115]
	v_pk_mul_f32 v[52:53], v[52:53], v[92:93]
	v_pk_mul_f32 v[54:55], v[54:55], v[94:95]
	v_pk_mul_f32 v[56:57], v[56:57], v[96:97]
	v_pk_mul_f32 v[58:59], v[58:59], v[98:99]
	v_pk_mul_f32 v[60:61], v[60:61], v[108:109]
	v_pk_mul_f32 v[62:63], v[62:63], v[110:111]
	v_pk_mul_f32 v[64:65], v[64:65], v[112:113]
	v_pk_mul_f32 v[66:67], v[66:67], v[114:115]
	v_pk_mul_f32 v[68:69], v[68:69], v[92:93]
	v_pk_mul_f32 v[70:71], v[70:71], v[94:95]
	v_pk_mul_f32 v[72:73], v[72:73], v[96:97]
	v_pk_mul_f32 v[74:75], v[74:75], v[98:99]
	v_pk_mul_f32 v[76:77], v[76:77], v[108:109]
	v_pk_mul_f32 v[78:79], v[78:79], v[110:111]
	v_pk_mul_f32 v[80:81], v[80:81], v[112:113]
	v_pk_mul_f32 v[82:83], v[82:83], v[114:115]
	v_mov_b32_e32 v252, v253
	v_pk_add_f32 v[188:189], v[188:189], v[252:253] neg_lo:[0,1] neg_hi:[0,1]
	v_pk_add_f32 v[190:191], v[190:191], v[252:253] neg_lo:[0,1] neg_hi:[0,1]
	v_pk_add_f32 v[192:193], v[192:193], v[252:253] neg_lo:[0,1] neg_hi:[0,1]
	v_pk_add_f32 v[194:195], v[194:195], v[252:253] neg_lo:[0,1] neg_hi:[0,1]
	v_pk_add_f32 v[196:197], v[196:197], v[252:253] neg_lo:[0,1] neg_hi:[0,1]
	v_pk_add_f32 v[198:199], v[198:199], v[252:253] neg_lo:[0,1] neg_hi:[0,1]
	v_pk_add_f32 v[200:201], v[200:201], v[252:253] neg_lo:[0,1] neg_hi:[0,1]
	v_pk_add_f32 v[202:203], v[202:203], v[252:253] neg_lo:[0,1] neg_hi:[0,1]
	v_pk_add_f32 v[204:205], v[204:205], v[252:253] neg_lo:[0,1] neg_hi:[0,1]
	v_pk_add_f32 v[206:207], v[206:207], v[252:253] neg_lo:[0,1] neg_hi:[0,1]
	v_pk_add_f32 v[208:209], v[208:209], v[252:253] neg_lo:[0,1] neg_hi:[0,1]
	v_pk_add_f32 v[210:211], v[210:211], v[252:253] neg_lo:[0,1] neg_hi:[0,1]
	v_pk_add_f32 v[212:213], v[212:213], v[252:253] neg_lo:[0,1] neg_hi:[0,1]
	v_pk_add_f32 v[214:215], v[214:215], v[252:253] neg_lo:[0,1] neg_hi:[0,1]
	v_pk_add_f32 v[216:217], v[216:217], v[252:253] neg_lo:[0,1] neg_hi:[0,1]
	v_pk_add_f32 v[218:219], v[218:219], v[252:253] neg_lo:[0,1] neg_hi:[0,1]
	v_mov_b64_e32 v[84:85], 0
	v_mov_b64_e32 v[86:87], 0
	v_mov_b64_e32 v[88:89], 0
	v_mov_b64_e32 v[90:91], 0
	v_mov_b64_e32 v[100:101], 0
	v_mov_b64_e32 v[102:103], 0
	v_mov_b64_e32 v[104:105], 0
	v_mov_b64_e32 v[106:107], 0
	s_sub_u32 s5, s8, s4
	s_lshr_b32 s5, s5, 12
	s_sub_u32 s5, s5, 64
	s_add_u32 s38, s5, 64
	s_cmp_lt_u32 s38, s11
	s_cselect_b32 s37, 1, 0
	s_cmp_gt_u32 s38, s31
	s_cselect_b32 s40, 2, 0
	s_or_b32 s37, s37, s40
	s_mov_b32 s35, s37
	v_mov_b32_e32 v251, 0
	s_cmp_eq_u32 s37, 1
	s_cselect_b64 vcc, -1, 0
	v_cndmask_b32_e32 v251, v251, v177, vcc
	s_cmp_eq_u32 s37, 2
	s_cselect_b64 vcc, -1, 0
	v_cndmask_b32_e32 v251, v251, v178, vcc
	v_sub_f32_e32 v2, v251, v186
	v_mov_b32_e32 v3, v2
	v_mov_b64_e32 v[4:5], v[2:3]
	v_mov_b64_e32 v[6:7], v[2:3]
	v_mov_b64_e32 v[8:9], v[2:3]
	v_mov_b64_e32 v[10:11], v[2:3]
	v_mov_b64_e32 v[12:13], v[2:3]
	v_mov_b64_e32 v[14:15], v[2:3]
	v_mov_b64_e32 v[16:17], v[2:3]
	s_nop 1
	s_cmp_eq_u32 s42, 0
	s_cbranch_scc1 .LatA_rareret_h3
	s_branch .LatA_rareret_m3
; __device__ __forceinline__ void attn_unit(LAS unsigned char* lds, const bf16_t* Z, bf16_t* A2, const float* tabg, int seq_base, int S, int h, int qb, float lam) {
;     ...
;         bool near = true; float cc = 0.f;
;         if (kv0 - (qlo + 31) >= 128) { near = false; cc = tabR; } else if (qlo - (kv0 + 63) >= 128) { near = false; cc = tabL; }
;         { const float coff = cc - mu;
;           if (__any(!(coff == coff_cur))) { coff_cur = coff;
; #pragma unroll
;               for (int r = 0; r < 16; ++r) cblk[r] = coff;
;               asm volatile("" : "+v"(cblk)); } }
;         f32x16 p0, p1;
;         {
;             bf16x8 kf[8];
; #pragma unroll
;             for (int ds = 0; ds < 4; ++ds) { kf[2 * ds] = *(const LAS bf16x8*)(Kt + (kfo ^ (unsigned)(ds << 5))); kf[2 * ds + 1] = *(const LAS bf16x8*)(Kt + 32 * 256 + (kfo ^ (unsigned)(ds << 5))); }
;             __builtin_amdgcn_sched_barrier(0);
;             p0 = __builtin_amdgcn_mfma_f32_32x32x16_bf16(kf[0], qf[0], cblk, 0, 0, 0);
;             p1 = __builtin_amdgcn_mfma_f32_32x32x16_bf16(kf[1], qf[0], cblk, 0, 0, 0);
; #pragma unroll
;             for (int ds = 1; ds < 4; ++ds) {
;                 p0 = __builtin_amdgcn_mfma_f32_32x32x16_bf16(kf[2 * ds], qf[ds], p0, 0, 0, 0);
;                 p1 = __builtin_amdgcn_mfma_f32_32x32x16_bf16(kf[2 * ds + 1], qf[ds], p1, 0, 0, 0);
;             }
;         }
;     ...
;         const unsigned vbase = (unsigned)(size_t)Vt + vfo;
;         s16x4 va[8], vb[8];
;         VREADS1(va, 0);
;         if (near) {
;             const LAS float* tp = tab + (kv0 + 4 * hi - (qlo + r32) + 224);
; #pragma unroll
;             for (int r = 0; r < 16; ++r) { p0[r] += tp[(r & 3) + 8 * (r >> 2)]; p1[r] += tp[32 + (r & 3) + 8 * (r >> 2)]; }
;         }
;         float mx = max2f(max16f(p0), max16f(p1));
;         const bool first = (t == 0);
;         if (first || __any(mx > THR)) {
;             { auto rr = __builtin_amdgcn_permlane32_swap(__float_as_uint(mx), __float_as_uint(mx), false, false); mx = max2f(__uint_as_float(rr[0]), __uint_as_float(rr[1])); }
;             const float delta = first ? mx : fmaxf(mx, 0.f);
;             const float alpha = first ? 1.0f : __builtin_amdgcn_exp2f(-delta);
;             mu += delta; ls2 *= alpha;
;             if (!first) {
;                 asm volatile("" ::: "memory");
;                 scr[r32] = alpha;
.LatA_rare_0114:
	v_mov_b32_e32 v252, v251
	s_nop 1
	v_permlane32_swap_b32_e32 v251, v252
	v_max_f32_e32 v251, v251, v252
	v_max_f32_e32 v253, 0, v251
	v_exp_f32_e64 v254, -v253
	v_add_f32_e32 v186, v186, v253
	s_nop 0
	v_mul_f32_e32 v150, v150, v254
	v_mul_f32_e32 v151, v151, v254
	ds_write_b32 v184, v254
	s_waitcnt lgkmcnt(0)
	v_mfma_f32_32x32x16_bf16 v[20:35], v[192:195], v[220:223], v[20:35]
	v_mfma_f32_32x32x16_bf16 v[36:51], v[192:195], v[224:227], v[36:51]
	v_mfma_f32_32x32x16_bf16 v[52:67], v[192:195], v[232:235], v[52:67]
	v_mfma_f32_32x32x16_bf16 v[68:83], v[192:195], v[236:239], v[68:83]
	v_mfma_f32_32x32x16_bf16 v[20:35], v[204:207], v[132:135], v[20:35]
	v_mfma_f32_32x32x16_bf16 v[36:51], v[204:207], v[136:139], v[36:51]
	v_mfma_f32_32x32x16_bf16 v[52:67], v[204:207], v[140:143], v[52:67]
	ds_read_b64_tr_b16 v[144:145], v171 offset:8192
	ds_read_b64_tr_b16 v[146:147], v171 offset:10240
	ds_read_b64_tr_b16 v[220:221], v168 offset:12288
	ds_read_b64_tr_b16 v[222:223], v168 offset:14336
	ds_read_b64_tr_b16 v[224:225], v169 offset:12288
	ds_read_b64_tr_b16 v[226:227], v169 offset:14336
	ds_read_b64_tr_b16 v[232:233], v170 offset:12288
	ds_read_b64_tr_b16 v[234:235], v170 offset:14336
	ds_read_b64_tr_b16 v[236:237], v171 offset:12288
	ds_read_b64_tr_b16 v[238:239], v171 offset:14336
	s_waitcnt lgkmcnt(0)
	v_mfma_f32_32x32x16_bf16 v[68:83], v[204:207], v[144:147], v[68:83]
	v_mfma_f32_32x32x16_bf16 v[20:35], v[208:211], v[220:223], v[20:35]
	v_mfma_f32_32x32x16_bf16 v[36:51], v[208:211], v[224:227], v[36:51]
	v_mfma_f32_32x32x16_bf16 v[52:67], v[208:211], v[232:235], v[52:67]
	v_mfma_f32_32x32x16_bf16 v[68:83], v[208:211], v[236:239], v[68:83]
	ds_read_b128 v[196:199], v185
	ds_read_b128 v[200:203], v185 offset:32
	ds_read_b128 v[212:215], v185 offset:64
	ds_read_b128 v[216:219], v185 offset:96
	s_waitcnt lgkmcnt(0)
	s_nop 15
	s_nop 15
	v_pk_mul_f32 v[20:21], v[20:21], v[196:197]
	v_pk_mul_f32 v[22:23], v[22:23], v[198:199]
	v_pk_mul_f32 v[24:25], v[24:25], v[200:201]
	v_pk_mul_f32 v[26:27], v[26:27], v[202:203]
	v_pk_mul_f32 v[28:29], v[28:29], v[212:213]
	v_pk_mul_f32 v[30:31], v[30:31], v[214:215]
	v_pk_mul_f32 v[32:33], v[32:33], v[216:217]
	v_pk_mul_f32 v[34:35], v[34:35], v[218:219]
	v_pk_mul_f32 v[36:37], v[36:37], v[196:197]
	v_pk_mul_f32 v[38:39], v[38:39], v[198:199]
	v_pk_mul_f32 v[40:41], v[40:41], v[200:201]
	v_pk_mul_f32 v[42:43], v[42:43], v[202:203]
	v_pk_mul_f32 v[44:45], v[44:45], v[212:213]
	v_pk_mul_f32 v[46:47], v[46:47], v[214:215]
	v_pk_mul_f32 v[48:49], v[48:49], v[216:217]
	v_pk_mul_f32 v[50:51], v[50:51], v[218:219]
	v_pk_mul_f32 v[52:53], v[52:53], v[196:197]
	v_pk_mul_f32 v[54:55], v[54:55], v[198:199]
	v_pk_mul_f32 v[56:57], v[56:57], v[200:201]
	v_pk_mul_f32 v[58:59], v[58:59], v[202:203]
	v_pk_mul_f32 v[60:61], v[60:61], v[212:213]
	v_pk_mul_f32 v[62:63], v[62:63], v[214:215]
	v_pk_mul_f32 v[64:65], v[64:65], v[216:217]
	v_pk_mul_f32 v[66:67], v[66:67], v[218:219]
	v_pk_mul_f32 v[68:69], v[68:69], v[196:197]
	v_pk_mul_f32 v[70:71], v[70:71], v[198:199]
	v_pk_mul_f32 v[72:73], v[72:73], v[200:201]
	v_pk_mul_f32 v[74:75], v[74:75], v[202:203]
	v_pk_mul_f32 v[76:77], v[76:77], v[212:213]
	v_pk_mul_f32 v[78:79], v[78:79], v[214:215]
	v_pk_mul_f32 v[80:81], v[80:81], v[216:217]
	v_pk_mul_f32 v[82:83], v[82:83], v[218:219]
	v_mov_b32_e32 v252, v253
	v_pk_add_f32 v[84:85], v[84:85], v[252:253] neg_lo:[0,1] neg_hi:[0,1]
	v_pk_add_f32 v[86:87], v[86:87], v[252:253] neg_lo:[0,1] neg_hi:[0,1]
	v_pk_add_f32 v[88:89], v[88:89], v[252:253] neg_lo:[0,1] neg_hi:[0,1]
	v_pk_add_f32 v[90:91], v[90:91], v[252:253] neg_lo:[0,1] neg_hi:[0,1]
	v_pk_add_f32 v[92:93], v[92:93], v[252:253] neg_lo:[0,1] neg_hi:[0,1]
	v_pk_add_f32 v[94:95], v[94:95], v[252:253] neg_lo:[0,1] neg_hi:[0,1]
	v_pk_add_f32 v[96:97], v[96:97], v[252:253] neg_lo:[0,1] neg_hi:[0,1]
	v_pk_add_f32 v[98:99], v[98:99], v[252:253] neg_lo:[0,1] neg_hi:[0,1]
	v_pk_add_f32 v[100:101], v[100:101], v[252:253] neg_lo:[0,1] neg_hi:[0,1]
	v_pk_add_f32 v[102:103], v[102:103], v[252:253] neg_lo:[0,1] neg_hi:[0,1]
	v_pk_add_f32 v[104:105], v[104:105], v[252:253] neg_lo:[0,1] neg_hi:[0,1]
	v_pk_add_f32 v[106:107], v[106:107], v[252:253] neg_lo:[0,1] neg_hi:[0,1]
	v_pk_add_f32 v[108:109], v[108:109], v[252:253] neg_lo:[0,1] neg_hi:[0,1]
	v_pk_add_f32 v[110:111], v[110:111], v[252:253] neg_lo:[0,1] neg_hi:[0,1]
	v_pk_add_f32 v[112:113], v[112:113], v[252:253] neg_lo:[0,1] neg_hi:[0,1]
	v_pk_add_f32 v[114:115], v[114:115], v[252:253] neg_lo:[0,1] neg_hi:[0,1]
	v_mov_b64_e32 v[188:189], 0
	v_mov_b64_e32 v[190:191], 0
	v_mov_b64_e32 v[192:193], 0
	v_mov_b64_e32 v[194:195], 0
	v_mov_b64_e32 v[204:205], 0
	v_mov_b64_e32 v[206:207], 0
	v_mov_b64_e32 v[208:209], 0
	v_mov_b64_e32 v[210:211], 0
	s_sub_u32 s5, s8, s4
	s_lshr_b32 s5, s5, 12
	s_sub_u32 s5, s5, 64
	s_add_u32 s38, s5, 64
	s_cmp_lt_u32 s38, s11
	s_cselect_b32 s37, 1, 0
	s_cmp_gt_u32 s38, s31
	s_cselect_b32 s40, 2, 0
	s_or_b32 s37, s37, s40
	s_mov_b32 s35, s37
	v_mov_b32_e32 v251, 0
	s_cmp_eq_u32 s37, 1
	s_cselect_b64 vcc, -1, 0
	v_cndmask_b32_e32 v251, v251, v177, vcc
	s_cmp_eq_u32 s37, 2
	s_cselect_b64 vcc, -1, 0
	v_cndmask_b32_e32 v251, v251, v178, vcc
	v_sub_f32_e32 v2, v251, v186
	v_mov_b32_e32 v3, v2
	v_mov_b64_e32 v[4:5], v[2:3]
	v_mov_b64_e32 v[6:7], v[2:3]
	v_mov_b64_e32 v[8:9], v[2:3]
	v_mov_b64_e32 v[10:11], v[2:3]
	v_mov_b64_e32 v[12:13], v[2:3]
	v_mov_b64_e32 v[14:15], v[2:3]
	v_mov_b64_e32 v[16:17], v[2:3]
	s_nop 1
	s_cmp_eq_u32 s42, 0
	s_cbranch_scc1 .LatA_rareret_m0
	s_branch .LatA_rareret_x4
; #define LAS __attribute__((address_space(3)))
; __device__ __forceinline__ float max2f(float a, float b) { float r; asm("v_max_f32_e32 %0, %1, %2" : "=v"(r) : "v"(a), "v"(b)); return r; }
; #define VREADS1(arr, d_) do { const unsigned ad_ = vbase ^ (unsigned)((d_) << 6); __builtin_amdgcn_sched_barrier(0); \
;         _Pragma("unroll") for (int ks_ = 0; ks_ < 4; ++ks_) { VTR(arr[ks_ * 2], ad_, ks_ * 4096); VTR(arr[ks_ * 2 + 1], ad_, ks_ * 4096 + 2048); } __builtin_amdgcn_sched_barrier(0); } while (0)
; __device__ __forceinline__ void attn_unit(LAS unsigned char* lds, const bf16_t* Z, bf16_t* A2, const float* tabg, int seq_base, int S, int h, int qb, float lam) {
;     ...
;         if (first || __any(mx > THR)) {
;             { auto rr = __builtin_amdgcn_permlane32_swap(__float_as_uint(mx), __float_as_uint(mx), false, false); mx = max2f(__uint_as_float(rr[0]), __uint_as_float(rr[1])); }
;             const float delta = first ? mx : fmaxf(mx, 0.f);
;             const float alpha = first ? 1.0f : __builtin_amdgcn_exp2f(-delta);
;             mu += delta; ls2 *= alpha;
;             if (!first) {
;                 asm volatile("" ::: "memory");
;                 scr[r32] = alpha;
;                 asm volatile("s_waitcnt lgkmcnt(0)" ::: "memory");
; #pragma unroll
;                 for (int g = 0; g < 4; ++g) { const f32x4 a4 = *(const LAS f32x4*)(scr + 8 * g + 4 * hi);
; #pragma unroll
;                     for (int d = 0; d < 4; ++d) { O[d][4 * g + 0] *= a4[0]; O[d][4 * g + 1] *= a4[1]; O[d][4 * g + 2] *= a4[2]; O[d][4 * g + 3] *= a4[3]; } }
;                 asm volatile("s_waitcnt lgkmcnt(0)" ::: "memory");
;             }
; #pragma unroll
;             for (int r = 0; r < 16; ++r) { p0[r] -= delta; p1[r] -= delta; }
;             asm volatile("" : "+v"(p0), "+v"(p1));
;         }
; #pragma unroll
;         for (int r = 0; r < 16; ++r) { p0[r] = __builtin_amdgcn_exp2f(p0[r]); p1[r] = __builtin_amdgcn_exp2f(p1[r]); }
; #pragma unroll
;         for (int r = 0; r < 16; r += 2) { ls2 += (f32x2){p0[r], p0[r + 1]}; ls2 += (f32x2){p1[r], p1[r + 1]}; }
;         bf16x8 pa[4]; pa[0] = pack8(p0, 0); pa[1] = pack8(p0, 8); pa[2] = pack8(p1, 0); pa[3] = pack8(p1, 8);
;         LGKM0(); VREADS1(vb, 1); PV1(va, 0); LGKM0(); VREADS1(va, 2); PV1(vb, 1); LGKM0(); VREADS1(vb, 3); PV1(va, 2); LGKM0(); PV1(vb, 3);
.LatA_rare_3104:
	v_mov_b32_e32 v252, v251
	s_nop 1
	v_permlane32_swap_b32_e32 v251, v252
	v_max_f32_e32 v251, v251, v252
	v_max_f32_e32 v253, 0, v251
	v_exp_f32_e64 v254, -v253
	v_add_f32_e32 v186, v186, v253
	s_nop 0
	v_mul_f32_e32 v150, v150, v254
	v_mul_f32_e32 v151, v151, v254
	ds_write_b32 v184, v254
	s_waitcnt lgkmcnt(0)
	v_mfma_f32_32x32x16_bf16 v[20:35], v[88:91], v[220:223], v[20:35]
	v_mfma_f32_32x32x16_bf16 v[36:51], v[88:91], v[224:227], v[36:51]
	v_mfma_f32_32x32x16_bf16 v[52:67], v[88:91], v[232:235], v[52:67]
	v_mfma_f32_32x32x16_bf16 v[68:83], v[88:91], v[236:239], v[68:83]
	v_mfma_f32_32x32x16_bf16 v[20:35], v[100:103], v[132:135], v[20:35]
	v_mfma_f32_32x32x16_bf16 v[36:51], v[100:103], v[136:139], v[36:51]
	v_mfma_f32_32x32x16_bf16 v[52:67], v[100:103], v[140:143], v[52:67]
	ds_read_b64_tr_b16 v[144:145], v231 offset:40960
	ds_read_b64_tr_b16 v[146:147], v231 offset:43008
	ds_read_b64_tr_b16 v[220:221], v228 offset:45056
	ds_read_b64_tr_b16 v[222:223], v228 offset:47104
	ds_read_b64_tr_b16 v[224:225], v229 offset:45056
	ds_read_b64_tr_b16 v[226:227], v229 offset:47104
	ds_read_b64_tr_b16 v[232:233], v230 offset:45056
	ds_read_b64_tr_b16 v[234:235], v230 offset:47104
	ds_read_b64_tr_b16 v[236:237], v231 offset:45056
	ds_read_b64_tr_b16 v[238:239], v231 offset:47104
	s_waitcnt lgkmcnt(0)
	v_mfma_f32_32x32x16_bf16 v[68:83], v[100:103], v[144:147], v[68:83]
	v_mfma_f32_32x32x16_bf16 v[20:35], v[104:107], v[220:223], v[20:35]
	v_mfma_f32_32x32x16_bf16 v[36:51], v[104:107], v[224:227], v[36:51]
	v_mfma_f32_32x32x16_bf16 v[52:67], v[104:107], v[232:235], v[52:67]
	v_mfma_f32_32x32x16_bf16 v[68:83], v[104:107], v[236:239], v[68:83]
	ds_read_b128 v[92:95], v185
	ds_read_b128 v[96:99], v185 offset:32
	ds_read_b128 v[108:111], v185 offset:64
	ds_read_b128 v[112:115], v185 offset:96
	s_waitcnt lgkmcnt(0)
	s_nop 15
	s_nop 15
	v_pk_mul_f32 v[20:21], v[20:21], v[92:93]
	v_pk_mul_f32 v[22:23], v[22:23], v[94:95]
	v_pk_mul_f32 v[24:25], v[24:25], v[96:97]
	v_pk_mul_f32 v[26:27], v[26:27], v[98:99]
	v_pk_mul_f32 v[28:29], v[28:29], v[108:109]
	v_pk_mul_f32 v[30:31], v[30:31], v[110:111]
	v_pk_mul_f32 v[32:33], v[32:33], v[112:113]
	v_pk_mul_f32 v[34:35], v[34:35], v[114:115]
	v_pk_mul_f32 v[36:37], v[36:37], v[92:93]
	v_pk_mul_f32 v[38:39], v[38:39], v[94:95]
	v_pk_mul_f32 v[40:41], v[40:41], v[96:97]
	v_pk_mul_f32 v[42:43], v[42:43], v[98:99]
	v_pk_mul_f32 v[44:45], v[44:45], v[108:109]
	v_pk_mul_f32 v[46:47], v[46:47], v[110:111]
	v_pk_mul_f32 v[48:49], v[48:49], v[112:113]
	v_pk_mul_f32 v[50:51], v[50:51], v[114:115]
	v_pk_mul_f32 v[52:53], v[52:53], v[92:93]
	v_pk_mul_f32 v[54:55], v[54:55], v[94:95]
	v_pk_mul_f32 v[56:57], v[56:57], v[96:97]
	v_pk_mul_f32 v[58:59], v[58:59], v[98:99]
	v_pk_mul_f32 v[60:61], v[60:61], v[108:109]
	v_pk_mul_f32 v[62:63], v[62:63], v[110:111]
	v_pk_mul_f32 v[64:65], v[64:65], v[112:113]
	v_pk_mul_f32 v[66:67], v[66:67], v[114:115]
	v_pk_mul_f32 v[68:69], v[68:69], v[92:93]
	v_pk_mul_f32 v[70:71], v[70:71], v[94:95]
	v_pk_mul_f32 v[72:73], v[72:73], v[96:97]
	v_pk_mul_f32 v[74:75], v[74:75], v[98:99]
	v_pk_mul_f32 v[76:77], v[76:77], v[108:109]
	v_pk_mul_f32 v[78:79], v[78:79], v[110:111]
	v_pk_mul_f32 v[80:81], v[80:81], v[112:113]
	v_pk_mul_f32 v[82:83], v[82:83], v[114:115]
	v_mov_b32_e32 v252, v253
	v_pk_add_f32 v[188:189], v[188:189], v[252:253] neg_lo:[0,1] neg_hi:[0,1]
	v_pk_add_f32 v[190:191], v[190:191], v[252:253] neg_lo:[0,1] neg_hi:[0,1]
	v_pk_add_f32 v[192:193], v[192:193], v[252:253] neg_lo:[0,1] neg_hi:[0,1]
	v_pk_add_f32 v[194:195], v[194:195], v[252:253] neg_lo:[0,1] neg_hi:[0,1]
	v_pk_add_f32 v[196:197], v[196:197], v[252:253] neg_lo:[0,1] neg_hi:[0,1]
	v_pk_add_f32 v[198:199], v[198:199], v[252:253] neg_lo:[0,1] neg_hi:[0,1]
	v_pk_add_f32 v[200:201], v[200:201], v[252:253] neg_lo:[0,1] neg_hi:[0,1]
	v_pk_add_f32 v[202:203], v[202:203], v[252:253] neg_lo:[0,1] neg_hi:[0,1]
	v_pk_add_f32 v[204:205], v[204:205], v[252:253] neg_lo:[0,1] neg_hi:[0,1]
	v_pk_add_f32 v[206:207], v[206:207], v[252:253] neg_lo:[0,1] neg_hi:[0,1]
	v_pk_add_f32 v[208:209], v[208:209], v[252:253] neg_lo:[0,1] neg_hi:[0,1]
	v_pk_add_f32 v[210:211], v[210:211], v[252:253] neg_lo:[0,1] neg_hi:[0,1]
	v_pk_add_f32 v[212:213], v[212:213], v[252:253] neg_lo:[0,1] neg_hi:[0,1]
	v_pk_add_f32 v[214:215], v[214:215], v[252:253] neg_lo:[0,1] neg_hi:[0,1]
	v_pk_add_f32 v[216:217], v[216:217], v[252:253] neg_lo:[0,1] neg_hi:[0,1]
	v_pk_add_f32 v[218:219], v[218:219], v[252:253] neg_lo:[0,1] neg_hi:[0,1]
	v_mov_b64_e32 v[84:85], 0
	v_mov_b64_e32 v[86:87], 0
	v_mov_b64_e32 v[88:89], 0
	v_mov_b64_e32 v[90:91], 0
	v_mov_b64_e32 v[100:101], 0
	v_mov_b64_e32 v[102:103], 0
	v_mov_b64_e32 v[104:105], 0
	v_mov_b64_e32 v[106:107], 0
	s_nop 1
	s_branch .LatA_rareret_x1

; __device__ __forceinline__ void attn_unit(LAS unsigned char* lds, const bf16_t* Z, bf16_t* A2, const float* tabg, int seq_base, int S, int h, int qb, float lam) {
;     ...
;     const int qlo = qb * 128 + rg * 32;
;     bf16x8 qf[4];
;     { const bf16_t* qrow = Z + (size_t)(seq_base + qlo + r32) * NZ + h * 128 + m * 64 + 8 * hi;
; #pragma unroll
;       for (int ds = 0; ds < 4; ++ds) qf[ds] = *(const bf16x8*)(qrow + 16 * ds); }
;     const char* kvbase = (const char*)(Z + (size_t)seq_base * NZ + h * 128);
;     unsigned koff[2], voff[2];
; #pragma unroll
;     for (int i = 0; i < 2; ++i) { const int row = (i * 8 + w) * 4 + (lane >> 4), cp = lane & 15;
;         koff[i] = (unsigned)(row * NZ + 512 + ((cp ^ (row & 15)) << 3)) * 2u; voff[i] = (unsigned)(row * NZ + 1024 + ((cp ^ (4 * (row & 3))) << 3)) * 2u; }
;     const unsigned kb_u = (unsigned)(size_t)Kb + (unsigned)w * 1024u, vb_u = (unsigned)(size_t)Vb + (unsigned)w * 1024u;
;     ...
;     ATT_STAGE(0, 0); ATT_STAGE(1, 1);
;     asm volatile("s_waitcnt vmcnt(4) lgkmcnt(0)" ::: "memory"); __builtin_amdgcn_s_barrier(); asm volatile("" ::: "memory");
; #pragma unroll
;     for (int ds = 0; ds < 4; ++ds) asm volatile("" : "+v"(qf[ds]));
;     const float tabL = tab[0], tabR = tab[448];
;     f32x16 O[4];
; #pragma unroll
;     for (int d = 0; d < 4; ++d)
; #pragma unroll
;         for (int r = 0; r < 16; ++r) O[d][r] = 0.f;
;     float mu = 0.f; f32x2 ls2 = {0.f, 0.f};
;     f32x16 cblk; float coff_cur = __builtin_nanf("");
; #pragma unroll
;     for (int r = 0; r < 16; ++r) cblk[r] = 0.f;
;     const int NT = S >> 6;
;     const unsigned kfo = r32 * 256 + ((unsigned)((m * 8 + hi) ^ (r32 & 15)) << 4);
;     const unsigned vj = (i16 >> 2) & 3;
;     const unsigned vfo = (4 * hi + (i16 >> 2)) * 256 + (vj << 6) + 32 * (g4 & 1) + 8 * (i16 & 3);
;     int bc = 0, bn = 2;
.LBB0_325:
	s_or_b64 exec, exec, s[8:9]
	s_lshl_b32 s9, s21, 6
	s_and_b32 s8, s25, 32
	s_and_b32 s9, s9, 64
	s_or_b32 s8, s9, s8
	s_ashr_i32 s15, s26, 6
	s_or_b32 s8, s8, s23
	s_and_b32 s17, s15, 3
	s_lshl_b32 s8, s8, 7
	s_waitcnt lgkmcnt(0)
	s_lshl_b32 s10, s17, 5
	s_or_b32 s11, s10, s8
	v_and_b32_e32 v148, 31, v68
	s_or_b32 s14, s11, 0x4000
	v_or_b32_e32 v2, s14, v148
	s_ashr_i32 s16, s26, 8
	v_lshlrev_b32_e32 v162, 12, v2
	v_lshl_add_u64 v[2:3], s[4:5], 0, v[162:163]
	s_lshl_b32 s48, s28, 8
	s_lshl_b32 s8, s16, 6
	v_bfe_u32 v159, v68, 5, 1
	v_lshl_add_u64 v[2:3], v[2:3], 0, s[48:49]
	s_ashr_i32 s9, s8, 31
	v_lshl_add_u64 v[2:3], s[8:9], 1, v[2:3]
	v_lshlrev_b32_e32 v162, 4, v159
	v_lshl_add_u64 v[2:3], v[2:3], 0, v[162:163]
	s_mov_b64 s[8:9], 0x7800000
	v_lshl_add_u64 v[4:5], v[2:3], 0, s[8:9]
	s_mov_b32 s8, 0x7800000
	v_add_co_u32_e32 v2, vcc, s8, v2
	v_readlane_b32 s8, v255, 29
	s_nop 0
	v_addc_co_u32_e32 v3, vcc, 0, v3, vcc
	global_load_dwordx4 v[116:119], v[2:3], off
	global_load_dwordx4 v[120:123], v[4:5], off offset:32
	global_load_dwordx4 v[124:127], v[4:5], off offset:64
	global_load_dwordx4 v[128:131], v[4:5], off offset:96
	v_mov_b32_e32 v3, s8
	v_readlane_b32 s8, v255, 30
	v_bfe_u32 v2, v68, 4, 2
	v_lshlrev_b32_e32 v35, 5, v2
	v_mov_b32_e32 v4, s8
	s_lshl_b32 s8, s15, 2
	v_or_b32_e32 v6, s8, v2
	v_bitop3_b32 v2, s8, v68, v2 bitop3:0x36
	s_add_u32 s29, s4, s48
	v_and_b32_e32 v34, 15, v68
	v_lshlrev_b32_e32 v6, 11, v6
	v_lshlrev_b32_e32 v2, 3, v2
	s_addc_u32 s30, s5, 0
	v_lshlrev_b32_e32 v5, 3, v34
	v_and_b32_e32 v2, 0x78, v2
	v_add_u32_e32 v8, 0x10000, v6
	s_add_u32 s8, s29, 0xb800000
	v_bitop3_b32 v7, v6, v35, v5 bitop3:0xf6
	v_or_b32_e32 v6, v2, v6
	v_or_b32_e32 v2, v2, v8
	v_bitop3_b32 v5, v8, v35, v5 bitop3:0xf6
	s_addc_u32 s9, s30, 0
	s_lshl_b32 s27, s15, 10
	s_add_i32 s15, 0, 0xc000
	v_lshl_or_b32 v149, v7, 1, v250
	v_lshl_or_b32 v160, v6, 1, v249
	v_lshl_or_b32 v161, v2, 1, v249
	v_lshl_or_b32 v176, v5, 1, v250
	s_add_i32 s25, s27, 0
	s_add_i32 s27, s27, s15
	s_mov_b32 s31, m0
	s_mov_b32 m0, s25
	s_nop 0
	global_load_lds_dwordx4 v160, s[8:9]
	s_mov_b32 m0, s27
	s_nop 0
	global_load_lds_dwordx4 v149, s[8:9]
	s_add_u32 m0, s25, 0x2000
	s_nop 0
	global_load_lds_dwordx4 v161, s[8:9]
	s_add_u32 m0, s27, 0x2000
	s_nop 0
	global_load_lds_dwordx4 v176, s[8:9]
	s_mov_b32 m0, s31
	s_add_u32 s8, s29, 0xb840000
	s_addc_u32 s9, s30, 0
	s_add_i32 s31, s25, 0x4000
	s_add_i32 s33, s27, 0x4000
	s_mov_b32 s34, m0
	s_mov_b32 m0, s31
	s_nop 0
	global_load_lds_dwordx4 v160, s[8:9]
	s_mov_b32 m0, s33
	s_nop 0
	global_load_lds_dwordx4 v149, s[8:9]
	s_add_u32 m0, s31, 0x2000
	s_nop 0
	global_load_lds_dwordx4 v161, s[8:9]
	s_add_u32 m0, s33, 0x2000
	s_nop 0
	global_load_lds_dwordx4 v176, s[8:9]
	s_mov_b32 m0, s34
	s_mov_b32 s32, m0
	s_add_u32 s8, s29, 0xb800000
	s_addc_u32 s9, s30, 0
	s_mov_b32 s4, s8
	s_add_u32 s8, s8, 0x40000
	s_addc_u32 s9, s9, 0
	s_add_u32 s22, s8, 0x40000
	s_addc_u32 s23, s9, 0
	s_add_u32 m0, s25, 0x8000
	v_add_u32_e32 v172, 0x80000, v160
	global_load_lds_dwordx4 v160, s[22:23]
	s_add_u32 m0, s25, 0xa000
	v_add_u32_e32 v173, 0x80000, v161
	global_load_lds_dwordx4 v161, s[22:23]
	v_add_u32_e32 v174, 0x40000, v149
	v_add_u32_e32 v175, 0x40000, v176
	s_lshl_b32 s15, s28, 7
	s_and_b32 s24, s26, 0x3fffffc0
	s_lshl_b32 s24, s24, 2
	s_add_i32 s28, s24, 0x18000
	v_and_b32_e32 v183, 63, v68
	v_lshl_add_u32 v185, v159, 4, s28
	v_lshl_add_u32 v184, v148, 2, s28
	s_add_i32 s33, s11, 0x9f
	v_add_lshl_u32 v251, s11, v148, 2
	v_lshlrev_b32_e32 v252, 4, v159
	v_sub_u32_e32 v162, v252, v251
	s_add_i32 s34, s11, 0xffffff41
	s_ashr_i32 s11, s34, 6
	s_add_i32 s11, s11, 1
	s_lshl_b32 s11, s11, 6
	s_max_i32 s11, s11, 0
	s_add_i32 s31, s33, 63
	s_andn2_b32 s31, s31, 63
	s_sub_u32 s31, s31, 64
	s_lshr_b32 s10, s11, 6
	s_sub_i32 s10, s10, 2
	s_max_i32 s10, s10, 0
	s_lshl_b32 s24, s16, 3
	v_lshlrev_b32_e32 v19, 8, v148
	v_bitop3_b32 v251, s24, v34, v159 bitop3:0x36
	v_lshlrev_b32_e32 v252, 2, v159
	v_lshrrev_b32_e32 v253, 2, v34
	v_lshlrev_b32_e32 v254, 3, v68
	v_lshl_add_u32 v19, v251, 4, v19
	v_or_b32_e32 v252, v252, v253
	v_and_b32_e32 v254, 24, v254
	v_and_b32_e32 v251, 32, v35
	v_lshlrev_b32_e32 v252, 8, v252
	v_lshl_or_b32 v253, v253, 6, v254
	v_xor_b32_e32 v180, 32, v19
	v_or3_b32 v179, v252, v251, v253
	v_xor_b32_e32 v181, 64, v19
	v_xor_b32_e32 v182, 0x60, v19
	v_add_u32_e32 v228, 0xc000, v179
	v_xor_b32_e32 v229, 0x40, v179
	v_add_u32_e32 v229, 0xc000, v229
	v_xor_b32_e32 v230, 0x80, v179
	v_add_u32_e32 v230, 0xc000, v230
	v_xor_b32_e32 v231, 0xc0, v179
	v_add_u32_e32 v231, 0xc000, v231
	v_add_u32_e32 v164, 0x1d000, v19
	v_add_u32_e32 v168, 0xd000, v228
	v_add_u32_e32 v165, 0x1d000, v180
	v_add_u32_e32 v169, 0xd000, v229
	v_add_u32_e32 v166, 0x1d000, v181
	v_add_u32_e32 v170, 0xd000, v230
	v_add_u32_e32 v167, 0x1d000, v182
	v_add_u32_e32 v171, 0xd000, v231
	v_mov_b64_e32 v[20:21], 0
	v_mov_b64_e32 v[22:23], 0
	v_mov_b64_e32 v[24:25], 0
	v_mov_b64_e32 v[26:27], 0
	v_mov_b64_e32 v[28:29], 0
	v_mov_b64_e32 v[30:31], 0
	v_mov_b64_e32 v[32:33], 0
	v_mov_b64_e32 v[34:35], 0
	v_mov_b64_e32 v[36:37], 0
	v_mov_b64_e32 v[38:39], 0
	v_mov_b64_e32 v[40:41], 0
	v_mov_b64_e32 v[42:43], 0
	v_mov_b64_e32 v[44:45], 0
	v_mov_b64_e32 v[46:47], 0
	v_mov_b64_e32 v[48:49], 0
	v_mov_b64_e32 v[50:51], 0
	v_mov_b64_e32 v[52:53], 0
	v_mov_b64_e32 v[54:55], 0
	v_mov_b64_e32 v[56:57], 0
	v_mov_b64_e32 v[58:59], 0
	v_mov_b64_e32 v[60:61], 0
	v_mov_b64_e32 v[62:63], 0
	v_mov_b64_e32 v[64:65], 0
	v_mov_b64_e32 v[66:67], 0
	v_mov_b64_e32 v[68:69], 0
	v_mov_b64_e32 v[70:71], 0
	v_mov_b64_e32 v[72:73], 0
	v_mov_b64_e32 v[74:75], 0
	v_mov_b64_e32 v[76:77], 0
	v_mov_b64_e32 v[78:79], 0
	v_mov_b64_e32 v[80:81], 0
	v_mov_b64_e32 v[82:83], 0
	v_mov_b64_e32 v[150:151], 0
	v_mov_b32_e32 v186, 0
	s_waitcnt vmcnt(6) lgkmcnt(0)
	s_barrier
; __device__ __forceinline__ void attn_unit(LAS unsigned char* lds, const bf16_t* Z, bf16_t* A2, const float* tabg, int seq_base, int S, int h, int qb, float lam) {
;     ...
;     const float tabL = tab[0], tabR = tab[448];
;     f32x16 O[4];
; #pragma unroll
;     for (int d = 0; d < 4; ++d)
; #pragma unroll
;         for (int r = 0; r < 16; ++r) O[d][r] = 0.f;
;     float mu = 0.f; f32x2 ls2 = {0.f, 0.f};
;     f32x16 cblk; float coff_cur = __builtin_nanf("");
; #pragma unroll
;     for (int r = 0; r < 16; ++r) cblk[r] = 0.f;
;     const int NT = S >> 6;
;     const unsigned kfo = r32 * 256 + ((unsigned)((m * 8 + hi) ^ (r32 & 15)) << 4);
;     const unsigned vj = (i16 >> 2) & 3;
;     const unsigned vfo = (4 * hi + (i16 >> 2)) * 256 + (vj << 6) + 32 * (g4 & 1) + 8 * (i16 & 3);
;     int bc = 0, bn = 2;
;     for (int t = 0; t < NT; ++t) {
;         if (t + 2 < NT) ATT_STAGE(t + 2, bn);
;         const LAS unsigned char* Kt = Kb + bc * KT; const LAS unsigned char* Vt = Vb + bc * VT;
;         const int kv0 = t * 64;
;         bool near = true; float cc = 0.f;
;         if (kv0 - (qlo + 31) >= 128) { near = false; cc = tabR; } else if (qlo - (kv0 + 63) >= 128) { near = false; cc = tabL; }
;         { const float coff = cc - mu;
;           if (__any(!(coff == coff_cur))) { coff_cur = coff;
; #pragma unroll
;               for (int r = 0; r < 16; ++r) cblk[r] = coff;
;               asm volatile("" : "+v"(cblk)); } }
;         f32x16 p0, p1;
;         {
;             bf16x8 kf[8];
; #pragma unroll
;             for (int ds = 0; ds < 4; ++ds) { kf[2 * ds] = *(const LAS bf16x8*)(Kt + (kfo ^ (unsigned)(ds << 5))); kf[2 * ds + 1] = *(const LAS bf16x8*)(Kt + 32 * 256 + (kfo ^ (unsigned)(ds << 5))); }
;             __builtin_amdgcn_sched_barrier(0);
;             p0 = __builtin_amdgcn_mfma_f32_32x32x16_bf16(kf[0], qf[0], cblk, 0, 0, 0);
;             p1 = __builtin_amdgcn_mfma_f32_32x32x16_bf16(kf[1], qf[0], cblk, 0, 0, 0);
; #pragma unroll
;             for (int ds = 1; ds < 4; ++ds) {
;                 p0 = __builtin_amdgcn_mfma_f32_32x32x16_bf16(kf[2 * ds], qf[ds], p0, 0, 0, 0);
;                 p1 = __builtin_amdgcn_mfma_f32_32x32x16_bf16(kf[2 * ds + 1], qf[ds], p1, 0, 0, 0);
;             }
;         }
;     ...
;         const unsigned vbase = (unsigned)(size_t)Vt + vfo;
;         s16x4 va[8], vb[8];
;         VREADS1(va, 0);
;         if (near) {
	v_mov_b32_e32 v187, 0x18800
	ds_read_b32 v177, v187
	ds_read_b32 v178, v187 offset:1792
	ds_read_b128 v[132:135], v19
	ds_read_b128 v[136:139], v19 offset:8192
	ds_read_b128 v[140:143], v180
	ds_read_b128 v[144:147], v180 offset:8192
	ds_read_b128 v[220:223], v181
	ds_read_b128 v[224:227], v181 offset:8192
	ds_read_b128 v[232:235], v182
	ds_read_b128 v[236:239], v182 offset:8192
	s_waitcnt lgkmcnt(8)
	s_cmp_eq_u32 s11, 0
	s_cselect_b32 s24, 0, 1
	s_mov_b32 s35, s24
	v_mov_b32_e32 v251, 0
	s_cmp_eq_u32 s24, 1
	s_cselect_b64 vcc, -1, 0
	v_cndmask_b32_e32 v251, v251, v177, vcc
	s_cmp_eq_u32 s24, 2
	s_cselect_b64 vcc, -1, 0
	v_cndmask_b32_e32 v251, v251, v178, vcc
	v_sub_f32_e32 v2, v251, v186
	v_mov_b32_e32 v3, v2
	v_mov_b64_e32 v[4:5], v[2:3]
	v_mov_b64_e32 v[6:7], v[2:3]
	v_mov_b64_e32 v[8:9], v[2:3]
	v_mov_b64_e32 v[10:11], v[2:3]
	v_mov_b64_e32 v[12:13], v[2:3]
	v_mov_b64_e32 v[14:15], v[2:3]
	v_mov_b64_e32 v[16:17], v[2:3]
	s_waitcnt lgkmcnt(7)
	v_mfma_f32_32x32x16_bf16 v[84:99], v[132:135], v[116:119], v[2:17]
	s_waitcnt lgkmcnt(6)
	v_mfma_f32_32x32x16_bf16 v[100:115], v[136:139], v[116:119], v[2:17]
	s_waitcnt lgkmcnt(5)
	v_mfma_f32_32x32x16_bf16 v[84:99], v[140:143], v[120:123], v[84:99]
	s_waitcnt lgkmcnt(4)
	v_mfma_f32_32x32x16_bf16 v[100:115], v[144:147], v[120:123], v[100:115]
	s_waitcnt lgkmcnt(3)
	v_mfma_f32_32x32x16_bf16 v[84:99], v[220:223], v[124:127], v[84:99]
	s_waitcnt lgkmcnt(2)
	v_mfma_f32_32x32x16_bf16 v[100:115], v[224:227], v[124:127], v[100:115]
	s_waitcnt lgkmcnt(1)
	v_mfma_f32_32x32x16_bf16 v[84:99], v[232:235], v[128:131], v[84:99]
	s_waitcnt lgkmcnt(0)
	v_mfma_f32_32x32x16_bf16 v[100:115], v[236:239], v[128:131], v[100:115]
	s_nop 15
	s_nop 15
	s_mov_b32 s5, 0
	s_cmp_lg_u32 s11, 0
	s_cbranch_scc1 .LatB_p0_nonear
	s_lshl_b32 s29, s5, 2
	s_add_i32 s29, s29, 0x18b80
	v_add_u32_e32 v187, s29, v162
	ds_read2_b32 v[196:197], v187 offset0:0 offset1:1
	ds_read2_b32 v[198:199], v187 offset0:2 offset1:3
	ds_read2_b32 v[200:201], v187 offset0:8 offset1:9
	ds_read2_b32 v[202:203], v187 offset0:10 offset1:11
	ds_read2_b32 v[212:213], v187 offset0:16 offset1:17
	ds_read2_b32 v[214:215], v187 offset0:18 offset1:19
	ds_read2_b32 v[216:217], v187 offset0:24 offset1:25
	ds_read2_b32 v[218:219], v187 offset0:26 offset1:27
	s_waitcnt lgkmcnt(0)
	v_pk_add_f32 v[84:85], v[84:85], v[196:197]
	v_pk_add_f32 v[86:87], v[86:87], v[198:199]
	v_pk_add_f32 v[88:89], v[88:89], v[200:201]
	v_pk_add_f32 v[90:91], v[90:91], v[202:203]
	v_pk_add_f32 v[92:93], v[92:93], v[212:213]
	v_pk_add_f32 v[94:95], v[94:95], v[214:215]
	v_pk_add_f32 v[96:97], v[96:97], v[216:217]
	v_pk_add_f32 v[98:99], v[98:99], v[218:219]
	ds_read2_b32 v[196:197], v187 offset0:32 offset1:33
	ds_read2_b32 v[198:199], v187 offset0:34 offset1:35
	ds_read2_b32 v[200:201], v187 offset0:40 offset1:41
	ds_read2_b32 v[202:203], v187 offset0:42 offset1:43
	ds_read2_b32 v[212:213], v187 offset0:48 offset1:49
	ds_read2_b32 v[214:215], v187 offset0:50 offset1:51
	ds_read2_b32 v[216:217], v187 offset0:56 offset1:57
	ds_read2_b32 v[218:219], v187 offset0:58 offset1:59
	s_waitcnt lgkmcnt(0)
	v_pk_add_f32 v[100:101], v[100:101], v[196:197]
	v_pk_add_f32 v[102:103], v[102:103], v[198:199]
	v_pk_add_f32 v[104:105], v[104:105], v[200:201]
	v_pk_add_f32 v[106:107], v[106:107], v[202:203]
	v_pk_add_f32 v[108:109], v[108:109], v[212:213]
	v_pk_add_f32 v[110:111], v[110:111], v[214:215]
	v_pk_add_f32 v[112:113], v[112:113], v[216:217]
	v_pk_add_f32 v[114:115], v[114:115], v[218:219]

; __device__ __forceinline__ void attn_unit(LAS unsigned char* lds, const bf16_t* Z, bf16_t* A2, const float* tabg, int seq_base, int S, int h, int qb, float lam) {
;     ...
;             bf16x8 kf[8];
; #pragma unroll
;             for (int ds = 0; ds < 4; ++ds) { kf[2 * ds] = *(const LAS bf16x8*)(Kt + (kfo ^ (unsigned)(ds << 5))); kf[2 * ds + 1] = *(const LAS bf16x8*)(Kt + 32 * 256 + (kfo ^ (unsigned)(ds << 5))); }
;             __builtin_amdgcn_sched_barrier(0);
;             p0 = __builtin_amdgcn_mfma_f32_32x32x16_bf16(kf[0], qf[0], cblk, 0, 0, 0);
;             p1 = __builtin_amdgcn_mfma_f32_32x32x16_bf16(kf[1], qf[0], cblk, 0, 0, 0);
; #pragma unroll
;             for (int ds = 1; ds < 4; ++ds) {
;                 p0 = __builtin_amdgcn_mfma_f32_32x32x16_bf16(kf[2 * ds], qf[ds], p0, 0, 0, 0);
;                 p1 = __builtin_amdgcn_mfma_f32_32x32x16_bf16(kf[2 * ds + 1], qf[ds], p1, 0, 0, 0);
;             }
;         }
;     ...
;         const unsigned vbase = (unsigned)(size_t)Vt + vfo;
;         s16x4 va[8], vb[8];
;         VREADS1(va, 0);
;         if (near) {
;             const LAS float* tp = tab + (kv0 + 4 * hi - (qlo + r32) + 224);
; #pragma unroll
;             for (int r = 0; r < 16; ++r) { p0[r] += tp[(r & 3) + 8 * (r >> 2)]; p1[r] += tp[32 + (r & 3) + 8 * (r >> 2)]; }
;         }
;         float mx = max2f(max16f(p0), max16f(p1));
;         const bool first = (t == 0);
;         if (first || __any(mx > THR)) {
;             { auto rr = __builtin_amdgcn_permlane32_swap(__float_as_uint(mx), __float_as_uint(mx), false, false); mx = max2f(__uint_as_float(rr[0]), __uint_as_float(rr[1])); }
;             const float delta = first ? mx : fmaxf(mx, 0.f);
;             const float alpha = first ? 1.0f : __builtin_amdgcn_exp2f(-delta);
;             mu += delta; ls2 *= alpha;
;             if (!first) {
;                 asm volatile("" ::: "memory");
;                 scr[r32] = alpha;
;                 asm volatile("s_waitcnt lgkmcnt(0)" ::: "memory");
; #pragma unroll
;                 for (int g = 0; g < 4; ++g) { const f32x4 a4 = *(const LAS f32x4*)(scr + 8 * g + 4 * hi);
; #pragma unroll
;                     for (int d = 0; d < 4; ++d) { O[d][4 * g + 0] *= a4[0]; O[d][4 * g + 1] *= a4[1]; O[d][4 * g + 2] *= a4[2]; O[d][4 * g + 3] *= a4[3]; } }
;                 asm volatile("s_waitcnt lgkmcnt(0)" ::: "memory");
;             }
; #pragma unroll
.LatB_rareret_h0:
	s_waitcnt lgkmcnt(6)
	s_add_u32 m0, s25, 0x1d000
	v_mfma_f32_32x32x16_bf16 v[188:203], v[132:135], v[116:119], v[2:17]
	global_load_lds_dwordx4 v172, s[8:9]
	ds_read_b128 v[236:239], v182 offset:24576
	v_exp_f32_e32 v84, v84
	v_exp_f32_e32 v85, v85
	v_exp_f32_e32 v86, v86
	v_exp_f32_e32 v87, v87
	v_pk_add_f32 v[150:151], v[150:151], v[84:85]
	v_pk_add_f32 v[150:151], v[150:151], v[86:87]
	v_exp_f32_e32 v88, v88
	s_waitcnt lgkmcnt(6)
	s_add_u32 m0, s27, 0x8000
	v_mfma_f32_32x32x16_bf16 v[204:219], v[136:139], v[116:119], v[2:17]
	global_load_lds_dwordx4 v174, s[8:9]
	ds_read_b64_tr_b16 v[132:133], v228 offset:0
	ds_read_b64_tr_b16 v[134:135], v228 offset:2048
	v_exp_f32_e32 v89, v89
	v_cvt_pk_bf16_f32 v84, v84, v85
	v_cvt_pk_bf16_f32 v85, v86, v87
	v_exp_f32_e32 v90, v90
	v_exp_f32_e32 v91, v91
	v_pk_add_f32 v[150:151], v[150:151], v[88:89]
	v_pk_add_f32 v[150:151], v[150:151], v[90:91]
	v_cvt_pk_bf16_f32 v86, v88, v89
	v_cvt_pk_bf16_f32 v87, v90, v91
	s_waitcnt lgkmcnt(7)
	s_add_u32 m0, s25, 0x1f000
	v_mfma_f32_32x32x16_bf16 v[188:203], v[140:143], v[120:123], v[188:203]
	global_load_lds_dwordx4 v173, s[8:9]
	ds_read_b64_tr_b16 v[136:137], v229 offset:0
	ds_read_b64_tr_b16 v[138:139], v229 offset:2048
	v_exp_f32_e32 v92, v92
	v_exp_f32_e32 v93, v93
	v_exp_f32_e32 v94, v94
	v_exp_f32_e32 v95, v95
	v_pk_add_f32 v[150:151], v[150:151], v[92:93]
	v_pk_add_f32 v[150:151], v[150:151], v[94:95]
	v_exp_f32_e32 v96, v96
	s_waitcnt lgkmcnt(8)
	s_add_u32 m0, s27, 0xa000
	v_mfma_f32_32x32x16_bf16 v[204:219], v[144:147], v[120:123], v[204:219]
	global_load_lds_dwordx4 v175, s[8:9]
	ds_read_b64_tr_b16 v[140:141], v230 offset:0
	ds_read_b64_tr_b16 v[142:143], v230 offset:2048
	v_exp_f32_e32 v97, v97
	v_cvt_pk_bf16_f32 v88, v92, v93
	v_cvt_pk_bf16_f32 v89, v94, v95
	v_exp_f32_e32 v98, v98
	v_exp_f32_e32 v99, v99
	v_pk_add_f32 v[150:151], v[150:151], v[96:97]
	v_pk_add_f32 v[150:151], v[150:151], v[98:99]
	v_cvt_pk_bf16_f32 v90, v96, v97
	v_cvt_pk_bf16_f32 v91, v98, v99
	s_waitcnt lgkmcnt(9)
	v_mfma_f32_32x32x16_bf16 v[188:203], v[220:223], v[124:127], v[188:203]
	ds_read_b64_tr_b16 v[144:145], v231 offset:0
	ds_read_b64_tr_b16 v[146:147], v231 offset:2048
	v_exp_f32_e32 v100, v100
	v_exp_f32_e32 v101, v101
	v_exp_f32_e32 v102, v102
	v_exp_f32_e32 v103, v103
	v_pk_add_f32 v[150:151], v[150:151], v[100:101]
	v_pk_add_f32 v[150:151], v[150:151], v[102:103]
	v_exp_f32_e32 v104, v104
	s_waitcnt lgkmcnt(10)
	v_mfma_f32_32x32x16_bf16 v[204:219], v[224:227], v[124:127], v[204:219]
	ds_read_b64_tr_b16 v[220:221], v228 offset:4096
	ds_read_b64_tr_b16 v[222:223], v228 offset:6144
	v_exp_f32_e32 v105, v105
	v_cvt_pk_bf16_f32 v100, v100, v101
	v_cvt_pk_bf16_f32 v101, v102, v103
	v_exp_f32_e32 v106, v106
	v_exp_f32_e32 v107, v107
	v_pk_add_f32 v[150:151], v[150:151], v[104:105]
	v_pk_add_f32 v[150:151], v[150:151], v[106:107]
	v_cvt_pk_bf16_f32 v102, v104, v105
	v_cvt_pk_bf16_f32 v103, v106, v107
	s_waitcnt lgkmcnt(11)
	v_mfma_f32_32x32x16_bf16 v[188:203], v[232:235], v[128:131], v[188:203]
	ds_read_b64_tr_b16 v[224:225], v229 offset:4096
	ds_read_b64_tr_b16 v[226:227], v229 offset:6144
	v_exp_f32_e32 v108, v108
	v_exp_f32_e32 v109, v109
	v_exp_f32_e32 v110, v110
	v_exp_f32_e32 v111, v111
	v_pk_add_f32 v[150:151], v[150:151], v[108:109]
	v_pk_add_f32 v[150:151], v[150:151], v[110:111]
	v_exp_f32_e32 v112, v112
	s_waitcnt lgkmcnt(12)
	v_mfma_f32_32x32x16_bf16 v[204:219], v[236:239], v[128:131], v[204:219]
	ds_read_b64_tr_b16 v[232:233], v230 offset:4096
	ds_read_b64_tr_b16 v[234:235], v230 offset:6144
	v_exp_f32_e32 v113, v113
	v_cvt_pk_bf16_f32 v104, v108, v109
	v_cvt_pk_bf16_f32 v105, v110, v111
	v_exp_f32_e32 v114, v114
	v_exp_f32_e32 v115, v115
	v_pk_add_f32 v[150:151], v[150:151], v[112:113]
	v_pk_add_f32 v[150:151], v[150:151], v[114:115]
	v_cvt_pk_bf16_f32 v106, v112, v113
	v_cvt_pk_bf16_f32 v107, v114, v115
	s_add_u32 s8, s8, 0x40000
	s_addc_u32 s9, s9, 0
	s_waitcnt vmcnt(4)
	s_barrier
	s_sub_u32 s10, s10, 1
	s_cbranch_scc1 .LatB_evs_h1
.LatB_evret_h1:
	s_waitcnt lgkmcnt(12)
	v_mfma_f32_32x32x16_bf16 v[20:35], v[84:87], v[132:135], v[20:35]
	ds_read_b64_tr_b16 v[236:237], v231 offset:4096
	ds_read_b64_tr_b16 v[238:239], v231 offset:6144
	s_waitcnt lgkmcnt(12)
	v_mfma_f32_32x32x16_bf16 v[36:51], v[84:87], v[136:139], v[36:51]
	ds_read_b64_tr_b16 v[132:133], v228 offset:8192
	ds_read_b64_tr_b16 v[134:135], v228 offset:10240
	s_waitcnt lgkmcnt(12)
	v_mfma_f32_32x32x16_bf16 v[52:67], v[84:87], v[140:143], v[52:67]
	ds_read_b64_tr_b16 v[136:137], v229 offset:8192
	ds_read_b64_tr_b16 v[138:139], v229 offset:10240
	s_waitcnt lgkmcnt(12)
	s_mov_b32 m0, s25
	v_mfma_f32_32x32x16_bf16 v[68:83], v[84:87], v[144:147], v[68:83]
	global_load_lds_dwordx4 v172, s[8:9]
	ds_read_b64_tr_b16 v[140:141], v230 offset:8192
	ds_read_b64_tr_b16 v[142:143], v230 offset:10240
	v_max3_f32 v251, v188, v189, v190
	v_max3_f32 v252, v191, v192, v193
	v_max3_f32 v251, v251, v194, v195
	v_max3_f32 v252, v252, v196, v197
	v_max3_f32 v251, v251, v198, v199
	v_max3_f32 v252, v252, v200, v201
	v_max3_f32 v251, v251, v202, v203
	v_max3_f32 v252, v252, v204, v205
	v_max3_f32 v251, v251, v206, v207
	v_max3_f32 v252, v252, v208, v209
	v_max3_f32 v251, v251, v210, v211
	v_max3_f32 v252, v252, v212, v213
	v_max3_f32 v251, v251, v214, v215
	v_max3_f32 v252, v252, v216, v217
	v_max3_f32 v251, v251, v218, v219
	v_max_f32_e32 v251, v251, v252
	v_cmp_lt_f32_e32 vcc, 0x41000000, v251
	s_cbranch_vccnz .LatB_rs_h1
; #define LAS __attribute__((address_space(3)))
; #define VREADS1(arr, d_) do { const unsigned ad_ = vbase ^ (unsigned)((d_) << 6); __builtin_amdgcn_sched_barrier(0); \
;         _Pragma("unroll") for (int ks_ = 0; ks_ < 4; ++ks_) { VTR(arr[ks_ * 2], ad_, ks_ * 4096); VTR(arr[ks_ * 2 + 1], ad_, ks_ * 4096 + 2048); } __builtin_amdgcn_sched_barrier(0); } while (0)
; #define PV1(arr, d_) do { _Pragma("unroll") for (int ks_ = 0; ks_ < 4; ++ks_) { const s16x4 lo_ = arr[ks_ * 2], hh_ = arr[ks_ * 2 + 1]; \
;         const bf16x8 bv_ = (bf16x8){lo_[0], lo_[1], lo_[2], lo_[3], hh_[0], hh_[1], hh_[2], hh_[3]}; \
;         O[d_] = __builtin_amdgcn_mfma_f32_32x32x16_bf16(pa[ks_], bv_, O[d_], 0, 0, 0); } __builtin_amdgcn_sched_barrier(0); } while (0)
; __device__ __forceinline__ void attn_unit(LAS unsigned char* lds, const bf16_t* Z, bf16_t* A2, const float* tabg, int seq_base, int S, int h, int qb, float lam) {
;     ...
;             for (int ds = 0; ds < 4; ++ds) { kf[2 * ds] = *(const LAS bf16x8*)(Kt + (kfo ^ (unsigned)(ds << 5))); kf[2 * ds + 1] = *(const LAS bf16x8*)(Kt + 32 * 256 + (kfo ^ (unsigned)(ds << 5))); }
;             __builtin_amdgcn_sched_barrier(0);
;             p0 = __builtin_amdgcn_mfma_f32_32x32x16_bf16(kf[0], qf[0], cblk, 0, 0, 0);
;             p1 = __builtin_amdgcn_mfma_f32_32x32x16_bf16(kf[1], qf[0], cblk, 0, 0, 0);
; #pragma unroll
;             for (int ds = 1; ds < 4; ++ds) {
;                 p0 = __builtin_amdgcn_mfma_f32_32x32x16_bf16(kf[2 * ds], qf[ds], p0, 0, 0, 0);
;                 p1 = __builtin_amdgcn_mfma_f32_32x32x16_bf16(kf[2 * ds + 1], qf[ds], p1, 0, 0, 0);
;             }
;     ...
; #pragma unroll
;         for (int r = 0; r < 16; ++r) { p0[r] = __builtin_amdgcn_exp2f(p0[r]); p1[r] = __builtin_amdgcn_exp2f(p1[r]); }
; #pragma unroll
;         for (int r = 0; r < 16; r += 2) { ls2 += (f32x2){p0[r], p0[r + 1]}; ls2 += (f32x2){p1[r], p1[r + 1]}; }
;         bf16x8 pa[4]; pa[0] = pack8(p0, 0); pa[1] = pack8(p0, 8); pa[2] = pack8(p1, 0); pa[3] = pack8(p1, 8);
;         LGKM0(); VREADS1(vb, 1); PV1(va, 0); LGKM0(); VREADS1(va, 2); PV1(vb, 1); LGKM0(); VREADS1(vb, 3); PV1(va, 2); LGKM0(); PV1(vb, 3);
;     ...
;         if (t + 2 < NT) asm volatile("s_waitcnt vmcnt(4) lgkmcnt(0)" ::: "memory"); else asm volatile("s_waitcnt vmcnt(0) lgkmcnt(0)" ::: "memory");
;         __builtin_amdgcn_s_barrier(); asm volatile("" ::: "memory");
.LatB_rareret_h1:
	s_waitcnt lgkmcnt(12)
	v_mfma_f32_32x32x16_bf16 v[20:35], v[88:91], v[220:223], v[20:35]
	ds_read_b64_tr_b16 v[144:145], v231 offset:8192
	ds_read_b64_tr_b16 v[146:147], v231 offset:10240
	v_exp_f32_e32 v188, v188
	v_exp_f32_e32 v189, v189
	v_exp_f32_e32 v190, v190
	s_waitcnt lgkmcnt(12)
	v_mfma_f32_32x32x16_bf16 v[36:51], v[88:91], v[224:227], v[36:51]
	ds_read_b64_tr_b16 v[220:221], v228 offset:12288
	ds_read_b64_tr_b16 v[222:223], v228 offset:14336
	v_exp_f32_e32 v191, v191
	v_pk_add_f32 v[150:151], v[150:151], v[188:189]
	s_waitcnt lgkmcnt(12)
	v_mfma_f32_32x32x16_bf16 v[52:67], v[88:91], v[232:235], v[52:67]
	ds_read_b64_tr_b16 v[224:225], v229 offset:12288
	ds_read_b64_tr_b16 v[226:227], v229 offset:14336
	v_pk_add_f32 v[150:151], v[150:151], v[190:191]
	v_exp_f32_e32 v192, v192
	v_exp_f32_e32 v193, v193
	v_cvt_pk_bf16_f32 v188, v188, v189
	s_waitcnt lgkmcnt(12)
	s_add_u32 m0, s27, 0xd000
	v_mfma_f32_32x32x16_bf16 v[68:83], v[88:91], v[236:239], v[68:83]
	global_load_lds_dwordx4 v174, s[8:9]
	ds_read_b64_tr_b16 v[232:233], v230 offset:12288
	ds_read_b64_tr_b16 v[234:235], v230 offset:14336
	v_cvt_pk_bf16_f32 v189, v190, v191
	v_exp_f32_e32 v194, v194
	v_exp_f32_e32 v195, v195
	s_waitcnt lgkmcnt(12)
	v_mfma_f32_32x32x16_bf16 v[20:35], v[100:103], v[132:135], v[20:35]
	ds_read_b64_tr_b16 v[236:237], v231 offset:12288
	ds_read_b64_tr_b16 v[238:239], v231 offset:14336
	v_pk_add_f32 v[150:151], v[150:151], v[192:193]
	v_pk_add_f32 v[150:151], v[150:151], v[194:195]
	v_cvt_pk_bf16_f32 v190, v192, v193
	v_cvt_pk_bf16_f32 v191, v194, v195
	s_waitcnt lgkmcnt(12)
	v_mfma_f32_32x32x16_bf16 v[36:51], v[100:103], v[136:139], v[36:51]
	ds_read_b128 v[132:135], v19 offset:32768
	v_exp_f32_e32 v196, v196
	v_exp_f32_e32 v197, v197
	v_exp_f32_e32 v198, v198
	s_waitcnt lgkmcnt(11)
	v_mfma_f32_32x32x16_bf16 v[52:67], v[100:103], v[140:143], v[52:67]
	ds_read_b128 v[136:139], v19 offset:40960
	v_exp_f32_e32 v199, v199
	v_pk_add_f32 v[150:151], v[150:151], v[196:197]
	s_waitcnt lgkmcnt(10)
	s_add_u32 m0, s25, 0x2000
	v_mfma_f32_32x32x16_bf16 v[68:83], v[100:103], v[144:147], v[68:83]
	global_load_lds_dwordx4 v173, s[8:9]
	ds_read_b128 v[140:143], v180 offset:32768
	v_pk_add_f32 v[150:151], v[150:151], v[198:199]
	v_exp_f32_e32 v200, v200
	v_exp_f32_e32 v201, v201
	v_cvt_pk_bf16_f32 v192, v196, v197
	s_waitcnt lgkmcnt(9)
	v_mfma_f32_32x32x16_bf16 v[20:35], v[104:107], v[220:223], v[20:35]
	ds_read_b128 v[144:147], v180 offset:40960
	v_cvt_pk_bf16_f32 v193, v198, v199
	v_exp_f32_e32 v202, v202
	v_exp_f32_e32 v203, v203
	s_waitcnt lgkmcnt(8)
	v_mfma_f32_32x32x16_bf16 v[36:51], v[104:107], v[224:227], v[36:51]
	ds_read_b128 v[220:223], v181 offset:32768
	v_pk_add_f32 v[150:151], v[150:151], v[200:201]
	v_pk_add_f32 v[150:151], v[150:151], v[202:203]
	v_cvt_pk_bf16_f32 v194, v200, v201
	v_cvt_pk_bf16_f32 v195, v202, v203
	s_waitcnt lgkmcnt(7)
	v_mfma_f32_32x32x16_bf16 v[52:67], v[104:107], v[232:235], v[52:67]
	ds_read_b128 v[224:227], v181 offset:40960
	v_exp_f32_e32 v204, v204
	v_exp_f32_e32 v205, v205
	v_exp_f32_e32 v206, v206
	s_waitcnt lgkmcnt(6)
	s_add_u32 m0, s27, 0xf000
	v_mfma_f32_32x32x16_bf16 v[68:83], v[104:107], v[236:239], v[68:83]
	global_load_lds_dwordx4 v175, s[8:9]
	ds_read_b128 v[232:235], v182 offset:32768
	v_exp_f32_e32 v207, v207
	v_pk_add_f32 v[150:151], v[150:151], v[204:205]
	s_waitcnt lgkmcnt(6)
	v_mfma_f32_32x32x16_bf16 v[84:99], v[132:135], v[116:119], v[2:17]
	ds_read_b128 v[236:239], v182 offset:40960
	v_pk_add_f32 v[150:151], v[150:151], v[206:207]
	v_exp_f32_e32 v208, v208
	v_exp_f32_e32 v209, v209
	v_cvt_pk_bf16_f32 v204, v204, v205
	s_waitcnt lgkmcnt(6)
	v_mfma_f32_32x32x16_bf16 v[100:115], v[136:139], v[116:119], v[2:17]
	ds_read_b64_tr_b16 v[132:133], v228 offset:16384
	ds_read_b64_tr_b16 v[134:135], v228 offset:18432
	v_cvt_pk_bf16_f32 v205, v206, v207
	v_exp_f32_e32 v210, v210
	v_exp_f32_e32 v211, v211
	s_waitcnt lgkmcnt(7)
	v_mfma_f32_32x32x16_bf16 v[84:99], v[140:143], v[120:123], v[84:99]
	ds_read_b64_tr_b16 v[136:137], v229 offset:16384
	ds_read_b64_tr_b16 v[138:139], v229 offset:18432
	v_pk_add_f32 v[150:151], v[150:151], v[208:209]
	v_pk_add_f32 v[150:151], v[150:151], v[210:211]
	v_cvt_pk_bf16_f32 v206, v208, v209
	v_cvt_pk_bf16_f32 v207, v210, v211
	s_waitcnt lgkmcnt(8)
	v_mfma_f32_32x32x16_bf16 v[100:115], v[144:147], v[120:123], v[100:115]
	ds_read_b64_tr_b16 v[140:141], v230 offset:16384
	ds_read_b64_tr_b16 v[142:143], v230 offset:18432
	v_exp_f32_e32 v212, v212
	v_exp_f32_e32 v213, v213
	v_exp_f32_e32 v214, v214
	s_waitcnt lgkmcnt(9)
	v_mfma_f32_32x32x16_bf16 v[84:99], v[220:223], v[124:127], v[84:99]
	ds_read_b64_tr_b16 v[144:145], v231 offset:16384
	ds_read_b64_tr_b16 v[146:147], v231 offset:18432
	v_exp_f32_e32 v215, v215
	v_pk_add_f32 v[150:151], v[150:151], v[212:213]
	s_waitcnt lgkmcnt(10)
	v_mfma_f32_32x32x16_bf16 v[100:115], v[224:227], v[124:127], v[100:115]
	ds_read_b64_tr_b16 v[220:221], v228 offset:20480
	ds_read_b64_tr_b16 v[222:223], v228 offset:22528
	v_pk_add_f32 v[150:151], v[150:151], v[214:215]
	v_exp_f32_e32 v216, v216
	v_exp_f32_e32 v217, v217
	v_cvt_pk_bf16_f32 v208, v212, v213
	s_waitcnt lgkmcnt(11)
	v_mfma_f32_32x32x16_bf16 v[84:99], v[232:235], v[128:131], v[84:99]
	ds_read_b64_tr_b16 v[224:225], v229 offset:20480
	ds_read_b64_tr_b16 v[226:227], v229 offset:22528
	v_cvt_pk_bf16_f32 v209, v214, v215
	v_exp_f32_e32 v218, v218
	v_exp_f32_e32 v219, v219
	s_waitcnt lgkmcnt(12)
	v_mfma_f32_32x32x16_bf16 v[100:115], v[236:239], v[128:131], v[100:115]
	ds_read_b64_tr_b16 v[232:233], v230 offset:20480
	ds_read_b64_tr_b16 v[234:235], v230 offset:22528
	v_pk_add_f32 v[150:151], v[150:151], v[216:217]
	v_pk_add_f32 v[150:151], v[150:151], v[218:219]
	v_cvt_pk_bf16_f32 v210, v216, v217
	v_cvt_pk_bf16_f32 v211, v218, v219
	s_add_u32 s8, s8, 0x40000
	s_addc_u32 s9, s9, 0
	s_waitcnt vmcnt(4)
	s_barrier
	s_sub_u32 s10, s10, 1
	s_cbranch_scc1 .LatB_evs_h2
; #define LAS __attribute__((address_space(3)))
; __device__ __forceinline__ float max2f(float a, float b) { float r; asm("v_max_f32_e32 %0, %1, %2" : "=v"(r) : "v"(a), "v"(b)); return r; }
; #define VREADS1(arr, d_) do { const unsigned ad_ = vbase ^ (unsigned)((d_) << 6); __builtin_amdgcn_sched_barrier(0); \
;         _Pragma("unroll") for (int ks_ = 0; ks_ < 4; ++ks_) { VTR(arr[ks_ * 2], ad_, ks_ * 4096); VTR(arr[ks_ * 2 + 1], ad_, ks_ * 4096 + 2048); } __builtin_amdgcn_sched_barrier(0); } while (0)
; #define PV1(arr, d_) do { _Pragma("unroll") for (int ks_ = 0; ks_ < 4; ++ks_) { const s16x4 lo_ = arr[ks_ * 2], hh_ = arr[ks_ * 2 + 1]; \
;         const bf16x8 bv_ = (bf16x8){lo_[0], lo_[1], lo_[2], lo_[3], hh_[0], hh_[1], hh_[2], hh_[3]}; \
;         O[d_] = __builtin_amdgcn_mfma_f32_32x32x16_bf16(pa[ks_], bv_, O[d_], 0, 0, 0); } __builtin_amdgcn_sched_barrier(0); } while (0)
; __device__ __forceinline__ void attn_unit(LAS unsigned char* lds, const bf16_t* Z, bf16_t* A2, const float* tabg, int seq_base, int S, int h, int qb, float lam) {
;     ...
;         const unsigned vbase = (unsigned)(size_t)Vt + vfo;
;         s16x4 va[8], vb[8];
;         VREADS1(va, 0);
;         if (near) {
;             const LAS float* tp = tab + (kv0 + 4 * hi - (qlo + r32) + 224);
; #pragma unroll
;             for (int r = 0; r < 16; ++r) { p0[r] += tp[(r & 3) + 8 * (r >> 2)]; p1[r] += tp[32 + (r & 3) + 8 * (r >> 2)]; }
;         }
;         float mx = max2f(max16f(p0), max16f(p1));
;         const bool first = (t == 0);
;         if (first || __any(mx > THR)) {
;     ...
; #pragma unroll
;         for (int r = 0; r < 16; ++r) { p0[r] = __builtin_amdgcn_exp2f(p0[r]); p1[r] = __builtin_amdgcn_exp2f(p1[r]); }
; #pragma unroll
;         for (int r = 0; r < 16; r += 2) { ls2 += (f32x2){p0[r], p0[r + 1]}; ls2 += (f32x2){p1[r], p1[r + 1]}; }
;         bf16x8 pa[4]; pa[0] = pack8(p0, 0); pa[1] = pack8(p0, 8); pa[2] = pack8(p1, 0); pa[3] = pack8(p1, 8);
;         LGKM0(); VREADS1(vb, 1); PV1(va, 0); LGKM0(); VREADS1(va, 2); PV1(vb, 1); LGKM0(); VREADS1(vb, 3); PV1(va, 2); LGKM0(); PV1(vb, 3);
;     ...
;         if (t + 2 < NT) asm volatile("s_waitcnt vmcnt(4) lgkmcnt(0)" ::: "memory"); else asm volatile("s_waitcnt vmcnt(0) lgkmcnt(0)" ::: "memory");
;         __builtin_amdgcn_s_barrier(); asm volatile("" ::: "memory");
.LatB_evret_h2:
	s_waitcnt lgkmcnt(12)
	v_mfma_f32_32x32x16_bf16 v[20:35], v[188:191], v[132:135], v[20:35]
	ds_read_b64_tr_b16 v[236:237], v231 offset:20480
	ds_read_b64_tr_b16 v[238:239], v231 offset:22528
	s_waitcnt lgkmcnt(12)
	v_mfma_f32_32x32x16_bf16 v[36:51], v[188:191], v[136:139], v[36:51]
	ds_read_b64_tr_b16 v[132:133], v228 offset:24576
	ds_read_b64_tr_b16 v[134:135], v228 offset:26624
	s_waitcnt lgkmcnt(12)
	v_mfma_f32_32x32x16_bf16 v[52:67], v[188:191], v[140:143], v[52:67]
	ds_read_b64_tr_b16 v[136:137], v229 offset:24576
	ds_read_b64_tr_b16 v[138:139], v229 offset:26624
	s_waitcnt lgkmcnt(12)
	s_add_u32 m0, s25, 0x4000
	v_mfma_f32_32x32x16_bf16 v[68:83], v[188:191], v[144:147], v[68:83]
	global_load_lds_dwordx4 v172, s[8:9]
	ds_read_b64_tr_b16 v[140:141], v230 offset:24576
	ds_read_b64_tr_b16 v[142:143], v230 offset:26624
	v_max3_f32 v251, v84, v85, v86
	v_max3_f32 v252, v87, v88, v89
	v_max3_f32 v251, v251, v90, v91
	v_max3_f32 v252, v252, v92, v93
	v_max3_f32 v251, v251, v94, v95
	v_max3_f32 v252, v252, v96, v97
	v_max3_f32 v251, v251, v98, v99
	v_max3_f32 v252, v252, v100, v101
	v_max3_f32 v251, v251, v102, v103
	v_max3_f32 v252, v252, v104, v105
	v_max3_f32 v251, v251, v106, v107
	v_max3_f32 v252, v252, v108, v109
	v_max3_f32 v251, v251, v110, v111
	v_max3_f32 v252, v252, v112, v113
	v_max3_f32 v251, v251, v114, v115
	v_max_f32_e32 v251, v251, v252
	v_cmp_lt_f32_e32 vcc, 0x41000000, v251
	s_cbranch_vccnz .LatB_rs_h2
.LatB_rareret_h2:
	s_waitcnt lgkmcnt(12)
	v_mfma_f32_32x32x16_bf16 v[20:35], v[192:195], v[220:223], v[20:35]
	ds_read_b64_tr_b16 v[144:145], v231 offset:24576
	ds_read_b64_tr_b16 v[146:147], v231 offset:26624
	v_exp_f32_e32 v84, v84
	v_exp_f32_e32 v85, v85
	v_exp_f32_e32 v86, v86
	s_waitcnt lgkmcnt(12)
	v_mfma_f32_32x32x16_bf16 v[36:51], v[192:195], v[224:227], v[36:51]
	ds_read_b64_tr_b16 v[220:221], v228 offset:28672
	ds_read_b64_tr_b16 v[222:223], v228 offset:30720
	v_exp_f32_e32 v87, v87
	v_pk_add_f32 v[150:151], v[150:151], v[84:85]
	s_waitcnt lgkmcnt(12)
	v_mfma_f32_32x32x16_bf16 v[52:67], v[192:195], v[232:235], v[52:67]
	ds_read_b64_tr_b16 v[224:225], v229 offset:28672
	ds_read_b64_tr_b16 v[226:227], v229 offset:30720
	v_pk_add_f32 v[150:151], v[150:151], v[86:87]
	v_exp_f32_e32 v88, v88
	v_exp_f32_e32 v89, v89
	v_cvt_pk_bf16_f32 v84, v84, v85
	s_waitcnt lgkmcnt(12)
	s_mov_b32 m0, s27
	v_mfma_f32_32x32x16_bf16 v[68:83], v[192:195], v[236:239], v[68:83]
	global_load_lds_dwordx4 v174, s[8:9]
	ds_read_b64_tr_b16 v[232:233], v230 offset:28672
	ds_read_b64_tr_b16 v[234:235], v230 offset:30720
	v_cvt_pk_bf16_f32 v85, v86, v87
	v_exp_f32_e32 v90, v90
	v_exp_f32_e32 v91, v91
	s_waitcnt lgkmcnt(12)
	v_mfma_f32_32x32x16_bf16 v[20:35], v[204:207], v[132:135], v[20:35]
	ds_read_b64_tr_b16 v[236:237], v231 offset:28672
	ds_read_b64_tr_b16 v[238:239], v231 offset:30720
	v_pk_add_f32 v[150:151], v[150:151], v[88:89]
	v_pk_add_f32 v[150:151], v[150:151], v[90:91]
	v_cvt_pk_bf16_f32 v86, v88, v89
	v_cvt_pk_bf16_f32 v87, v90, v91
	s_waitcnt lgkmcnt(12)
	v_mfma_f32_32x32x16_bf16 v[36:51], v[204:207], v[136:139], v[36:51]
	ds_read_b128 v[132:135], v164
	v_exp_f32_e32 v92, v92
	v_exp_f32_e32 v93, v93
	v_exp_f32_e32 v94, v94
	s_waitcnt lgkmcnt(11)
	v_mfma_f32_32x32x16_bf16 v[52:67], v[204:207], v[140:143], v[52:67]
	ds_read_b128 v[136:139], v164 offset:8192
	v_exp_f32_e32 v95, v95
	v_pk_add_f32 v[150:151], v[150:151], v[92:93]
	s_waitcnt lgkmcnt(10)
	s_add_u32 m0, s25, 0x6000
	v_mfma_f32_32x32x16_bf16 v[68:83], v[204:207], v[144:147], v[68:83]
	global_load_lds_dwordx4 v173, s[8:9]
	ds_read_b128 v[140:143], v165
	v_pk_add_f32 v[150:151], v[150:151], v[94:95]
	v_exp_f32_e32 v96, v96
	v_exp_f32_e32 v97, v97
	v_cvt_pk_bf16_f32 v88, v92, v93
	s_waitcnt lgkmcnt(9)
	v_mfma_f32_32x32x16_bf16 v[20:35], v[208:211], v[220:223], v[20:35]
	ds_read_b128 v[144:147], v165 offset:8192
	v_cvt_pk_bf16_f32 v89, v94, v95
	v_exp_f32_e32 v98, v98
	v_exp_f32_e32 v99, v99
	s_waitcnt lgkmcnt(8)
	v_mfma_f32_32x32x16_bf16 v[36:51], v[208:211], v[224:227], v[36:51]
	ds_read_b128 v[220:223], v166
	v_pk_add_f32 v[150:151], v[150:151], v[96:97]
	v_pk_add_f32 v[150:151], v[150:151], v[98:99]
	v_cvt_pk_bf16_f32 v90, v96, v97
	v_cvt_pk_bf16_f32 v91, v98, v99
	s_waitcnt lgkmcnt(7)
	v_mfma_f32_32x32x16_bf16 v[52:67], v[208:211], v[232:235], v[52:67]
	ds_read_b128 v[224:227], v166 offset:8192
	v_exp_f32_e32 v100, v100
	v_exp_f32_e32 v101, v101
	v_exp_f32_e32 v102, v102
	s_waitcnt lgkmcnt(6)
	s_add_u32 m0, s27, 0x2000
	v_mfma_f32_32x32x16_bf16 v[68:83], v[208:211], v[236:239], v[68:83]
	global_load_lds_dwordx4 v175, s[8:9]
	ds_read_b128 v[232:235], v167
	v_exp_f32_e32 v103, v103
	v_pk_add_f32 v[150:151], v[150:151], v[100:101]
	s_waitcnt lgkmcnt(6)
	v_mfma_f32_32x32x16_bf16 v[188:203], v[132:135], v[116:119], v[2:17]
	ds_read_b128 v[236:239], v167 offset:8192
	v_pk_add_f32 v[150:151], v[150:151], v[102:103]
	v_exp_f32_e32 v104, v104
	v_exp_f32_e32 v105, v105
	v_cvt_pk_bf16_f32 v100, v100, v101
	s_waitcnt lgkmcnt(6)
	v_mfma_f32_32x32x16_bf16 v[204:219], v[136:139], v[116:119], v[2:17]
	ds_read_b64_tr_b16 v[132:133], v228 offset:32768
	ds_read_b64_tr_b16 v[134:135], v228 offset:34816
	v_cvt_pk_bf16_f32 v101, v102, v103
	v_exp_f32_e32 v106, v106
	v_exp_f32_e32 v107, v107
	s_waitcnt lgkmcnt(7)
	v_mfma_f32_32x32x16_bf16 v[188:203], v[140:143], v[120:123], v[188:203]
	ds_read_b64_tr_b16 v[136:137], v229 offset:32768
	ds_read_b64_tr_b16 v[138:139], v229 offset:34816
	v_pk_add_f32 v[150:151], v[150:151], v[104:105]
	v_pk_add_f32 v[150:151], v[150:151], v[106:107]
	v_cvt_pk_bf16_f32 v102, v104, v105
	v_cvt_pk_bf16_f32 v103, v106, v107
	s_waitcnt lgkmcnt(8)
; #define LAS __attribute__((address_space(3)))
; __device__ __forceinline__ float max2f(float a, float b) { float r; asm("v_max_f32_e32 %0, %1, %2" : "=v"(r) : "v"(a), "v"(b)); return r; }
; #define VREADS1(arr, d_) do { const unsigned ad_ = vbase ^ (unsigned)((d_) << 6); __builtin_amdgcn_sched_barrier(0); \
;         _Pragma("unroll") for (int ks_ = 0; ks_ < 4; ++ks_) { VTR(arr[ks_ * 2], ad_, ks_ * 4096); VTR(arr[ks_ * 2 + 1], ad_, ks_ * 4096 + 2048); } __builtin_amdgcn_sched_barrier(0); } while (0)
; #define PV1(arr, d_) do { _Pragma("unroll") for (int ks_ = 0; ks_ < 4; ++ks_) { const s16x4 lo_ = arr[ks_ * 2], hh_ = arr[ks_ * 2 + 1]; \
;         const bf16x8 bv_ = (bf16x8){lo_[0], lo_[1], lo_[2], lo_[3], hh_[0], hh_[1], hh_[2], hh_[3]}; \
;         O[d_] = __builtin_amdgcn_mfma_f32_32x32x16_bf16(pa[ks_], bv_, O[d_], 0, 0, 0); } __builtin_amdgcn_sched_barrier(0); } while (0)
; __device__ __forceinline__ void attn_unit(LAS unsigned char* lds, const bf16_t* Z, bf16_t* A2, const float* tabg, int seq_base, int S, int h, int qb, float lam) {
;     ...
;         const unsigned vbase = (unsigned)(size_t)Vt + vfo;
;         s16x4 va[8], vb[8];
;         VREADS1(va, 0);
;         if (near) {
;             const LAS float* tp = tab + (kv0 + 4 * hi - (qlo + r32) + 224);
; #pragma unroll
;             for (int r = 0; r < 16; ++r) { p0[r] += tp[(r & 3) + 8 * (r >> 2)]; p1[r] += tp[32 + (r & 3) + 8 * (r >> 2)]; }
;         }
;         float mx = max2f(max16f(p0), max16f(p1));
;         const bool first = (t == 0);
;         if (first || __any(mx > THR)) {
;     ...
; #pragma unroll
;         for (int r = 0; r < 16; ++r) { p0[r] = __builtin_amdgcn_exp2f(p0[r]); p1[r] = __builtin_amdgcn_exp2f(p1[r]); }
; #pragma unroll
;         for (int r = 0; r < 16; r += 2) { ls2 += (f32x2){p0[r], p0[r + 1]}; ls2 += (f32x2){p1[r], p1[r + 1]}; }
;         bf16x8 pa[4]; pa[0] = pack8(p0, 0); pa[1] = pack8(p0, 8); pa[2] = pack8(p1, 0); pa[3] = pack8(p1, 8);
;         LGKM0(); VREADS1(vb, 1); PV1(va, 0); LGKM0(); VREADS1(va, 2); PV1(vb, 1); LGKM0(); VREADS1(vb, 3); PV1(va, 2); LGKM0(); PV1(vb, 3);
;     ...
;         if (t + 2 < NT) asm volatile("s_waitcnt vmcnt(4) lgkmcnt(0)" ::: "memory"); else asm volatile("s_waitcnt vmcnt(0) lgkmcnt(0)" ::: "memory");
;         __builtin_amdgcn_s_barrier(); asm volatile("" ::: "memory");
	v_mfma_f32_32x32x16_bf16 v[204:219], v[144:147], v[120:123], v[204:219]
	ds_read_b64_tr_b16 v[140:141], v230 offset:32768
	ds_read_b64_tr_b16 v[142:143], v230 offset:34816
	v_exp_f32_e32 v108, v108
	v_exp_f32_e32 v109, v109
	v_exp_f32_e32 v110, v110
	s_waitcnt lgkmcnt(9)
	v_mfma_f32_32x32x16_bf16 v[188:203], v[220:223], v[124:127], v[188:203]
	ds_read_b64_tr_b16 v[144:145], v231 offset:32768
	ds_read_b64_tr_b16 v[146:147], v231 offset:34816
	v_exp_f32_e32 v111, v111
	v_pk_add_f32 v[150:151], v[150:151], v[108:109]
	s_waitcnt lgkmcnt(10)
	v_mfma_f32_32x32x16_bf16 v[204:219], v[224:227], v[124:127], v[204:219]
	ds_read_b64_tr_b16 v[220:221], v228 offset:36864
	ds_read_b64_tr_b16 v[222:223], v228 offset:38912
	v_pk_add_f32 v[150:151], v[150:151], v[110:111]
	v_exp_f32_e32 v112, v112
	v_exp_f32_e32 v113, v113
	v_cvt_pk_bf16_f32 v104, v108, v109
	s_waitcnt lgkmcnt(11)
	v_mfma_f32_32x32x16_bf16 v[188:203], v[232:235], v[128:131], v[188:203]
	ds_read_b64_tr_b16 v[224:225], v229 offset:36864
	ds_read_b64_tr_b16 v[226:227], v229 offset:38912
	v_cvt_pk_bf16_f32 v105, v110, v111
	v_exp_f32_e32 v114, v114
	v_exp_f32_e32 v115, v115
	s_waitcnt lgkmcnt(12)
	v_mfma_f32_32x32x16_bf16 v[204:219], v[236:239], v[128:131], v[204:219]
	ds_read_b64_tr_b16 v[232:233], v230 offset:36864
	ds_read_b64_tr_b16 v[234:235], v230 offset:38912
	v_pk_add_f32 v[150:151], v[150:151], v[112:113]
	v_pk_add_f32 v[150:151], v[150:151], v[114:115]
	v_cvt_pk_bf16_f32 v106, v112, v113
	v_cvt_pk_bf16_f32 v107, v114, v115
	s_add_u32 s8, s8, 0x40000
	s_addc_u32 s9, s9, 0
	s_waitcnt vmcnt(4)
	s_barrier
	s_sub_u32 s10, s10, 1
	s_cbranch_scc1 .LatB_evs_h3
.LatB_evret_h3:
	s_waitcnt lgkmcnt(12)
	v_mfma_f32_32x32x16_bf16 v[20:35], v[84:87], v[132:135], v[20:35]
	ds_read_b64_tr_b16 v[236:237], v231 offset:36864
	ds_read_b64_tr_b16 v[238:239], v231 offset:38912
	s_waitcnt lgkmcnt(12)
	v_mfma_f32_32x32x16_bf16 v[36:51], v[84:87], v[136:139], v[36:51]
	ds_read_b64_tr_b16 v[132:133], v228 offset:40960
	ds_read_b64_tr_b16 v[134:135], v228 offset:43008
	s_waitcnt lgkmcnt(12)
	v_mfma_f32_32x32x16_bf16 v[52:67], v[84:87], v[140:143], v[52:67]
	ds_read_b64_tr_b16 v[136:137], v229 offset:40960
	ds_read_b64_tr_b16 v[138:139], v229 offset:43008
	s_waitcnt lgkmcnt(12)
	s_add_u32 m0, s25, 0x8000
	v_mfma_f32_32x32x16_bf16 v[68:83], v[84:87], v[144:147], v[68:83]
	global_load_lds_dwordx4 v172, s[8:9]
	ds_read_b64_tr_b16 v[140:141], v230 offset:40960
	ds_read_b64_tr_b16 v[142:143], v230 offset:43008
	v_max3_f32 v251, v188, v189, v190
	v_max3_f32 v252, v191, v192, v193
	v_max3_f32 v251, v251, v194, v195
	v_max3_f32 v252, v252, v196, v197
	v_max3_f32 v251, v251, v198, v199
	v_max3_f32 v252, v252, v200, v201
	v_max3_f32 v251, v251, v202, v203
	v_max3_f32 v252, v252, v204, v205
	v_max3_f32 v251, v251, v206, v207
	v_max3_f32 v252, v252, v208, v209
	v_max3_f32 v251, v251, v210, v211
	v_max3_f32 v252, v252, v212, v213
	v_max3_f32 v251, v251, v214, v215
	v_max3_f32 v252, v252, v216, v217
	v_max3_f32 v251, v251, v218, v219
	v_max_f32_e32 v251, v251, v252
	v_cmp_lt_f32_e32 vcc, 0x41000000, v251
	s_cbranch_vccnz .LatB_rs_h3
; #define LAS __attribute__((address_space(3)))
; #define VREADS1(arr, d_) do { const unsigned ad_ = vbase ^ (unsigned)((d_) << 6); __builtin_amdgcn_sched_barrier(0); \
;         _Pragma("unroll") for (int ks_ = 0; ks_ < 4; ++ks_) { VTR(arr[ks_ * 2], ad_, ks_ * 4096); VTR(arr[ks_ * 2 + 1], ad_, ks_ * 4096 + 2048); } __builtin_amdgcn_sched_barrier(0); } while (0)
; #define PV1(arr, d_) do { _Pragma("unroll") for (int ks_ = 0; ks_ < 4; ++ks_) { const s16x4 lo_ = arr[ks_ * 2], hh_ = arr[ks_ * 2 + 1]; \
;         const bf16x8 bv_ = (bf16x8){lo_[0], lo_[1], lo_[2], lo_[3], hh_[0], hh_[1], hh_[2], hh_[3]}; \
;         O[d_] = __builtin_amdgcn_mfma_f32_32x32x16_bf16(pa[ks_], bv_, O[d_], 0, 0, 0); } __builtin_amdgcn_sched_barrier(0); } while (0)
; __device__ __forceinline__ void attn_unit(LAS unsigned char* lds, const bf16_t* Z, bf16_t* A2, const float* tabg, int seq_base, int S, int h, int qb, float lam) {
;     ...
;             for (int ds = 0; ds < 4; ++ds) { kf[2 * ds] = *(const LAS bf16x8*)(Kt + (kfo ^ (unsigned)(ds << 5))); kf[2 * ds + 1] = *(const LAS bf16x8*)(Kt + 32 * 256 + (kfo ^ (unsigned)(ds << 5))); }
;             __builtin_amdgcn_sched_barrier(0);
;             p0 = __builtin_amdgcn_mfma_f32_32x32x16_bf16(kf[0], qf[0], cblk, 0, 0, 0);
;             p1 = __builtin_amdgcn_mfma_f32_32x32x16_bf16(kf[1], qf[0], cblk, 0, 0, 0);
; #pragma unroll
;             for (int ds = 1; ds < 4; ++ds) {
;                 p0 = __builtin_amdgcn_mfma_f32_32x32x16_bf16(kf[2 * ds], qf[ds], p0, 0, 0, 0);
;                 p1 = __builtin_amdgcn_mfma_f32_32x32x16_bf16(kf[2 * ds + 1], qf[ds], p1, 0, 0, 0);
;             }
;     ...
; #pragma unroll
;         for (int r = 0; r < 16; ++r) { p0[r] = __builtin_amdgcn_exp2f(p0[r]); p1[r] = __builtin_amdgcn_exp2f(p1[r]); }
; #pragma unroll
;         for (int r = 0; r < 16; r += 2) { ls2 += (f32x2){p0[r], p0[r + 1]}; ls2 += (f32x2){p1[r], p1[r + 1]}; }
;         bf16x8 pa[4]; pa[0] = pack8(p0, 0); pa[1] = pack8(p0, 8); pa[2] = pack8(p1, 0); pa[3] = pack8(p1, 8);
;         LGKM0(); VREADS1(vb, 1); PV1(va, 0); LGKM0(); VREADS1(va, 2); PV1(vb, 1); LGKM0(); VREADS1(vb, 3); PV1(va, 2); LGKM0(); PV1(vb, 3);
;     ...
;         if (t + 2 < NT) asm volatile("s_waitcnt vmcnt(4) lgkmcnt(0)" ::: "memory"); else asm volatile("s_waitcnt vmcnt(0) lgkmcnt(0)" ::: "memory");
;         __builtin_amdgcn_s_barrier(); asm volatile("" ::: "memory");
.LatB_rareret_h3:
	s_waitcnt lgkmcnt(12)
	v_mfma_f32_32x32x16_bf16 v[20:35], v[88:91], v[220:223], v[20:35]
	ds_read_b64_tr_b16 v[144:145], v231 offset:40960
	ds_read_b64_tr_b16 v[146:147], v231 offset:43008
	v_exp_f32_e32 v188, v188
	v_exp_f32_e32 v189, v189
	v_exp_f32_e32 v190, v190
	s_waitcnt lgkmcnt(12)
	v_mfma_f32_32x32x16_bf16 v[36:51], v[88:91], v[224:227], v[36:51]
	ds_read_b64_tr_b16 v[220:221], v228 offset:45056
	ds_read_b64_tr_b16 v[222:223], v228 offset:47104
	v_exp_f32_e32 v191, v191
	v_pk_add_f32 v[150:151], v[150:151], v[188:189]
	s_waitcnt lgkmcnt(12)
	v_mfma_f32_32x32x16_bf16 v[52:67], v[88:91], v[232:235], v[52:67]
	ds_read_b64_tr_b16 v[224:225], v229 offset:45056
	ds_read_b64_tr_b16 v[226:227], v229 offset:47104
	v_pk_add_f32 v[150:151], v[150:151], v[190:191]
	v_exp_f32_e32 v192, v192
	v_exp_f32_e32 v193, v193
	v_cvt_pk_bf16_f32 v188, v188, v189
	s_waitcnt lgkmcnt(12)
	s_add_u32 m0, s27, 0x4000
	v_mfma_f32_32x32x16_bf16 v[68:83], v[88:91], v[236:239], v[68:83]
	global_load_lds_dwordx4 v174, s[8:9]
	ds_read_b64_tr_b16 v[232:233], v230 offset:45056
	ds_read_b64_tr_b16 v[234:235], v230 offset:47104
	v_cvt_pk_bf16_f32 v189, v190, v191
	v_exp_f32_e32 v194, v194
	v_exp_f32_e32 v195, v195
	s_waitcnt lgkmcnt(12)
	v_mfma_f32_32x32x16_bf16 v[20:35], v[100:103], v[132:135], v[20:35]
	ds_read_b64_tr_b16 v[236:237], v231 offset:45056
	ds_read_b64_tr_b16 v[238:239], v231 offset:47104
	v_pk_add_f32 v[150:151], v[150:151], v[192:193]
	v_pk_add_f32 v[150:151], v[150:151], v[194:195]
	v_cvt_pk_bf16_f32 v190, v192, v193
	v_cvt_pk_bf16_f32 v191, v194, v195
	s_waitcnt lgkmcnt(12)
	v_mfma_f32_32x32x16_bf16 v[36:51], v[100:103], v[136:139], v[36:51]
	ds_read_b128 v[132:135], v19
	v_exp_f32_e32 v196, v196
	v_exp_f32_e32 v197, v197
	v_exp_f32_e32 v198, v198
	s_waitcnt lgkmcnt(11)
	v_mfma_f32_32x32x16_bf16 v[52:67], v[100:103], v[140:143], v[52:67]
	ds_read_b128 v[136:139], v19 offset:8192
	v_exp_f32_e32 v199, v199
	v_pk_add_f32 v[150:151], v[150:151], v[196:197]
	s_waitcnt lgkmcnt(10)
	s_add_u32 m0, s25, 0xa000
	v_mfma_f32_32x32x16_bf16 v[68:83], v[100:103], v[144:147], v[68:83]
	global_load_lds_dwordx4 v173, s[8:9]
	ds_read_b128 v[140:143], v180
	v_pk_add_f32 v[150:151], v[150:151], v[198:199]
	v_exp_f32_e32 v200, v200
	v_exp_f32_e32 v201, v201
	v_cvt_pk_bf16_f32 v192, v196, v197
	s_waitcnt lgkmcnt(9)
	v_mfma_f32_32x32x16_bf16 v[20:35], v[104:107], v[220:223], v[20:35]
	ds_read_b128 v[144:147], v180 offset:8192
	v_cvt_pk_bf16_f32 v193, v198, v199
	v_exp_f32_e32 v202, v202
	v_exp_f32_e32 v203, v203
	s_waitcnt lgkmcnt(8)
	v_mfma_f32_32x32x16_bf16 v[36:51], v[104:107], v[224:227], v[36:51]
	ds_read_b128 v[220:223], v181
	v_pk_add_f32 v[150:151], v[150:151], v[200:201]
	v_pk_add_f32 v[150:151], v[150:151], v[202:203]
	v_cvt_pk_bf16_f32 v194, v200, v201
	v_cvt_pk_bf16_f32 v195, v202, v203
	s_waitcnt lgkmcnt(7)
	v_mfma_f32_32x32x16_bf16 v[52:67], v[104:107], v[232:235], v[52:67]
	ds_read_b128 v[224:227], v181 offset:8192
	v_exp_f32_e32 v204, v204
	v_exp_f32_e32 v205, v205
	v_exp_f32_e32 v206, v206
	s_waitcnt lgkmcnt(6)
	s_add_u32 m0, s27, 0x6000
	v_mfma_f32_32x32x16_bf16 v[68:83], v[104:107], v[236:239], v[68:83]
	global_load_lds_dwordx4 v175, s[8:9]
	ds_read_b128 v[232:235], v182
	v_exp_f32_e32 v207, v207
	v_pk_add_f32 v[150:151], v[150:151], v[204:205]
	s_waitcnt lgkmcnt(6)
	v_mfma_f32_32x32x16_bf16 v[84:99], v[132:135], v[116:119], v[2:17]
	ds_read_b128 v[236:239], v182 offset:8192
	v_pk_add_f32 v[150:151], v[150:151], v[206:207]
	v_exp_f32_e32 v208, v208
	v_exp_f32_e32 v209, v209
	v_cvt_pk_bf16_f32 v204, v204, v205
	s_waitcnt lgkmcnt(6)
	v_mfma_f32_32x32x16_bf16 v[100:115], v[136:139], v[116:119], v[2:17]
	ds_read_b64_tr_b16 v[132:133], v168 offset:0
	ds_read_b64_tr_b16 v[134:135], v168 offset:2048
	v_cvt_pk_bf16_f32 v205, v206, v207
	v_exp_f32_e32 v210, v210
	v_exp_f32_e32 v211, v211
	s_waitcnt lgkmcnt(7)
	v_mfma_f32_32x32x16_bf16 v[84:99], v[140:143], v[120:123], v[84:99]
	ds_read_b64_tr_b16 v[136:137], v169 offset:0
	ds_read_b64_tr_b16 v[138:139], v169 offset:2048
	v_pk_add_f32 v[150:151], v[150:151], v[208:209]
	v_pk_add_f32 v[150:151], v[150:151], v[210:211]
	v_cvt_pk_bf16_f32 v206, v208, v209
	v_cvt_pk_bf16_f32 v207, v210, v211
	s_waitcnt lgkmcnt(8)
	v_mfma_f32_32x32x16_bf16 v[100:115], v[144:147], v[120:123], v[100:115]
	ds_read_b64_tr_b16 v[140:141], v170 offset:0
	ds_read_b64_tr_b16 v[142:143], v170 offset:2048
	v_exp_f32_e32 v212, v212
	v_exp_f32_e32 v213, v213
	v_exp_f32_e32 v214, v214
	s_waitcnt lgkmcnt(9)
	v_mfma_f32_32x32x16_bf16 v[84:99], v[220:223], v[124:127], v[84:99]
	ds_read_b64_tr_b16 v[144:145], v171 offset:0
	ds_read_b64_tr_b16 v[146:147], v171 offset:2048
	v_exp_f32_e32 v215, v215
	v_pk_add_f32 v[150:151], v[150:151], v[212:213]
	s_waitcnt lgkmcnt(10)
	v_mfma_f32_32x32x16_bf16 v[100:115], v[224:227], v[124:127], v[100:115]
	ds_read_b64_tr_b16 v[220:221], v168 offset:4096
	ds_read_b64_tr_b16 v[222:223], v168 offset:6144
	v_pk_add_f32 v[150:151], v[150:151], v[214:215]
	v_exp_f32_e32 v216, v216
	v_exp_f32_e32 v217, v217
	v_cvt_pk_bf16_f32 v208, v212, v213
	s_waitcnt lgkmcnt(11)
	v_mfma_f32_32x32x16_bf16 v[84:99], v[232:235], v[128:131], v[84:99]
	ds_read_b64_tr_b16 v[224:225], v169 offset:4096
	ds_read_b64_tr_b16 v[226:227], v169 offset:6144
	v_cvt_pk_bf16_f32 v209, v214, v215
	v_exp_f32_e32 v218, v218
	v_exp_f32_e32 v219, v219
	s_waitcnt lgkmcnt(12)
	v_mfma_f32_32x32x16_bf16 v[100:115], v[236:239], v[128:131], v[100:115]
	ds_read_b64_tr_b16 v[232:233], v170 offset:4096
	ds_read_b64_tr_b16 v[234:235], v170 offset:6144
	v_pk_add_f32 v[150:151], v[150:151], v[216:217]
	v_pk_add_f32 v[150:151], v[150:151], v[218:219]
	v_cvt_pk_bf16_f32 v210, v216, v217
	v_cvt_pk_bf16_f32 v211, v218, v219
	s_add_u32 s8, s8, 0x40000
	s_addc_u32 s9, s9, 0
	s_waitcnt vmcnt(4)
	s_barrier
	s_movk_i32 s36, 62

; #define LAS __attribute__((address_space(3)))
; __device__ __forceinline__ float max2f(float a, float b) { float r; asm("v_max_f32_e32 %0, %1, %2" : "=v"(r) : "v"(a), "v"(b)); return r; }
; #define VREADS1(arr, d_) do { const unsigned ad_ = vbase ^ (unsigned)((d_) << 6); __builtin_amdgcn_sched_barrier(0); \
;         _Pragma("unroll") for (int ks_ = 0; ks_ < 4; ++ks_) { VTR(arr[ks_ * 2], ad_, ks_ * 4096); VTR(arr[ks_ * 2 + 1], ad_, ks_ * 4096 + 2048); } __builtin_amdgcn_sched_barrier(0); } while (0)
; __device__ __forceinline__ void attn_unit(LAS unsigned char* lds, const bf16_t* Z, bf16_t* A2, const float* tabg, int seq_base, int S, int h, int qb, float lam) {
;     ...
;         const unsigned vbase = (unsigned)(size_t)Vt + vfo;
;         s16x4 va[8], vb[8];
;         VREADS1(va, 0);
;         if (near) {
;             const LAS float* tp = tab + (kv0 + 4 * hi - (qlo + r32) + 224);
; #pragma unroll
;             for (int r = 0; r < 16; ++r) { p0[r] += tp[(r & 3) + 8 * (r >> 2)]; p1[r] += tp[32 + (r & 3) + 8 * (r >> 2)]; }
;         }
;         float mx = max2f(max16f(p0), max16f(p1));
;         const bool first = (t == 0);
;         if (first || __any(mx > THR)) {
.LatB_evret_m0:
	s_waitcnt lgkmcnt(12)
	v_mfma_f32_32x32x16_bf16 v[20:35], v[188:191], v[132:135], v[20:35]
	ds_read_b64_tr_b16 v[236:237], v171 offset:4096
	ds_read_b64_tr_b16 v[238:239], v171 offset:6144
	s_waitcnt lgkmcnt(12)
	v_mfma_f32_32x32x16_bf16 v[36:51], v[188:191], v[136:139], v[36:51]
	ds_read_b64_tr_b16 v[132:133], v168 offset:8192
	ds_read_b64_tr_b16 v[134:135], v168 offset:10240
	s_waitcnt lgkmcnt(12)
	v_mfma_f32_32x32x16_bf16 v[52:67], v[188:191], v[140:143], v[52:67]
	ds_read_b64_tr_b16 v[136:137], v169 offset:8192
	ds_read_b64_tr_b16 v[138:139], v169 offset:10240
	s_waitcnt lgkmcnt(12)
	s_add_u32 m0, s25, 0x1d000
	v_mfma_f32_32x32x16_bf16 v[68:83], v[188:191], v[144:147], v[68:83]
	global_load_lds_dwordx4 v172, s[8:9]
	ds_read_b64_tr_b16 v[140:141], v170 offset:8192
	ds_read_b64_tr_b16 v[142:143], v170 offset:10240
	v_max3_f32 v251, v84, v85, v86
	v_max3_f32 v252, v87, v88, v89
	v_max3_f32 v251, v251, v90, v91
	v_max3_f32 v252, v252, v92, v93
	v_max3_f32 v251, v251, v94, v95
	v_max3_f32 v252, v252, v96, v97
	v_max3_f32 v251, v251, v98, v99
	v_max3_f32 v252, v252, v100, v101
	v_max3_f32 v251, v251, v102, v103
	v_max3_f32 v252, v252, v104, v105
	v_max3_f32 v251, v251, v106, v107
	v_max3_f32 v252, v252, v108, v109
	v_max3_f32 v251, v251, v110, v111
	v_max3_f32 v252, v252, v112, v113
	v_max3_f32 v251, v251, v114, v115
	v_max_f32_e32 v251, v251, v252
	v_cmp_lt_f32_e32 vcc, 0x41000000, v251
	s_cbranch_vccnz .LatB_rs_m0
; #define LAS __attribute__((address_space(3)))
; #define VREADS1(arr, d_) do { const unsigned ad_ = vbase ^ (unsigned)((d_) << 6); __builtin_amdgcn_sched_barrier(0); \
;         _Pragma("unroll") for (int ks_ = 0; ks_ < 4; ++ks_) { VTR(arr[ks_ * 2], ad_, ks_ * 4096); VTR(arr[ks_ * 2 + 1], ad_, ks_ * 4096 + 2048); } __builtin_amdgcn_sched_barrier(0); } while (0)
; #define PV1(arr, d_) do { _Pragma("unroll") for (int ks_ = 0; ks_ < 4; ++ks_) { const s16x4 lo_ = arr[ks_ * 2], hh_ = arr[ks_ * 2 + 1]; \
;         const bf16x8 bv_ = (bf16x8){lo_[0], lo_[1], lo_[2], lo_[3], hh_[0], hh_[1], hh_[2], hh_[3]}; \
;         O[d_] = __builtin_amdgcn_mfma_f32_32x32x16_bf16(pa[ks_], bv_, O[d_], 0, 0, 0); } __builtin_amdgcn_sched_barrier(0); } while (0)
; __device__ __forceinline__ void attn_unit(LAS unsigned char* lds, const bf16_t* Z, bf16_t* A2, const float* tabg, int seq_base, int S, int h, int qb, float lam) {
;     ...
;             for (int ds = 0; ds < 4; ++ds) { kf[2 * ds] = *(const LAS bf16x8*)(Kt + (kfo ^ (unsigned)(ds << 5))); kf[2 * ds + 1] = *(const LAS bf16x8*)(Kt + 32 * 256 + (kfo ^ (unsigned)(ds << 5))); }
;             __builtin_amdgcn_sched_barrier(0);
;             p0 = __builtin_amdgcn_mfma_f32_32x32x16_bf16(kf[0], qf[0], cblk, 0, 0, 0);
;             p1 = __builtin_amdgcn_mfma_f32_32x32x16_bf16(kf[1], qf[0], cblk, 0, 0, 0);
; #pragma unroll
;             for (int ds = 1; ds < 4; ++ds) {
;                 p0 = __builtin_amdgcn_mfma_f32_32x32x16_bf16(kf[2 * ds], qf[ds], p0, 0, 0, 0);
;                 p1 = __builtin_amdgcn_mfma_f32_32x32x16_bf16(kf[2 * ds + 1], qf[ds], p1, 0, 0, 0);
;             }
;     ...
; #pragma unroll
;         for (int r = 0; r < 16; ++r) { p0[r] = __builtin_amdgcn_exp2f(p0[r]); p1[r] = __builtin_amdgcn_exp2f(p1[r]); }
; #pragma unroll
;         for (int r = 0; r < 16; r += 2) { ls2 += (f32x2){p0[r], p0[r + 1]}; ls2 += (f32x2){p1[r], p1[r + 1]}; }
;         bf16x8 pa[4]; pa[0] = pack8(p0, 0); pa[1] = pack8(p0, 8); pa[2] = pack8(p1, 0); pa[3] = pack8(p1, 8);
;         LGKM0(); VREADS1(vb, 1); PV1(va, 0); LGKM0(); VREADS1(va, 2); PV1(vb, 1); LGKM0(); VREADS1(vb, 3); PV1(va, 2); LGKM0(); PV1(vb, 3);
;     ...
;         if (t + 2 < NT) asm volatile("s_waitcnt vmcnt(4) lgkmcnt(0)" ::: "memory"); else asm volatile("s_waitcnt vmcnt(0) lgkmcnt(0)" ::: "memory");
;         __builtin_amdgcn_s_barrier(); asm volatile("" ::: "memory");
.LatB_rareret_m0:
	s_waitcnt lgkmcnt(12)
	v_mfma_f32_32x32x16_bf16 v[20:35], v[192:195], v[220:223], v[20:35]
	ds_read_b64_tr_b16 v[144:145], v171 offset:8192
	ds_read_b64_tr_b16 v[146:147], v171 offset:10240
	v_exp_f32_e32 v84, v84
	v_exp_f32_e32 v85, v85
	v_exp_f32_e32 v86, v86
	s_waitcnt lgkmcnt(12)
	v_mfma_f32_32x32x16_bf16 v[36:51], v[192:195], v[224:227], v[36:51]
	ds_read_b64_tr_b16 v[220:221], v168 offset:12288
	ds_read_b64_tr_b16 v[222:223], v168 offset:14336
	v_exp_f32_e32 v87, v87
	v_pk_add_f32 v[150:151], v[150:151], v[84:85]
	s_waitcnt lgkmcnt(12)
	v_mfma_f32_32x32x16_bf16 v[52:67], v[192:195], v[232:235], v[52:67]
	ds_read_b64_tr_b16 v[224:225], v169 offset:12288
	ds_read_b64_tr_b16 v[226:227], v169 offset:14336
	v_pk_add_f32 v[150:151], v[150:151], v[86:87]
	v_exp_f32_e32 v88, v88
	v_exp_f32_e32 v89, v89
	v_cvt_pk_bf16_f32 v84, v84, v85
	s_waitcnt lgkmcnt(12)
	s_add_u32 m0, s27, 0x8000
	v_mfma_f32_32x32x16_bf16 v[68:83], v[192:195], v[236:239], v[68:83]
	global_load_lds_dwordx4 v174, s[8:9]
	ds_read_b64_tr_b16 v[232:233], v170 offset:12288
	ds_read_b64_tr_b16 v[234:235], v170 offset:14336
	v_cvt_pk_bf16_f32 v85, v86, v87
	v_exp_f32_e32 v90, v90
	v_exp_f32_e32 v91, v91
	s_waitcnt lgkmcnt(12)
	v_mfma_f32_32x32x16_bf16 v[20:35], v[204:207], v[132:135], v[20:35]
	ds_read_b64_tr_b16 v[236:237], v171 offset:12288
	ds_read_b64_tr_b16 v[238:239], v171 offset:14336
	v_pk_add_f32 v[150:151], v[150:151], v[88:89]
	v_pk_add_f32 v[150:151], v[150:151], v[90:91]
	v_cvt_pk_bf16_f32 v86, v88, v89
	v_cvt_pk_bf16_f32 v87, v90, v91
	s_waitcnt lgkmcnt(12)
	v_mfma_f32_32x32x16_bf16 v[36:51], v[204:207], v[136:139], v[36:51]
	ds_read_b128 v[132:135], v19 offset:16384
	v_exp_f32_e32 v92, v92
	v_exp_f32_e32 v93, v93
	v_exp_f32_e32 v94, v94
	s_waitcnt lgkmcnt(11)
	v_mfma_f32_32x32x16_bf16 v[52:67], v[204:207], v[140:143], v[52:67]
	ds_read_b128 v[136:139], v19 offset:24576
	v_exp_f32_e32 v95, v95
	v_pk_add_f32 v[150:151], v[150:151], v[92:93]
	s_waitcnt lgkmcnt(10)
	s_add_u32 m0, s25, 0x1f000
	v_mfma_f32_32x32x16_bf16 v[68:83], v[204:207], v[144:147], v[68:83]
	global_load_lds_dwordx4 v173, s[8:9]
	ds_read_b128 v[140:143], v180 offset:16384
	v_pk_add_f32 v[150:151], v[150:151], v[94:95]
	v_exp_f32_e32 v96, v96
	v_exp_f32_e32 v97, v97
	v_cvt_pk_bf16_f32 v88, v92, v93
	s_waitcnt lgkmcnt(9)
	v_mfma_f32_32x32x16_bf16 v[20:35], v[208:211], v[220:223], v[20:35]
	ds_read_b128 v[144:147], v180 offset:24576
	v_cvt_pk_bf16_f32 v89, v94, v95
	v_exp_f32_e32 v98, v98
	v_exp_f32_e32 v99, v99
	s_waitcnt lgkmcnt(8)
	v_mfma_f32_32x32x16_bf16 v[36:51], v[208:211], v[224:227], v[36:51]
	ds_read_b128 v[220:223], v181 offset:16384
	v_pk_add_f32 v[150:151], v[150:151], v[96:97]
	v_pk_add_f32 v[150:151], v[150:151], v[98:99]
	v_cvt_pk_bf16_f32 v90, v96, v97
	v_cvt_pk_bf16_f32 v91, v98, v99
	s_waitcnt lgkmcnt(7)
	v_mfma_f32_32x32x16_bf16 v[52:67], v[208:211], v[232:235], v[52:67]
	ds_read_b128 v[224:227], v181 offset:24576
	v_exp_f32_e32 v100, v100
	v_exp_f32_e32 v101, v101
	v_exp_f32_e32 v102, v102
	s_waitcnt lgkmcnt(6)
	s_add_u32 m0, s27, 0xa000
	v_mfma_f32_32x32x16_bf16 v[68:83], v[208:211], v[236:239], v[68:83]
	global_load_lds_dwordx4 v175, s[8:9]
	ds_read_b128 v[232:235], v182 offset:16384
	v_exp_f32_e32 v103, v103
	v_pk_add_f32 v[150:151], v[150:151], v[100:101]
	s_waitcnt lgkmcnt(6)
	v_mfma_f32_32x32x16_bf16 v[188:203], v[132:135], v[116:119], v[2:17]
	ds_read_b128 v[236:239], v182 offset:24576
	v_pk_add_f32 v[150:151], v[150:151], v[102:103]
	v_exp_f32_e32 v104, v104
	v_exp_f32_e32 v105, v105
	v_cvt_pk_bf16_f32 v100, v100, v101
	s_waitcnt lgkmcnt(6)
	v_mfma_f32_32x32x16_bf16 v[204:219], v[136:139], v[116:119], v[2:17]
	ds_read_b64_tr_b16 v[132:133], v228 offset:0
	ds_read_b64_tr_b16 v[134:135], v228 offset:2048
	v_cvt_pk_bf16_f32 v101, v102, v103
	v_exp_f32_e32 v106, v106
	v_exp_f32_e32 v107, v107
	s_waitcnt lgkmcnt(7)
	v_mfma_f32_32x32x16_bf16 v[188:203], v[140:143], v[120:123], v[188:203]
	ds_read_b64_tr_b16 v[136:137], v229 offset:0
	ds_read_b64_tr_b16 v[138:139], v229 offset:2048
	v_pk_add_f32 v[150:151], v[150:151], v[104:105]
	v_pk_add_f32 v[150:151], v[150:151], v[106:107]
	v_cvt_pk_bf16_f32 v102, v104, v105
	v_cvt_pk_bf16_f32 v103, v106, v107
	s_waitcnt lgkmcnt(8)
	v_mfma_f32_32x32x16_bf16 v[204:219], v[144:147], v[120:123], v[204:219]
	ds_read_b64_tr_b16 v[140:141], v230 offset:0
	ds_read_b64_tr_b16 v[142:143], v230 offset:2048
	v_exp_f32_e32 v108, v108
	v_exp_f32_e32 v109, v109
	v_exp_f32_e32 v110, v110
	s_waitcnt lgkmcnt(9)
	v_mfma_f32_32x32x16_bf16 v[188:203], v[220:223], v[124:127], v[188:203]
	ds_read_b64_tr_b16 v[144:145], v231 offset:0
	ds_read_b64_tr_b16 v[146:147], v231 offset:2048
	v_exp_f32_e32 v111, v111
	v_pk_add_f32 v[150:151], v[150:151], v[108:109]
	s_waitcnt lgkmcnt(10)
	v_mfma_f32_32x32x16_bf16 v[204:219], v[224:227], v[124:127], v[204:219]
	ds_read_b64_tr_b16 v[220:221], v228 offset:4096
	ds_read_b64_tr_b16 v[222:223], v228 offset:6144
	v_pk_add_f32 v[150:151], v[150:151], v[110:111]
	v_exp_f32_e32 v112, v112
	v_exp_f32_e32 v113, v113
	v_cvt_pk_bf16_f32 v104, v108, v109
	s_waitcnt lgkmcnt(11)
	v_mfma_f32_32x32x16_bf16 v[188:203], v[232:235], v[128:131], v[188:203]
	ds_read_b64_tr_b16 v[224:225], v229 offset:4096
	ds_read_b64_tr_b16 v[226:227], v229 offset:6144
	v_cvt_pk_bf16_f32 v105, v110, v111
	v_exp_f32_e32 v114, v114
	v_exp_f32_e32 v115, v115
	s_waitcnt lgkmcnt(12)
	v_mfma_f32_32x32x16_bf16 v[204:219], v[236:239], v[128:131], v[204:219]
	ds_read_b64_tr_b16 v[232:233], v230 offset:4096
	ds_read_b64_tr_b16 v[234:235], v230 offset:6144
	v_pk_add_f32 v[150:151], v[150:151], v[112:113]
	v_pk_add_f32 v[150:151], v[150:151], v[114:115]
	v_cvt_pk_bf16_f32 v106, v112, v113
	v_cvt_pk_bf16_f32 v107, v114, v115
	s_add_u32 s8, s8, 0x40000
	s_addc_u32 s9, s9, 0
	s_waitcnt vmcnt(4)
	s_barrier
	s_sub_u32 s10, s10, 1
	s_cbranch_scc1 .LatB_evs_m1

; #define VREADS1(arr, d_) do { const unsigned ad_ = vbase ^ (unsigned)((d_) << 6); __builtin_amdgcn_sched_barrier(0); \
;         _Pragma("unroll") for (int ks_ = 0; ks_ < 4; ++ks_) { VTR(arr[ks_ * 2], ad_, ks_ * 4096); VTR(arr[ks_ * 2 + 1], ad_, ks_ * 4096 + 2048); } __builtin_amdgcn_sched_barrier(0); } while (0)
; #define PV1(arr, d_) do { _Pragma("unroll") for (int ks_ = 0; ks_ < 4; ++ks_) { const s16x4 lo_ = arr[ks_ * 2], hh_ = arr[ks_ * 2 + 1]; \
;         const bf16x8 bv_ = (bf16x8){lo_[0], lo_[1], lo_[2], lo_[3], hh_[0], hh_[1], hh_[2], hh_[3]}; \
;         O[d_] = __builtin_amdgcn_mfma_f32_32x32x16_bf16(pa[ks_], bv_, O[d_], 0, 0, 0); } __builtin_amdgcn_sched_barrier(0); } while (0)
; #define LGKM0() do { __builtin_amdgcn_sched_barrier(0); asm volatile("s_waitcnt lgkmcnt(0)" ::: "memory"); __builtin_amdgcn_sched_barrier(0); } while (0)
; __device__ __forceinline__ void attn_unit(LAS unsigned char* lds, const bf16_t* Z, bf16_t* A2, const float* tabg, int seq_base, int S, int h, int qb, float lam) {
;     ...
; #pragma unroll
;         for (int r = 0; r < 16; ++r) { p0[r] = __builtin_amdgcn_exp2f(p0[r]); p1[r] = __builtin_amdgcn_exp2f(p1[r]); }
; #pragma unroll
;         for (int r = 0; r < 16; r += 2) { ls2 += (f32x2){p0[r], p0[r + 1]}; ls2 += (f32x2){p1[r], p1[r + 1]}; }
;         bf16x8 pa[4]; pa[0] = pack8(p0, 0); pa[1] = pack8(p0, 8); pa[2] = pack8(p1, 0); pa[3] = pack8(p1, 8);
;         LGKM0(); VREADS1(vb, 1); PV1(va, 0); LGKM0(); VREADS1(va, 2); PV1(vb, 1); LGKM0(); VREADS1(vb, 3); PV1(va, 2); LGKM0(); PV1(vb, 3);
;     ...
;         if (t + 2 < NT) asm volatile("s_waitcnt vmcnt(4) lgkmcnt(0)" ::: "memory"); else asm volatile("s_waitcnt vmcnt(0) lgkmcnt(0)" ::: "memory");
;         __builtin_amdgcn_s_barrier(); asm volatile("" ::: "memory");
;         bc = (bc == NST - 1) ? 0 : bc + 1; bn = (bn == NST - 1) ? 0 : bn + 1;
;     }
.LatB_rareret_m3:
	s_waitcnt lgkmcnt(12)
	v_mfma_f32_32x32x16_bf16 v[20:35], v[88:91], v[220:223], v[20:35]
	ds_read_b64_tr_b16 v[144:145], v231 offset:40960
	ds_read_b64_tr_b16 v[146:147], v231 offset:43008
	v_exp_f32_e32 v188, v188
	v_exp_f32_e32 v189, v189
	v_exp_f32_e32 v190, v190
	s_waitcnt lgkmcnt(12)
	v_mfma_f32_32x32x16_bf16 v[36:51], v[88:91], v[224:227], v[36:51]
	ds_read_b64_tr_b16 v[220:221], v228 offset:45056
	ds_read_b64_tr_b16 v[222:223], v228 offset:47104
	v_exp_f32_e32 v191, v191
	v_pk_add_f32 v[150:151], v[150:151], v[188:189]
	s_waitcnt lgkmcnt(12)
	v_mfma_f32_32x32x16_bf16 v[52:67], v[88:91], v[232:235], v[52:67]
	ds_read_b64_tr_b16 v[224:225], v229 offset:45056
	ds_read_b64_tr_b16 v[226:227], v229 offset:47104
	v_pk_add_f32 v[150:151], v[150:151], v[190:191]
	v_exp_f32_e32 v192, v192
	v_exp_f32_e32 v193, v193
	v_cvt_pk_bf16_f32 v188, v188, v189
	s_waitcnt lgkmcnt(12)
	s_add_u32 m0, s27, 0x4000
	v_mfma_f32_32x32x16_bf16 v[68:83], v[88:91], v[236:239], v[68:83]
	global_load_lds_dwordx4 v174, s[8:9]
	ds_read_b64_tr_b16 v[232:233], v230 offset:45056
	ds_read_b64_tr_b16 v[234:235], v230 offset:47104
	v_cvt_pk_bf16_f32 v189, v190, v191
	v_exp_f32_e32 v194, v194
	v_exp_f32_e32 v195, v195
	s_waitcnt lgkmcnt(12)
	v_mfma_f32_32x32x16_bf16 v[20:35], v[100:103], v[132:135], v[20:35]
	ds_read_b64_tr_b16 v[236:237], v231 offset:45056
	ds_read_b64_tr_b16 v[238:239], v231 offset:47104
	v_pk_add_f32 v[150:151], v[150:151], v[192:193]
	v_pk_add_f32 v[150:151], v[150:151], v[194:195]
	v_cvt_pk_bf16_f32 v190, v192, v193
	v_cvt_pk_bf16_f32 v191, v194, v195
	s_waitcnt lgkmcnt(12)
	v_mfma_f32_32x32x16_bf16 v[36:51], v[100:103], v[136:139], v[36:51]
	ds_read_b128 v[132:135], v19
	v_exp_f32_e32 v196, v196
	v_exp_f32_e32 v197, v197
	v_exp_f32_e32 v198, v198
	s_waitcnt lgkmcnt(11)
	v_mfma_f32_32x32x16_bf16 v[52:67], v[100:103], v[140:143], v[52:67]
	ds_read_b128 v[136:139], v19 offset:8192
	v_exp_f32_e32 v199, v199
	v_pk_add_f32 v[150:151], v[150:151], v[196:197]
	s_waitcnt lgkmcnt(10)
	s_add_u32 m0, s25, 0xa000
	v_mfma_f32_32x32x16_bf16 v[68:83], v[100:103], v[144:147], v[68:83]
	global_load_lds_dwordx4 v173, s[8:9]
	ds_read_b128 v[140:143], v180
	v_pk_add_f32 v[150:151], v[150:151], v[198:199]
	v_exp_f32_e32 v200, v200
	v_exp_f32_e32 v201, v201
	v_cvt_pk_bf16_f32 v192, v196, v197
	s_waitcnt lgkmcnt(9)
	v_mfma_f32_32x32x16_bf16 v[20:35], v[104:107], v[220:223], v[20:35]
	ds_read_b128 v[144:147], v180 offset:8192
	v_cvt_pk_bf16_f32 v193, v198, v199
	v_exp_f32_e32 v202, v202
	v_exp_f32_e32 v203, v203
	s_waitcnt lgkmcnt(8)
	v_mfma_f32_32x32x16_bf16 v[36:51], v[104:107], v[224:227], v[36:51]
	ds_read_b128 v[220:223], v181
	v_pk_add_f32 v[150:151], v[150:151], v[200:201]
	v_pk_add_f32 v[150:151], v[150:151], v[202:203]
	v_cvt_pk_bf16_f32 v194, v200, v201
	v_cvt_pk_bf16_f32 v195, v202, v203
	s_waitcnt lgkmcnt(7)
	v_mfma_f32_32x32x16_bf16 v[52:67], v[104:107], v[232:235], v[52:67]
	ds_read_b128 v[224:227], v181 offset:8192
	v_exp_f32_e32 v204, v204
	v_exp_f32_e32 v205, v205
	v_exp_f32_e32 v206, v206
	s_waitcnt lgkmcnt(6)
	s_add_u32 m0, s27, 0x6000
	v_mfma_f32_32x32x16_bf16 v[68:83], v[104:107], v[236:239], v[68:83]
	global_load_lds_dwordx4 v175, s[8:9]
	ds_read_b128 v[232:235], v182
	v_exp_f32_e32 v207, v207
	v_pk_add_f32 v[150:151], v[150:151], v[204:205]
	s_waitcnt lgkmcnt(6)
	v_mfma_f32_32x32x16_bf16 v[84:99], v[132:135], v[116:119], v[2:17]
	ds_read_b128 v[236:239], v182 offset:8192
	v_pk_add_f32 v[150:151], v[150:151], v[206:207]
	v_exp_f32_e32 v208, v208
	v_exp_f32_e32 v209, v209
	v_cvt_pk_bf16_f32 v204, v204, v205
	s_waitcnt lgkmcnt(6)
	v_mfma_f32_32x32x16_bf16 v[100:115], v[136:139], v[116:119], v[2:17]
	ds_read_b64_tr_b16 v[132:133], v168 offset:0
	ds_read_b64_tr_b16 v[134:135], v168 offset:2048
	v_cvt_pk_bf16_f32 v205, v206, v207
	v_exp_f32_e32 v210, v210
	v_exp_f32_e32 v211, v211
	s_waitcnt lgkmcnt(7)
	v_mfma_f32_32x32x16_bf16 v[84:99], v[140:143], v[120:123], v[84:99]
	ds_read_b64_tr_b16 v[136:137], v169 offset:0
	ds_read_b64_tr_b16 v[138:139], v169 offset:2048
	v_pk_add_f32 v[150:151], v[150:151], v[208:209]
	v_pk_add_f32 v[150:151], v[150:151], v[210:211]
	v_cvt_pk_bf16_f32 v206, v208, v209
	v_cvt_pk_bf16_f32 v207, v210, v211
	s_waitcnt lgkmcnt(8)
	v_mfma_f32_32x32x16_bf16 v[100:115], v[144:147], v[120:123], v[100:115]
	ds_read_b64_tr_b16 v[140:141], v170 offset:0
	ds_read_b64_tr_b16 v[142:143], v170 offset:2048
	v_exp_f32_e32 v212, v212
	v_exp_f32_e32 v213, v213
	v_exp_f32_e32 v214, v214
	s_waitcnt lgkmcnt(9)
	v_mfma_f32_32x32x16_bf16 v[84:99], v[220:223], v[124:127], v[84:99]
	ds_read_b64_tr_b16 v[144:145], v171 offset:0
	ds_read_b64_tr_b16 v[146:147], v171 offset:2048
	v_exp_f32_e32 v215, v215
	v_pk_add_f32 v[150:151], v[150:151], v[212:213]
	s_waitcnt lgkmcnt(10)
	v_mfma_f32_32x32x16_bf16 v[100:115], v[224:227], v[124:127], v[100:115]
	ds_read_b64_tr_b16 v[220:221], v168 offset:4096
	ds_read_b64_tr_b16 v[222:223], v168 offset:6144
	v_pk_add_f32 v[150:151], v[150:151], v[214:215]
	v_exp_f32_e32 v216, v216
	v_exp_f32_e32 v217, v217
	v_cvt_pk_bf16_f32 v208, v212, v213
	s_waitcnt lgkmcnt(11)
	v_mfma_f32_32x32x16_bf16 v[84:99], v[232:235], v[128:131], v[84:99]
	ds_read_b64_tr_b16 v[224:225], v169 offset:4096
	ds_read_b64_tr_b16 v[226:227], v169 offset:6144
	v_cvt_pk_bf16_f32 v209, v214, v215
	v_exp_f32_e32 v218, v218
	v_exp_f32_e32 v219, v219
	s_waitcnt lgkmcnt(12)
	v_mfma_f32_32x32x16_bf16 v[100:115], v[236:239], v[128:131], v[100:115]
	ds_read_b64_tr_b16 v[232:233], v170 offset:4096
	ds_read_b64_tr_b16 v[234:235], v170 offset:6144
	v_pk_add_f32 v[150:151], v[150:151], v[216:217]
	v_pk_add_f32 v[150:151], v[150:151], v[218:219]
	v_cvt_pk_bf16_f32 v210, v216, v217
	v_cvt_pk_bf16_f32 v211, v218, v219
	s_add_u32 s8, s8, 0x40000
	s_addc_u32 s9, s9, 0
	s_waitcnt vmcnt(4)
	s_barrier
	s_sub_u32 s36, s36, 1
	s_cmp_lg_u32 s36, 0
	s_cbranch_scc1 .LatB_loop
	s_sub_u32 s10, s10, 1
	s_cbranch_scc1 .LatB_evs_x4

; #define VREADS1(arr, d_) do { const unsigned ad_ = vbase ^ (unsigned)((d_) << 6); __builtin_amdgcn_sched_barrier(0); \
;         _Pragma("unroll") for (int ks_ = 0; ks_ < 4; ++ks_) { VTR(arr[ks_ * 2], ad_, ks_ * 4096); VTR(arr[ks_ * 2 + 1], ad_, ks_ * 4096 + 2048); } __builtin_amdgcn_sched_barrier(0); } while (0)
; #define PV1(arr, d_) do { _Pragma("unroll") for (int ks_ = 0; ks_ < 4; ++ks_) { const s16x4 lo_ = arr[ks_ * 2], hh_ = arr[ks_ * 2 + 1]; \
;         const bf16x8 bv_ = (bf16x8){lo_[0], lo_[1], lo_[2], lo_[3], hh_[0], hh_[1], hh_[2], hh_[3]}; \
;         O[d_] = __builtin_amdgcn_mfma_f32_32x32x16_bf16(pa[ks_], bv_, O[d_], 0, 0, 0); } __builtin_amdgcn_sched_barrier(0); } while (0)
; #define LGKM0() do { __builtin_amdgcn_sched_barrier(0); asm volatile("s_waitcnt lgkmcnt(0)" ::: "memory"); __builtin_amdgcn_sched_barrier(0); } while (0)
; __device__ __forceinline__ void attn_unit(LAS unsigned char* lds, const bf16_t* Z, bf16_t* A2, const float* tabg, int seq_base, int S, int h, int qb, float lam) {
;     ...
; #pragma unroll
;         for (int r = 0; r < 16; ++r) { p0[r] = __builtin_amdgcn_exp2f(p0[r]); p1[r] = __builtin_amdgcn_exp2f(p1[r]); }
; #pragma unroll
;         for (int r = 0; r < 16; r += 2) { ls2 += (f32x2){p0[r], p0[r + 1]}; ls2 += (f32x2){p1[r], p1[r + 1]}; }
;         bf16x8 pa[4]; pa[0] = pack8(p0, 0); pa[1] = pack8(p0, 8); pa[2] = pack8(p1, 0); pa[3] = pack8(p1, 8);
;         LGKM0(); VREADS1(vb, 1); PV1(va, 0); LGKM0(); VREADS1(va, 2); PV1(vb, 1); LGKM0(); VREADS1(vb, 3); PV1(va, 2); LGKM0(); PV1(vb, 3);
;     ...
;         if (t + 2 < NT) asm volatile("s_waitcnt vmcnt(4) lgkmcnt(0)" ::: "memory"); else asm volatile("s_waitcnt vmcnt(0) lgkmcnt(0)" ::: "memory");
;         __builtin_amdgcn_s_barrier(); asm volatile("" ::: "memory");
;         bc = (bc == NST - 1) ? 0 : bc + 1; bn = (bn == NST - 1) ? 0 : bn + 1;
;     }
.LatB_rareret_x3:
	s_waitcnt lgkmcnt(12)
	v_mfma_f32_32x32x16_bf16 v[20:35], v[88:91], v[220:223], v[20:35]
	ds_read_b64_tr_b16 v[144:145], v231 offset:8192
	ds_read_b64_tr_b16 v[146:147], v231 offset:10240
	v_exp_f32_e32 v188, v188
	v_exp_f32_e32 v189, v189
	v_exp_f32_e32 v190, v190
	s_waitcnt lgkmcnt(12)
	v_mfma_f32_32x32x16_bf16 v[36:51], v[88:91], v[224:227], v[36:51]
	ds_read_b64_tr_b16 v[220:221], v228 offset:12288
	ds_read_b64_tr_b16 v[222:223], v228 offset:14336
	v_exp_f32_e32 v191, v191
	v_pk_add_f32 v[150:151], v[150:151], v[188:189]
	s_waitcnt lgkmcnt(12)
	v_mfma_f32_32x32x16_bf16 v[52:67], v[88:91], v[232:235], v[52:67]
	ds_read_b64_tr_b16 v[224:225], v229 offset:12288
	ds_read_b64_tr_b16 v[226:227], v229 offset:14336
	v_pk_add_f32 v[150:151], v[150:151], v[190:191]
	v_exp_f32_e32 v192, v192
	v_exp_f32_e32 v193, v193
	v_cvt_pk_bf16_f32 v188, v188, v189
	s_waitcnt lgkmcnt(12)
	s_add_u32 m0, s27, 0xd000
	v_mfma_f32_32x32x16_bf16 v[68:83], v[88:91], v[236:239], v[68:83]
	global_load_lds_dwordx4 v174, s[8:9]
	ds_read_b64_tr_b16 v[232:233], v230 offset:12288
	ds_read_b64_tr_b16 v[234:235], v230 offset:14336
	v_cvt_pk_bf16_f32 v189, v190, v191
	v_exp_f32_e32 v194, v194
	v_exp_f32_e32 v195, v195
	s_waitcnt lgkmcnt(12)
	v_mfma_f32_32x32x16_bf16 v[20:35], v[100:103], v[132:135], v[20:35]
	ds_read_b64_tr_b16 v[236:237], v231 offset:12288
	ds_read_b64_tr_b16 v[238:239], v231 offset:14336
	v_pk_add_f32 v[150:151], v[150:151], v[192:193]
	v_pk_add_f32 v[150:151], v[150:151], v[194:195]
	v_cvt_pk_bf16_f32 v190, v192, v193
	v_cvt_pk_bf16_f32 v191, v194, v195
	s_waitcnt lgkmcnt(12)
	v_mfma_f32_32x32x16_bf16 v[36:51], v[100:103], v[136:139], v[36:51]
	ds_read_b128 v[132:135], v19 offset:32768
	v_exp_f32_e32 v196, v196
	v_exp_f32_e32 v197, v197
	v_exp_f32_e32 v198, v198
	s_waitcnt lgkmcnt(11)
	v_mfma_f32_32x32x16_bf16 v[52:67], v[100:103], v[140:143], v[52:67]
	ds_read_b128 v[136:139], v19 offset:40960
	v_exp_f32_e32 v199, v199
	v_pk_add_f32 v[150:151], v[150:151], v[196:197]
	s_waitcnt lgkmcnt(10)
	v_mfma_f32_32x32x16_bf16 v[68:83], v[100:103], v[144:147], v[68:83]
	ds_read_b128 v[140:143], v180 offset:32768
	v_pk_add_f32 v[150:151], v[150:151], v[198:199]
	v_exp_f32_e32 v200, v200
	v_exp_f32_e32 v201, v201
	v_cvt_pk_bf16_f32 v192, v196, v197
	s_waitcnt lgkmcnt(9)
	v_mfma_f32_32x32x16_bf16 v[20:35], v[104:107], v[220:223], v[20:35]
	ds_read_b128 v[144:147], v180 offset:40960
	v_cvt_pk_bf16_f32 v193, v198, v199
	v_exp_f32_e32 v202, v202
	v_exp_f32_e32 v203, v203
	s_waitcnt lgkmcnt(8)
	v_mfma_f32_32x32x16_bf16 v[36:51], v[104:107], v[224:227], v[36:51]
	ds_read_b128 v[220:223], v181 offset:32768
	v_pk_add_f32 v[150:151], v[150:151], v[200:201]
	v_pk_add_f32 v[150:151], v[150:151], v[202:203]
	v_cvt_pk_bf16_f32 v194, v200, v201
	v_cvt_pk_bf16_f32 v195, v202, v203
	s_waitcnt lgkmcnt(7)
	v_mfma_f32_32x32x16_bf16 v[52:67], v[104:107], v[232:235], v[52:67]
	ds_read_b128 v[224:227], v181 offset:40960
	v_exp_f32_e32 v204, v204
	v_exp_f32_e32 v205, v205
	v_exp_f32_e32 v206, v206
	s_waitcnt lgkmcnt(6)
	s_add_u32 m0, s27, 0xf000
	v_mfma_f32_32x32x16_bf16 v[68:83], v[104:107], v[236:239], v[68:83]
	global_load_lds_dwordx4 v175, s[8:9]
	ds_read_b128 v[232:235], v182 offset:32768
	v_exp_f32_e32 v207, v207
	v_pk_add_f32 v[150:151], v[150:151], v[204:205]
	s_waitcnt lgkmcnt(6)
	v_mfma_f32_32x32x16_bf16 v[84:99], v[132:135], v[116:119], v[2:17]
	ds_read_b128 v[236:239], v182 offset:40960
	v_pk_add_f32 v[150:151], v[150:151], v[206:207]
	v_exp_f32_e32 v208, v208
	v_exp_f32_e32 v209, v209
	v_cvt_pk_bf16_f32 v204, v204, v205
	s_waitcnt lgkmcnt(6)
	v_mfma_f32_32x32x16_bf16 v[100:115], v[136:139], v[116:119], v[2:17]
	ds_read_b64_tr_b16 v[132:133], v228 offset:16384
	ds_read_b64_tr_b16 v[134:135], v228 offset:18432
	v_cvt_pk_bf16_f32 v205, v206, v207
	v_exp_f32_e32 v210, v210
	v_exp_f32_e32 v211, v211
	s_waitcnt lgkmcnt(7)
	v_mfma_f32_32x32x16_bf16 v[84:99], v[140:143], v[120:123], v[84:99]
	ds_read_b64_tr_b16 v[136:137], v229 offset:16384
	ds_read_b64_tr_b16 v[138:139], v229 offset:18432
	v_pk_add_f32 v[150:151], v[150:151], v[208:209]
	v_pk_add_f32 v[150:151], v[150:151], v[210:211]
	v_cvt_pk_bf16_f32 v206, v208, v209
	v_cvt_pk_bf16_f32 v207, v210, v211
	s_waitcnt lgkmcnt(8)
	v_mfma_f32_32x32x16_bf16 v[100:115], v[144:147], v[120:123], v[100:115]
	ds_read_b64_tr_b16 v[140:141], v230 offset:16384
	ds_read_b64_tr_b16 v[142:143], v230 offset:18432
	v_exp_f32_e32 v212, v212
	v_exp_f32_e32 v213, v213
	v_exp_f32_e32 v214, v214
	s_waitcnt lgkmcnt(9)
	v_mfma_f32_32x32x16_bf16 v[84:99], v[220:223], v[124:127], v[84:99]
	ds_read_b64_tr_b16 v[144:145], v231 offset:16384
	ds_read_b64_tr_b16 v[146:147], v231 offset:18432
	v_exp_f32_e32 v215, v215
	v_pk_add_f32 v[150:151], v[150:151], v[212:213]
	s_waitcnt lgkmcnt(10)
	v_mfma_f32_32x32x16_bf16 v[100:115], v[224:227], v[124:127], v[100:115]
	ds_read_b64_tr_b16 v[220:221], v228 offset:20480
	ds_read_b64_tr_b16 v[222:223], v228 offset:22528
	v_pk_add_f32 v[150:151], v[150:151], v[214:215]
	v_exp_f32_e32 v216, v216
	v_exp_f32_e32 v217, v217
	v_cvt_pk_bf16_f32 v208, v212, v213
	s_waitcnt lgkmcnt(11)
	v_mfma_f32_32x32x16_bf16 v[84:99], v[232:235], v[128:131], v[84:99]
	ds_read_b64_tr_b16 v[224:225], v229 offset:20480
	ds_read_b64_tr_b16 v[226:227], v229 offset:22528
	v_cvt_pk_bf16_f32 v209, v214, v215
	v_exp_f32_e32 v218, v218
	v_exp_f32_e32 v219, v219
	s_waitcnt lgkmcnt(12)
	v_mfma_f32_32x32x16_bf16 v[100:115], v[236:239], v[128:131], v[100:115]
	ds_read_b64_tr_b16 v[232:233], v230 offset:20480
	ds_read_b64_tr_b16 v[234:235], v230 offset:22528
	v_pk_add_f32 v[150:151], v[150:151], v[216:217]
	v_pk_add_f32 v[150:151], v[150:151], v[218:219]
	v_cvt_pk_bf16_f32 v210, v216, v217
	v_cvt_pk_bf16_f32 v211, v218, v219
	s_add_u32 s8, s8, 0x40000
	s_addc_u32 s9, s9, 0
	s_waitcnt vmcnt(2)
	s_barrier
	s_sub_u32 s10, s10, 1
	s_cbranch_scc1 .LatB_evs_x2

; #define LAS __attribute__((address_space(3)))
; __device__ __forceinline__ float max2f(float a, float b) { float r; asm("v_max_f32_e32 %0, %1, %2" : "=v"(r) : "v"(a), "v"(b)); return r; }
; __device__ __forceinline__ void attn_unit(LAS unsigned char* lds, const bf16_t* Z, bf16_t* A2, const float* tabg, int seq_base, int S, int h, int qb, float lam) {
;     ...
;         if (first || __any(mx > THR)) {
;             { auto rr = __builtin_amdgcn_permlane32_swap(__float_as_uint(mx), __float_as_uint(mx), false, false); mx = max2f(__uint_as_float(rr[0]), __uint_as_float(rr[1])); }
;             const float delta = first ? mx : fmaxf(mx, 0.f);
;             const float alpha = first ? 1.0f : __builtin_amdgcn_exp2f(-delta);
;             mu += delta; ls2 *= alpha;
;             if (!first) {
;                 asm volatile("" ::: "memory");
;                 scr[r32] = alpha;
;                 asm volatile("s_waitcnt lgkmcnt(0)" ::: "memory");
; #pragma unroll
;                 for (int g = 0; g < 4; ++g) { const f32x4 a4 = *(const LAS f32x4*)(scr + 8 * g + 4 * hi);
; #pragma unroll
;                     for (int d = 0; d < 4; ++d) { O[d][4 * g + 0] *= a4[0]; O[d][4 * g + 1] *= a4[1]; O[d][4 * g + 2] *= a4[2]; O[d][4 * g + 3] *= a4[3]; } }
;                 asm volatile("s_waitcnt lgkmcnt(0)" ::: "memory");
;             }
; #pragma unroll
;             for (int r = 0; r < 16; ++r) { p0[r] -= delta; p1[r] -= delta; }
;             asm volatile("" : "+v"(p0), "+v"(p1));
;         }
.LatB_evs_m1:
	s_mov_b32 s22, 2
	s_branch .LatB_ev_11
.LatB_rs_m1:
	s_mov_b32 s22, 1
	s_branch .LatB_rare_1114
.LatB_evs_m2:
	s_mov_b32 s22, 2
	s_branch .LatB_ev_01
.LatB_rs_m2:
	s_mov_b32 s22, 1
	s_branch .LatB_rare_2114

; #define LAS __attribute__((address_space(3)))
; __device__ __forceinline__ float max2f(float a, float b) { float r; asm("v_max_f32_e32 %0, %1, %2" : "=v"(r) : "v"(a), "v"(b)); return r; }
; __device__ __forceinline__ void attn_unit(LAS unsigned char* lds, const bf16_t* Z, bf16_t* A2, const float* tabg, int seq_base, int S, int h, int qb, float lam) {
;     ...
;         if (first || __any(mx > THR)) {
;             { auto rr = __builtin_amdgcn_permlane32_swap(__float_as_uint(mx), __float_as_uint(mx), false, false); mx = max2f(__uint_as_float(rr[0]), __uint_as_float(rr[1])); }
;             const float delta = first ? mx : fmaxf(mx, 0.f);
;             const float alpha = first ? 1.0f : __builtin_amdgcn_exp2f(-delta);
;             mu += delta; ls2 *= alpha;
;             if (!first) {
;                 asm volatile("" ::: "memory");
;                 scr[r32] = alpha;
;                 asm volatile("s_waitcnt lgkmcnt(0)" ::: "memory");
; #pragma unroll
;                 for (int g = 0; g < 4; ++g) { const f32x4 a4 = *(const LAS f32x4*)(scr + 8 * g + 4 * hi);
; #pragma unroll
;                     for (int d = 0; d < 4; ++d) { O[d][4 * g + 0] *= a4[0]; O[d][4 * g + 1] *= a4[1]; O[d][4 * g + 2] *= a4[2]; O[d][4 * g + 3] *= a4[3]; } }
;                 asm volatile("s_waitcnt lgkmcnt(0)" ::: "memory");
;             }
; #pragma unroll
;             for (int r = 0; r < 16; ++r) { p0[r] -= delta; p1[r] -= delta; }
;             asm volatile("" : "+v"(p0), "+v"(p1));
;         }
.LatB_evs_x3:
	s_mov_b32 s22, 4
	s_branch .LatB_ev_11
.LatB_rs_x3:
	s_mov_b32 s22, 2
	s_branch .LatB_rare_1114
.LatB_evs_x2:
	s_mov_b32 s22, 4
	s_branch .LatB_ev_01
.LatB_rs_x2:
	s_mov_b32 s22, 2
	s_branch .LatB_rare_2114

; #define LAS __attribute__((address_space(3)))
; __device__ __forceinline__ void attn_unit(LAS unsigned char* lds, const bf16_t* Z, bf16_t* A2, const float* tabg, int seq_base, int S, int h, int qb, float lam) {
;     ...
;         if (near) {
;             const LAS float* tp = tab + (kv0 + 4 * hi - (qlo + r32) + 224);
; #pragma unroll
;             for (int r = 0; r < 16; ++r) { p0[r] += tp[(r & 3) + 8 * (r >> 2)]; p1[r] += tp[32 + (r & 3) + 8 * (r >> 2)]; }
;         }
.LatB_ev_11:
	s_sub_u32 s5, s8, s4
	s_lshr_b32 s5, s5, 12
	s_sub_u32 s5, s5, 64
	s_cmp_ge_u32 s5, s11
	s_cselect_b32 s24, 1, 0
	s_cmp_le_u32 s5, s31
	s_cselect_b32 s29, 1, 0
	s_and_b32 s24, s24, s29
	s_add_u32 s29, s5, 64
	s_cmp_le_u32 s29, s31
	s_cselect_b32 s10, 0, 0x7fffffff
	s_cmp_eq_u32 s24, 0
	s_cbranch_scc1 .LatB_evnn_11
	s_lshl_b32 s29, s5, 2
	s_add_i32 s29, s29, 0x18b80
	v_add_u32_e32 v187, s29, v162
	ds_read2_b32 v[92:93], v187 offset0:0 offset1:1
	ds_read2_b32 v[94:95], v187 offset0:2 offset1:3
	ds_read2_b32 v[96:97], v187 offset0:8 offset1:9
	ds_read2_b32 v[98:99], v187 offset0:10 offset1:11
	ds_read2_b32 v[108:109], v187 offset0:16 offset1:17
	ds_read2_b32 v[110:111], v187 offset0:18 offset1:19
	ds_read2_b32 v[112:113], v187 offset0:24 offset1:25
	ds_read2_b32 v[114:115], v187 offset0:26 offset1:27
	s_waitcnt lgkmcnt(0)
	v_pk_add_f32 v[188:189], v[188:189], v[92:93]
	v_pk_add_f32 v[190:191], v[190:191], v[94:95]
	v_pk_add_f32 v[192:193], v[192:193], v[96:97]
	v_pk_add_f32 v[194:195], v[194:195], v[98:99]
	v_pk_add_f32 v[196:197], v[196:197], v[108:109]
	v_pk_add_f32 v[198:199], v[198:199], v[110:111]
	v_pk_add_f32 v[200:201], v[200:201], v[112:113]
	v_pk_add_f32 v[202:203], v[202:203], v[114:115]
	ds_read2_b32 v[92:93], v187 offset0:32 offset1:33
	ds_read2_b32 v[94:95], v187 offset0:34 offset1:35
	ds_read2_b32 v[96:97], v187 offset0:40 offset1:41
	ds_read2_b32 v[98:99], v187 offset0:42 offset1:43
	ds_read2_b32 v[108:109], v187 offset0:48 offset1:49
	ds_read2_b32 v[110:111], v187 offset0:50 offset1:51
	ds_read2_b32 v[112:113], v187 offset0:56 offset1:57
	ds_read2_b32 v[114:115], v187 offset0:58 offset1:59
	s_waitcnt lgkmcnt(0)
	v_pk_add_f32 v[204:205], v[204:205], v[92:93]
	v_pk_add_f32 v[206:207], v[206:207], v[94:95]
	v_pk_add_f32 v[208:209], v[208:209], v[96:97]
	v_pk_add_f32 v[210:211], v[210:211], v[98:99]
	v_pk_add_f32 v[212:213], v[212:213], v[108:109]
	v_pk_add_f32 v[214:215], v[214:215], v[110:111]
	v_pk_add_f32 v[216:217], v[216:217], v[112:113]
	v_pk_add_f32 v[218:219], v[218:219], v[114:115]

; #define LAS __attribute__((address_space(3)))
; __device__ __forceinline__ void attn_unit(LAS unsigned char* lds, const bf16_t* Z, bf16_t* A2, const float* tabg, int seq_base, int S, int h, int qb, float lam) {
;     ...
;         if (near) {
;             const LAS float* tp = tab + (kv0 + 4 * hi - (qlo + r32) + 224);
; #pragma unroll
;             for (int r = 0; r < 16; ++r) { p0[r] += tp[(r & 3) + 8 * (r >> 2)]; p1[r] += tp[32 + (r & 3) + 8 * (r >> 2)]; }
;         }
.LatB_evdisp_11:
	s_cmp_eq_u32 s22, 0
	s_cbranch_scc1 .LatB_evret_h1
	s_cmp_eq_u32 s22, 1
	s_cbranch_scc1 .LatB_evret_h3
	s_cmp_eq_u32 s22, 2
	s_cbranch_scc1 .LatB_evret_m1
	s_cmp_eq_u32 s22, 3
	s_cbranch_scc1 .LatB_evret_m3
	s_branch .LatB_evret_x3
.LatB_ev_01:
	s_sub_u32 s5, s8, s4
	s_lshr_b32 s5, s5, 12
	s_sub_u32 s5, s5, 64
	s_cmp_ge_u32 s5, s11
	s_cselect_b32 s24, 1, 0
	s_cmp_le_u32 s5, s31
	s_cselect_b32 s29, 1, 0
	s_and_b32 s24, s24, s29
	s_add_u32 s29, s5, 64
	s_cmp_le_u32 s29, s31
	s_cselect_b32 s10, 0, 0x7fffffff
	s_cmp_eq_u32 s24, 0
	s_cbranch_scc1 .LatB_evnn_01
	s_lshl_b32 s29, s5, 2
	s_add_i32 s29, s29, 0x18b80
	v_add_u32_e32 v187, s29, v162
	ds_read2_b32 v[196:197], v187 offset0:0 offset1:1
	ds_read2_b32 v[198:199], v187 offset0:2 offset1:3
	ds_read2_b32 v[200:201], v187 offset0:8 offset1:9
	ds_read2_b32 v[202:203], v187 offset0:10 offset1:11
	ds_read2_b32 v[212:213], v187 offset0:16 offset1:17
	ds_read2_b32 v[214:215], v187 offset0:18 offset1:19
	ds_read2_b32 v[216:217], v187 offset0:24 offset1:25
	ds_read2_b32 v[218:219], v187 offset0:26 offset1:27
	s_waitcnt lgkmcnt(0)
	v_pk_add_f32 v[84:85], v[84:85], v[196:197]
	v_pk_add_f32 v[86:87], v[86:87], v[198:199]
	v_pk_add_f32 v[88:89], v[88:89], v[200:201]
	v_pk_add_f32 v[90:91], v[90:91], v[202:203]
	v_pk_add_f32 v[92:93], v[92:93], v[212:213]
	v_pk_add_f32 v[94:95], v[94:95], v[214:215]
	v_pk_add_f32 v[96:97], v[96:97], v[216:217]
	v_pk_add_f32 v[98:99], v[98:99], v[218:219]
	ds_read2_b32 v[196:197], v187 offset0:32 offset1:33
	ds_read2_b32 v[198:199], v187 offset0:34 offset1:35
	ds_read2_b32 v[200:201], v187 offset0:40 offset1:41
	ds_read2_b32 v[202:203], v187 offset0:42 offset1:43
	ds_read2_b32 v[212:213], v187 offset0:48 offset1:49
	ds_read2_b32 v[214:215], v187 offset0:50 offset1:51
	ds_read2_b32 v[216:217], v187 offset0:56 offset1:57
	ds_read2_b32 v[218:219], v187 offset0:58 offset1:59
	s_waitcnt lgkmcnt(0)
	v_pk_add_f32 v[100:101], v[100:101], v[196:197]
	v_pk_add_f32 v[102:103], v[102:103], v[198:199]
	v_pk_add_f32 v[104:105], v[104:105], v[200:201]
	v_pk_add_f32 v[106:107], v[106:107], v[202:203]
	v_pk_add_f32 v[108:109], v[108:109], v[212:213]
	v_pk_add_f32 v[110:111], v[110:111], v[214:215]
	v_pk_add_f32 v[112:113], v[112:113], v[216:217]
	v_pk_add_f32 v[114:115], v[114:115], v[218:219]

; #define LAS __attribute__((address_space(3)))
; __device__ __forceinline__ float max2f(float a, float b) { float r; asm("v_max_f32_e32 %0, %1, %2" : "=v"(r) : "v"(a), "v"(b)); return r; }
; __device__ __forceinline__ void attn_unit(LAS unsigned char* lds, const bf16_t* Z, bf16_t* A2, const float* tabg, int seq_base, int S, int h, int qb, float lam) {
;     ...
;         if (first || __any(mx > THR)) {
;             { auto rr = __builtin_amdgcn_permlane32_swap(__float_as_uint(mx), __float_as_uint(mx), false, false); mx = max2f(__uint_as_float(rr[0]), __uint_as_float(rr[1])); }
;             const float delta = first ? mx : fmaxf(mx, 0.f);
;             const float alpha = first ? 1.0f : __builtin_amdgcn_exp2f(-delta);
;             mu += delta; ls2 *= alpha;
;             if (!first) {
;                 asm volatile("" ::: "memory");
;                 scr[r32] = alpha;
;                 asm volatile("s_waitcnt lgkmcnt(0)" ::: "memory");
; #pragma unroll
;                 for (int g = 0; g < 4; ++g) { const f32x4 a4 = *(const LAS f32x4*)(scr + 8 * g + 4 * hi);
; #pragma unroll
;                     for (int d = 0; d < 4; ++d) { O[d][4 * g + 0] *= a4[0]; O[d][4 * g + 1] *= a4[1]; O[d][4 * g + 2] *= a4[2]; O[d][4 * g + 3] *= a4[3]; } }
;                 asm volatile("s_waitcnt lgkmcnt(0)" ::: "memory");
;             }
; #pragma unroll
;             for (int r = 0; r < 16; ++r) { p0[r] -= delta; p1[r] -= delta; }
;             asm volatile("" : "+v"(p0), "+v"(p1));
;         }
.LatB_rare_1114:
	v_mov_b32_e32 v252, v251
	s_nop 1
	v_permlane32_swap_b32_e32 v251, v252
	v_max_f32_e32 v251, v251, v252
	v_max_f32_e32 v253, 0, v251
	v_exp_f32_e64 v254, -v253
	v_add_f32_e32 v186, v186, v253
	s_nop 0
	v_mul_f32_e32 v150, v150, v254
	v_mul_f32_e32 v151, v151, v254
	ds_write_b32 v184, v254
	s_waitcnt lgkmcnt(0)
	v_mfma_f32_32x32x16_bf16 v[20:35], v[88:91], v[220:223], v[20:35]
	v_mfma_f32_32x32x16_bf16 v[36:51], v[88:91], v[224:227], v[36:51]
	v_mfma_f32_32x32x16_bf16 v[52:67], v[88:91], v[232:235], v[52:67]
	v_mfma_f32_32x32x16_bf16 v[68:83], v[88:91], v[236:239], v[68:83]
	v_mfma_f32_32x32x16_bf16 v[20:35], v[100:103], v[132:135], v[20:35]
	v_mfma_f32_32x32x16_bf16 v[36:51], v[100:103], v[136:139], v[36:51]
	v_mfma_f32_32x32x16_bf16 v[52:67], v[100:103], v[140:143], v[52:67]
	ds_read_b64_tr_b16 v[144:145], v231 offset:8192
	ds_read_b64_tr_b16 v[146:147], v231 offset:10240
	ds_read_b64_tr_b16 v[220:221], v228 offset:12288
	ds_read_b64_tr_b16 v[222:223], v228 offset:14336
	ds_read_b64_tr_b16 v[224:225], v229 offset:12288
	ds_read_b64_tr_b16 v[226:227], v229 offset:14336
	ds_read_b64_tr_b16 v[232:233], v230 offset:12288
	ds_read_b64_tr_b16 v[234:235], v230 offset:14336
	ds_read_b64_tr_b16 v[236:237], v231 offset:12288
	ds_read_b64_tr_b16 v[238:239], v231 offset:14336
	s_waitcnt lgkmcnt(0)
	v_mfma_f32_32x32x16_bf16 v[68:83], v[100:103], v[144:147], v[68:83]
	v_mfma_f32_32x32x16_bf16 v[20:35], v[104:107], v[220:223], v[20:35]
	v_mfma_f32_32x32x16_bf16 v[36:51], v[104:107], v[224:227], v[36:51]
	v_mfma_f32_32x32x16_bf16 v[52:67], v[104:107], v[232:235], v[52:67]
	v_mfma_f32_32x32x16_bf16 v[68:83], v[104:107], v[236:239], v[68:83]
	ds_read_b128 v[92:95], v185
	ds_read_b128 v[96:99], v185 offset:32
	ds_read_b128 v[108:111], v185 offset:64
	ds_read_b128 v[112:115], v185 offset:96
	s_waitcnt lgkmcnt(0)
	s_nop 15
	s_nop 15
	v_pk_mul_f32 v[20:21], v[20:21], v[92:93]
	v_pk_mul_f32 v[22:23], v[22:23], v[94:95]
	v_pk_mul_f32 v[24:25], v[24:25], v[96:97]
	v_pk_mul_f32 v[26:27], v[26:27], v[98:99]
	v_pk_mul_f32 v[28:29], v[28:29], v[108:109]
	v_pk_mul_f32 v[30:31], v[30:31], v[110:111]
	v_pk_mul_f32 v[32:33], v[32:33], v[112:113]
	v_pk_mul_f32 v[34:35], v[34:35], v[114:115]
	v_pk_mul_f32 v[36:37], v[36:37], v[92:93]
	v_pk_mul_f32 v[38:39], v[38:39], v[94:95]
	v_pk_mul_f32 v[40:41], v[40:41], v[96:97]
	v_pk_mul_f32 v[42:43], v[42:43], v[98:99]
	v_pk_mul_f32 v[44:45], v[44:45], v[108:109]
	v_pk_mul_f32 v[46:47], v[46:47], v[110:111]
	v_pk_mul_f32 v[48:49], v[48:49], v[112:113]
	v_pk_mul_f32 v[50:51], v[50:51], v[114:115]
	v_pk_mul_f32 v[52:53], v[52:53], v[92:93]
	v_pk_mul_f32 v[54:55], v[54:55], v[94:95]
	v_pk_mul_f32 v[56:57], v[56:57], v[96:97]
	v_pk_mul_f32 v[58:59], v[58:59], v[98:99]
	v_pk_mul_f32 v[60:61], v[60:61], v[108:109]
	v_pk_mul_f32 v[62:63], v[62:63], v[110:111]
	v_pk_mul_f32 v[64:65], v[64:65], v[112:113]
	v_pk_mul_f32 v[66:67], v[66:67], v[114:115]
	v_pk_mul_f32 v[68:69], v[68:69], v[92:93]
	v_pk_mul_f32 v[70:71], v[70:71], v[94:95]
	v_pk_mul_f32 v[72:73], v[72:73], v[96:97]
	v_pk_mul_f32 v[74:75], v[74:75], v[98:99]
	v_pk_mul_f32 v[76:77], v[76:77], v[108:109]
	v_pk_mul_f32 v[78:79], v[78:79], v[110:111]
	v_pk_mul_f32 v[80:81], v[80:81], v[112:113]
	v_pk_mul_f32 v[82:83], v[82:83], v[114:115]
	v_mov_b32_e32 v252, v253
	v_pk_add_f32 v[188:189], v[188:189], v[252:253] neg_lo:[0,1] neg_hi:[0,1]
	v_pk_add_f32 v[190:191], v[190:191], v[252:253] neg_lo:[0,1] neg_hi:[0,1]
	v_pk_add_f32 v[192:193], v[192:193], v[252:253] neg_lo:[0,1] neg_hi:[0,1]
	v_pk_add_f32 v[194:195], v[194:195], v[252:253] neg_lo:[0,1] neg_hi:[0,1]
	v_pk_add_f32 v[196:197], v[196:197], v[252:253] neg_lo:[0,1] neg_hi:[0,1]
	v_pk_add_f32 v[198:199], v[198:199], v[252:253] neg_lo:[0,1] neg_hi:[0,1]
	v_pk_add_f32 v[200:201], v[200:201], v[252:253] neg_lo:[0,1] neg_hi:[0,1]
	v_pk_add_f32 v[202:203], v[202:203], v[252:253] neg_lo:[0,1] neg_hi:[0,1]
	v_pk_add_f32 v[204:205], v[204:205], v[252:253] neg_lo:[0,1] neg_hi:[0,1]
	v_pk_add_f32 v[206:207], v[206:207], v[252:253] neg_lo:[0,1] neg_hi:[0,1]
	v_pk_add_f32 v[208:209], v[208:209], v[252:253] neg_lo:[0,1] neg_hi:[0,1]
	v_pk_add_f32 v[210:211], v[210:211], v[252:253] neg_lo:[0,1] neg_hi:[0,1]
	v_pk_add_f32 v[212:213], v[212:213], v[252:253] neg_lo:[0,1] neg_hi:[0,1]
	v_pk_add_f32 v[214:215], v[214:215], v[252:253] neg_lo:[0,1] neg_hi:[0,1]
	v_pk_add_f32 v[216:217], v[216:217], v[252:253] neg_lo:[0,1] neg_hi:[0,1]
	v_pk_add_f32 v[218:219], v[218:219], v[252:253] neg_lo:[0,1] neg_hi:[0,1]
	v_mov_b64_e32 v[84:85], 0
	v_mov_b64_e32 v[86:87], 0
	v_mov_b64_e32 v[88:89], 0
	v_mov_b64_e32 v[90:91], 0
	v_mov_b64_e32 v[100:101], 0
	v_mov_b64_e32 v[102:103], 0
	v_mov_b64_e32 v[104:105], 0
	v_mov_b64_e32 v[106:107], 0
	s_sub_u32 s5, s8, s4
	s_lshr_b32 s5, s5, 12
	s_sub_u32 s5, s5, 64
	s_add_u32 s29, s5, 64
	s_cmp_lt_u32 s29, s11
	s_cselect_b32 s24, 1, 0
	s_cmp_gt_u32 s29, s31
	s_cselect_b32 s30, 2, 0
	s_or_b32 s24, s24, s30
	s_mov_b32 s35, s24
	v_mov_b32_e32 v251, 0
	s_cmp_eq_u32 s24, 1
	s_cselect_b64 vcc, -1, 0
	v_cndmask_b32_e32 v251, v251, v177, vcc
	s_cmp_eq_u32 s24, 2
	s_cselect_b64 vcc, -1, 0
	v_cndmask_b32_e32 v251, v251, v178, vcc
	v_sub_f32_e32 v2, v251, v186
	v_mov_b32_e32 v3, v2
	v_mov_b64_e32 v[4:5], v[2:3]
	v_mov_b64_e32 v[6:7], v[2:3]
	v_mov_b64_e32 v[8:9], v[2:3]
	v_mov_b64_e32 v[10:11], v[2:3]
	v_mov_b64_e32 v[12:13], v[2:3]
	v_mov_b64_e32 v[14:15], v[2:3]
	v_mov_b64_e32 v[16:17], v[2:3]
	s_nop 1
	s_cmp_eq_u32 s22, 0
	s_cbranch_scc1 .LatB_rareret_h1
	s_cmp_eq_u32 s22, 1
	s_cbranch_scc1 .LatB_rareret_m1
	s_branch .LatB_rareret_x3
; #define LAS __attribute__((address_space(3)))
; __device__ __forceinline__ float max2f(float a, float b) { float r; asm("v_max_f32_e32 %0, %1, %2" : "=v"(r) : "v"(a), "v"(b)); return r; }
; __device__ __forceinline__ void attn_unit(LAS unsigned char* lds, const bf16_t* Z, bf16_t* A2, const float* tabg, int seq_base, int S, int h, int qb, float lam) {
;     ...
;         if (first || __any(mx > THR)) {
;             { auto rr = __builtin_amdgcn_permlane32_swap(__float_as_uint(mx), __float_as_uint(mx), false, false); mx = max2f(__uint_as_float(rr[0]), __uint_as_float(rr[1])); }
;             const float delta = first ? mx : fmaxf(mx, 0.f);
;             const float alpha = first ? 1.0f : __builtin_amdgcn_exp2f(-delta);
;             mu += delta; ls2 *= alpha;
;             if (!first) {
;                 asm volatile("" ::: "memory");
;                 scr[r32] = alpha;
;                 asm volatile("s_waitcnt lgkmcnt(0)" ::: "memory");
; #pragma unroll
;                 for (int g = 0; g < 4; ++g) { const f32x4 a4 = *(const LAS f32x4*)(scr + 8 * g + 4 * hi);
; #pragma unroll
;                     for (int d = 0; d < 4; ++d) { O[d][4 * g + 0] *= a4[0]; O[d][4 * g + 1] *= a4[1]; O[d][4 * g + 2] *= a4[2]; O[d][4 * g + 3] *= a4[3]; } }
;                 asm volatile("s_waitcnt lgkmcnt(0)" ::: "memory");
;             }
; #pragma unroll
;             for (int r = 0; r < 16; ++r) { p0[r] -= delta; p1[r] -= delta; }
;             asm volatile("" : "+v"(p0), "+v"(p1));
;         }
.LatB_rare_2114:
	v_mov_b32_e32 v252, v251
	s_nop 1
	v_permlane32_swap_b32_e32 v251, v252
	v_max_f32_e32 v251, v251, v252
	v_max_f32_e32 v253, 0, v251
	v_exp_f32_e64 v254, -v253
	v_add_f32_e32 v186, v186, v253
	s_nop 0
	v_mul_f32_e32 v150, v150, v254
	v_mul_f32_e32 v151, v151, v254
	ds_write_b32 v184, v254
	s_waitcnt lgkmcnt(0)
	v_mfma_f32_32x32x16_bf16 v[20:35], v[192:195], v[220:223], v[20:35]
	v_mfma_f32_32x32x16_bf16 v[36:51], v[192:195], v[224:227], v[36:51]
	v_mfma_f32_32x32x16_bf16 v[52:67], v[192:195], v[232:235], v[52:67]
	v_mfma_f32_32x32x16_bf16 v[68:83], v[192:195], v[236:239], v[68:83]
	v_mfma_f32_32x32x16_bf16 v[20:35], v[204:207], v[132:135], v[20:35]
	v_mfma_f32_32x32x16_bf16 v[36:51], v[204:207], v[136:139], v[36:51]
	v_mfma_f32_32x32x16_bf16 v[52:67], v[204:207], v[140:143], v[52:67]
	ds_read_b64_tr_b16 v[144:145], v231 offset:24576
	ds_read_b64_tr_b16 v[146:147], v231 offset:26624
	ds_read_b64_tr_b16 v[220:221], v228 offset:28672
	ds_read_b64_tr_b16 v[222:223], v228 offset:30720
	ds_read_b64_tr_b16 v[224:225], v229 offset:28672
	ds_read_b64_tr_b16 v[226:227], v229 offset:30720
	ds_read_b64_tr_b16 v[232:233], v230 offset:28672
	ds_read_b64_tr_b16 v[234:235], v230 offset:30720
	ds_read_b64_tr_b16 v[236:237], v231 offset:28672
	ds_read_b64_tr_b16 v[238:239], v231 offset:30720
	s_waitcnt lgkmcnt(0)
	v_mfma_f32_32x32x16_bf16 v[68:83], v[204:207], v[144:147], v[68:83]
	v_mfma_f32_32x32x16_bf16 v[20:35], v[208:211], v[220:223], v[20:35]
	v_mfma_f32_32x32x16_bf16 v[36:51], v[208:211], v[224:227], v[36:51]
	v_mfma_f32_32x32x16_bf16 v[52:67], v[208:211], v[232:235], v[52:67]
	v_mfma_f32_32x32x16_bf16 v[68:83], v[208:211], v[236:239], v[68:83]
	ds_read_b128 v[196:199], v185
	ds_read_b128 v[200:203], v185 offset:32
	ds_read_b128 v[212:215], v185 offset:64
	ds_read_b128 v[216:219], v185 offset:96
	s_waitcnt lgkmcnt(0)
	s_nop 15
	s_nop 15
	v_pk_mul_f32 v[20:21], v[20:21], v[196:197]
	v_pk_mul_f32 v[22:23], v[22:23], v[198:199]
	v_pk_mul_f32 v[24:25], v[24:25], v[200:201]
	v_pk_mul_f32 v[26:27], v[26:27], v[202:203]
	v_pk_mul_f32 v[28:29], v[28:29], v[212:213]
	v_pk_mul_f32 v[30:31], v[30:31], v[214:215]
	v_pk_mul_f32 v[32:33], v[32:33], v[216:217]
	v_pk_mul_f32 v[34:35], v[34:35], v[218:219]
	v_pk_mul_f32 v[36:37], v[36:37], v[196:197]
	v_pk_mul_f32 v[38:39], v[38:39], v[198:199]
	v_pk_mul_f32 v[40:41], v[40:41], v[200:201]
	v_pk_mul_f32 v[42:43], v[42:43], v[202:203]
	v_pk_mul_f32 v[44:45], v[44:45], v[212:213]
	v_pk_mul_f32 v[46:47], v[46:47], v[214:215]
	v_pk_mul_f32 v[48:49], v[48:49], v[216:217]
	v_pk_mul_f32 v[50:51], v[50:51], v[218:219]
	v_pk_mul_f32 v[52:53], v[52:53], v[196:197]
	v_pk_mul_f32 v[54:55], v[54:55], v[198:199]
	v_pk_mul_f32 v[56:57], v[56:57], v[200:201]
	v_pk_mul_f32 v[58:59], v[58:59], v[202:203]
	v_pk_mul_f32 v[60:61], v[60:61], v[212:213]
	v_pk_mul_f32 v[62:63], v[62:63], v[214:215]
	v_pk_mul_f32 v[64:65], v[64:65], v[216:217]
	v_pk_mul_f32 v[66:67], v[66:67], v[218:219]
	v_pk_mul_f32 v[68:69], v[68:69], v[196:197]
	v_pk_mul_f32 v[70:71], v[70:71], v[198:199]
	v_pk_mul_f32 v[72:73], v[72:73], v[200:201]
	v_pk_mul_f32 v[74:75], v[74:75], v[202:203]
	v_pk_mul_f32 v[76:77], v[76:77], v[212:213]
	v_pk_mul_f32 v[78:79], v[78:79], v[214:215]
	v_pk_mul_f32 v[80:81], v[80:81], v[216:217]
	v_pk_mul_f32 v[82:83], v[82:83], v[218:219]
	v_mov_b32_e32 v252, v253
	v_pk_add_f32 v[84:85], v[84:85], v[252:253] neg_lo:[0,1] neg_hi:[0,1]
	v_pk_add_f32 v[86:87], v[86:87], v[252:253] neg_lo:[0,1] neg_hi:[0,1]
	v_pk_add_f32 v[88:89], v[88:89], v[252:253] neg_lo:[0,1] neg_hi:[0,1]
	v_pk_add_f32 v[90:91], v[90:91], v[252:253] neg_lo:[0,1] neg_hi:[0,1]
	v_pk_add_f32 v[92:93], v[92:93], v[252:253] neg_lo:[0,1] neg_hi:[0,1]
	v_pk_add_f32 v[94:95], v[94:95], v[252:253] neg_lo:[0,1] neg_hi:[0,1]
	v_pk_add_f32 v[96:97], v[96:97], v[252:253] neg_lo:[0,1] neg_hi:[0,1]
	v_pk_add_f32 v[98:99], v[98:99], v[252:253] neg_lo:[0,1] neg_hi:[0,1]
	v_pk_add_f32 v[100:101], v[100:101], v[252:253] neg_lo:[0,1] neg_hi:[0,1]
	v_pk_add_f32 v[102:103], v[102:103], v[252:253] neg_lo:[0,1] neg_hi:[0,1]
	v_pk_add_f32 v[104:105], v[104:105], v[252:253] neg_lo:[0,1] neg_hi:[0,1]
	v_pk_add_f32 v[106:107], v[106:107], v[252:253] neg_lo:[0,1] neg_hi:[0,1]
	v_pk_add_f32 v[108:109], v[108:109], v[252:253] neg_lo:[0,1] neg_hi:[0,1]
	v_pk_add_f32 v[110:111], v[110:111], v[252:253] neg_lo:[0,1] neg_hi:[0,1]
	v_pk_add_f32 v[112:113], v[112:113], v[252:253] neg_lo:[0,1] neg_hi:[0,1]
	v_pk_add_f32 v[114:115], v[114:115], v[252:253] neg_lo:[0,1] neg_hi:[0,1]
	v_mov_b64_e32 v[188:189], 0
	v_mov_b64_e32 v[190:191], 0
	v_mov_b64_e32 v[192:193], 0
	v_mov_b64_e32 v[194:195], 0
	v_mov_b64_e32 v[204:205], 0
	v_mov_b64_e32 v[206:207], 0
	v_mov_b64_e32 v[208:209], 0
	v_mov_b64_e32 v[210:211], 0
	s_sub_u32 s5, s8, s4
	s_lshr_b32 s5, s5, 12
	s_sub_u32 s5, s5, 64
	s_add_u32 s29, s5, 64
	s_cmp_lt_u32 s29, s11
	s_cselect_b32 s24, 1, 0
	s_cmp_gt_u32 s29, s31
	s_cselect_b32 s30, 2, 0
	s_or_b32 s24, s24, s30
	s_mov_b32 s35, s24
	v_mov_b32_e32 v251, 0
	s_cmp_eq_u32 s24, 1
	s_cselect_b64 vcc, -1, 0
	v_cndmask_b32_e32 v251, v251, v177, vcc
	s_cmp_eq_u32 s24, 2
	s_cselect_b64 vcc, -1, 0
	v_cndmask_b32_e32 v251, v251, v178, vcc
	v_sub_f32_e32 v2, v251, v186
	v_mov_b32_e32 v3, v2
	v_mov_b64_e32 v[4:5], v[2:3]
	v_mov_b64_e32 v[6:7], v[2:3]
	v_mov_b64_e32 v[8:9], v[2:3]
	v_mov_b64_e32 v[10:11], v[2:3]
	v_mov_b64_e32 v[12:13], v[2:3]
	v_mov_b64_e32 v[14:15], v[2:3]
	v_mov_b64_e32 v[16:17], v[2:3]
	s_nop 1
	s_cmp_eq_u32 s22, 0
	s_cbranch_scc1 .LatB_rareret_h2
	s_cmp_eq_u32 s22, 1
	s_cbranch_scc1 .LatB_rareret_m2
	s_branch .LatB_rareret_x2
; #define LAS __attribute__((address_space(3)))
; __device__ __forceinline__ float max2f(float a, float b) { float r; asm("v_max_f32_e32 %0, %1, %2" : "=v"(r) : "v"(a), "v"(b)); return r; }
; __device__ __forceinline__ void attn_unit(LAS unsigned char* lds, const bf16_t* Z, bf16_t* A2, const float* tabg, int seq_base, int S, int h, int qb, float lam) {
;     ...
;         if (first || __any(mx > THR)) {
;             { auto rr = __builtin_amdgcn_permlane32_swap(__float_as_uint(mx), __float_as_uint(mx), false, false); mx = max2f(__uint_as_float(rr[0]), __uint_as_float(rr[1])); }
;             const float delta = first ? mx : fmaxf(mx, 0.f);
;             const float alpha = first ? 1.0f : __builtin_amdgcn_exp2f(-delta);
;             mu += delta; ls2 *= alpha;
;             if (!first) {
;                 asm volatile("" ::: "memory");
;                 scr[r32] = alpha;
;                 asm volatile("s_waitcnt lgkmcnt(0)" ::: "memory");
; #pragma unroll
;                 for (int g = 0; g < 4; ++g) { const f32x4 a4 = *(const LAS f32x4*)(scr + 8 * g + 4 * hi);
; #pragma unroll
;                     for (int d = 0; d < 4; ++d) { O[d][4 * g + 0] *= a4[0]; O[d][4 * g + 1] *= a4[1]; O[d][4 * g + 2] *= a4[2]; O[d][4 * g + 3] *= a4[3]; } }
;                 asm volatile("s_waitcnt lgkmcnt(0)" ::: "memory");
;             }
; #pragma unroll
;             for (int r = 0; r < 16; ++r) { p0[r] -= delta; p1[r] -= delta; }
;             asm volatile("" : "+v"(p0), "+v"(p1));
;         }
.LatB_rare_3114:
	v_mov_b32_e32 v252, v251
	s_nop 1
	v_permlane32_swap_b32_e32 v251, v252
	v_max_f32_e32 v251, v251, v252
	v_max_f32_e32 v253, 0, v251
	v_exp_f32_e64 v254, -v253
	v_add_f32_e32 v186, v186, v253
	s_nop 0
	v_mul_f32_e32 v150, v150, v254
	v_mul_f32_e32 v151, v151, v254
	ds_write_b32 v184, v254
	s_waitcnt lgkmcnt(0)
	v_mfma_f32_32x32x16_bf16 v[20:35], v[88:91], v[220:223], v[20:35]
	v_mfma_f32_32x32x16_bf16 v[36:51], v[88:91], v[224:227], v[36:51]
	v_mfma_f32_32x32x16_bf16 v[52:67], v[88:91], v[232:235], v[52:67]
	v_mfma_f32_32x32x16_bf16 v[68:83], v[88:91], v[236:239], v[68:83]
	v_mfma_f32_32x32x16_bf16 v[20:35], v[100:103], v[132:135], v[20:35]
	v_mfma_f32_32x32x16_bf16 v[36:51], v[100:103], v[136:139], v[36:51]
	v_mfma_f32_32x32x16_bf16 v[52:67], v[100:103], v[140:143], v[52:67]
	ds_read_b64_tr_b16 v[144:145], v231 offset:40960
	ds_read_b64_tr_b16 v[146:147], v231 offset:43008
	ds_read_b64_tr_b16 v[220:221], v228 offset:45056
	ds_read_b64_tr_b16 v[222:223], v228 offset:47104
	ds_read_b64_tr_b16 v[224:225], v229 offset:45056
	ds_read_b64_tr_b16 v[226:227], v229 offset:47104
	ds_read_b64_tr_b16 v[232:233], v230 offset:45056
	ds_read_b64_tr_b16 v[234:235], v230 offset:47104
	ds_read_b64_tr_b16 v[236:237], v231 offset:45056
	ds_read_b64_tr_b16 v[238:239], v231 offset:47104
	s_waitcnt lgkmcnt(0)
	v_mfma_f32_32x32x16_bf16 v[68:83], v[100:103], v[144:147], v[68:83]
	v_mfma_f32_32x32x16_bf16 v[20:35], v[104:107], v[220:223], v[20:35]
	v_mfma_f32_32x32x16_bf16 v[36:51], v[104:107], v[224:227], v[36:51]
	v_mfma_f32_32x32x16_bf16 v[52:67], v[104:107], v[232:235], v[52:67]
	v_mfma_f32_32x32x16_bf16 v[68:83], v[104:107], v[236:239], v[68:83]
	ds_read_b128 v[92:95], v185
	ds_read_b128 v[96:99], v185 offset:32
	ds_read_b128 v[108:111], v185 offset:64
	ds_read_b128 v[112:115], v185 offset:96
	s_waitcnt lgkmcnt(0)
	s_nop 15
	s_nop 15
	v_pk_mul_f32 v[20:21], v[20:21], v[92:93]
	v_pk_mul_f32 v[22:23], v[22:23], v[94:95]
	v_pk_mul_f32 v[24:25], v[24:25], v[96:97]
	v_pk_mul_f32 v[26:27], v[26:27], v[98:99]
	v_pk_mul_f32 v[28:29], v[28:29], v[108:109]
	v_pk_mul_f32 v[30:31], v[30:31], v[110:111]
	v_pk_mul_f32 v[32:33], v[32:33], v[112:113]
	v_pk_mul_f32 v[34:35], v[34:35], v[114:115]
	v_pk_mul_f32 v[36:37], v[36:37], v[92:93]
	v_pk_mul_f32 v[38:39], v[38:39], v[94:95]
	v_pk_mul_f32 v[40:41], v[40:41], v[96:97]
	v_pk_mul_f32 v[42:43], v[42:43], v[98:99]
	v_pk_mul_f32 v[44:45], v[44:45], v[108:109]
	v_pk_mul_f32 v[46:47], v[46:47], v[110:111]
	v_pk_mul_f32 v[48:49], v[48:49], v[112:113]
	v_pk_mul_f32 v[50:51], v[50:51], v[114:115]
	v_pk_mul_f32 v[52:53], v[52:53], v[92:93]
	v_pk_mul_f32 v[54:55], v[54:55], v[94:95]
	v_pk_mul_f32 v[56:57], v[56:57], v[96:97]
	v_pk_mul_f32 v[58:59], v[58:59], v[98:99]
	v_pk_mul_f32 v[60:61], v[60:61], v[108:109]
	v_pk_mul_f32 v[62:63], v[62:63], v[110:111]
	v_pk_mul_f32 v[64:65], v[64:65], v[112:113]
	v_pk_mul_f32 v[66:67], v[66:67], v[114:115]
	v_pk_mul_f32 v[68:69], v[68:69], v[92:93]
	v_pk_mul_f32 v[70:71], v[70:71], v[94:95]
	v_pk_mul_f32 v[72:73], v[72:73], v[96:97]
	v_pk_mul_f32 v[74:75], v[74:75], v[98:99]
	v_pk_mul_f32 v[76:77], v[76:77], v[108:109]
	v_pk_mul_f32 v[78:79], v[78:79], v[110:111]
	v_pk_mul_f32 v[80:81], v[80:81], v[112:113]
	v_pk_mul_f32 v[82:83], v[82:83], v[114:115]
	v_mov_b32_e32 v252, v253
	v_pk_add_f32 v[188:189], v[188:189], v[252:253] neg_lo:[0,1] neg_hi:[0,1]
	v_pk_add_f32 v[190:191], v[190:191], v[252:253] neg_lo:[0,1] neg_hi:[0,1]
	v_pk_add_f32 v[192:193], v[192:193], v[252:253] neg_lo:[0,1] neg_hi:[0,1]
	v_pk_add_f32 v[194:195], v[194:195], v[252:253] neg_lo:[0,1] neg_hi:[0,1]
	v_pk_add_f32 v[196:197], v[196:197], v[252:253] neg_lo:[0,1] neg_hi:[0,1]
	v_pk_add_f32 v[198:199], v[198:199], v[252:253] neg_lo:[0,1] neg_hi:[0,1]
	v_pk_add_f32 v[200:201], v[200:201], v[252:253] neg_lo:[0,1] neg_hi:[0,1]
	v_pk_add_f32 v[202:203], v[202:203], v[252:253] neg_lo:[0,1] neg_hi:[0,1]
	v_pk_add_f32 v[204:205], v[204:205], v[252:253] neg_lo:[0,1] neg_hi:[0,1]
	v_pk_add_f32 v[206:207], v[206:207], v[252:253] neg_lo:[0,1] neg_hi:[0,1]
	v_pk_add_f32 v[208:209], v[208:209], v[252:253] neg_lo:[0,1] neg_hi:[0,1]
	v_pk_add_f32 v[210:211], v[210:211], v[252:253] neg_lo:[0,1] neg_hi:[0,1]
	v_pk_add_f32 v[212:213], v[212:213], v[252:253] neg_lo:[0,1] neg_hi:[0,1]
	v_pk_add_f32 v[214:215], v[214:215], v[252:253] neg_lo:[0,1] neg_hi:[0,1]
	v_pk_add_f32 v[216:217], v[216:217], v[252:253] neg_lo:[0,1] neg_hi:[0,1]
	v_pk_add_f32 v[218:219], v[218:219], v[252:253] neg_lo:[0,1] neg_hi:[0,1]
	v_mov_b64_e32 v[84:85], 0
	v_mov_b64_e32 v[86:87], 0
	v_mov_b64_e32 v[88:89], 0
	v_mov_b64_e32 v[90:91], 0
	v_mov_b64_e32 v[100:101], 0
	v_mov_b64_e32 v[102:103], 0
	v_mov_b64_e32 v[104:105], 0
	v_mov_b64_e32 v[106:107], 0
	s_sub_u32 s5, s8, s4
	s_lshr_b32 s5, s5, 12
	s_sub_u32 s5, s5, 64
	s_add_u32 s29, s5, 64
	s_cmp_lt_u32 s29, s11
	s_cselect_b32 s24, 1, 0
	s_cmp_gt_u32 s29, s31
	s_cselect_b32 s30, 2, 0
	s_or_b32 s24, s24, s30
	s_mov_b32 s35, s24
	v_mov_b32_e32 v251, 0
	s_cmp_eq_u32 s24, 1
	s_cselect_b64 vcc, -1, 0
	v_cndmask_b32_e32 v251, v251, v177, vcc
	s_cmp_eq_u32 s24, 2
	s_cselect_b64 vcc, -1, 0
	v_cndmask_b32_e32 v251, v251, v178, vcc
	v_sub_f32_e32 v2, v251, v186
	v_mov_b32_e32 v3, v2
	v_mov_b64_e32 v[4:5], v[2:3]
	v_mov_b64_e32 v[6:7], v[2:3]
	v_mov_b64_e32 v[8:9], v[2:3]
	v_mov_b64_e32 v[10:11], v[2:3]
	v_mov_b64_e32 v[12:13], v[2:3]
	v_mov_b64_e32 v[14:15], v[2:3]
	v_mov_b64_e32 v[16:17], v[2:3]
	s_nop 1
	s_cmp_eq_u32 s22, 0
	s_cbranch_scc1 .LatB_rareret_h3
	s_branch .LatB_rareret_m3
; #define LAS __attribute__((address_space(3)))
; __device__ __forceinline__ float max2f(float a, float b) { float r; asm("v_max_f32_e32 %0, %1, %2" : "=v"(r) : "v"(a), "v"(b)); return r; }
; __device__ __forceinline__ void attn_unit(LAS unsigned char* lds, const bf16_t* Z, bf16_t* A2, const float* tabg, int seq_base, int S, int h, int qb, float lam) {
;     ...
;         if (first || __any(mx > THR)) {
;             { auto rr = __builtin_amdgcn_permlane32_swap(__float_as_uint(mx), __float_as_uint(mx), false, false); mx = max2f(__uint_as_float(rr[0]), __uint_as_float(rr[1])); }
;             const float delta = first ? mx : fmaxf(mx, 0.f);
;             const float alpha = first ? 1.0f : __builtin_amdgcn_exp2f(-delta);
;             mu += delta; ls2 *= alpha;
;             if (!first) {
;                 asm volatile("" ::: "memory");
;                 scr[r32] = alpha;
;                 asm volatile("s_waitcnt lgkmcnt(0)" ::: "memory");
; #pragma unroll
;                 for (int g = 0; g < 4; ++g) { const f32x4 a4 = *(const LAS f32x4*)(scr + 8 * g + 4 * hi);
; #pragma unroll
;                     for (int d = 0; d < 4; ++d) { O[d][4 * g + 0] *= a4[0]; O[d][4 * g + 1] *= a4[1]; O[d][4 * g + 2] *= a4[2]; O[d][4 * g + 3] *= a4[3]; } }
;                 asm volatile("s_waitcnt lgkmcnt(0)" ::: "memory");
;             }
; #pragma unroll
;             for (int r = 0; r < 16; ++r) { p0[r] -= delta; p1[r] -= delta; }
;             asm volatile("" : "+v"(p0), "+v"(p1));
;         }
.LatB_rare_0114:
	v_mov_b32_e32 v252, v251
	s_nop 1
	v_permlane32_swap_b32_e32 v251, v252
	v_max_f32_e32 v251, v251, v252
	v_max_f32_e32 v253, 0, v251
	v_exp_f32_e64 v254, -v253
	v_add_f32_e32 v186, v186, v253
	s_nop 0
	v_mul_f32_e32 v150, v150, v254
	v_mul_f32_e32 v151, v151, v254
	ds_write_b32 v184, v254
	s_waitcnt lgkmcnt(0)
	v_mfma_f32_32x32x16_bf16 v[20:35], v[192:195], v[220:223], v[20:35]
	v_mfma_f32_32x32x16_bf16 v[36:51], v[192:195], v[224:227], v[36:51]
	v_mfma_f32_32x32x16_bf16 v[52:67], v[192:195], v[232:235], v[52:67]
	v_mfma_f32_32x32x16_bf16 v[68:83], v[192:195], v[236:239], v[68:83]
	v_mfma_f32_32x32x16_bf16 v[20:35], v[204:207], v[132:135], v[20:35]
	v_mfma_f32_32x32x16_bf16 v[36:51], v[204:207], v[136:139], v[36:51]
	v_mfma_f32_32x32x16_bf16 v[52:67], v[204:207], v[140:143], v[52:67]
	ds_read_b64_tr_b16 v[144:145], v171 offset:8192
	ds_read_b64_tr_b16 v[146:147], v171 offset:10240
	ds_read_b64_tr_b16 v[220:221], v168 offset:12288
	ds_read_b64_tr_b16 v[222:223], v168 offset:14336
	ds_read_b64_tr_b16 v[224:225], v169 offset:12288
	ds_read_b64_tr_b16 v[226:227], v169 offset:14336
	ds_read_b64_tr_b16 v[232:233], v170 offset:12288
	ds_read_b64_tr_b16 v[234:235], v170 offset:14336
	ds_read_b64_tr_b16 v[236:237], v171 offset:12288
	ds_read_b64_tr_b16 v[238:239], v171 offset:14336
	s_waitcnt lgkmcnt(0)
	v_mfma_f32_32x32x16_bf16 v[68:83], v[204:207], v[144:147], v[68:83]
	v_mfma_f32_32x32x16_bf16 v[20:35], v[208:211], v[220:223], v[20:35]
	v_mfma_f32_32x32x16_bf16 v[36:51], v[208:211], v[224:227], v[36:51]
	v_mfma_f32_32x32x16_bf16 v[52:67], v[208:211], v[232:235], v[52:67]
	v_mfma_f32_32x32x16_bf16 v[68:83], v[208:211], v[236:239], v[68:83]
	ds_read_b128 v[196:199], v185
	ds_read_b128 v[200:203], v185 offset:32
	ds_read_b128 v[212:215], v185 offset:64
	ds_read_b128 v[216:219], v185 offset:96
	s_waitcnt lgkmcnt(0)
	s_nop 15
	s_nop 15
	v_pk_mul_f32 v[20:21], v[20:21], v[196:197]
	v_pk_mul_f32 v[22:23], v[22:23], v[198:199]
	v_pk_mul_f32 v[24:25], v[24:25], v[200:201]
	v_pk_mul_f32 v[26:27], v[26:27], v[202:203]
	v_pk_mul_f32 v[28:29], v[28:29], v[212:213]
	v_pk_mul_f32 v[30:31], v[30:31], v[214:215]
	v_pk_mul_f32 v[32:33], v[32:33], v[216:217]
	v_pk_mul_f32 v[34:35], v[34:35], v[218:219]
	v_pk_mul_f32 v[36:37], v[36:37], v[196:197]
	v_pk_mul_f32 v[38:39], v[38:39], v[198:199]
	v_pk_mul_f32 v[40:41], v[40:41], v[200:201]
	v_pk_mul_f32 v[42:43], v[42:43], v[202:203]
	v_pk_mul_f32 v[44:45], v[44:45], v[212:213]
	v_pk_mul_f32 v[46:47], v[46:47], v[214:215]
	v_pk_mul_f32 v[48:49], v[48:49], v[216:217]
	v_pk_mul_f32 v[50:51], v[50:51], v[218:219]
	v_pk_mul_f32 v[52:53], v[52:53], v[196:197]
	v_pk_mul_f32 v[54:55], v[54:55], v[198:199]
	v_pk_mul_f32 v[56:57], v[56:57], v[200:201]
	v_pk_mul_f32 v[58:59], v[58:59], v[202:203]
	v_pk_mul_f32 v[60:61], v[60:61], v[212:213]
	v_pk_mul_f32 v[62:63], v[62:63], v[214:215]
	v_pk_mul_f32 v[64:65], v[64:65], v[216:217]
	v_pk_mul_f32 v[66:67], v[66:67], v[218:219]
	v_pk_mul_f32 v[68:69], v[68:69], v[196:197]
	v_pk_mul_f32 v[70:71], v[70:71], v[198:199]
	v_pk_mul_f32 v[72:73], v[72:73], v[200:201]
	v_pk_mul_f32 v[74:75], v[74:75], v[202:203]
	v_pk_mul_f32 v[76:77], v[76:77], v[212:213]
	v_pk_mul_f32 v[78:79], v[78:79], v[214:215]
	v_pk_mul_f32 v[80:81], v[80:81], v[216:217]
	v_pk_mul_f32 v[82:83], v[82:83], v[218:219]
	v_mov_b32_e32 v252, v253
	v_pk_add_f32 v[84:85], v[84:85], v[252:253] neg_lo:[0,1] neg_hi:[0,1]
	v_pk_add_f32 v[86:87], v[86:87], v[252:253] neg_lo:[0,1] neg_hi:[0,1]
	v_pk_add_f32 v[88:89], v[88:89], v[252:253] neg_lo:[0,1] neg_hi:[0,1]
	v_pk_add_f32 v[90:91], v[90:91], v[252:253] neg_lo:[0,1] neg_hi:[0,1]
	v_pk_add_f32 v[92:93], v[92:93], v[252:253] neg_lo:[0,1] neg_hi:[0,1]
	v_pk_add_f32 v[94:95], v[94:95], v[252:253] neg_lo:[0,1] neg_hi:[0,1]
	v_pk_add_f32 v[96:97], v[96:97], v[252:253] neg_lo:[0,1] neg_hi:[0,1]
	v_pk_add_f32 v[98:99], v[98:99], v[252:253] neg_lo:[0,1] neg_hi:[0,1]
	v_pk_add_f32 v[100:101], v[100:101], v[252:253] neg_lo:[0,1] neg_hi:[0,1]
	v_pk_add_f32 v[102:103], v[102:103], v[252:253] neg_lo:[0,1] neg_hi:[0,1]
	v_pk_add_f32 v[104:105], v[104:105], v[252:253] neg_lo:[0,1] neg_hi:[0,1]
	v_pk_add_f32 v[106:107], v[106:107], v[252:253] neg_lo:[0,1] neg_hi:[0,1]
	v_pk_add_f32 v[108:109], v[108:109], v[252:253] neg_lo:[0,1] neg_hi:[0,1]
	v_pk_add_f32 v[110:111], v[110:111], v[252:253] neg_lo:[0,1] neg_hi:[0,1]
	v_pk_add_f32 v[112:113], v[112:113], v[252:253] neg_lo:[0,1] neg_hi:[0,1]
	v_pk_add_f32 v[114:115], v[114:115], v[252:253] neg_lo:[0,1] neg_hi:[0,1]
	v_mov_b64_e32 v[188:189], 0
	v_mov_b64_e32 v[190:191], 0
	v_mov_b64_e32 v[192:193], 0
	v_mov_b64_e32 v[194:195], 0
	v_mov_b64_e32 v[204:205], 0
	v_mov_b64_e32 v[206:207], 0
	v_mov_b64_e32 v[208:209], 0
	v_mov_b64_e32 v[210:211], 0
	s_sub_u32 s5, s8, s4
	s_lshr_b32 s5, s5, 12
	s_sub_u32 s5, s5, 64
	s_add_u32 s29, s5, 64
	s_cmp_lt_u32 s29, s11
	s_cselect_b32 s24, 1, 0
	s_cmp_gt_u32 s29, s31
	s_cselect_b32 s30, 2, 0
	s_or_b32 s24, s24, s30
	s_mov_b32 s35, s24
	v_mov_b32_e32 v251, 0
	s_cmp_eq_u32 s24, 1
	s_cselect_b64 vcc, -1, 0
	v_cndmask_b32_e32 v251, v251, v177, vcc
	s_cmp_eq_u32 s24, 2
	s_cselect_b64 vcc, -1, 0
	v_cndmask_b32_e32 v251, v251, v178, vcc
	v_sub_f32_e32 v2, v251, v186
	v_mov_b32_e32 v3, v2
	v_mov_b64_e32 v[4:5], v[2:3]
	v_mov_b64_e32 v[6:7], v[2:3]
	v_mov_b64_e32 v[8:9], v[2:3]
	v_mov_b64_e32 v[10:11], v[2:3]
	v_mov_b64_e32 v[12:13], v[2:3]
	v_mov_b64_e32 v[14:15], v[2:3]
	v_mov_b64_e32 v[16:17], v[2:3]
	s_nop 1
	s_cmp_eq_u32 s22, 0
	s_cbranch_scc1 .LatB_rareret_m0
	s_branch .LatB_rareret_x4
